# stack + first grid sync as plain counter barrier + GEMM loops: per-phase s_setprio flips removed, one static s_setprio 1 for waves 4-7 per GEMM phase
# speedup vs baseline: 1.0305x; 1.0100x over previous
; #define PG8_STAGE(bufoff, gbase, voff) do { _Pragma("unroll") for (int _i = 0; _i < 2; ++_i) \
;         __builtin_amdgcn_global_load_lds((const unsigned*)((const char*)(gbase) + (voff)[_i]), (LAS unsigned*)(lds + (bufoff) + ldsw + _i * 8192), 16, 0, 0); } while (0)
; #define PG8_BAR __builtin_amdgcn_s_barrier()
; template <class Epi, bool ALIGN_EPI, class Hook = NoHook>
; __device__ __forceinline__ void gemm_phase(LAS unsigned char* lds, const Gemm g, const StaticOrder& S, const Epi& E, const Hook& HK = Hook()) {
;     int tid = threadIdx.x; asm volatile("" : "+v"(tid));
;     const int wid = __builtin_amdgcn_readfirstlane(tid >> 6), lane = tid & 63, wr = wid >> 2, wc = wid & 3, fr = lane & 15, fq = lane >> 4;
;     const int K = g.K, nt = K / BK;
;     unsigned voffA[2], voffB[2];
; #pragma unroll
;     for (int i = 0; i < 2; ++i) { int R, C; stage_rc(tid * 16 + i * 8192, R, C); const int Rb = Epi::PERM ? ((R & ~31) + perm32(R & 31)) : R;
;         voffA[i] = (unsigned)(R * g.lda + C) * 2u; voffB[i] = (unsigned)(Rb * g.ldb + C) * 2u; }
;     const size_t kstep = (size_t)(BK * 2);
;     const size_t hstepA = (size_t)HALF * g.lda * 2, hstepB = (size_t)HALF * g.ldb * 2;
;     const size_t tstepA = 2 * hstepA, tstepB = 2 * hstepB;
;     const unsigned ldsw = (unsigned)wid * 1024u;
;     const int aoff = lds_byte(wr * 64 + fr, fq * 8), boff = lds_byte(wc * 32 + fr, fq * 8);
;     ...
;     Unit cur, nxt; int ui = 0;
;     if (!S.next(0, cur)) return;
;     f32x4 acc[2][2][4][2];
; #pragma unroll
;     for (int a = 0; a < 2; ++a)
; #pragma unroll
;         for (int b = 0; b < 2; ++b)
; #pragma unroll
;             for (int m = 0; m < 4; ++m)
; #pragma unroll
;                 for (int n = 0; n < 2; ++n) acc[a][b][m][n] = (f32x4){0.f, 0.f, 0.f, 0.f};
;     bf16x8 At[4][2], B0[2][2], B1[2][2];
;     const char* cA = (const char*)g.A + (size_t)cur.pm * tstepA; const char* cB = (const char*)g.Bt + (size_t)cur.pn * tstepB;
;     PG8_STAGE(PG8_SB(0, 0), cB, voffB); PG8_STAGE(PG8_SB(0, 1), cB + hstepB, voffB); PG8_STAGE(PG8_SA(0, 0), cA, voffA); PG8_STAGE(PG8_SA(0, 1), cA + hstepA, voffA);
;     if (wr == 1) PG8_BAR;
; __global__ void __launch_bounds__(NWAVES * 64, 2) fwd_megakernel(Args args) {
;     ...
;     grid.sync();
.LBB0_29:
	v_cmp_eq_u32_e32 vcc, 0, v136
	s_waitcnt vmcnt(0) lgkmcnt(0)
	s_barrier
	s_and_saveexec_b64 s[0:1], vcc
	s_cbranch_execz .LBB0_39
	buffer_wbl2 sc1
	s_waitcnt vmcnt(0)
	v_mov_b32_e32 v0, 0xc3700
	v_mov_b32_e32 v1, 1
	global_atomic_add v0, v1, s[62:63]
	s_mov_b32 s4, 0
.Lgsync_spin:
	global_load_dword v2, v0, s[62:63] sc1
	s_waitcnt vmcnt(0)
	v_readfirstlane_b32 s5, v2
	s_nop 3
	s_cmp_ge_u32 s5, s30
	s_cbranch_scc1 .Lgsync_done
	s_sleep 1
	s_add_i32 s4, s4, 1
	s_cmp_lt_u32 s4, 0x200000
	s_cbranch_scc1 .Lgsync_spin
.Lgsync_done:
	buffer_inv sc1
	s_waitcnt vmcnt(0)
.LBB0_39:
	s_or_b64 exec, exec, s[0:1]
	s_add_u32 s48, s62, 0x7c00000
	s_addc_u32 s49, s63, 0
	s_add_u32 s46, s62, 0xbc00000
	s_addc_u32 s47, s63, 0
	s_cmpk_lt_i32 s2, 0xb00
	s_cselect_b64 s[0:1], -1, 0
	v_writelane_b32 v254, s0, 16
	v_mov_b32_e32 v9, v136
	s_barrier
	v_writelane_b32 v254, s1, 17
	s_cmpk_gt_i32 s2, 0xaff
	v_readfirstlane_b32 s1, v9
	v_writelane_b32 v254, s56, 18
	s_nop 1
	v_writelane_b32 v254, s57, 19
	s_cbranch_scc1 .LBB0_55
	v_lshlrev_b32_e32 v0, 4, v9
	v_add_u32_e32 v1, 0x2000, v0
	v_ashrrev_i32_e32 v2, 31, v1
	v_lshrrev_b32_e32 v2, 22, v2
	v_add_u32_e32 v2, v1, v2
	v_ashrrev_i32_e32 v8, 10, v2
	v_mul_i32_i24_e32 v2, 0x400, v8
	v_sub_u32_e32 v1, v1, v2
	v_lshrrev_b32_e32 v2, 4, v1
	v_bitop3_b32 v1, v2, v1, 32 bitop3:0x6c
	v_ashrrev_i32_e32 v2, 31, v1
	v_lshrrev_b32_e32 v2, 26, v2
	v_add_u32_e32 v2, v1, v2
	v_lshlrev_b32_e32 v3, 3, v8
	v_ashrrev_i32_e32 v10, 6, v2
	v_and_b32_e32 v3, -16, v3
	v_add_u32_e32 v3, v10, v3
	v_and_b32_e32 v4, 3, v10
	s_mov_b32 s0, 0xfffe0
	v_lshrrev_b32_e32 v5, 2, v3
	v_lshlrev_b32_e32 v6, 1, v3
	v_and_b32_e32 v2, 0xc0, v2
	v_and_or_b32 v4, v3, s0, v4
	v_and_b32_e32 v5, 4, v5
	v_and_b32_e32 v6, 24, v6
	v_sub_u32_e32 v1, v1, v2
	v_mov_b32_e32 v2, 1
	v_or3_b32 v4, v4, v5, v6
	v_lshlrev_b32_e32 v5, 5, v8
	v_ashrrev_i16_sdwa v1, v2, sext(v1) dst_sel:DWORD dst_unused:UNUSED_PAD src0_sel:DWORD src1_sel:BYTE_0
	v_and_b32_e32 v5, 32, v5
	v_bfe_i32 v11, v1, 0, 16
	v_add_lshl_u32 v1, v5, v11, 1
	v_lshl_add_u32 v128, v4, 12, v1
	v_lshl_add_u32 v130, v3, 12, v1
	v_bfe_i32 v1, v9, 27, 1
	v_lshrrev_b32_e32 v1, 22, v1
	v_add_u32_e32 v1, v0, v1
	v_and_b32_e32 v1, 0xfffffc00, v1
	v_sub_u32_e32 v0, v0, v1
	v_lshrrev_b32_e32 v1, 4, v0
	v_ashrrev_i32_e32 v3, 31, v9
	v_bitop3_b32 v0, v1, v0, 32 bitop3:0x6c
	v_lshrrev_b32_e32 v3, 26, v3
	v_ashrrev_i32_e32 v1, 31, v0
	v_add_u32_e32 v3, v9, v3
	v_lshrrev_b32_e32 v1, 26, v1
	v_ashrrev_i32_e32 v13, 6, v3
	v_add_u32_e32 v1, v0, v1
	v_lshlrev_b32_e32 v3, 3, v13
	v_ashrrev_i32_e32 v12, 6, v1
	v_and_b32_e32 v3, -16, v3
	v_add_u32_e32 v3, v12, v3
	v_and_b32_e32 v4, 3, v12
	s_ashr_i32 s50, s2, 31
	v_and_or_b32 v4, v3, s0, v4
	s_lshr_b32 s0, s50, 29
	s_add_i32 s0, s2, s0
	s_ashr_i32 s6, s1, 6
	s_ashr_i32 s4, s0, 3
	s_and_b32 s0, s0, -8
	s_ashr_i32 s7, s1, 8
	s_lshl_b32 s17, s6, 10
	s_sub_i32 s0, s2, s0
	s_cmp_lt_i32 s0, 0
	s_movk_i32 s51, 0x161
	s_cselect_b32 s5, s51, 0x160
	s_mul_i32 s0, s0, s5
	s_add_i32 s0, s0, s4
	s_mul_hi_i32 s4, s0, 0x2e8ba2e9
	s_lshr_b32 s5, s4, 31
	s_ashr_i32 s4, s4, 6
	s_add_i32 s4, s4, s5
	s_lshl_b32 s5, s4, 3
	s_mulk_i32 s4, 0x160
	s_sub_i32 s4, s0, s4
	s_sext_i32_i16 s0, s4
	s_bfe_u32 s0, s0, 0x3001c
	s_add_i32 s12, s4, s0
	s_sext_i32_i16 s0, s12
	s_and_b32 s12, s12, 0xfff8
	s_sub_i32 s4, s4, s12
	s_sext_i32_i16 s4, s4
	v_lshrrev_b32_e32 v5, 2, v3
	v_lshlrev_b32_e32 v6, 1, v3
	v_and_b32_e32 v1, 0xc0, v1
	s_lshr_b32 s0, s0, 3
	s_add_i32 s82, s5, s4
	v_and_b32_e32 v5, 4, v5
	v_and_b32_e32 v6, 24, v6
	v_sub_u32_e32 v0, v0, v1
	s_ashr_i32 s83, s82, 31
	s_bfe_i64 s[12:13], s[0:1], 0x100000
	v_or3_b32 v4, v4, v5, v6
	v_lshlrev_b32_e32 v5, 5, v13
	v_ashrrev_i16_sdwa v0, v2, sext(v0) dst_sel:DWORD dst_unused:UNUSED_PAD src0_sel:DWORD src1_sel:BYTE_0
	s_lshl_b64 s[4:5], s[82:83], 20
	s_lshl_b64 s[12:13], s[12:13], 20
	v_and_b32_e32 v5, 32, v5
	v_bfe_i32 v14, v0, 0, 16
	s_add_u32 s86, s66, s12
	v_add_lshl_u32 v0, v5, v14, 1
	s_addc_u32 s87, s67, s13
	s_add_i32 s71, s17, 0
	v_lshl_add_u32 v132, v4, 12, v0
	s_add_i32 m0, s71, 0x10000
	v_lshl_add_u32 v134, v3, 12, v0
	global_load_lds_dwordx4 v132, s[86:87]
	s_add_i32 m0, s71, 0x12000
	s_add_u32 s12, s86, 0x80000
	global_load_lds_dwordx4 v128, s[86:87]
	s_addc_u32 s13, s87, 0
	s_add_i32 m0, s71, 0x14000
	v_mov_b32_e32 v133, 0
	global_load_lds_dwordx4 v132, s[12:13]
	s_add_i32 m0, s71, 0x16000
	s_add_u32 s84, s48, s4
	s_addc_u32 s85, s49, s5
	s_add_i32 s72, s71, 0x2000
	global_load_lds_dwordx4 v128, s[12:13]
	s_mov_b32 m0, s71
	s_add_u32 s4, s84, 0x80000
	global_load_lds_dwordx4 v134, s[84:85]
	s_mov_b32 m0, s72
	s_addc_u32 s5, s85, 0
	s_add_i32 s73, s71, 0x4000
	global_load_lds_dwordx4 v130, s[84:85]
	s_mov_b32 m0, s73
	s_add_i32 s83, s71, 0x6000
	global_load_lds_dwordx4 v134, s[4:5]
	s_mov_b32 m0, s83
	v_mov_b32_e32 v129, v133
	global_load_lds_dwordx4 v130, s[4:5]
	v_mov_b32_e32 v135, v133
	v_mov_b32_e32 v131, v133
	s_cmp_eq_u32 s7, 1
	s_mov_b32 s90, 0
	v_lshl_add_u64 v[6:7], s[86:87], 0, v[132:133]
	v_lshl_add_u64 v[4:5], s[86:87], 0, v[128:129]
	v_lshl_add_u64 v[0:1], s[84:85], 0, v[134:135]
	s_cselect_b64 s[4:5], -1, 0
	s_cmp_lg_u32 s7, 1
	v_lshl_add_u64 v[2:3], s[84:85], 0, v[130:131]
	s_cbranch_scc1 .LBB0_42
	s_barrier
	s_setprio 1

; #define PG8_STAGE(bufoff, gbase, voff) do { _Pragma("unroll") for (int _i = 0; _i < 2; ++_i) \
;         __builtin_amdgcn_global_load_lds((const unsigned*)((const char*)(gbase) + (voff)[_i]), (LAS unsigned*)(lds + (bufoff) + ldsw + _i * 8192), 16, 0, 0); } while (0)
; #define PG8_LDA(dst, b, h) do { _Pragma("unroll") for (int m = 0; m < 4; ++m) _Pragma("unroll") for (int k = 0; k < 2; ++k) dst[m][k] = *(const LAS bf16x8*)(lds + PG8_SA(b, h) + aoff + m * 2048 + k * 1024); } while (0)
; #define PG8_LDB(dst, b, h) do { _Pragma("unroll") for (int n = 0; n < 2; ++n) _Pragma("unroll") for (int k = 0; k < 2; ++k) dst[n][k] = *(const LAS bf16x8*)(lds + PG8_SB(b, h) + boff + n * 2048 + k * 1024); } while (0)
; #define PG8_MMA(ai, bj, At, Bt) do { __builtin_amdgcn_s_setprio(1); _Pragma("unroll") for (int m = 0; m < 4; ++m) _Pragma("unroll") for (int n = 0; n < 2; ++n) _Pragma("unroll") for (int k = 0; k < 2; ++k) \
;         acc[ai][bj][m][n] = __builtin_amdgcn_mfma_f32_16x16x32_bf16(Bt[n][k], At[m][k], acc[ai][bj][m][n], 0, 0, 0); __builtin_amdgcn_s_setprio(0); } while (0)
; #define PG8_BAR __builtin_amdgcn_s_barrier()
; template <class Epi, bool ALIGN_EPI, class Hook = NoHook>
; __device__ __forceinline__ void gemm_phase(LAS unsigned char* lds, const Gemm g, const StaticOrder& S, const Epi& E, const Hook& HK = Hook()) {
;     ...
;         const bool has_next = S.next(ui + 1, nxt);
;         const char* nA = has_next ? (const char*)g.A + (size_t)nxt.pm * tstepA : cA; const char* nB = has_next ? (const char*)g.Bt + (size_t)nxt.pn * tstepB : cB;
;         for (int t = 0; t < nt; t += 2) {
;             if (Hook::AT > 0 && t == Hook::AT) HK(acc, cur, wr, wc, fr, fq);
;             const bool last = (t == nt - 2);
;             const char* a1 = cA + (size_t)(t + 1) * kstep;
;             const char* a2 = last ? nA : cA + (size_t)(t + 2) * kstep; const char* b2 = last ? nB : cB + (size_t)(t + 2) * kstep;
;             const char* a3 = a2 + kstep; const char* b3 = b2 + kstep;
;             PG8_LDB(B0, 0, 0); PG8_LDB(B1, 0, 1); PG8_SCHED; PG8_LDA(At, 0, 0); PG8_STAGE(PG8_SA(1, 1), a1 + hstepA, voffA);
;             PG8_WAIT_V(8); PG8_WAIT_L(0); PG8_BAR; PG8_MMA(0, 0, At, B0); PG8_MMA(0, 1, At, B1); PG8_BAR; PG8_SCHED;
;             PG8_LDA(At, 0, 1); PG8_STAGE(PG8_SB(0, 0), b2, voffB); PG8_STAGE(PG8_SB(0, 1), b2 + hstepB, voffB); PG8_STAGE(PG8_SA(0, 0), a2, voffA);
.LBB0_47:
	s_ashr_i32 s25, s24, 31
	s_lshl_b64 s[26:27], s[24:25], 20
	s_add_u32 s28, s48, s26
	s_addc_u32 s29, s49, s27
	s_and_b64 s[26:27], s[0:1], exec
	s_cselect_b32 s7, s29, s85
	s_cselect_b32 s25, s28, s84
	s_ashr_i32 s19, s18, 31
	s_lshl_b64 s[26:27], s[18:19], 20
	s_add_u32 s76, s66, s26
	s_addc_u32 s77, s67, s27
	s_and_b64 s[26:27], s[0:1], exec
	s_cselect_b32 s19, s77, s87
	s_cselect_b32 s26, s76, s86
	s_add_u32 s84, s84, 0x80080
	s_addc_u32 s85, s85, 0
	s_add_u32 s27, s86, 0x100
	s_addc_u32 vcc_lo, s87, 0
	s_mov_b32 vcc_hi, -2
	ds_read_b128 v[152:155], v156
	ds_read_b128 v[160:163], v156 offset:1024
	ds_read_b128 v[168:171], v156 offset:2048
	ds_read_b128 v[172:175], v156 offset:3072
	ds_read_b128 v[176:179], v157
	ds_read_b128 v[180:183], v157 offset:1024
	ds_read_b128 v[184:187], v157 offset:2048
	ds_read_b128 v[188:191], v157 offset:3072
	s_add_u32 s34, s84, 0xfff80080
	s_addc_u32 s35, s85, -1
	s_cmp_eq_u32 vcc_hi, 28
	s_cselect_b32 s89, s7, s35
	s_cselect_b32 s88, s25, s34
	s_cselect_b32 s87, s19, vcc_lo
	s_cselect_b32 s86, s26, s27
	v_lshl_add_u64 v[164:165], s[84:85], 0, v[144:145]
	s_add_i32 m0, s71, 0xc000
	ds_read_b128 v[192:195], v158
	ds_read_b128 v[196:199], v158 offset:1024
	ds_read_b128 v[204:207], v158 offset:2048
	ds_read_b128 v[208:211], v158 offset:3072
	ds_read_b128 v[212:215], v158 offset:4096
	ds_read_b128 v[216:219], v158 offset:5120
	ds_read_b128 v[220:223], v158 offset:6144
	ds_read_b128 v[224:227], v158 offset:7168
	global_load_lds_dwordx4 v[164:165], off
	v_lshl_add_u64 v[164:165], s[84:85], 0, v[146:147]
	s_add_i32 m0, s71, 0xe000
	s_nop 0
	global_load_lds_dwordx4 v[164:165], off
	s_waitcnt vmcnt(8)
	s_waitcnt lgkmcnt(0)
	s_barrier
	s_waitcnt lgkmcnt(0)
	v_mfma_f32_16x16x32_bf16 v[124:127], v[152:155], v[192:195], 0
	v_mfma_f32_16x16x32_bf16 v[120:123], v[168:171], v[192:195], 0
	v_mfma_f32_16x16x32_bf16 v[108:111], v[152:155], v[204:207], 0
	v_mfma_f32_16x16x32_bf16 v[104:107], v[168:171], v[204:207], 0
	v_mfma_f32_16x16x32_bf16 v[92:95], v[152:155], v[212:215], 0
	v_mfma_f32_16x16x32_bf16 v[88:91], v[168:171], v[212:215], 0
	v_mfma_f32_16x16x32_bf16 v[76:79], v[152:155], v[220:223], 0
	v_mfma_f32_16x16x32_bf16 v[72:75], v[168:171], v[220:223], 0
	v_mfma_f32_16x16x32_bf16 v[124:127], v[160:163], v[196:199], v[124:127]
	v_mfma_f32_16x16x32_bf16 v[120:123], v[172:175], v[196:199], v[120:123]
	v_mfma_f32_16x16x32_bf16 v[108:111], v[160:163], v[208:211], v[108:111]
	v_mfma_f32_16x16x32_bf16 v[104:107], v[172:175], v[208:211], v[104:107]
	v_mfma_f32_16x16x32_bf16 v[92:95], v[160:163], v[216:219], v[92:95]
	v_mfma_f32_16x16x32_bf16 v[88:91], v[172:175], v[216:219], v[88:91]
	v_mfma_f32_16x16x32_bf16 v[76:79], v[160:163], v[224:227], v[76:79]
	v_mfma_f32_16x16x32_bf16 v[72:75], v[172:175], v[224:227], v[72:75]
	v_mfma_f32_16x16x32_bf16 v[116:119], v[176:179], v[192:195], 0
	v_mfma_f32_16x16x32_bf16 v[112:115], v[184:187], v[192:195], 0
	v_mfma_f32_16x16x32_bf16 v[100:103], v[176:179], v[204:207], 0
	v_mfma_f32_16x16x32_bf16 v[96:99], v[184:187], v[204:207], 0
	v_mfma_f32_16x16x32_bf16 v[84:87], v[176:179], v[212:215], 0
	v_mfma_f32_16x16x32_bf16 v[80:83], v[184:187], v[212:215], 0
	v_mfma_f32_16x16x32_bf16 v[68:71], v[176:179], v[220:223], 0
	v_mfma_f32_16x16x32_bf16 v[64:67], v[184:187], v[220:223], 0
	v_mfma_f32_16x16x32_bf16 v[116:119], v[180:183], v[196:199], v[116:119]
	v_mfma_f32_16x16x32_bf16 v[112:115], v[188:191], v[196:199], v[112:115]
	v_mfma_f32_16x16x32_bf16 v[100:103], v[180:183], v[208:211], v[100:103]
	v_mfma_f32_16x16x32_bf16 v[96:99], v[188:191], v[208:211], v[96:99]
	v_mfma_f32_16x16x32_bf16 v[84:87], v[180:183], v[216:219], v[84:87]
	v_mfma_f32_16x16x32_bf16 v[80:83], v[188:191], v[216:219], v[80:83]
	v_mfma_f32_16x16x32_bf16 v[68:71], v[180:183], v[224:227], v[68:71]
	v_mfma_f32_16x16x32_bf16 v[64:67], v[188:191], v[224:227], v[64:67]
	s_barrier
	s_add_i32 s34, s95, s17
	v_lshl_add_u64 v[164:165], s[86:87], 0, v[132:133]
	s_mov_b32 m0, s34
	ds_read_b128 v[192:195], v158 offset:16384
	ds_read_b128 v[196:199], v158 offset:17408
	ds_read_b128 v[204:207], v158 offset:18432
	ds_read_b128 v[208:211], v158 offset:19456
	ds_read_b128 v[212:215], v158 offset:20480
	ds_read_b128 v[216:219], v158 offset:21504
	ds_read_b128 v[220:223], v158 offset:22528
	ds_read_b128 v[224:227], v158 offset:23552
	global_load_lds_dwordx4 v[164:165], off
	s_add_i32 m0, s34, 0x2000
	s_add_u32 s34, s86, 0x80000
	v_lshl_add_u64 v[228:229], s[86:87], 0, v[128:129]
	s_addc_u32 s35, s87, 0
	s_add_i32 s64, s96, s17
	global_load_lds_dwordx4 v[228:229], off
	v_lshl_add_u64 v[230:231], s[34:35], 0, v[132:133]
	s_mov_b32 m0, s64
	v_lshl_add_u64 v[232:233], s[88:89], 0, v[130:131]
	global_load_lds_dwordx4 v[230:231], off
	v_lshl_add_u64 v[230:231], s[34:35], 0, v[128:129]
	s_add_i32 m0, s64, 0x2000
	s_nop 0
	global_load_lds_dwordx4 v[230:231], off
	v_lshl_add_u64 v[230:231], s[88:89], 0, v[134:135]
	s_mov_b32 m0, s71
	s_nop 0
	global_load_lds_dwordx4 v[230:231], off
	s_mov_b32 m0, s72
	s_nop 0
	global_load_lds_dwordx4 v[232:233], off
	s_waitcnt vmcnt(8)
	s_waitcnt lgkmcnt(0)
	s_barrier
; #define PG8_STAGE(bufoff, gbase, voff) do { _Pragma("unroll") for (int _i = 0; _i < 2; ++_i) \
;         __builtin_amdgcn_global_load_lds((const unsigned*)((const char*)(gbase) + (voff)[_i]), (LAS unsigned*)(lds + (bufoff) + ldsw + _i * 8192), 16, 0, 0); } while (0)
; #define PG8_LDA(dst, b, h) do { _Pragma("unroll") for (int m = 0; m < 4; ++m) _Pragma("unroll") for (int k = 0; k < 2; ++k) dst[m][k] = *(const LAS bf16x8*)(lds + PG8_SA(b, h) + aoff + m * 2048 + k * 1024); } while (0)
; #define PG8_LDB(dst, b, h) do { _Pragma("unroll") for (int n = 0; n < 2; ++n) _Pragma("unroll") for (int k = 0; k < 2; ++k) dst[n][k] = *(const LAS bf16x8*)(lds + PG8_SB(b, h) + boff + n * 2048 + k * 1024); } while (0)
; #define PG8_MMA(ai, bj, At, Bt) do { __builtin_amdgcn_s_setprio(1); _Pragma("unroll") for (int m = 0; m < 4; ++m) _Pragma("unroll") for (int n = 0; n < 2; ++n) _Pragma("unroll") for (int k = 0; k < 2; ++k) \
;         acc[ai][bj][m][n] = __builtin_amdgcn_mfma_f32_16x16x32_bf16(Bt[n][k], At[m][k], acc[ai][bj][m][n], 0, 0, 0); __builtin_amdgcn_s_setprio(0); } while (0)
; #define PG8_WAIT_V(n) asm volatile("s_waitcnt vmcnt(" #n ")" ::: "memory")
; #define PG8_WAIT_L(n) asm volatile("s_waitcnt lgkmcnt(" #n ")" ::: "memory")
; #define PG8_BAR __builtin_amdgcn_s_barrier()
; #define PG8_SCHED __builtin_amdgcn_sched_barrier(0)
; template <class Epi, bool ALIGN_EPI, class Hook = NoHook>
; __device__ __forceinline__ void gemm_phase(LAS unsigned char* lds, const Gemm g, const StaticOrder& S, const Epi& E, const Hook& HK = Hook()) {
;     ...
;             PG8_WAIT_V(8); PG8_WAIT_L(0); PG8_BAR; PG8_MMA(1, 0, At, B0); PG8_MMA(1, 1, At, B1); PG8_BAR; PG8_SCHED;
;             PG8_LDB(B0, 1, 0); PG8_LDB(B1, 1, 1); PG8_SCHED; PG8_LDA(At, 1, 0); PG8_STAGE(PG8_SA(0, 1), a2 + hstepA, voffA);
;             PG8_WAIT_V(8); PG8_WAIT_L(0); PG8_BAR; PG8_MMA(0, 0, At, B0); PG8_MMA(0, 1, At, B1); PG8_BAR; PG8_SCHED;
	s_waitcnt lgkmcnt(0)
	v_mfma_f32_16x16x32_bf16 v[60:63], v[152:155], v[192:195], 0
	v_mfma_f32_16x16x32_bf16 v[56:59], v[168:171], v[192:195], 0
	v_mfma_f32_16x16x32_bf16 v[44:47], v[152:155], v[204:207], 0
	v_mfma_f32_16x16x32_bf16 v[40:43], v[168:171], v[204:207], 0
	v_mfma_f32_16x16x32_bf16 v[28:31], v[152:155], v[212:215], 0
	v_mfma_f32_16x16x32_bf16 v[24:27], v[168:171], v[212:215], 0
	v_mfma_f32_16x16x32_bf16 v[12:15], v[152:155], v[220:223], 0
	v_mfma_f32_16x16x32_bf16 v[8:11], v[168:171], v[220:223], 0
	v_mfma_f32_16x16x32_bf16 v[60:63], v[160:163], v[196:199], v[60:63]
	v_mfma_f32_16x16x32_bf16 v[56:59], v[172:175], v[196:199], v[56:59]
	v_mfma_f32_16x16x32_bf16 v[44:47], v[160:163], v[208:211], v[44:47]
	v_mfma_f32_16x16x32_bf16 v[40:43], v[172:175], v[208:211], v[40:43]
	v_mfma_f32_16x16x32_bf16 v[28:31], v[160:163], v[216:219], v[28:31]
	v_mfma_f32_16x16x32_bf16 v[24:27], v[172:175], v[216:219], v[24:27]
	v_mfma_f32_16x16x32_bf16 v[12:15], v[160:163], v[224:227], v[12:15]
	v_mfma_f32_16x16x32_bf16 v[8:11], v[172:175], v[224:227], v[8:11]
	v_mfma_f32_16x16x32_bf16 v[52:55], v[176:179], v[192:195], 0
	v_mfma_f32_16x16x32_bf16 v[48:51], v[184:187], v[192:195], 0
	v_mfma_f32_16x16x32_bf16 v[36:39], v[176:179], v[204:207], 0
	v_mfma_f32_16x16x32_bf16 v[32:35], v[184:187], v[204:207], 0
	v_mfma_f32_16x16x32_bf16 v[20:23], v[176:179], v[212:215], 0
	v_mfma_f32_16x16x32_bf16 v[16:19], v[184:187], v[212:215], 0
	v_mfma_f32_16x16x32_bf16 v[4:7], v[176:179], v[220:223], 0
	v_mfma_f32_16x16x32_bf16 v[0:3], v[184:187], v[220:223], 0
	v_mfma_f32_16x16x32_bf16 v[52:55], v[180:183], v[196:199], v[52:55]
	v_mfma_f32_16x16x32_bf16 v[48:51], v[188:191], v[196:199], v[48:51]
	v_mfma_f32_16x16x32_bf16 v[36:39], v[180:183], v[208:211], v[36:39]
	v_mfma_f32_16x16x32_bf16 v[32:35], v[188:191], v[208:211], v[32:35]
	v_mfma_f32_16x16x32_bf16 v[20:23], v[180:183], v[216:219], v[20:23]
	v_mfma_f32_16x16x32_bf16 v[16:19], v[188:191], v[216:219], v[16:19]
	v_mfma_f32_16x16x32_bf16 v[4:7], v[180:183], v[224:227], v[4:7]
	v_mfma_f32_16x16x32_bf16 v[0:3], v[188:191], v[224:227], v[0:3]
	s_barrier
	s_add_i32 s64, 0, 0x18000
	v_add_u32_e32 v159, s64, v141
	s_add_i32 s52, 0, 0x1c000
	ds_read_b128 v[152:155], v159
	ds_read_b128 v[160:163], v159 offset:1024
	ds_read_b128 v[168:171], v159 offset:2048
	ds_read_b128 v[172:175], v159 offset:3072
	v_add_u32_e32 v159, s52, v141
	ds_read_b128 v[176:179], v159
	ds_read_b128 v[180:183], v159 offset:1024
	ds_read_b128 v[184:187], v159 offset:2048
	ds_read_b128 v[188:191], v159 offset:3072
	s_add_u32 s34, s88, 0x80000
	s_addc_u32 s35, s89, 0
	s_mov_b32 m0, s73
	v_lshl_add_u64 v[234:235], s[34:35], 0, v[134:135]
	ds_read_b128 v[192:195], v158 offset:32768
	ds_read_b128 v[196:199], v158 offset:33792
	ds_read_b128 v[204:207], v158 offset:34816
	ds_read_b128 v[208:211], v158 offset:35840
	ds_read_b128 v[212:215], v158 offset:36864
	ds_read_b128 v[216:219], v158 offset:37888
	ds_read_b128 v[220:223], v158 offset:38912
	ds_read_b128 v[224:227], v158 offset:39936
	global_load_lds_dwordx4 v[234:235], off
	v_lshl_add_u64 v[234:235], s[34:35], 0, v[130:131]
	s_mov_b32 m0, s83
	s_nop 0
	global_load_lds_dwordx4 v[234:235], off
	s_waitcnt vmcnt(8)
	s_waitcnt lgkmcnt(0)
	s_barrier
	s_waitcnt lgkmcnt(0)
	v_mfma_f32_16x16x32_bf16 v[124:127], v[152:155], v[192:195], v[124:127]
	v_mfma_f32_16x16x32_bf16 v[120:123], v[168:171], v[192:195], v[120:123]
	v_mfma_f32_16x16x32_bf16 v[108:111], v[152:155], v[204:207], v[108:111]
	v_mfma_f32_16x16x32_bf16 v[104:107], v[168:171], v[204:207], v[104:107]
	v_mfma_f32_16x16x32_bf16 v[92:95], v[152:155], v[212:215], v[92:95]
	v_mfma_f32_16x16x32_bf16 v[88:91], v[168:171], v[212:215], v[88:91]
	v_mfma_f32_16x16x32_bf16 v[76:79], v[152:155], v[220:223], v[76:79]
	v_mfma_f32_16x16x32_bf16 v[72:75], v[168:171], v[220:223], v[72:75]
	v_mfma_f32_16x16x32_bf16 v[124:127], v[160:163], v[196:199], v[124:127]
	v_mfma_f32_16x16x32_bf16 v[120:123], v[172:175], v[196:199], v[120:123]
	v_mfma_f32_16x16x32_bf16 v[108:111], v[160:163], v[208:211], v[108:111]
	v_mfma_f32_16x16x32_bf16 v[104:107], v[172:175], v[208:211], v[104:107]
	v_mfma_f32_16x16x32_bf16 v[92:95], v[160:163], v[216:219], v[92:95]
	v_mfma_f32_16x16x32_bf16 v[88:91], v[172:175], v[216:219], v[88:91]
	v_mfma_f32_16x16x32_bf16 v[76:79], v[160:163], v[224:227], v[76:79]
	v_mfma_f32_16x16x32_bf16 v[72:75], v[172:175], v[224:227], v[72:75]
	v_mfma_f32_16x16x32_bf16 v[116:119], v[176:179], v[192:195], v[116:119]
	v_mfma_f32_16x16x32_bf16 v[112:115], v[184:187], v[192:195], v[112:115]
	v_mfma_f32_16x16x32_bf16 v[100:103], v[176:179], v[204:207], v[100:103]
	v_mfma_f32_16x16x32_bf16 v[96:99], v[184:187], v[204:207], v[96:99]
	v_mfma_f32_16x16x32_bf16 v[84:87], v[176:179], v[212:215], v[84:87]
	v_mfma_f32_16x16x32_bf16 v[80:83], v[184:187], v[212:215], v[80:83]
	v_mfma_f32_16x16x32_bf16 v[68:71], v[176:179], v[220:223], v[68:71]
	v_mfma_f32_16x16x32_bf16 v[64:67], v[184:187], v[220:223], v[64:67]
	v_mfma_f32_16x16x32_bf16 v[116:119], v[180:183], v[196:199], v[116:119]
	v_mfma_f32_16x16x32_bf16 v[112:115], v[188:191], v[196:199], v[112:115]
	v_mfma_f32_16x16x32_bf16 v[100:103], v[180:183], v[208:211], v[100:103]
	v_mfma_f32_16x16x32_bf16 v[96:99], v[188:191], v[208:211], v[96:99]
	v_mfma_f32_16x16x32_bf16 v[84:87], v[180:183], v[216:219], v[84:87]
	v_mfma_f32_16x16x32_bf16 v[80:83], v[188:191], v[216:219], v[80:83]
	v_mfma_f32_16x16x32_bf16 v[68:71], v[180:183], v[224:227], v[68:71]
	v_mfma_f32_16x16x32_bf16 v[64:67], v[188:191], v[224:227], v[64:67]
	s_barrier
; #define PG8_STAGE(bufoff, gbase, voff) do { _Pragma("unroll") for (int _i = 0; _i < 2; ++_i) \
;         __builtin_amdgcn_global_load_lds((const unsigned*)((const char*)(gbase) + (voff)[_i]), (LAS unsigned*)(lds + (bufoff) + ldsw + _i * 8192), 16, 0, 0); } while (0)
; #define PG8_LDA(dst, b, h) do { _Pragma("unroll") for (int m = 0; m < 4; ++m) _Pragma("unroll") for (int k = 0; k < 2; ++k) dst[m][k] = *(const LAS bf16x8*)(lds + PG8_SA(b, h) + aoff + m * 2048 + k * 1024); } while (0)
; #define PG8_LDB(dst, b, h) do { _Pragma("unroll") for (int n = 0; n < 2; ++n) _Pragma("unroll") for (int k = 0; k < 2; ++k) dst[n][k] = *(const LAS bf16x8*)(lds + PG8_SB(b, h) + boff + n * 2048 + k * 1024); } while (0)
; #define PG8_WAIT_V(n) asm volatile("s_waitcnt vmcnt(" #n ")" ::: "memory")
; #define PG8_BAR __builtin_amdgcn_s_barrier()
; template <class Epi, bool ALIGN_EPI, class Hook = NoHook>
; __device__ __forceinline__ void gemm_phase(LAS unsigned char* lds, const Gemm g, const StaticOrder& S, const Epi& E, const Hook& HK = Hook()) {
;     ...
;             const bool last = (t == nt - 2);
;             const char* a1 = cA + (size_t)(t + 1) * kstep;
;             const char* a2 = last ? nA : cA + (size_t)(t + 2) * kstep; const char* b2 = last ? nB : cB + (size_t)(t + 2) * kstep;
;             const char* a3 = a2 + kstep; const char* b3 = b2 + kstep;
;             PG8_LDB(B0, 0, 0); PG8_LDB(B1, 0, 1); PG8_SCHED; PG8_LDA(At, 0, 0); PG8_STAGE(PG8_SA(1, 1), a1 + hstepA, voffA);
;             PG8_WAIT_V(8); PG8_WAIT_L(0); PG8_BAR; PG8_MMA(0, 0, At, B0); PG8_MMA(0, 1, At, B1); PG8_BAR; PG8_SCHED;
;             PG8_LDA(At, 0, 1); PG8_STAGE(PG8_SB(0, 0), b2, voffB); PG8_STAGE(PG8_SB(0, 1), b2 + hstepB, voffB); PG8_STAGE(PG8_SA(0, 0), a2, voffA);
;             PG8_WAIT_V(8); PG8_WAIT_L(0); PG8_BAR; PG8_MMA(1, 0, At, B0); PG8_MMA(1, 1, At, B1); PG8_BAR; PG8_SCHED;
;             PG8_LDB(B0, 1, 0); PG8_LDB(B1, 1, 1); PG8_SCHED; PG8_LDA(At, 1, 0); PG8_STAGE(PG8_SA(0, 1), a2 + hstepA, voffA);
;             PG8_WAIT_V(8); PG8_WAIT_L(0); PG8_BAR; PG8_MMA(0, 0, At, B0); PG8_MMA(0, 1, At, B1); PG8_BAR; PG8_SCHED;
;             PG8_LDA(At, 1, 1); PG8_STAGE(PG8_SB(1, 0), b3, voffB); PG8_STAGE(PG8_SB(1, 1), b3 + hstepB, voffB); PG8_STAGE(PG8_SA(1, 0), a3, voffA);
;             PG8_WAIT_V(8); PG8_WAIT_L(0); PG8_BAR; PG8_MMA(1, 0, At, B0); PG8_MMA(1, 1, At, B1); PG8_BAR; PG8_SCHED;
	s_add_i32 s34, s64, s17
	v_lshl_add_u64 v[164:165], v[164:165], 0, s[12:13]
	s_mov_b32 m0, s34
	ds_read_b128 v[192:195], v158 offset:49152
	ds_read_b128 v[196:199], v158 offset:50176
	ds_read_b128 v[204:207], v158 offset:51200
	ds_read_b128 v[208:211], v158 offset:52224
	ds_read_b128 v[212:215], v158 offset:53248
	ds_read_b128 v[216:219], v158 offset:54272
	ds_read_b128 v[220:223], v158 offset:55296
	ds_read_b128 v[224:227], v158 offset:56320
	global_load_lds_dwordx4 v[164:165], off
	s_add_i32 m0, s34, 0x2000
	s_add_u32 s34, s86, 0x80080
	v_lshl_add_u64 v[164:165], v[228:229], 0, s[12:13]
	s_addc_u32 s35, s87, 0
	s_add_i32 s52, s52, s17
	global_load_lds_dwordx4 v[164:165], off
	v_lshl_add_u64 v[164:165], s[34:35], 0, v[132:133]
	s_mov_b32 m0, s52
	s_nop 0
	global_load_lds_dwordx4 v[164:165], off
	v_lshl_add_u64 v[164:165], s[34:35], 0, v[128:129]
	s_add_i32 m0, s52, 0x2000
	s_nop 0
	global_load_lds_dwordx4 v[164:165], off
	v_lshl_add_u64 v[164:165], v[230:231], 0, s[12:13]
	s_mov_b32 m0, s91
	s_nop 0
	global_load_lds_dwordx4 v[164:165], off
	v_lshl_add_u64 v[164:165], v[232:233], 0, s[12:13]
	s_mov_b32 m0, s92
	s_nop 0
	global_load_lds_dwordx4 v[164:165], off
	s_waitcnt vmcnt(8)
	s_waitcnt lgkmcnt(0)
	s_barrier
	s_waitcnt lgkmcnt(0)
	v_mfma_f32_16x16x32_bf16 v[60:63], v[152:155], v[192:195], v[60:63]
	v_mfma_f32_16x16x32_bf16 v[56:59], v[168:171], v[192:195], v[56:59]
	v_mfma_f32_16x16x32_bf16 v[44:47], v[152:155], v[204:207], v[44:47]
	v_mfma_f32_16x16x32_bf16 v[40:43], v[168:171], v[204:207], v[40:43]
	v_mfma_f32_16x16x32_bf16 v[28:31], v[152:155], v[212:215], v[28:31]
	v_mfma_f32_16x16x32_bf16 v[24:27], v[168:171], v[212:215], v[24:27]
	v_mfma_f32_16x16x32_bf16 v[12:15], v[152:155], v[220:223], v[12:15]
	v_mfma_f32_16x16x32_bf16 v[8:11], v[168:171], v[220:223], v[8:11]
	v_mfma_f32_16x16x32_bf16 v[60:63], v[160:163], v[196:199], v[60:63]
	v_mfma_f32_16x16x32_bf16 v[56:59], v[172:175], v[196:199], v[56:59]
	v_mfma_f32_16x16x32_bf16 v[44:47], v[160:163], v[208:211], v[44:47]
	v_mfma_f32_16x16x32_bf16 v[40:43], v[172:175], v[208:211], v[40:43]
	v_mfma_f32_16x16x32_bf16 v[28:31], v[160:163], v[216:219], v[28:31]
	v_mfma_f32_16x16x32_bf16 v[24:27], v[172:175], v[216:219], v[24:27]
	v_mfma_f32_16x16x32_bf16 v[12:15], v[160:163], v[224:227], v[12:15]
	v_mfma_f32_16x16x32_bf16 v[8:11], v[172:175], v[224:227], v[8:11]
	v_mfma_f32_16x16x32_bf16 v[52:55], v[176:179], v[192:195], v[52:55]
	v_mfma_f32_16x16x32_bf16 v[48:51], v[184:187], v[192:195], v[48:51]
	v_mfma_f32_16x16x32_bf16 v[36:39], v[176:179], v[204:207], v[36:39]
	v_mfma_f32_16x16x32_bf16 v[32:35], v[184:187], v[204:207], v[32:35]
	v_mfma_f32_16x16x32_bf16 v[20:23], v[176:179], v[212:215], v[20:23]
	v_mfma_f32_16x16x32_bf16 v[16:19], v[184:187], v[212:215], v[16:19]
	v_mfma_f32_16x16x32_bf16 v[4:7], v[176:179], v[220:223], v[4:7]
	v_mfma_f32_16x16x32_bf16 v[0:3], v[184:187], v[220:223], v[0:3]
	v_mfma_f32_16x16x32_bf16 v[52:55], v[180:183], v[196:199], v[52:55]
	v_mfma_f32_16x16x32_bf16 v[48:51], v[188:191], v[196:199], v[48:51]
	v_mfma_f32_16x16x32_bf16 v[36:39], v[180:183], v[208:211], v[36:39]
	v_mfma_f32_16x16x32_bf16 v[32:35], v[188:191], v[208:211], v[32:35]
	v_mfma_f32_16x16x32_bf16 v[20:23], v[180:183], v[216:219], v[20:23]
	v_mfma_f32_16x16x32_bf16 v[16:19], v[188:191], v[216:219], v[16:19]
	v_mfma_f32_16x16x32_bf16 v[4:7], v[180:183], v[224:227], v[4:7]
	v_mfma_f32_16x16x32_bf16 v[0:3], v[188:191], v[224:227], v[0:3]
	s_barrier
	s_add_i32 vcc_hi, vcc_hi, 2
	s_add_u32 s84, s84, 0x100
	s_addc_u32 s85, s85, 0
	s_add_u32 s27, s27, 0x100
	s_addc_u32 vcc_lo, vcc_lo, 0
	s_cmp_gt_u32 vcc_hi, 29
.LBB0_48:
	ds_read_b128 v[152:155], v156
	ds_read_b128 v[160:163], v156 offset:1024
	ds_read_b128 v[168:171], v156 offset:2048
	ds_read_b128 v[172:175], v156 offset:3072
	ds_read_b128 v[176:179], v157
	ds_read_b128 v[180:183], v157 offset:1024
	ds_read_b128 v[184:187], v157 offset:2048
	ds_read_b128 v[188:191], v157 offset:3072
	s_add_u32 s34, s84, 0xfff80080
	s_addc_u32 s35, s85, -1
	s_cmp_eq_u32 vcc_hi, 28
	s_cselect_b32 s89, s7, s35
	s_cselect_b32 s88, s25, s34
	s_cselect_b32 s87, s19, vcc_lo
	s_cselect_b32 s86, s26, s27
	v_lshl_add_u64 v[164:165], s[84:85], 0, v[144:145]
	s_add_i32 m0, s71, 0xc000
	ds_read_b128 v[192:195], v158
	ds_read_b128 v[196:199], v158 offset:1024
	ds_read_b128 v[204:207], v158 offset:2048
	ds_read_b128 v[208:211], v158 offset:3072
	ds_read_b128 v[212:215], v158 offset:4096
	ds_read_b128 v[216:219], v158 offset:5120
	ds_read_b128 v[220:223], v158 offset:6144
	ds_read_b128 v[224:227], v158 offset:7168
	global_load_lds_dwordx4 v[164:165], off
	v_lshl_add_u64 v[164:165], s[84:85], 0, v[146:147]
	s_add_i32 m0, s71, 0xe000
	s_nop 0
	global_load_lds_dwordx4 v[164:165], off
	s_waitcnt vmcnt(8)
	s_waitcnt lgkmcnt(0)
	s_barrier
; #define PG8_STAGE(bufoff, gbase, voff) do { _Pragma("unroll") for (int _i = 0; _i < 2; ++_i) \
;         __builtin_amdgcn_global_load_lds((const unsigned*)((const char*)(gbase) + (voff)[_i]), (LAS unsigned*)(lds + (bufoff) + ldsw + _i * 8192), 16, 0, 0); } while (0)
; #define PG8_LDA(dst, b, h) do { _Pragma("unroll") for (int m = 0; m < 4; ++m) _Pragma("unroll") for (int k = 0; k < 2; ++k) dst[m][k] = *(const LAS bf16x8*)(lds + PG8_SA(b, h) + aoff + m * 2048 + k * 1024); } while (0)
; #define PG8_MMA(ai, bj, At, Bt) do { __builtin_amdgcn_s_setprio(1); _Pragma("unroll") for (int m = 0; m < 4; ++m) _Pragma("unroll") for (int n = 0; n < 2; ++n) _Pragma("unroll") for (int k = 0; k < 2; ++k) \
;         acc[ai][bj][m][n] = __builtin_amdgcn_mfma_f32_16x16x32_bf16(Bt[n][k], At[m][k], acc[ai][bj][m][n], 0, 0, 0); __builtin_amdgcn_s_setprio(0); } while (0)
; #define PG8_WAIT_V(n) asm volatile("s_waitcnt vmcnt(" #n ")" ::: "memory")
; #define PG8_WAIT_L(n) asm volatile("s_waitcnt lgkmcnt(" #n ")" ::: "memory")
; #define PG8_BAR __builtin_amdgcn_s_barrier()
; #define PG8_SCHED __builtin_amdgcn_sched_barrier(0)
; template <class Epi, bool ALIGN_EPI, class Hook = NoHook>
; __device__ __forceinline__ void gemm_phase(LAS unsigned char* lds, const Gemm g, const StaticOrder& S, const Epi& E, const Hook& HK = Hook()) {
;     ...
;             PG8_WAIT_V(8); PG8_WAIT_L(0); PG8_BAR; PG8_MMA(0, 0, At, B0); PG8_MMA(0, 1, At, B1); PG8_BAR; PG8_SCHED;
;             PG8_LDA(At, 0, 1); PG8_STAGE(PG8_SB(0, 0), b2, voffB); PG8_STAGE(PG8_SB(0, 1), b2 + hstepB, voffB); PG8_STAGE(PG8_SA(0, 0), a2, voffA);
;             PG8_WAIT_V(8); PG8_WAIT_L(0); PG8_BAR; PG8_MMA(1, 0, At, B0); PG8_MMA(1, 1, At, B1); PG8_BAR; PG8_SCHED;
	s_waitcnt lgkmcnt(0)
	v_mfma_f32_16x16x32_bf16 v[124:127], v[152:155], v[192:195], v[124:127]
	v_mfma_f32_16x16x32_bf16 v[120:123], v[168:171], v[192:195], v[120:123]
	v_mfma_f32_16x16x32_bf16 v[108:111], v[152:155], v[204:207], v[108:111]
	v_mfma_f32_16x16x32_bf16 v[104:107], v[168:171], v[204:207], v[104:107]
	v_mfma_f32_16x16x32_bf16 v[92:95], v[152:155], v[212:215], v[92:95]
	v_mfma_f32_16x16x32_bf16 v[88:91], v[168:171], v[212:215], v[88:91]
	v_mfma_f32_16x16x32_bf16 v[76:79], v[152:155], v[220:223], v[76:79]
	v_mfma_f32_16x16x32_bf16 v[72:75], v[168:171], v[220:223], v[72:75]
	v_mfma_f32_16x16x32_bf16 v[124:127], v[160:163], v[196:199], v[124:127]
	v_mfma_f32_16x16x32_bf16 v[120:123], v[172:175], v[196:199], v[120:123]
	v_mfma_f32_16x16x32_bf16 v[108:111], v[160:163], v[208:211], v[108:111]
	v_mfma_f32_16x16x32_bf16 v[104:107], v[172:175], v[208:211], v[104:107]
	v_mfma_f32_16x16x32_bf16 v[92:95], v[160:163], v[216:219], v[92:95]
	v_mfma_f32_16x16x32_bf16 v[88:91], v[172:175], v[216:219], v[88:91]
	v_mfma_f32_16x16x32_bf16 v[76:79], v[160:163], v[224:227], v[76:79]
	v_mfma_f32_16x16x32_bf16 v[72:75], v[172:175], v[224:227], v[72:75]
	v_mfma_f32_16x16x32_bf16 v[116:119], v[176:179], v[192:195], v[116:119]
	v_mfma_f32_16x16x32_bf16 v[112:115], v[184:187], v[192:195], v[112:115]
	v_mfma_f32_16x16x32_bf16 v[100:103], v[176:179], v[204:207], v[100:103]
	v_mfma_f32_16x16x32_bf16 v[96:99], v[184:187], v[204:207], v[96:99]
	v_mfma_f32_16x16x32_bf16 v[84:87], v[176:179], v[212:215], v[84:87]
	v_mfma_f32_16x16x32_bf16 v[80:83], v[184:187], v[212:215], v[80:83]
	v_mfma_f32_16x16x32_bf16 v[68:71], v[176:179], v[220:223], v[68:71]
	v_mfma_f32_16x16x32_bf16 v[64:67], v[184:187], v[220:223], v[64:67]
	v_mfma_f32_16x16x32_bf16 v[116:119], v[180:183], v[196:199], v[116:119]
	v_mfma_f32_16x16x32_bf16 v[112:115], v[188:191], v[196:199], v[112:115]
	v_mfma_f32_16x16x32_bf16 v[100:103], v[180:183], v[208:211], v[100:103]
	v_mfma_f32_16x16x32_bf16 v[96:99], v[188:191], v[208:211], v[96:99]
	v_mfma_f32_16x16x32_bf16 v[84:87], v[180:183], v[216:219], v[84:87]
	v_mfma_f32_16x16x32_bf16 v[80:83], v[188:191], v[216:219], v[80:83]
	v_mfma_f32_16x16x32_bf16 v[68:71], v[180:183], v[224:227], v[68:71]
	v_mfma_f32_16x16x32_bf16 v[64:67], v[188:191], v[224:227], v[64:67]
	s_barrier
	s_add_i32 s34, s95, s17
	v_lshl_add_u64 v[164:165], s[86:87], 0, v[132:133]
	s_mov_b32 m0, s34
	ds_read_b128 v[192:195], v158 offset:16384
	ds_read_b128 v[196:199], v158 offset:17408
	ds_read_b128 v[204:207], v158 offset:18432
	ds_read_b128 v[208:211], v158 offset:19456
	ds_read_b128 v[212:215], v158 offset:20480
	ds_read_b128 v[216:219], v158 offset:21504
	ds_read_b128 v[220:223], v158 offset:22528
	ds_read_b128 v[224:227], v158 offset:23552
	global_load_lds_dwordx4 v[164:165], off
	s_add_i32 m0, s34, 0x2000
	s_add_u32 s34, s86, 0x80000
	v_lshl_add_u64 v[228:229], s[86:87], 0, v[128:129]
	s_addc_u32 s35, s87, 0
	s_add_i32 s64, s96, s17
	global_load_lds_dwordx4 v[228:229], off
	v_lshl_add_u64 v[230:231], s[34:35], 0, v[132:133]
	s_mov_b32 m0, s64
	v_lshl_add_u64 v[232:233], s[88:89], 0, v[130:131]
	global_load_lds_dwordx4 v[230:231], off
	v_lshl_add_u64 v[230:231], s[34:35], 0, v[128:129]
	s_add_i32 m0, s64, 0x2000
	s_nop 0
	global_load_lds_dwordx4 v[230:231], off
	v_lshl_add_u64 v[230:231], s[88:89], 0, v[134:135]
	s_mov_b32 m0, s71
	s_nop 0
	global_load_lds_dwordx4 v[230:231], off
	s_mov_b32 m0, s72
	s_nop 0
	global_load_lds_dwordx4 v[232:233], off
	s_waitcnt vmcnt(8)
	s_waitcnt lgkmcnt(0)
	s_barrier
	s_waitcnt lgkmcnt(0)
	v_mfma_f32_16x16x32_bf16 v[60:63], v[152:155], v[192:195], v[60:63]
	v_mfma_f32_16x16x32_bf16 v[56:59], v[168:171], v[192:195], v[56:59]
	v_mfma_f32_16x16x32_bf16 v[44:47], v[152:155], v[204:207], v[44:47]
	v_mfma_f32_16x16x32_bf16 v[40:43], v[168:171], v[204:207], v[40:43]
	v_mfma_f32_16x16x32_bf16 v[28:31], v[152:155], v[212:215], v[28:31]
	v_mfma_f32_16x16x32_bf16 v[24:27], v[168:171], v[212:215], v[24:27]
	v_mfma_f32_16x16x32_bf16 v[12:15], v[152:155], v[220:223], v[12:15]
	v_mfma_f32_16x16x32_bf16 v[8:11], v[168:171], v[220:223], v[8:11]
	v_mfma_f32_16x16x32_bf16 v[60:63], v[160:163], v[196:199], v[60:63]
	v_mfma_f32_16x16x32_bf16 v[56:59], v[172:175], v[196:199], v[56:59]
	v_mfma_f32_16x16x32_bf16 v[44:47], v[160:163], v[208:211], v[44:47]
	v_mfma_f32_16x16x32_bf16 v[40:43], v[172:175], v[208:211], v[40:43]
	v_mfma_f32_16x16x32_bf16 v[28:31], v[160:163], v[216:219], v[28:31]
	v_mfma_f32_16x16x32_bf16 v[24:27], v[172:175], v[216:219], v[24:27]
	v_mfma_f32_16x16x32_bf16 v[12:15], v[160:163], v[224:227], v[12:15]
	v_mfma_f32_16x16x32_bf16 v[8:11], v[172:175], v[224:227], v[8:11]
	v_mfma_f32_16x16x32_bf16 v[52:55], v[176:179], v[192:195], v[52:55]
	v_mfma_f32_16x16x32_bf16 v[48:51], v[184:187], v[192:195], v[48:51]
	v_mfma_f32_16x16x32_bf16 v[36:39], v[176:179], v[204:207], v[36:39]
	v_mfma_f32_16x16x32_bf16 v[32:35], v[184:187], v[204:207], v[32:35]
	v_mfma_f32_16x16x32_bf16 v[20:23], v[176:179], v[212:215], v[20:23]
	v_mfma_f32_16x16x32_bf16 v[16:19], v[184:187], v[212:215], v[16:19]
	v_mfma_f32_16x16x32_bf16 v[4:7], v[176:179], v[220:223], v[4:7]
	v_mfma_f32_16x16x32_bf16 v[0:3], v[184:187], v[220:223], v[0:3]
	v_mfma_f32_16x16x32_bf16 v[52:55], v[180:183], v[196:199], v[52:55]
	v_mfma_f32_16x16x32_bf16 v[48:51], v[188:191], v[196:199], v[48:51]
	v_mfma_f32_16x16x32_bf16 v[36:39], v[180:183], v[208:211], v[36:39]
	v_mfma_f32_16x16x32_bf16 v[32:35], v[188:191], v[208:211], v[32:35]
	v_mfma_f32_16x16x32_bf16 v[20:23], v[180:183], v[216:219], v[20:23]
	v_mfma_f32_16x16x32_bf16 v[16:19], v[188:191], v[216:219], v[16:19]
	v_mfma_f32_16x16x32_bf16 v[4:7], v[180:183], v[224:227], v[4:7]
	v_mfma_f32_16x16x32_bf16 v[0:3], v[188:191], v[224:227], v[0:3]
	s_barrier
; #define PG8_STAGE(bufoff, gbase, voff) do { _Pragma("unroll") for (int _i = 0; _i < 2; ++_i) \
;         __builtin_amdgcn_global_load_lds((const unsigned*)((const char*)(gbase) + (voff)[_i]), (LAS unsigned*)(lds + (bufoff) + ldsw + _i * 8192), 16, 0, 0); } while (0)
; #define PG8_LDA(dst, b, h) do { _Pragma("unroll") for (int m = 0; m < 4; ++m) _Pragma("unroll") for (int k = 0; k < 2; ++k) dst[m][k] = *(const LAS bf16x8*)(lds + PG8_SA(b, h) + aoff + m * 2048 + k * 1024); } while (0)
; #define PG8_LDB(dst, b, h) do { _Pragma("unroll") for (int n = 0; n < 2; ++n) _Pragma("unroll") for (int k = 0; k < 2; ++k) dst[n][k] = *(const LAS bf16x8*)(lds + PG8_SB(b, h) + boff + n * 2048 + k * 1024); } while (0)
; #define PG8_MMA(ai, bj, At, Bt) do { __builtin_amdgcn_s_setprio(1); _Pragma("unroll") for (int m = 0; m < 4; ++m) _Pragma("unroll") for (int n = 0; n < 2; ++n) _Pragma("unroll") for (int k = 0; k < 2; ++k) \
;         acc[ai][bj][m][n] = __builtin_amdgcn_mfma_f32_16x16x32_bf16(Bt[n][k], At[m][k], acc[ai][bj][m][n], 0, 0, 0); __builtin_amdgcn_s_setprio(0); } while (0)
; #define PG8_WAIT_V(n) asm volatile("s_waitcnt vmcnt(" #n ")" ::: "memory")
; #define PG8_WAIT_L(n) asm volatile("s_waitcnt lgkmcnt(" #n ")" ::: "memory")
; #define PG8_BAR __builtin_amdgcn_s_barrier()
; #define PG8_SCHED __builtin_amdgcn_sched_barrier(0)
; template <class Epi, bool ALIGN_EPI, class Hook = NoHook>
; __device__ __forceinline__ void gemm_phase(LAS unsigned char* lds, const Gemm g, const StaticOrder& S, const Epi& E, const Hook& HK = Hook()) {
;     ...
;             PG8_LDB(B0, 1, 0); PG8_LDB(B1, 1, 1); PG8_SCHED; PG8_LDA(At, 1, 0); PG8_STAGE(PG8_SA(0, 1), a2 + hstepA, voffA);
;             PG8_WAIT_V(8); PG8_WAIT_L(0); PG8_BAR; PG8_MMA(0, 0, At, B0); PG8_MMA(0, 1, At, B1); PG8_BAR; PG8_SCHED;
	s_add_i32 s64, 0, 0x18000
	v_add_u32_e32 v159, s64, v141
	s_add_i32 s52, 0, 0x1c000
	ds_read_b128 v[152:155], v159
	ds_read_b128 v[160:163], v159 offset:1024
	ds_read_b128 v[168:171], v159 offset:2048
	ds_read_b128 v[172:175], v159 offset:3072
	v_add_u32_e32 v159, s52, v141
	ds_read_b128 v[176:179], v159
	ds_read_b128 v[180:183], v159 offset:1024
	ds_read_b128 v[184:187], v159 offset:2048
	ds_read_b128 v[188:191], v159 offset:3072
	s_add_u32 s34, s88, 0x80000
	s_addc_u32 s35, s89, 0
	s_mov_b32 m0, s73
	v_lshl_add_u64 v[234:235], s[34:35], 0, v[134:135]
	ds_read_b128 v[192:195], v158 offset:32768
	ds_read_b128 v[196:199], v158 offset:33792
	ds_read_b128 v[204:207], v158 offset:34816
	ds_read_b128 v[208:211], v158 offset:35840
	ds_read_b128 v[212:215], v158 offset:36864
	ds_read_b128 v[216:219], v158 offset:37888
	ds_read_b128 v[220:223], v158 offset:38912
	ds_read_b128 v[224:227], v158 offset:39936
	global_load_lds_dwordx4 v[234:235], off
	v_lshl_add_u64 v[234:235], s[34:35], 0, v[130:131]
	s_mov_b32 m0, s83
	s_nop 0
	global_load_lds_dwordx4 v[234:235], off
	s_waitcnt vmcnt(8)
	s_waitcnt lgkmcnt(0)
	s_barrier
	s_waitcnt lgkmcnt(0)
	v_mfma_f32_16x16x32_bf16 v[124:127], v[152:155], v[192:195], v[124:127]
	v_mfma_f32_16x16x32_bf16 v[120:123], v[168:171], v[192:195], v[120:123]
	v_mfma_f32_16x16x32_bf16 v[108:111], v[152:155], v[204:207], v[108:111]
	v_mfma_f32_16x16x32_bf16 v[104:107], v[168:171], v[204:207], v[104:107]
	v_mfma_f32_16x16x32_bf16 v[92:95], v[152:155], v[212:215], v[92:95]
	v_mfma_f32_16x16x32_bf16 v[88:91], v[168:171], v[212:215], v[88:91]
	v_mfma_f32_16x16x32_bf16 v[76:79], v[152:155], v[220:223], v[76:79]
	v_mfma_f32_16x16x32_bf16 v[72:75], v[168:171], v[220:223], v[72:75]
	v_mfma_f32_16x16x32_bf16 v[124:127], v[160:163], v[196:199], v[124:127]
	v_mfma_f32_16x16x32_bf16 v[120:123], v[172:175], v[196:199], v[120:123]
	v_mfma_f32_16x16x32_bf16 v[108:111], v[160:163], v[208:211], v[108:111]
	v_mfma_f32_16x16x32_bf16 v[104:107], v[172:175], v[208:211], v[104:107]
	v_mfma_f32_16x16x32_bf16 v[92:95], v[160:163], v[216:219], v[92:95]
	v_mfma_f32_16x16x32_bf16 v[88:91], v[172:175], v[216:219], v[88:91]
	v_mfma_f32_16x16x32_bf16 v[76:79], v[160:163], v[224:227], v[76:79]
	v_mfma_f32_16x16x32_bf16 v[72:75], v[172:175], v[224:227], v[72:75]
	v_mfma_f32_16x16x32_bf16 v[116:119], v[176:179], v[192:195], v[116:119]
	v_mfma_f32_16x16x32_bf16 v[112:115], v[184:187], v[192:195], v[112:115]
	v_mfma_f32_16x16x32_bf16 v[100:103], v[176:179], v[204:207], v[100:103]
	v_mfma_f32_16x16x32_bf16 v[96:99], v[184:187], v[204:207], v[96:99]
	v_mfma_f32_16x16x32_bf16 v[84:87], v[176:179], v[212:215], v[84:87]
	v_mfma_f32_16x16x32_bf16 v[80:83], v[184:187], v[212:215], v[80:83]
	v_mfma_f32_16x16x32_bf16 v[68:71], v[176:179], v[220:223], v[68:71]
	v_mfma_f32_16x16x32_bf16 v[64:67], v[184:187], v[220:223], v[64:67]
	v_mfma_f32_16x16x32_bf16 v[116:119], v[180:183], v[196:199], v[116:119]
	v_mfma_f32_16x16x32_bf16 v[112:115], v[188:191], v[196:199], v[112:115]
	v_mfma_f32_16x16x32_bf16 v[100:103], v[180:183], v[208:211], v[100:103]
	v_mfma_f32_16x16x32_bf16 v[96:99], v[188:191], v[208:211], v[96:99]
	v_mfma_f32_16x16x32_bf16 v[84:87], v[180:183], v[216:219], v[84:87]
	v_mfma_f32_16x16x32_bf16 v[80:83], v[188:191], v[216:219], v[80:83]
	v_mfma_f32_16x16x32_bf16 v[68:71], v[180:183], v[224:227], v[68:71]
	v_mfma_f32_16x16x32_bf16 v[64:67], v[188:191], v[224:227], v[64:67]
	s_barrier
; #define PG8_STAGE(bufoff, gbase, voff) do { _Pragma("unroll") for (int _i = 0; _i < 2; ++_i) \
;         __builtin_amdgcn_global_load_lds((const unsigned*)((const char*)(gbase) + (voff)[_i]), (LAS unsigned*)(lds + (bufoff) + ldsw + _i * 8192), 16, 0, 0); } while (0)
; #define PG8_LDA(dst, b, h) do { _Pragma("unroll") for (int m = 0; m < 4; ++m) _Pragma("unroll") for (int k = 0; k < 2; ++k) dst[m][k] = *(const LAS bf16x8*)(lds + PG8_SA(b, h) + aoff + m * 2048 + k * 1024); } while (0)
; #define PG8_MMA(ai, bj, At, Bt) do { __builtin_amdgcn_s_setprio(1); _Pragma("unroll") for (int m = 0; m < 4; ++m) _Pragma("unroll") for (int n = 0; n < 2; ++n) _Pragma("unroll") for (int k = 0; k < 2; ++k) \
;         acc[ai][bj][m][n] = __builtin_amdgcn_mfma_f32_16x16x32_bf16(Bt[n][k], At[m][k], acc[ai][bj][m][n], 0, 0, 0); __builtin_amdgcn_s_setprio(0); } while (0)
; #define PG8_WAIT_V(n) asm volatile("s_waitcnt vmcnt(" #n ")" ::: "memory")
; #define PG8_WAIT_L(n) asm volatile("s_waitcnt lgkmcnt(" #n ")" ::: "memory")
; #define PG8_BAR __builtin_amdgcn_s_barrier()
; #define PG8_SCHED __builtin_amdgcn_sched_barrier(0)
; template <class Epi, bool ALIGN_EPI, class Hook = NoHook>
; __device__ __forceinline__ void gemm_phase(LAS unsigned char* lds, const Gemm g, const StaticOrder& S, const Epi& E, const Hook& HK = Hook()) {
;     ...
;             PG8_LDA(At, 1, 1); PG8_STAGE(PG8_SB(1, 0), b3, voffB); PG8_STAGE(PG8_SB(1, 1), b3 + hstepB, voffB); PG8_STAGE(PG8_SA(1, 0), a3, voffA);
;             PG8_WAIT_V(8); PG8_WAIT_L(0); PG8_BAR; PG8_MMA(1, 0, At, B0); PG8_MMA(1, 1, At, B1); PG8_BAR; PG8_SCHED;
;         }
;         if constexpr (ALIGN_EPI) { if (wr == 0) PG8_BAR; }
	s_add_i32 s34, s64, s17
	v_lshl_add_u64 v[164:165], v[164:165], 0, s[12:13]
	s_mov_b32 m0, s34
	ds_read_b128 v[192:195], v158 offset:49152
	ds_read_b128 v[196:199], v158 offset:50176
	ds_read_b128 v[204:207], v158 offset:51200
	ds_read_b128 v[208:211], v158 offset:52224
	ds_read_b128 v[212:215], v158 offset:53248
	ds_read_b128 v[216:219], v158 offset:54272
	ds_read_b128 v[220:223], v158 offset:55296
	ds_read_b128 v[224:227], v158 offset:56320
	global_load_lds_dwordx4 v[164:165], off
	s_add_i32 m0, s34, 0x2000
	s_add_u32 s34, s86, 0x80080
	v_lshl_add_u64 v[164:165], v[228:229], 0, s[12:13]
	s_addc_u32 s35, s87, 0
	s_add_i32 s52, s52, s17
	global_load_lds_dwordx4 v[164:165], off
	v_lshl_add_u64 v[164:165], s[34:35], 0, v[132:133]
	s_mov_b32 m0, s52
	s_nop 0
	global_load_lds_dwordx4 v[164:165], off
	v_lshl_add_u64 v[164:165], s[34:35], 0, v[128:129]
	s_add_i32 m0, s52, 0x2000
	s_nop 0
	global_load_lds_dwordx4 v[164:165], off
	v_lshl_add_u64 v[164:165], v[230:231], 0, s[12:13]
	s_mov_b32 m0, s91
	s_nop 0
	global_load_lds_dwordx4 v[164:165], off
	v_lshl_add_u64 v[164:165], v[232:233], 0, s[12:13]
	s_mov_b32 m0, s92
	s_nop 0
	global_load_lds_dwordx4 v[164:165], off
	s_waitcnt vmcnt(8)
	s_waitcnt lgkmcnt(0)
	s_barrier
	s_waitcnt lgkmcnt(0)
	v_mfma_f32_16x16x32_bf16 v[60:63], v[152:155], v[192:195], v[60:63]
	v_mfma_f32_16x16x32_bf16 v[56:59], v[168:171], v[192:195], v[56:59]
	v_mfma_f32_16x16x32_bf16 v[44:47], v[152:155], v[204:207], v[44:47]
	v_mfma_f32_16x16x32_bf16 v[40:43], v[168:171], v[204:207], v[40:43]
	v_mfma_f32_16x16x32_bf16 v[28:31], v[152:155], v[212:215], v[28:31]
	v_mfma_f32_16x16x32_bf16 v[24:27], v[168:171], v[212:215], v[24:27]
	v_mfma_f32_16x16x32_bf16 v[12:15], v[152:155], v[220:223], v[12:15]
	v_mfma_f32_16x16x32_bf16 v[8:11], v[168:171], v[220:223], v[8:11]
	v_mfma_f32_16x16x32_bf16 v[60:63], v[160:163], v[196:199], v[60:63]
	v_mfma_f32_16x16x32_bf16 v[56:59], v[172:175], v[196:199], v[56:59]
	v_mfma_f32_16x16x32_bf16 v[44:47], v[160:163], v[208:211], v[44:47]
	v_mfma_f32_16x16x32_bf16 v[40:43], v[172:175], v[208:211], v[40:43]
	v_mfma_f32_16x16x32_bf16 v[28:31], v[160:163], v[216:219], v[28:31]
	v_mfma_f32_16x16x32_bf16 v[24:27], v[172:175], v[216:219], v[24:27]
	v_mfma_f32_16x16x32_bf16 v[12:15], v[160:163], v[224:227], v[12:15]
	v_mfma_f32_16x16x32_bf16 v[8:11], v[172:175], v[224:227], v[8:11]
	v_mfma_f32_16x16x32_bf16 v[52:55], v[176:179], v[192:195], v[52:55]
	v_mfma_f32_16x16x32_bf16 v[48:51], v[184:187], v[192:195], v[48:51]
	v_mfma_f32_16x16x32_bf16 v[36:39], v[176:179], v[204:207], v[36:39]
	v_mfma_f32_16x16x32_bf16 v[32:35], v[184:187], v[204:207], v[32:35]
	v_mfma_f32_16x16x32_bf16 v[20:23], v[176:179], v[212:215], v[20:23]
	v_mfma_f32_16x16x32_bf16 v[16:19], v[184:187], v[212:215], v[16:19]
	v_mfma_f32_16x16x32_bf16 v[4:7], v[176:179], v[220:223], v[4:7]
	v_mfma_f32_16x16x32_bf16 v[0:3], v[184:187], v[220:223], v[0:3]
	v_mfma_f32_16x16x32_bf16 v[52:55], v[180:183], v[196:199], v[52:55]
	v_mfma_f32_16x16x32_bf16 v[48:51], v[188:191], v[196:199], v[48:51]
	v_mfma_f32_16x16x32_bf16 v[36:39], v[180:183], v[208:211], v[36:39]
	v_mfma_f32_16x16x32_bf16 v[32:35], v[188:191], v[208:211], v[32:35]
	v_mfma_f32_16x16x32_bf16 v[20:23], v[180:183], v[216:219], v[20:23]
	v_mfma_f32_16x16x32_bf16 v[16:19], v[188:191], v[216:219], v[16:19]
	v_mfma_f32_16x16x32_bf16 v[4:7], v[180:183], v[224:227], v[4:7]
	v_mfma_f32_16x16x32_bf16 v[0:3], v[188:191], v[224:227], v[0:3]
	s_barrier
	s_add_i32 vcc_hi, vcc_hi, 2
	s_add_u32 s84, s84, 0x100
	s_addc_u32 s85, s85, 0
	s_add_u32 s27, s27, 0x100
	s_addc_u32 vcc_lo, vcc_lo, 0
	s_cmp_gt_u32 vcc_hi, 29
	s_cbranch_scc0 .LBB0_48
	s_and_b64 vcc, exec, s[14:15]
	s_cbranch_vccz .LBB0_51
	s_barrier

; #define PG8_WAIT_V(n) asm volatile("s_waitcnt vmcnt(" #n ")" ::: "memory")
; #define PG8_BAR __builtin_amdgcn_s_barrier()
; template <class Epi, bool ALIGN_EPI, class Hook = NoHook>
; __device__ __forceinline__ void gemm_phase(LAS unsigned char* lds, const Gemm g, const StaticOrder& S, const Epi& E, const Hook& HK = Hook()) {
;     ...
;     PG8_WAIT_V(0);
;     if constexpr (!ALIGN_EPI) { if (wr == 0) PG8_BAR; }
;     PG8_BAR;
.LBB0_54:
	s_setprio 0
	s_waitcnt vmcnt(0)
	v_readlane_b32 s56, v254, 18
	v_readlane_b32 s57, v254, 19
	s_barrier

; #define PG8_STAGE(bufoff, gbase, voff) do { _Pragma("unroll") for (int _i = 0; _i < 2; ++_i) \
;         __builtin_amdgcn_global_load_lds((const unsigned*)((const char*)(gbase) + (voff)[_i]), (LAS unsigned*)(lds + (bufoff) + ldsw + _i * 8192), 16, 0, 0); } while (0)
; #define PG8_BAR __builtin_amdgcn_s_barrier()
; template <class Epi, bool ALIGN_EPI, class Hook = NoHook>
; __device__ __forceinline__ void gemm_phase(LAS unsigned char* lds, const Gemm g, const StaticOrder& S, const Epi& E, const Hook& HK = Hook()) {
;     ...
;     const int wid = __builtin_amdgcn_readfirstlane(tid >> 6), lane = tid & 63, wr = wid >> 2, wc = wid & 3, fr = lane & 15, fq = lane >> 4;
;     const int K = g.K, nt = K / BK;
;     unsigned voffA[2], voffB[2];
; #pragma unroll
;     for (int i = 0; i < 2; ++i) { int R, C; stage_rc(tid * 16 + i * 8192, R, C); const int Rb = Epi::PERM ? ((R & ~31) + perm32(R & 31)) : R;
;         voffA[i] = (unsigned)(R * g.lda + C) * 2u; voffB[i] = (unsigned)(Rb * g.ldb + C) * 2u; }
;     const size_t kstep = (size_t)(BK * 2);
;     const size_t hstepA = (size_t)HALF * g.lda * 2, hstepB = (size_t)HALF * g.ldb * 2;
;     const size_t tstepA = 2 * hstepA, tstepB = 2 * hstepB;
;     const unsigned ldsw = (unsigned)wid * 1024u;
;     const int aoff = lds_byte(wr * 64 + fr, fq * 8), boff = lds_byte(wc * 32 + fr, fq * 8);
;     ...
;     Unit cur, nxt; int ui = 0;
;     if (!S.next(0, cur)) return;
;     f32x4 acc[2][2][4][2];
; #pragma unroll
;     for (int a = 0; a < 2; ++a)
; #pragma unroll
;         for (int b = 0; b < 2; ++b)
; #pragma unroll
;             for (int m = 0; m < 4; ++m)
; #pragma unroll
;                 for (int n = 0; n < 2; ++n) acc[a][b][m][n] = (f32x4){0.f, 0.f, 0.f, 0.f};
;     bf16x8 At[4][2], B0[2][2], B1[2][2];
;     const char* cA = (const char*)g.A + (size_t)cur.pm * tstepA; const char* cB = (const char*)g.Bt + (size_t)cur.pn * tstepB;
;     PG8_STAGE(PG8_SB(0, 0), cB, voffB); PG8_STAGE(PG8_SB(0, 1), cB + hstepB, voffB); PG8_STAGE(PG8_SA(0, 0), cA, voffA); PG8_STAGE(PG8_SA(0, 1), cA + hstepA, voffA);
;     if (wr == 1) PG8_BAR;
.LBB0_112:
	v_ashrrev_i32_e32 v1, 31, v8
	v_lshrrev_b32_e32 v1, 26, v1
	v_add_u32_e32 v1, v8, v1
	v_ashrrev_i32_e32 v9, 6, v1
	v_bfe_i32 v1, v8, 27, 1
	v_lshlrev_b32_e32 v0, 4, v8
	v_lshrrev_b32_e32 v1, 22, v1
	v_add_u32_e32 v1, v0, v1
	v_and_b32_e32 v1, 0xfffffc00, v1
	v_sub_u32_e32 v1, v0, v1
	v_lshrrev_b32_e32 v2, 4, v1
	v_bitop3_b32 v1, v2, v1, 32 bitop3:0x6c
	v_ashrrev_i32_e32 v3, 31, v1
	v_lshrrev_b32_e32 v3, 26, v3
	v_lshlrev_b32_e32 v2, 3, v9
	v_add_u32_e32 v3, v1, v3
	v_and_b32_e32 v2, -16, v2
	v_ashrrev_i32_e32 v10, 6, v3
	v_and_b32_e32 v3, 0xc0, v3
	v_add_u32_e32 v2, v10, v2
	v_lshlrev_b32_e32 v4, 5, v9
	v_sub_u32_e32 v1, v1, v3
	v_mov_b32_e32 v3, 1
	s_ashr_i32 s7, s6, 3
	v_and_b32_e32 v11, 32, v4
	v_ashrrev_i16_sdwa v1, v3, sext(v1) dst_sel:DWORD dst_unused:UNUSED_PAD src0_sel:DWORD src1_sel:BYTE_0
	v_lshlrev_b32_e32 v4, 1, v2
	v_lshrrev_b32_e32 v5, 2, v2
	v_and_b32_e32 v6, 3, v10
	s_mov_b32 s6, 0x7fffe0
	v_bfe_i32 v12, v1, 0, 16
	v_and_b32_e32 v4, 24, v4
	v_and_b32_e32 v5, 4, v5
	v_and_or_b32 v6, v2, s6, v6
	s_movk_i32 s1, 0x1600
	v_add_u32_e32 v1, v11, v12
	v_or3_b32 v4, v6, v5, v4
	v_mul_lo_u32 v2, v2, s1
	v_add_lshl_u32 v144, v1, v2, 1
	v_mul_u32_u24_e32 v2, 0x1600, v4
	v_add_u32_e32 v0, 0x2000, v0
	v_add_lshl_u32 v146, v2, v1, 1
	v_ashrrev_i32_e32 v1, 31, v0
	v_lshrrev_b32_e32 v1, 22, v1
	s_add_i32 s5, s5, s7
	v_add_u32_e32 v1, v0, v1
	s_ashr_i32 s7, s5, 31
	v_ashrrev_i32_e32 v13, 10, v1
	s_lshr_b32 s7, s7, 27
	v_mul_i32_i24_e32 v1, 0x400, v13
	s_add_i32 s7, s5, s7
	v_sub_u32_e32 v0, v0, v1
	s_ashr_i32 s12, s7, 5
	s_andn2_b32 s7, s7, 31
	v_lshrrev_b32_e32 v1, 4, v0
	s_sub_i32 s7, s5, s7
	v_bitop3_b32 v0, v1, v0, 32 bitop3:0x6c
	s_bfe_i32 s5, s7, 0x80000
	v_ashrrev_i32_e32 v2, 31, v0
	s_bfe_u32 s5, s5, 0x2000d
	v_lshrrev_b32_e32 v2, 26, v2
	s_add_i32 s13, s7, s5
	v_lshlrev_b32_e32 v1, 3, v13
	v_add_u32_e32 v2, v0, v2
	s_bfe_i32 s5, s13, 0x80000
	s_and_b32 s13, s13, 0xfc
	v_and_b32_e32 v1, -16, v1
	v_ashrrev_i32_e32 v14, 6, v2
	v_lshlrev_b32_e32 v4, 5, v13
	s_sub_i32 s7, s7, s13
	v_add_u32_e32 v1, v14, v1
	v_and_b32_e32 v15, 32, v4
	v_and_b32_e32 v4, 3, v14
	s_lshl_b32 s12, s12, 2
	s_sext_i32_i16 s14, s5
	s_sext_i32_i8 s7, s7
	v_and_b32_e32 v2, 0xc0, v2
	v_and_or_b32 v4, v1, s6, v4
	s_ashr_i32 s6, s4, 6
	s_add_i32 s92, s12, s7
	s_ashr_i32 s12, s14, 2
	s_ashr_i32 s0, s4, 8
	v_sub_u32_e32 v0, v0, v2
	s_lshl_b32 s27, s6, 10
	s_lshr_b32 s5, s14, 2
	s_mul_hi_i32 s13, s12, 0x2c0000
	s_mul_i32 s12, s12, 0x2c0000
	v_ashrrev_i16_sdwa v0, v3, sext(v0) dst_sel:DWORD dst_unused:UNUSED_PAD src0_sel:DWORD src1_sel:BYTE_0
	v_lshlrev_b32_e32 v2, 1, v1
	v_lshrrev_b32_e32 v3, 2, v1
	s_add_u32 s28, s56, s12
	v_bfe_i32 v16, v0, 0, 16
	v_and_b32_e32 v2, 24, v2
	v_and_b32_e32 v3, 4, v3
	s_addc_u32 s29, s57, s13
	s_add_i32 s50, s27, 0
	v_add_u32_e32 v0, v15, v16
	v_or3_b32 v2, v4, v3, v2
	v_mul_lo_u32 v1, v1, s1
	s_add_i32 m0, s50, 0x10000
	v_add_lshl_u32 v148, v0, v1, 1
	v_mul_u32_u24_e32 v1, 0x1600, v2
	global_load_lds_dwordx4 v146, s[28:29]
	s_add_i32 m0, s50, 0x12000
	v_add_lshl_u32 v150, v1, v0, 1
	s_add_u32 s12, s28, 0x160000
	global_load_lds_dwordx4 v150, s[28:29]
	s_addc_u32 s13, s29, 0
	s_add_i32 m0, s50, 0x14000
	s_mul_i32 s15, s92, 0x2c0000
	global_load_lds_dwordx4 v146, s[12:13]
	s_add_i32 m0, s50, 0x16000
	s_mul_hi_i32 s7, s92, 0x2c0000
	s_add_u32 s24, s46, s15
	s_addc_u32 s25, s47, s7
	s_add_i32 s51, s50, 0x2000
	global_load_lds_dwordx4 v150, s[12:13]
	s_mov_b32 m0, s50
	s_add_u32 s12, s24, 0x160000
	global_load_lds_dwordx4 v144, s[24:25]
	s_mov_b32 m0, s51
	s_addc_u32 s13, s25, 0
	s_add_i32 s71, s50, 0x4000
	global_load_lds_dwordx4 v148, s[24:25]
	s_mov_b32 m0, s71
	s_add_i32 s72, s50, 0x6000
	global_load_lds_dwordx4 v144, s[12:13]
	s_mov_b32 m0, s72
	v_mov_b32_e32 v147, 0
	global_load_lds_dwordx4 v148, s[12:13]
	v_mov_b32_e32 v151, v147
	v_mov_b32_e32 v145, v147
	v_mov_b32_e32 v149, v147
	s_cmp_eq_u32 s0, 1
	s_mov_b32 s73, 0
	v_lshl_add_u64 v[6:7], s[28:29], 0, v[146:147]
	v_lshl_add_u64 v[2:3], s[28:29], 0, v[150:151]
	s_mov_b32 s7, 0x16000
	v_lshl_add_u64 v[0:1], s[24:25], 0, v[144:145]
	s_cselect_b64 s[12:13], -1, 0
	s_cmp_lg_u32 s0, 1
	v_lshl_add_u64 v[4:5], s[24:25], 0, v[148:149]
	s_cbranch_scc1 .LBB0_114
	s_barrier
	s_setprio 1

; #define PG8_STAGE(bufoff, gbase, voff) do { _Pragma("unroll") for (int _i = 0; _i < 2; ++_i) \
;         __builtin_amdgcn_global_load_lds((const unsigned*)((const char*)(gbase) + (voff)[_i]), (LAS unsigned*)(lds + (bufoff) + ldsw + _i * 8192), 16, 0, 0); } while (0)
; #define PG8_LDA(dst, b, h) do { _Pragma("unroll") for (int m = 0; m < 4; ++m) _Pragma("unroll") for (int k = 0; k < 2; ++k) dst[m][k] = *(const LAS bf16x8*)(lds + PG8_SA(b, h) + aoff + m * 2048 + k * 1024); } while (0)
; #define PG8_LDB(dst, b, h) do { _Pragma("unroll") for (int n = 0; n < 2; ++n) _Pragma("unroll") for (int k = 0; k < 2; ++k) dst[n][k] = *(const LAS bf16x8*)(lds + PG8_SB(b, h) + boff + n * 2048 + k * 1024); } while (0)
; #define PG8_MMA(ai, bj, At, Bt) do { __builtin_amdgcn_s_setprio(1); _Pragma("unroll") for (int m = 0; m < 4; ++m) _Pragma("unroll") for (int n = 0; n < 2; ++n) _Pragma("unroll") for (int k = 0; k < 2; ++k) \
;         acc[ai][bj][m][n] = __builtin_amdgcn_mfma_f32_16x16x32_bf16(Bt[n][k], At[m][k], acc[ai][bj][m][n], 0, 0, 0); __builtin_amdgcn_s_setprio(0); } while (0)
; #define PG8_WAIT_V(n) asm volatile("s_waitcnt vmcnt(" #n ")" ::: "memory")
; #define PG8_WAIT_L(n) asm volatile("s_waitcnt lgkmcnt(" #n ")" ::: "memory")
; #define PG8_BAR __builtin_amdgcn_s_barrier()
; #define PG8_SCHED __builtin_amdgcn_sched_barrier(0)
; template <class Epi, bool ALIGN_EPI, class Hook = NoHook>
; __device__ __forceinline__ void gemm_phase(LAS unsigned char* lds, const Gemm g, const StaticOrder& S, const Epi& E, const Hook& HK = Hook()) {
;     ...
;             const bool last = (t == nt - 2);
;             const char* a1 = cA + (size_t)(t + 1) * kstep;
;             const char* a2 = last ? nA : cA + (size_t)(t + 2) * kstep; const char* b2 = last ? nB : cB + (size_t)(t + 2) * kstep;
;             const char* a3 = a2 + kstep; const char* b3 = b2 + kstep;
;             PG8_LDB(B0, 0, 0); PG8_LDB(B1, 0, 1); PG8_SCHED; PG8_LDA(At, 0, 0); PG8_STAGE(PG8_SA(1, 1), a1 + hstepA, voffA);
;             PG8_WAIT_V(8); PG8_WAIT_L(0); PG8_BAR; PG8_MMA(0, 0, At, B0); PG8_MMA(0, 1, At, B1); PG8_BAR; PG8_SCHED;
;             PG8_LDA(At, 0, 1); PG8_STAGE(PG8_SB(0, 0), b2, voffB); PG8_STAGE(PG8_SB(0, 1), b2 + hstepB, voffB); PG8_STAGE(PG8_SA(0, 0), a2, voffA);
.LBB0_127:
	s_add_u32 s6, s28, 0x100
	s_addc_u32 s7, s29, 0
	s_mov_b32 s94, -2
	ds_read_b128 v[128:131], v167
	ds_read_b128 v[132:135], v167 offset:1024
	ds_read_b128 v[160:163], v167 offset:2048
	ds_read_b128 v[170:173], v167 offset:3072
	ds_read_b128 v[174:177], v168
	ds_read_b128 v[178:181], v168 offset:1024
	ds_read_b128 v[182:185], v168 offset:2048
	ds_read_b128 v[186:189], v168 offset:3072
	s_add_u32 s28, s24, 0x100
	s_addc_u32 s29, s25, 0
	s_cmpk_eq_i32 s94, 0x54
	s_cselect_b32 s85, s5, s29
	s_cselect_b32 s84, s4, s28
	s_cselect_b32 s77, s19, s7
	s_cselect_b32 s76, s18, s6
	v_lshl_add_u64 v[164:165], s[24:25], 0, v[152:153]
	s_add_i32 m0, s50, 0xc000
	ds_read_b128 v[190:193], v169
	ds_read_b128 v[194:197], v169 offset:1024
	ds_read_b128 v[204:207], v169 offset:2048
	ds_read_b128 v[208:211], v169 offset:3072
	ds_read_b128 v[212:215], v169 offset:4096
	ds_read_b128 v[216:219], v169 offset:5120
	ds_read_b128 v[220:223], v169 offset:6144
	ds_read_b128 v[224:227], v169 offset:7168
	global_load_lds_dwordx4 v[164:165], off
	v_lshl_add_u64 v[164:165], s[24:25], 0, v[154:155]
	s_add_i32 m0, s50, 0xe000
	s_nop 0
	global_load_lds_dwordx4 v[164:165], off
	s_waitcnt vmcnt(8)
	s_waitcnt lgkmcnt(0)
	s_barrier
	s_waitcnt lgkmcnt(0)
	v_mfma_f32_16x16x32_bf16 v[124:127], v[128:131], v[190:193], 0
	v_mfma_f32_16x16x32_bf16 v[120:123], v[160:163], v[190:193], 0
	v_mfma_f32_16x16x32_bf16 v[116:119], v[128:131], v[204:207], 0
	v_mfma_f32_16x16x32_bf16 v[112:115], v[160:163], v[204:207], 0
	v_mfma_f32_16x16x32_bf16 v[108:111], v[128:131], v[212:215], 0
	v_mfma_f32_16x16x32_bf16 v[100:103], v[160:163], v[212:215], 0
	v_mfma_f32_16x16x32_bf16 v[80:83], v[128:131], v[220:223], 0
	v_mfma_f32_16x16x32_bf16 v[72:75], v[160:163], v[220:223], 0
	v_mfma_f32_16x16x32_bf16 v[124:127], v[132:135], v[194:197], v[124:127]
	v_mfma_f32_16x16x32_bf16 v[120:123], v[170:173], v[194:197], v[120:123]
	v_mfma_f32_16x16x32_bf16 v[116:119], v[132:135], v[208:211], v[116:119]
	v_mfma_f32_16x16x32_bf16 v[112:115], v[170:173], v[208:211], v[112:115]
	v_mfma_f32_16x16x32_bf16 v[108:111], v[132:135], v[216:219], v[108:111]
	v_mfma_f32_16x16x32_bf16 v[100:103], v[170:173], v[216:219], v[100:103]
	v_mfma_f32_16x16x32_bf16 v[80:83], v[132:135], v[224:227], v[80:83]
	v_mfma_f32_16x16x32_bf16 v[72:75], v[170:173], v[224:227], v[72:75]
	v_mfma_f32_16x16x32_bf16 v[104:107], v[174:177], v[190:193], 0
	v_mfma_f32_16x16x32_bf16 v[96:99], v[182:185], v[190:193], 0
	v_mfma_f32_16x16x32_bf16 v[92:95], v[174:177], v[204:207], 0
	v_mfma_f32_16x16x32_bf16 v[88:91], v[182:185], v[204:207], 0
	v_mfma_f32_16x16x32_bf16 v[84:87], v[174:177], v[212:215], 0
	v_mfma_f32_16x16x32_bf16 v[76:79], v[182:185], v[212:215], 0
	v_mfma_f32_16x16x32_bf16 v[68:71], v[174:177], v[220:223], 0
	v_mfma_f32_16x16x32_bf16 v[64:67], v[182:185], v[220:223], 0
	v_mfma_f32_16x16x32_bf16 v[104:107], v[178:181], v[194:197], v[104:107]
	v_mfma_f32_16x16x32_bf16 v[96:99], v[186:189], v[194:197], v[96:99]
	v_mfma_f32_16x16x32_bf16 v[92:95], v[178:181], v[208:211], v[92:95]
	v_mfma_f32_16x16x32_bf16 v[88:91], v[186:189], v[208:211], v[88:91]
	v_mfma_f32_16x16x32_bf16 v[84:87], v[178:181], v[216:219], v[84:87]
	v_mfma_f32_16x16x32_bf16 v[76:79], v[186:189], v[216:219], v[76:79]
	v_mfma_f32_16x16x32_bf16 v[68:71], v[178:181], v[224:227], v[68:71]
	v_mfma_f32_16x16x32_bf16 v[64:67], v[186:189], v[224:227], v[64:67]
	s_barrier
	s_add_i32 s24, s88, s27
	v_lshl_add_u64 v[164:165], s[76:77], 0, v[146:147]
	s_mov_b32 m0, s24
	ds_read_b128 v[190:193], v169 offset:16384
	ds_read_b128 v[194:197], v169 offset:17408
	ds_read_b128 v[204:207], v169 offset:18432
	ds_read_b128 v[208:211], v169 offset:19456
	ds_read_b128 v[212:215], v169 offset:20480
	ds_read_b128 v[216:219], v169 offset:21504
	ds_read_b128 v[220:223], v169 offset:22528
	ds_read_b128 v[224:227], v169 offset:23552
	global_load_lds_dwordx4 v[164:165], off
	s_add_i32 m0, s24, 0x2000
	s_add_u32 s24, s76, 0x160000
	v_lshl_add_u64 v[198:199], s[76:77], 0, v[150:151]
	s_addc_u32 s25, s77, 0
	s_add_i32 s34, s89, s27
	global_load_lds_dwordx4 v[198:199], off
	v_lshl_add_u64 v[228:229], s[24:25], 0, v[146:147]
	s_mov_b32 m0, s34
	v_lshl_add_u64 v[230:231], s[84:85], 0, v[148:149]
	global_load_lds_dwordx4 v[228:229], off
	v_lshl_add_u64 v[228:229], s[24:25], 0, v[150:151]
	s_add_i32 m0, s34, 0x2000
	s_nop 0
	global_load_lds_dwordx4 v[228:229], off
	v_lshl_add_u64 v[228:229], s[84:85], 0, v[144:145]
	s_mov_b32 m0, s50
	s_nop 0
	global_load_lds_dwordx4 v[228:229], off
	s_mov_b32 m0, s51
	s_nop 0
	global_load_lds_dwordx4 v[230:231], off
	s_waitcnt vmcnt(8)
	s_waitcnt lgkmcnt(0)
	s_barrier
; #define PG8_STAGE(bufoff, gbase, voff) do { _Pragma("unroll") for (int _i = 0; _i < 2; ++_i) \
;         __builtin_amdgcn_global_load_lds((const unsigned*)((const char*)(gbase) + (voff)[_i]), (LAS unsigned*)(lds + (bufoff) + ldsw + _i * 8192), 16, 0, 0); } while (0)
; #define PG8_LDA(dst, b, h) do { _Pragma("unroll") for (int m = 0; m < 4; ++m) _Pragma("unroll") for (int k = 0; k < 2; ++k) dst[m][k] = *(const LAS bf16x8*)(lds + PG8_SA(b, h) + aoff + m * 2048 + k * 1024); } while (0)
; #define PG8_LDB(dst, b, h) do { _Pragma("unroll") for (int n = 0; n < 2; ++n) _Pragma("unroll") for (int k = 0; k < 2; ++k) dst[n][k] = *(const LAS bf16x8*)(lds + PG8_SB(b, h) + boff + n * 2048 + k * 1024); } while (0)
; #define PG8_MMA(ai, bj, At, Bt) do { __builtin_amdgcn_s_setprio(1); _Pragma("unroll") for (int m = 0; m < 4; ++m) _Pragma("unroll") for (int n = 0; n < 2; ++n) _Pragma("unroll") for (int k = 0; k < 2; ++k) \
;         acc[ai][bj][m][n] = __builtin_amdgcn_mfma_f32_16x16x32_bf16(Bt[n][k], At[m][k], acc[ai][bj][m][n], 0, 0, 0); __builtin_amdgcn_s_setprio(0); } while (0)
; #define PG8_WAIT_V(n) asm volatile("s_waitcnt vmcnt(" #n ")" ::: "memory")
; #define PG8_WAIT_L(n) asm volatile("s_waitcnt lgkmcnt(" #n ")" ::: "memory")
; #define PG8_BAR __builtin_amdgcn_s_barrier()
; #define PG8_SCHED __builtin_amdgcn_sched_barrier(0)
; template <class Epi, bool ALIGN_EPI, class Hook = NoHook>
; __device__ __forceinline__ void gemm_phase(LAS unsigned char* lds, const Gemm g, const StaticOrder& S, const Epi& E, const Hook& HK = Hook()) {
;     ...
;             PG8_WAIT_V(8); PG8_WAIT_L(0); PG8_BAR; PG8_MMA(1, 0, At, B0); PG8_MMA(1, 1, At, B1); PG8_BAR; PG8_SCHED;
;             PG8_LDB(B0, 1, 0); PG8_LDB(B1, 1, 1); PG8_SCHED; PG8_LDA(At, 1, 0); PG8_STAGE(PG8_SA(0, 1), a2 + hstepA, voffA);
;             PG8_WAIT_V(8); PG8_WAIT_L(0); PG8_BAR; PG8_MMA(0, 0, At, B0); PG8_MMA(0, 1, At, B1); PG8_BAR; PG8_SCHED;
	s_waitcnt lgkmcnt(0)
	v_mfma_f32_16x16x32_bf16 v[60:63], v[128:131], v[190:193], 0
	v_mfma_f32_16x16x32_bf16 v[56:59], v[160:163], v[190:193], 0
	v_mfma_f32_16x16x32_bf16 v[52:55], v[128:131], v[204:207], 0
	v_mfma_f32_16x16x32_bf16 v[48:51], v[160:163], v[204:207], 0
	v_mfma_f32_16x16x32_bf16 v[32:35], v[128:131], v[212:215], 0
	v_mfma_f32_16x16x32_bf16 v[24:27], v[160:163], v[212:215], 0
	v_mfma_f32_16x16x32_bf16 v[16:19], v[128:131], v[220:223], 0
	v_mfma_f32_16x16x32_bf16 v[8:11], v[160:163], v[220:223], 0
	v_mfma_f32_16x16x32_bf16 v[60:63], v[132:135], v[194:197], v[60:63]
	v_mfma_f32_16x16x32_bf16 v[56:59], v[170:173], v[194:197], v[56:59]
	v_mfma_f32_16x16x32_bf16 v[52:55], v[132:135], v[208:211], v[52:55]
	v_mfma_f32_16x16x32_bf16 v[48:51], v[170:173], v[208:211], v[48:51]
	v_mfma_f32_16x16x32_bf16 v[32:35], v[132:135], v[216:219], v[32:35]
	v_mfma_f32_16x16x32_bf16 v[24:27], v[170:173], v[216:219], v[24:27]
	v_mfma_f32_16x16x32_bf16 v[16:19], v[132:135], v[224:227], v[16:19]
	v_mfma_f32_16x16x32_bf16 v[8:11], v[170:173], v[224:227], v[8:11]
	v_mfma_f32_16x16x32_bf16 v[44:47], v[174:177], v[190:193], 0
	v_mfma_f32_16x16x32_bf16 v[40:43], v[182:185], v[190:193], 0
	v_mfma_f32_16x16x32_bf16 v[36:39], v[174:177], v[204:207], 0
	v_mfma_f32_16x16x32_bf16 v[28:31], v[182:185], v[204:207], 0
	v_mfma_f32_16x16x32_bf16 v[20:23], v[174:177], v[212:215], 0
	v_mfma_f32_16x16x32_bf16 v[12:15], v[182:185], v[212:215], 0
	v_mfma_f32_16x16x32_bf16 v[4:7], v[174:177], v[220:223], 0
	v_mfma_f32_16x16x32_bf16 v[0:3], v[182:185], v[220:223], 0
	v_mfma_f32_16x16x32_bf16 v[44:47], v[178:181], v[194:197], v[44:47]
	v_mfma_f32_16x16x32_bf16 v[40:43], v[186:189], v[194:197], v[40:43]
	v_mfma_f32_16x16x32_bf16 v[36:39], v[178:181], v[208:211], v[36:39]
	v_mfma_f32_16x16x32_bf16 v[28:31], v[186:189], v[208:211], v[28:31]
	v_mfma_f32_16x16x32_bf16 v[20:23], v[178:181], v[216:219], v[20:23]
	v_mfma_f32_16x16x32_bf16 v[12:15], v[186:189], v[216:219], v[12:15]
	v_mfma_f32_16x16x32_bf16 v[4:7], v[178:181], v[224:227], v[4:7]
	v_mfma_f32_16x16x32_bf16 v[0:3], v[186:189], v[224:227], v[0:3]
	s_barrier
	s_add_i32 s34, 0, 0x18000
	s_add_i32 s35, 0, 0x1c000
	v_add_u32_e32 v170, s34, v141
	v_add_u32_e32 v186, s35, v141
	ds_read_b128 v[128:131], v170
	ds_read_b128 v[132:135], v170 offset:1024
	ds_read_b128 v[160:163], v170 offset:2048
	ds_read_b128 v[170:173], v170 offset:3072
	ds_read_b128 v[174:177], v186
	ds_read_b128 v[178:181], v186 offset:1024
	ds_read_b128 v[182:185], v186 offset:2048
	ds_read_b128 v[186:189], v186 offset:3072
	s_add_u32 s24, s84, 0x160000
	s_addc_u32 s25, s85, 0
	s_mov_b32 m0, s71
	v_lshl_add_u64 v[232:233], s[24:25], 0, v[144:145]
	ds_read_b128 v[190:193], v169 offset:32768
	ds_read_b128 v[194:197], v169 offset:33792
	ds_read_b128 v[204:207], v169 offset:34816
	ds_read_b128 v[208:211], v169 offset:35840
	ds_read_b128 v[212:215], v169 offset:36864
	ds_read_b128 v[216:219], v169 offset:37888
	ds_read_b128 v[220:223], v169 offset:38912
	ds_read_b128 v[224:227], v169 offset:39936
	global_load_lds_dwordx4 v[232:233], off
	v_lshl_add_u64 v[232:233], s[24:25], 0, v[148:149]
	s_mov_b32 m0, s72
	s_nop 0
	global_load_lds_dwordx4 v[232:233], off
	s_waitcnt vmcnt(8)
	s_waitcnt lgkmcnt(0)
	s_barrier
	s_waitcnt lgkmcnt(0)
	v_mfma_f32_16x16x32_bf16 v[124:127], v[128:131], v[190:193], v[124:127]
	v_mfma_f32_16x16x32_bf16 v[120:123], v[160:163], v[190:193], v[120:123]
	v_mfma_f32_16x16x32_bf16 v[116:119], v[128:131], v[204:207], v[116:119]
	v_mfma_f32_16x16x32_bf16 v[112:115], v[160:163], v[204:207], v[112:115]
	v_mfma_f32_16x16x32_bf16 v[108:111], v[128:131], v[212:215], v[108:111]
	v_mfma_f32_16x16x32_bf16 v[100:103], v[160:163], v[212:215], v[100:103]
	v_mfma_f32_16x16x32_bf16 v[80:83], v[128:131], v[220:223], v[80:83]
	v_mfma_f32_16x16x32_bf16 v[72:75], v[160:163], v[220:223], v[72:75]
	v_mfma_f32_16x16x32_bf16 v[124:127], v[132:135], v[194:197], v[124:127]
	v_mfma_f32_16x16x32_bf16 v[120:123], v[170:173], v[194:197], v[120:123]
	v_mfma_f32_16x16x32_bf16 v[116:119], v[132:135], v[208:211], v[116:119]
	v_mfma_f32_16x16x32_bf16 v[112:115], v[170:173], v[208:211], v[112:115]
	v_mfma_f32_16x16x32_bf16 v[108:111], v[132:135], v[216:219], v[108:111]
	v_mfma_f32_16x16x32_bf16 v[100:103], v[170:173], v[216:219], v[100:103]
	v_mfma_f32_16x16x32_bf16 v[80:83], v[132:135], v[224:227], v[80:83]
	v_mfma_f32_16x16x32_bf16 v[72:75], v[170:173], v[224:227], v[72:75]
	v_mfma_f32_16x16x32_bf16 v[104:107], v[174:177], v[190:193], v[104:107]
	v_mfma_f32_16x16x32_bf16 v[96:99], v[182:185], v[190:193], v[96:99]
	v_mfma_f32_16x16x32_bf16 v[92:95], v[174:177], v[204:207], v[92:95]
	v_mfma_f32_16x16x32_bf16 v[88:91], v[182:185], v[204:207], v[88:91]
	v_mfma_f32_16x16x32_bf16 v[84:87], v[174:177], v[212:215], v[84:87]
	v_mfma_f32_16x16x32_bf16 v[76:79], v[182:185], v[212:215], v[76:79]
	v_mfma_f32_16x16x32_bf16 v[68:71], v[174:177], v[220:223], v[68:71]
	v_mfma_f32_16x16x32_bf16 v[64:67], v[182:185], v[220:223], v[64:67]
	v_mfma_f32_16x16x32_bf16 v[104:107], v[178:181], v[194:197], v[104:107]
	v_mfma_f32_16x16x32_bf16 v[96:99], v[186:189], v[194:197], v[96:99]
	v_mfma_f32_16x16x32_bf16 v[92:95], v[178:181], v[208:211], v[92:95]
	v_mfma_f32_16x16x32_bf16 v[88:91], v[186:189], v[208:211], v[88:91]
	v_mfma_f32_16x16x32_bf16 v[84:87], v[178:181], v[216:219], v[84:87]
	v_mfma_f32_16x16x32_bf16 v[76:79], v[186:189], v[216:219], v[76:79]
	v_mfma_f32_16x16x32_bf16 v[68:71], v[178:181], v[224:227], v[68:71]
	v_mfma_f32_16x16x32_bf16 v[64:67], v[186:189], v[224:227], v[64:67]
	s_barrier
; #define PG8_STAGE(bufoff, gbase, voff) do { _Pragma("unroll") for (int _i = 0; _i < 2; ++_i) \
;         __builtin_amdgcn_global_load_lds((const unsigned*)((const char*)(gbase) + (voff)[_i]), (LAS unsigned*)(lds + (bufoff) + ldsw + _i * 8192), 16, 0, 0); } while (0)
; #define PG8_LDA(dst, b, h) do { _Pragma("unroll") for (int m = 0; m < 4; ++m) _Pragma("unroll") for (int k = 0; k < 2; ++k) dst[m][k] = *(const LAS bf16x8*)(lds + PG8_SA(b, h) + aoff + m * 2048 + k * 1024); } while (0)
; #define PG8_LDB(dst, b, h) do { _Pragma("unroll") for (int n = 0; n < 2; ++n) _Pragma("unroll") for (int k = 0; k < 2; ++k) dst[n][k] = *(const LAS bf16x8*)(lds + PG8_SB(b, h) + boff + n * 2048 + k * 1024); } while (0)
; #define PG8_WAIT_V(n) asm volatile("s_waitcnt vmcnt(" #n ")" ::: "memory")
; #define PG8_BAR __builtin_amdgcn_s_barrier()
; template <class Epi, bool ALIGN_EPI, class Hook = NoHook>
; __device__ __forceinline__ void gemm_phase(LAS unsigned char* lds, const Gemm g, const StaticOrder& S, const Epi& E, const Hook& HK = Hook()) {
;     ...
;             const bool last = (t == nt - 2);
;             const char* a1 = cA + (size_t)(t + 1) * kstep;
;             const char* a2 = last ? nA : cA + (size_t)(t + 2) * kstep; const char* b2 = last ? nB : cB + (size_t)(t + 2) * kstep;
;             const char* a3 = a2 + kstep; const char* b3 = b2 + kstep;
;             PG8_LDB(B0, 0, 0); PG8_LDB(B1, 0, 1); PG8_SCHED; PG8_LDA(At, 0, 0); PG8_STAGE(PG8_SA(1, 1), a1 + hstepA, voffA);
;             PG8_WAIT_V(8); PG8_WAIT_L(0); PG8_BAR; PG8_MMA(0, 0, At, B0); PG8_MMA(0, 1, At, B1); PG8_BAR; PG8_SCHED;
;             PG8_LDA(At, 0, 1); PG8_STAGE(PG8_SB(0, 0), b2, voffB); PG8_STAGE(PG8_SB(0, 1), b2 + hstepB, voffB); PG8_STAGE(PG8_SA(0, 0), a2, voffA);
;             PG8_WAIT_V(8); PG8_WAIT_L(0); PG8_BAR; PG8_MMA(1, 0, At, B0); PG8_MMA(1, 1, At, B1); PG8_BAR; PG8_SCHED;
;             PG8_LDB(B0, 1, 0); PG8_LDB(B1, 1, 1); PG8_SCHED; PG8_LDA(At, 1, 0); PG8_STAGE(PG8_SA(0, 1), a2 + hstepA, voffA);
;             PG8_WAIT_V(8); PG8_WAIT_L(0); PG8_BAR; PG8_MMA(0, 0, At, B0); PG8_MMA(0, 1, At, B1); PG8_BAR; PG8_SCHED;
;             PG8_LDA(At, 1, 1); PG8_STAGE(PG8_SB(1, 0), b3, voffB); PG8_STAGE(PG8_SB(1, 1), b3 + hstepB, voffB); PG8_STAGE(PG8_SA(1, 0), a3, voffA);
;             PG8_WAIT_V(8); PG8_WAIT_L(0); PG8_BAR; PG8_MMA(1, 0, At, B0); PG8_MMA(1, 1, At, B1); PG8_BAR; PG8_SCHED;
	s_add_i32 s24, s34, s27
	v_lshl_add_u64 v[164:165], v[164:165], 0, s[14:15]
	s_mov_b32 m0, s24
	ds_read_b128 v[190:193], v169 offset:49152
	ds_read_b128 v[194:197], v169 offset:50176
	ds_read_b128 v[204:207], v169 offset:51200
	ds_read_b128 v[208:211], v169 offset:52224
	ds_read_b128 v[212:215], v169 offset:53248
	ds_read_b128 v[216:219], v169 offset:54272
	ds_read_b128 v[220:223], v169 offset:55296
	ds_read_b128 v[224:227], v169 offset:56320
	global_load_lds_dwordx4 v[164:165], off
	s_add_i32 m0, s24, 0x2000
	s_add_u32 s24, s76, 0x160080
	v_lshl_add_u64 v[164:165], v[198:199], 0, s[14:15]
	s_addc_u32 s25, s77, 0
	s_add_i32 s34, s35, s27
	global_load_lds_dwordx4 v[164:165], off
	v_lshl_add_u64 v[164:165], s[24:25], 0, v[146:147]
	s_mov_b32 m0, s34
	s_nop 0
	global_load_lds_dwordx4 v[164:165], off
	v_lshl_add_u64 v[164:165], s[24:25], 0, v[150:151]
	s_add_i32 m0, s34, 0x2000
	s_nop 0
	global_load_lds_dwordx4 v[164:165], off
	v_lshl_add_u64 v[164:165], v[228:229], 0, s[14:15]
	s_mov_b32 m0, s82
	s_nop 0
	global_load_lds_dwordx4 v[164:165], off
	v_lshl_add_u64 v[164:165], v[230:231], 0, s[14:15]
	s_mov_b32 m0, s83
	s_nop 0
	global_load_lds_dwordx4 v[164:165], off
	s_waitcnt vmcnt(8)
	s_waitcnt lgkmcnt(0)
	s_barrier
	s_waitcnt lgkmcnt(0)
	v_mfma_f32_16x16x32_bf16 v[60:63], v[128:131], v[190:193], v[60:63]
	v_mfma_f32_16x16x32_bf16 v[56:59], v[160:163], v[190:193], v[56:59]
	v_mfma_f32_16x16x32_bf16 v[52:55], v[128:131], v[204:207], v[52:55]
	v_mfma_f32_16x16x32_bf16 v[48:51], v[160:163], v[204:207], v[48:51]
	v_mfma_f32_16x16x32_bf16 v[32:35], v[128:131], v[212:215], v[32:35]
	v_mfma_f32_16x16x32_bf16 v[24:27], v[160:163], v[212:215], v[24:27]
	v_mfma_f32_16x16x32_bf16 v[16:19], v[128:131], v[220:223], v[16:19]
	v_mfma_f32_16x16x32_bf16 v[8:11], v[160:163], v[220:223], v[8:11]
	v_mfma_f32_16x16x32_bf16 v[60:63], v[132:135], v[194:197], v[60:63]
	v_mfma_f32_16x16x32_bf16 v[56:59], v[170:173], v[194:197], v[56:59]
	v_mfma_f32_16x16x32_bf16 v[52:55], v[132:135], v[208:211], v[52:55]
	v_mfma_f32_16x16x32_bf16 v[48:51], v[170:173], v[208:211], v[48:51]
	v_mfma_f32_16x16x32_bf16 v[32:35], v[132:135], v[216:219], v[32:35]
	v_mfma_f32_16x16x32_bf16 v[24:27], v[170:173], v[216:219], v[24:27]
	v_mfma_f32_16x16x32_bf16 v[16:19], v[132:135], v[224:227], v[16:19]
	v_mfma_f32_16x16x32_bf16 v[8:11], v[170:173], v[224:227], v[8:11]
	v_mfma_f32_16x16x32_bf16 v[44:47], v[174:177], v[190:193], v[44:47]
	v_mfma_f32_16x16x32_bf16 v[40:43], v[182:185], v[190:193], v[40:43]
	v_mfma_f32_16x16x32_bf16 v[36:39], v[174:177], v[204:207], v[36:39]
	v_mfma_f32_16x16x32_bf16 v[28:31], v[182:185], v[204:207], v[28:31]
	v_mfma_f32_16x16x32_bf16 v[20:23], v[174:177], v[212:215], v[20:23]
	v_mfma_f32_16x16x32_bf16 v[12:15], v[182:185], v[212:215], v[12:15]
	v_mfma_f32_16x16x32_bf16 v[4:7], v[174:177], v[220:223], v[4:7]
	v_mfma_f32_16x16x32_bf16 v[0:3], v[182:185], v[220:223], v[0:3]
	v_mfma_f32_16x16x32_bf16 v[44:47], v[178:181], v[194:197], v[44:47]
	v_mfma_f32_16x16x32_bf16 v[40:43], v[186:189], v[194:197], v[40:43]
	v_mfma_f32_16x16x32_bf16 v[36:39], v[178:181], v[208:211], v[36:39]
	v_mfma_f32_16x16x32_bf16 v[28:31], v[186:189], v[208:211], v[28:31]
	v_mfma_f32_16x16x32_bf16 v[20:23], v[178:181], v[216:219], v[20:23]
	v_mfma_f32_16x16x32_bf16 v[12:15], v[186:189], v[216:219], v[12:15]
	v_mfma_f32_16x16x32_bf16 v[4:7], v[178:181], v[224:227], v[4:7]
	v_mfma_f32_16x16x32_bf16 v[0:3], v[186:189], v[224:227], v[0:3]
	s_barrier
	s_add_i32 s94, s94, 2
	s_add_u32 s6, s6, 0x100
	s_addc_u32 s7, s7, 0
	s_cmpk_gt_u32 s94, 0x55
	s_mov_b64 s[24:25], s[28:29]
.LBB0_128:
	ds_read_b128 v[128:131], v167
	ds_read_b128 v[132:135], v167 offset:1024
	ds_read_b128 v[160:163], v167 offset:2048
	ds_read_b128 v[170:173], v167 offset:3072
	ds_read_b128 v[174:177], v168
	ds_read_b128 v[178:181], v168 offset:1024
	ds_read_b128 v[182:185], v168 offset:2048
	ds_read_b128 v[186:189], v168 offset:3072
	s_add_u32 s28, s24, 0x100
	s_addc_u32 s29, s25, 0
	s_cmpk_eq_i32 s94, 0x54
	s_cselect_b32 s85, s5, s29
	s_cselect_b32 s84, s4, s28
	s_cselect_b32 s77, s19, s7
	s_cselect_b32 s76, s18, s6
	v_lshl_add_u64 v[164:165], s[24:25], 0, v[152:153]
	s_add_i32 m0, s50, 0xc000
	ds_read_b128 v[190:193], v169
	ds_read_b128 v[194:197], v169 offset:1024
	ds_read_b128 v[204:207], v169 offset:2048
	ds_read_b128 v[208:211], v169 offset:3072
	ds_read_b128 v[212:215], v169 offset:4096
	ds_read_b128 v[216:219], v169 offset:5120
	ds_read_b128 v[220:223], v169 offset:6144
	ds_read_b128 v[224:227], v169 offset:7168
	global_load_lds_dwordx4 v[164:165], off
	v_lshl_add_u64 v[164:165], s[24:25], 0, v[154:155]
	s_add_i32 m0, s50, 0xe000
	s_nop 0
	global_load_lds_dwordx4 v[164:165], off
	s_waitcnt vmcnt(8)
	s_waitcnt lgkmcnt(0)
	s_barrier
; #define PG8_STAGE(bufoff, gbase, voff) do { _Pragma("unroll") for (int _i = 0; _i < 2; ++_i) \
;         __builtin_amdgcn_global_load_lds((const unsigned*)((const char*)(gbase) + (voff)[_i]), (LAS unsigned*)(lds + (bufoff) + ldsw + _i * 8192), 16, 0, 0); } while (0)
; #define PG8_LDA(dst, b, h) do { _Pragma("unroll") for (int m = 0; m < 4; ++m) _Pragma("unroll") for (int k = 0; k < 2; ++k) dst[m][k] = *(const LAS bf16x8*)(lds + PG8_SA(b, h) + aoff + m * 2048 + k * 1024); } while (0)
; #define PG8_MMA(ai, bj, At, Bt) do { __builtin_amdgcn_s_setprio(1); _Pragma("unroll") for (int m = 0; m < 4; ++m) _Pragma("unroll") for (int n = 0; n < 2; ++n) _Pragma("unroll") for (int k = 0; k < 2; ++k) \
;         acc[ai][bj][m][n] = __builtin_amdgcn_mfma_f32_16x16x32_bf16(Bt[n][k], At[m][k], acc[ai][bj][m][n], 0, 0, 0); __builtin_amdgcn_s_setprio(0); } while (0)
; #define PG8_WAIT_V(n) asm volatile("s_waitcnt vmcnt(" #n ")" ::: "memory")
; #define PG8_WAIT_L(n) asm volatile("s_waitcnt lgkmcnt(" #n ")" ::: "memory")
; #define PG8_BAR __builtin_amdgcn_s_barrier()
; #define PG8_SCHED __builtin_amdgcn_sched_barrier(0)
; template <class Epi, bool ALIGN_EPI, class Hook = NoHook>
; __device__ __forceinline__ void gemm_phase(LAS unsigned char* lds, const Gemm g, const StaticOrder& S, const Epi& E, const Hook& HK = Hook()) {
;     ...
;             PG8_WAIT_V(8); PG8_WAIT_L(0); PG8_BAR; PG8_MMA(0, 0, At, B0); PG8_MMA(0, 1, At, B1); PG8_BAR; PG8_SCHED;
;             PG8_LDA(At, 0, 1); PG8_STAGE(PG8_SB(0, 0), b2, voffB); PG8_STAGE(PG8_SB(0, 1), b2 + hstepB, voffB); PG8_STAGE(PG8_SA(0, 0), a2, voffA);
;             PG8_WAIT_V(8); PG8_WAIT_L(0); PG8_BAR; PG8_MMA(1, 0, At, B0); PG8_MMA(1, 1, At, B1); PG8_BAR; PG8_SCHED;
	s_waitcnt lgkmcnt(0)
	v_mfma_f32_16x16x32_bf16 v[124:127], v[128:131], v[190:193], v[124:127]
	v_mfma_f32_16x16x32_bf16 v[120:123], v[160:163], v[190:193], v[120:123]
	v_mfma_f32_16x16x32_bf16 v[116:119], v[128:131], v[204:207], v[116:119]
	v_mfma_f32_16x16x32_bf16 v[112:115], v[160:163], v[204:207], v[112:115]
	v_mfma_f32_16x16x32_bf16 v[108:111], v[128:131], v[212:215], v[108:111]
	v_mfma_f32_16x16x32_bf16 v[100:103], v[160:163], v[212:215], v[100:103]
	v_mfma_f32_16x16x32_bf16 v[80:83], v[128:131], v[220:223], v[80:83]
	v_mfma_f32_16x16x32_bf16 v[72:75], v[160:163], v[220:223], v[72:75]
	v_mfma_f32_16x16x32_bf16 v[124:127], v[132:135], v[194:197], v[124:127]
	v_mfma_f32_16x16x32_bf16 v[120:123], v[170:173], v[194:197], v[120:123]
	v_mfma_f32_16x16x32_bf16 v[116:119], v[132:135], v[208:211], v[116:119]
	v_mfma_f32_16x16x32_bf16 v[112:115], v[170:173], v[208:211], v[112:115]
	v_mfma_f32_16x16x32_bf16 v[108:111], v[132:135], v[216:219], v[108:111]
	v_mfma_f32_16x16x32_bf16 v[100:103], v[170:173], v[216:219], v[100:103]
	v_mfma_f32_16x16x32_bf16 v[80:83], v[132:135], v[224:227], v[80:83]
	v_mfma_f32_16x16x32_bf16 v[72:75], v[170:173], v[224:227], v[72:75]
	v_mfma_f32_16x16x32_bf16 v[104:107], v[174:177], v[190:193], v[104:107]
	v_mfma_f32_16x16x32_bf16 v[96:99], v[182:185], v[190:193], v[96:99]
	v_mfma_f32_16x16x32_bf16 v[92:95], v[174:177], v[204:207], v[92:95]
	v_mfma_f32_16x16x32_bf16 v[88:91], v[182:185], v[204:207], v[88:91]
	v_mfma_f32_16x16x32_bf16 v[84:87], v[174:177], v[212:215], v[84:87]
	v_mfma_f32_16x16x32_bf16 v[76:79], v[182:185], v[212:215], v[76:79]
	v_mfma_f32_16x16x32_bf16 v[68:71], v[174:177], v[220:223], v[68:71]
	v_mfma_f32_16x16x32_bf16 v[64:67], v[182:185], v[220:223], v[64:67]
	v_mfma_f32_16x16x32_bf16 v[104:107], v[178:181], v[194:197], v[104:107]
	v_mfma_f32_16x16x32_bf16 v[96:99], v[186:189], v[194:197], v[96:99]
	v_mfma_f32_16x16x32_bf16 v[92:95], v[178:181], v[208:211], v[92:95]
	v_mfma_f32_16x16x32_bf16 v[88:91], v[186:189], v[208:211], v[88:91]
	v_mfma_f32_16x16x32_bf16 v[84:87], v[178:181], v[216:219], v[84:87]
	v_mfma_f32_16x16x32_bf16 v[76:79], v[186:189], v[216:219], v[76:79]
	v_mfma_f32_16x16x32_bf16 v[68:71], v[178:181], v[224:227], v[68:71]
	v_mfma_f32_16x16x32_bf16 v[64:67], v[186:189], v[224:227], v[64:67]
	s_barrier
	s_add_i32 s24, s88, s27
	v_lshl_add_u64 v[164:165], s[76:77], 0, v[146:147]
	s_mov_b32 m0, s24
	ds_read_b128 v[190:193], v169 offset:16384
	ds_read_b128 v[194:197], v169 offset:17408
	ds_read_b128 v[204:207], v169 offset:18432
	ds_read_b128 v[208:211], v169 offset:19456
	ds_read_b128 v[212:215], v169 offset:20480
	ds_read_b128 v[216:219], v169 offset:21504
	ds_read_b128 v[220:223], v169 offset:22528
	ds_read_b128 v[224:227], v169 offset:23552
	global_load_lds_dwordx4 v[164:165], off
	s_add_i32 m0, s24, 0x2000
	s_add_u32 s24, s76, 0x160000
	v_lshl_add_u64 v[198:199], s[76:77], 0, v[150:151]
	s_addc_u32 s25, s77, 0
	s_add_i32 s34, s89, s27
	global_load_lds_dwordx4 v[198:199], off
	v_lshl_add_u64 v[228:229], s[24:25], 0, v[146:147]
	s_mov_b32 m0, s34
	v_lshl_add_u64 v[230:231], s[84:85], 0, v[148:149]
	global_load_lds_dwordx4 v[228:229], off
	v_lshl_add_u64 v[228:229], s[24:25], 0, v[150:151]
	s_add_i32 m0, s34, 0x2000
	s_nop 0
	global_load_lds_dwordx4 v[228:229], off
	v_lshl_add_u64 v[228:229], s[84:85], 0, v[144:145]
	s_mov_b32 m0, s50
	s_nop 0
	global_load_lds_dwordx4 v[228:229], off
	s_mov_b32 m0, s51
	s_nop 0
	global_load_lds_dwordx4 v[230:231], off
	s_waitcnt vmcnt(8)
	s_waitcnt lgkmcnt(0)
	s_barrier
	s_waitcnt lgkmcnt(0)
	v_mfma_f32_16x16x32_bf16 v[60:63], v[128:131], v[190:193], v[60:63]
	v_mfma_f32_16x16x32_bf16 v[56:59], v[160:163], v[190:193], v[56:59]
	v_mfma_f32_16x16x32_bf16 v[52:55], v[128:131], v[204:207], v[52:55]
	v_mfma_f32_16x16x32_bf16 v[48:51], v[160:163], v[204:207], v[48:51]
	v_mfma_f32_16x16x32_bf16 v[32:35], v[128:131], v[212:215], v[32:35]
	v_mfma_f32_16x16x32_bf16 v[24:27], v[160:163], v[212:215], v[24:27]
	v_mfma_f32_16x16x32_bf16 v[16:19], v[128:131], v[220:223], v[16:19]
	v_mfma_f32_16x16x32_bf16 v[8:11], v[160:163], v[220:223], v[8:11]
	v_mfma_f32_16x16x32_bf16 v[60:63], v[132:135], v[194:197], v[60:63]
	v_mfma_f32_16x16x32_bf16 v[56:59], v[170:173], v[194:197], v[56:59]
	v_mfma_f32_16x16x32_bf16 v[52:55], v[132:135], v[208:211], v[52:55]
	v_mfma_f32_16x16x32_bf16 v[48:51], v[170:173], v[208:211], v[48:51]
	v_mfma_f32_16x16x32_bf16 v[32:35], v[132:135], v[216:219], v[32:35]
	v_mfma_f32_16x16x32_bf16 v[24:27], v[170:173], v[216:219], v[24:27]
	v_mfma_f32_16x16x32_bf16 v[16:19], v[132:135], v[224:227], v[16:19]
	v_mfma_f32_16x16x32_bf16 v[8:11], v[170:173], v[224:227], v[8:11]
	v_mfma_f32_16x16x32_bf16 v[44:47], v[174:177], v[190:193], v[44:47]
	v_mfma_f32_16x16x32_bf16 v[40:43], v[182:185], v[190:193], v[40:43]
	v_mfma_f32_16x16x32_bf16 v[36:39], v[174:177], v[204:207], v[36:39]
	v_mfma_f32_16x16x32_bf16 v[28:31], v[182:185], v[204:207], v[28:31]
	v_mfma_f32_16x16x32_bf16 v[20:23], v[174:177], v[212:215], v[20:23]
	v_mfma_f32_16x16x32_bf16 v[12:15], v[182:185], v[212:215], v[12:15]
	v_mfma_f32_16x16x32_bf16 v[4:7], v[174:177], v[220:223], v[4:7]
	v_mfma_f32_16x16x32_bf16 v[0:3], v[182:185], v[220:223], v[0:3]
	v_mfma_f32_16x16x32_bf16 v[44:47], v[178:181], v[194:197], v[44:47]
	v_mfma_f32_16x16x32_bf16 v[40:43], v[186:189], v[194:197], v[40:43]
	v_mfma_f32_16x16x32_bf16 v[36:39], v[178:181], v[208:211], v[36:39]
	v_mfma_f32_16x16x32_bf16 v[28:31], v[186:189], v[208:211], v[28:31]
	v_mfma_f32_16x16x32_bf16 v[20:23], v[178:181], v[216:219], v[20:23]
	v_mfma_f32_16x16x32_bf16 v[12:15], v[186:189], v[216:219], v[12:15]
	v_mfma_f32_16x16x32_bf16 v[4:7], v[178:181], v[224:227], v[4:7]
	v_mfma_f32_16x16x32_bf16 v[0:3], v[186:189], v[224:227], v[0:3]
	s_barrier
; #define PG8_STAGE(bufoff, gbase, voff) do { _Pragma("unroll") for (int _i = 0; _i < 2; ++_i) \
;         __builtin_amdgcn_global_load_lds((const unsigned*)((const char*)(gbase) + (voff)[_i]), (LAS unsigned*)(lds + (bufoff) + ldsw + _i * 8192), 16, 0, 0); } while (0)
; #define PG8_LDA(dst, b, h) do { _Pragma("unroll") for (int m = 0; m < 4; ++m) _Pragma("unroll") for (int k = 0; k < 2; ++k) dst[m][k] = *(const LAS bf16x8*)(lds + PG8_SA(b, h) + aoff + m * 2048 + k * 1024); } while (0)
; #define PG8_LDB(dst, b, h) do { _Pragma("unroll") for (int n = 0; n < 2; ++n) _Pragma("unroll") for (int k = 0; k < 2; ++k) dst[n][k] = *(const LAS bf16x8*)(lds + PG8_SB(b, h) + boff + n * 2048 + k * 1024); } while (0)
; #define PG8_MMA(ai, bj, At, Bt) do { __builtin_amdgcn_s_setprio(1); _Pragma("unroll") for (int m = 0; m < 4; ++m) _Pragma("unroll") for (int n = 0; n < 2; ++n) _Pragma("unroll") for (int k = 0; k < 2; ++k) \
;         acc[ai][bj][m][n] = __builtin_amdgcn_mfma_f32_16x16x32_bf16(Bt[n][k], At[m][k], acc[ai][bj][m][n], 0, 0, 0); __builtin_amdgcn_s_setprio(0); } while (0)
; #define PG8_WAIT_V(n) asm volatile("s_waitcnt vmcnt(" #n ")" ::: "memory")
; #define PG8_WAIT_L(n) asm volatile("s_waitcnt lgkmcnt(" #n ")" ::: "memory")
; #define PG8_BAR __builtin_amdgcn_s_barrier()
; #define PG8_SCHED __builtin_amdgcn_sched_barrier(0)
; template <class Epi, bool ALIGN_EPI, class Hook = NoHook>
; __device__ __forceinline__ void gemm_phase(LAS unsigned char* lds, const Gemm g, const StaticOrder& S, const Epi& E, const Hook& HK = Hook()) {
;     ...
;             PG8_LDB(B0, 1, 0); PG8_LDB(B1, 1, 1); PG8_SCHED; PG8_LDA(At, 1, 0); PG8_STAGE(PG8_SA(0, 1), a2 + hstepA, voffA);
;             PG8_WAIT_V(8); PG8_WAIT_L(0); PG8_BAR; PG8_MMA(0, 0, At, B0); PG8_MMA(0, 1, At, B1); PG8_BAR; PG8_SCHED;
	s_add_i32 s34, 0, 0x18000
	s_add_i32 s35, 0, 0x1c000
	v_add_u32_e32 v170, s34, v141
	v_add_u32_e32 v186, s35, v141
	ds_read_b128 v[128:131], v170
	ds_read_b128 v[132:135], v170 offset:1024
	ds_read_b128 v[160:163], v170 offset:2048
	ds_read_b128 v[170:173], v170 offset:3072
	ds_read_b128 v[174:177], v186
	ds_read_b128 v[178:181], v186 offset:1024
	ds_read_b128 v[182:185], v186 offset:2048
	ds_read_b128 v[186:189], v186 offset:3072
	s_add_u32 s24, s84, 0x160000
	s_addc_u32 s25, s85, 0
	s_mov_b32 m0, s71
	v_lshl_add_u64 v[232:233], s[24:25], 0, v[144:145]
	ds_read_b128 v[190:193], v169 offset:32768
	ds_read_b128 v[194:197], v169 offset:33792
	ds_read_b128 v[204:207], v169 offset:34816
	ds_read_b128 v[208:211], v169 offset:35840
	ds_read_b128 v[212:215], v169 offset:36864
	ds_read_b128 v[216:219], v169 offset:37888
	ds_read_b128 v[220:223], v169 offset:38912
	ds_read_b128 v[224:227], v169 offset:39936
	global_load_lds_dwordx4 v[232:233], off
	v_lshl_add_u64 v[232:233], s[24:25], 0, v[148:149]
	s_mov_b32 m0, s72
	s_nop 0
	global_load_lds_dwordx4 v[232:233], off
	s_waitcnt vmcnt(8)
	s_waitcnt lgkmcnt(0)
	s_barrier
	s_waitcnt lgkmcnt(0)
	v_mfma_f32_16x16x32_bf16 v[124:127], v[128:131], v[190:193], v[124:127]
	v_mfma_f32_16x16x32_bf16 v[120:123], v[160:163], v[190:193], v[120:123]
	v_mfma_f32_16x16x32_bf16 v[116:119], v[128:131], v[204:207], v[116:119]
	v_mfma_f32_16x16x32_bf16 v[112:115], v[160:163], v[204:207], v[112:115]
	v_mfma_f32_16x16x32_bf16 v[108:111], v[128:131], v[212:215], v[108:111]
	v_mfma_f32_16x16x32_bf16 v[100:103], v[160:163], v[212:215], v[100:103]
	v_mfma_f32_16x16x32_bf16 v[80:83], v[128:131], v[220:223], v[80:83]
	v_mfma_f32_16x16x32_bf16 v[72:75], v[160:163], v[220:223], v[72:75]
	v_mfma_f32_16x16x32_bf16 v[124:127], v[132:135], v[194:197], v[124:127]
	v_mfma_f32_16x16x32_bf16 v[120:123], v[170:173], v[194:197], v[120:123]
	v_mfma_f32_16x16x32_bf16 v[116:119], v[132:135], v[208:211], v[116:119]
	v_mfma_f32_16x16x32_bf16 v[112:115], v[170:173], v[208:211], v[112:115]
	v_mfma_f32_16x16x32_bf16 v[108:111], v[132:135], v[216:219], v[108:111]
	v_mfma_f32_16x16x32_bf16 v[100:103], v[170:173], v[216:219], v[100:103]
	v_mfma_f32_16x16x32_bf16 v[80:83], v[132:135], v[224:227], v[80:83]
	v_mfma_f32_16x16x32_bf16 v[72:75], v[170:173], v[224:227], v[72:75]
	v_mfma_f32_16x16x32_bf16 v[104:107], v[174:177], v[190:193], v[104:107]
	v_mfma_f32_16x16x32_bf16 v[96:99], v[182:185], v[190:193], v[96:99]
	v_mfma_f32_16x16x32_bf16 v[92:95], v[174:177], v[204:207], v[92:95]
	v_mfma_f32_16x16x32_bf16 v[88:91], v[182:185], v[204:207], v[88:91]
	v_mfma_f32_16x16x32_bf16 v[84:87], v[174:177], v[212:215], v[84:87]
	v_mfma_f32_16x16x32_bf16 v[76:79], v[182:185], v[212:215], v[76:79]
	v_mfma_f32_16x16x32_bf16 v[68:71], v[174:177], v[220:223], v[68:71]
	v_mfma_f32_16x16x32_bf16 v[64:67], v[182:185], v[220:223], v[64:67]
	v_mfma_f32_16x16x32_bf16 v[104:107], v[178:181], v[194:197], v[104:107]
	v_mfma_f32_16x16x32_bf16 v[96:99], v[186:189], v[194:197], v[96:99]
	v_mfma_f32_16x16x32_bf16 v[92:95], v[178:181], v[208:211], v[92:95]
	v_mfma_f32_16x16x32_bf16 v[88:91], v[186:189], v[208:211], v[88:91]
	v_mfma_f32_16x16x32_bf16 v[84:87], v[178:181], v[216:219], v[84:87]
	v_mfma_f32_16x16x32_bf16 v[76:79], v[186:189], v[216:219], v[76:79]
	v_mfma_f32_16x16x32_bf16 v[68:71], v[178:181], v[224:227], v[68:71]
	v_mfma_f32_16x16x32_bf16 v[64:67], v[186:189], v[224:227], v[64:67]
	s_barrier
; #define PG8_STAGE(bufoff, gbase, voff) do { _Pragma("unroll") for (int _i = 0; _i < 2; ++_i) \
;         __builtin_amdgcn_global_load_lds((const unsigned*)((const char*)(gbase) + (voff)[_i]), (LAS unsigned*)(lds + (bufoff) + ldsw + _i * 8192), 16, 0, 0); } while (0)
; #define PG8_LDA(dst, b, h) do { _Pragma("unroll") for (int m = 0; m < 4; ++m) _Pragma("unroll") for (int k = 0; k < 2; ++k) dst[m][k] = *(const LAS bf16x8*)(lds + PG8_SA(b, h) + aoff + m * 2048 + k * 1024); } while (0)
; #define PG8_MMA(ai, bj, At, Bt) do { __builtin_amdgcn_s_setprio(1); _Pragma("unroll") for (int m = 0; m < 4; ++m) _Pragma("unroll") for (int n = 0; n < 2; ++n) _Pragma("unroll") for (int k = 0; k < 2; ++k) \
;         acc[ai][bj][m][n] = __builtin_amdgcn_mfma_f32_16x16x32_bf16(Bt[n][k], At[m][k], acc[ai][bj][m][n], 0, 0, 0); __builtin_amdgcn_s_setprio(0); } while (0)
; #define PG8_WAIT_V(n) asm volatile("s_waitcnt vmcnt(" #n ")" ::: "memory")
; #define PG8_WAIT_L(n) asm volatile("s_waitcnt lgkmcnt(" #n ")" ::: "memory")
; #define PG8_BAR __builtin_amdgcn_s_barrier()
; #define PG8_SCHED __builtin_amdgcn_sched_barrier(0)
; template <class Epi, bool ALIGN_EPI, class Hook = NoHook>
; __device__ __forceinline__ void gemm_phase(LAS unsigned char* lds, const Gemm g, const StaticOrder& S, const Epi& E, const Hook& HK = Hook()) {
;     ...
;             PG8_LDA(At, 1, 1); PG8_STAGE(PG8_SB(1, 0), b3, voffB); PG8_STAGE(PG8_SB(1, 1), b3 + hstepB, voffB); PG8_STAGE(PG8_SA(1, 0), a3, voffA);
;             PG8_WAIT_V(8); PG8_WAIT_L(0); PG8_BAR; PG8_MMA(1, 0, At, B0); PG8_MMA(1, 1, At, B1); PG8_BAR; PG8_SCHED;
;         }
;         if constexpr (ALIGN_EPI) { if (wr == 0) PG8_BAR; }
	s_add_i32 s24, s34, s27
	v_lshl_add_u64 v[164:165], v[164:165], 0, s[14:15]
	s_mov_b32 m0, s24
	ds_read_b128 v[190:193], v169 offset:49152
	ds_read_b128 v[194:197], v169 offset:50176
	ds_read_b128 v[204:207], v169 offset:51200
	ds_read_b128 v[208:211], v169 offset:52224
	ds_read_b128 v[212:215], v169 offset:53248
	ds_read_b128 v[216:219], v169 offset:54272
	ds_read_b128 v[220:223], v169 offset:55296
	ds_read_b128 v[224:227], v169 offset:56320
	global_load_lds_dwordx4 v[164:165], off
	s_add_i32 m0, s24, 0x2000
	s_add_u32 s24, s76, 0x160080
	v_lshl_add_u64 v[164:165], v[198:199], 0, s[14:15]
	s_addc_u32 s25, s77, 0
	s_add_i32 s34, s35, s27
	global_load_lds_dwordx4 v[164:165], off
	v_lshl_add_u64 v[164:165], s[24:25], 0, v[146:147]
	s_mov_b32 m0, s34
	s_nop 0
	global_load_lds_dwordx4 v[164:165], off
	v_lshl_add_u64 v[164:165], s[24:25], 0, v[150:151]
	s_add_i32 m0, s34, 0x2000
	s_nop 0
	global_load_lds_dwordx4 v[164:165], off
	v_lshl_add_u64 v[164:165], v[228:229], 0, s[14:15]
	s_mov_b32 m0, s82
	s_nop 0
	global_load_lds_dwordx4 v[164:165], off
	v_lshl_add_u64 v[164:165], v[230:231], 0, s[14:15]
	s_mov_b32 m0, s83
	s_nop 0
	global_load_lds_dwordx4 v[164:165], off
	s_waitcnt vmcnt(8)
	s_waitcnt lgkmcnt(0)
	s_barrier
	s_waitcnt lgkmcnt(0)
	v_mfma_f32_16x16x32_bf16 v[60:63], v[128:131], v[190:193], v[60:63]
	v_mfma_f32_16x16x32_bf16 v[56:59], v[160:163], v[190:193], v[56:59]
	v_mfma_f32_16x16x32_bf16 v[52:55], v[128:131], v[204:207], v[52:55]
	v_mfma_f32_16x16x32_bf16 v[48:51], v[160:163], v[204:207], v[48:51]
	v_mfma_f32_16x16x32_bf16 v[32:35], v[128:131], v[212:215], v[32:35]
	v_mfma_f32_16x16x32_bf16 v[24:27], v[160:163], v[212:215], v[24:27]
	v_mfma_f32_16x16x32_bf16 v[16:19], v[128:131], v[220:223], v[16:19]
	v_mfma_f32_16x16x32_bf16 v[8:11], v[160:163], v[220:223], v[8:11]
	v_mfma_f32_16x16x32_bf16 v[60:63], v[132:135], v[194:197], v[60:63]
	v_mfma_f32_16x16x32_bf16 v[56:59], v[170:173], v[194:197], v[56:59]
	v_mfma_f32_16x16x32_bf16 v[52:55], v[132:135], v[208:211], v[52:55]
	v_mfma_f32_16x16x32_bf16 v[48:51], v[170:173], v[208:211], v[48:51]
	v_mfma_f32_16x16x32_bf16 v[32:35], v[132:135], v[216:219], v[32:35]
	v_mfma_f32_16x16x32_bf16 v[24:27], v[170:173], v[216:219], v[24:27]
	v_mfma_f32_16x16x32_bf16 v[16:19], v[132:135], v[224:227], v[16:19]
	v_mfma_f32_16x16x32_bf16 v[8:11], v[170:173], v[224:227], v[8:11]
	v_mfma_f32_16x16x32_bf16 v[44:47], v[174:177], v[190:193], v[44:47]
	v_mfma_f32_16x16x32_bf16 v[40:43], v[182:185], v[190:193], v[40:43]
	v_mfma_f32_16x16x32_bf16 v[36:39], v[174:177], v[204:207], v[36:39]
	v_mfma_f32_16x16x32_bf16 v[28:31], v[182:185], v[204:207], v[28:31]
	v_mfma_f32_16x16x32_bf16 v[20:23], v[174:177], v[212:215], v[20:23]
	v_mfma_f32_16x16x32_bf16 v[12:15], v[182:185], v[212:215], v[12:15]
	v_mfma_f32_16x16x32_bf16 v[4:7], v[174:177], v[220:223], v[4:7]
	v_mfma_f32_16x16x32_bf16 v[0:3], v[182:185], v[220:223], v[0:3]
	v_mfma_f32_16x16x32_bf16 v[44:47], v[178:181], v[194:197], v[44:47]
	v_mfma_f32_16x16x32_bf16 v[40:43], v[186:189], v[194:197], v[40:43]
	v_mfma_f32_16x16x32_bf16 v[36:39], v[178:181], v[208:211], v[36:39]
	v_mfma_f32_16x16x32_bf16 v[28:31], v[186:189], v[208:211], v[28:31]
	v_mfma_f32_16x16x32_bf16 v[20:23], v[178:181], v[216:219], v[20:23]
	v_mfma_f32_16x16x32_bf16 v[12:15], v[186:189], v[216:219], v[12:15]
	v_mfma_f32_16x16x32_bf16 v[4:7], v[178:181], v[224:227], v[4:7]
	v_mfma_f32_16x16x32_bf16 v[0:3], v[186:189], v[224:227], v[0:3]
	s_barrier
	s_add_i32 s94, s94, 2
	s_add_u32 s6, s6, 0x100
	s_addc_u32 s7, s7, 0
	s_cmpk_gt_u32 s94, 0x55
	s_mov_b64 s[24:25], s[28:29]
	s_cbranch_scc0 .LBB0_128
	s_and_b64 vcc, exec, s[16:17]
	s_cbranch_vccz .LBB0_131
	s_barrier

; #define PG8_WAIT_V(n) asm volatile("s_waitcnt vmcnt(" #n ")" ::: "memory")
; #define PG8_BAR __builtin_amdgcn_s_barrier()
; template <class Epi, bool ALIGN_EPI, class Hook = NoHook>
; __device__ __forceinline__ void gemm_phase(LAS unsigned char* lds, const Gemm g, const StaticOrder& S, const Epi& E, const Hook& HK = Hook()) {
;     ...
;     PG8_WAIT_V(0);
;     if constexpr (!ALIGN_EPI) { if (wr == 0) PG8_BAR; }
;     PG8_BAR;
.LBB0_134:
	s_setprio 0
	s_waitcnt vmcnt(0)
	s_barrier

; #define PG8_STAGE(bufoff, gbase, voff) do { _Pragma("unroll") for (int _i = 0; _i < 2; ++_i) \
;         __builtin_amdgcn_global_load_lds((const unsigned*)((const char*)(gbase) + (voff)[_i]), (LAS unsigned*)(lds + (bufoff) + ldsw + _i * 8192), 16, 0, 0); } while (0)
; #define PG8_BAR __builtin_amdgcn_s_barrier()
; template <class Epi, bool ALIGN_EPI, class Hook = NoHook>
; __device__ __forceinline__ void gemm_phase(LAS unsigned char* lds, const Gemm g, const StaticOrder& S, const Epi& E, const Hook& HK = Hook()) {
;     ...
;     const int wid = __builtin_amdgcn_readfirstlane(tid >> 6), lane = tid & 63, wr = wid >> 2, wc = wid & 3, fr = lane & 15, fq = lane >> 4;
;     const int K = g.K, nt = K / BK;
;     unsigned voffA[2], voffB[2];
; #pragma unroll
;     for (int i = 0; i < 2; ++i) { int R, C; stage_rc(tid * 16 + i * 8192, R, C); const int Rb = Epi::PERM ? ((R & ~31) + perm32(R & 31)) : R;
;         voffA[i] = (unsigned)(R * g.lda + C) * 2u; voffB[i] = (unsigned)(Rb * g.ldb + C) * 2u; }
;     const size_t kstep = (size_t)(BK * 2);
;     const size_t hstepA = (size_t)HALF * g.lda * 2, hstepB = (size_t)HALF * g.ldb * 2;
;     const size_t tstepA = 2 * hstepA, tstepB = 2 * hstepB;
;     const unsigned ldsw = (unsigned)wid * 1024u;
;     const int aoff = lds_byte(wr * 64 + fr, fq * 8), boff = lds_byte(wc * 32 + fr, fq * 8);
;     ...
;     Unit cur, nxt; int ui = 0;
;     if (!S.next(0, cur)) return;
;     f32x4 acc[2][2][4][2];
; #pragma unroll
;     for (int a = 0; a < 2; ++a)
; #pragma unroll
;         for (int b = 0; b < 2; ++b)
; #pragma unroll
;             for (int m = 0; m < 4; ++m)
; #pragma unroll
;                 for (int n = 0; n < 2; ++n) acc[a][b][m][n] = (f32x4){0.f, 0.f, 0.f, 0.f};
;     bf16x8 At[4][2], B0[2][2], B1[2][2];
;     const char* cA = (const char*)g.A + (size_t)cur.pm * tstepA; const char* cB = (const char*)g.Bt + (size_t)cur.pn * tstepB;
;     PG8_STAGE(PG8_SB(0, 0), cB, voffB); PG8_STAGE(PG8_SB(0, 1), cB + hstepB, voffB); PG8_STAGE(PG8_SA(0, 0), cA, voffA); PG8_STAGE(PG8_SA(0, 1), cA + hstepA, voffA);
;     if (wr == 1) PG8_BAR;
.LBB0_261:
	s_add_u32 s76, s62, 0x17c00000
	s_addc_u32 s77, s63, 0
	s_andn2_b64 vcc, exec, s[0:1]
	s_cbranch_vccnz .LBB0_349
	v_ashrrev_i32_e32 v1, 31, v8
	v_lshrrev_b32_e32 v1, 26, v1
	v_add_u32_e32 v1, v8, v1
	v_ashrrev_i32_e32 v9, 6, v1
	v_bfe_i32 v1, v8, 27, 1
	v_lshlrev_b32_e32 v0, 4, v8
	v_lshrrev_b32_e32 v1, 22, v1
	v_add_u32_e32 v1, v0, v1
	v_and_b32_e32 v1, 0xfffffc00, v1
	v_sub_u32_e32 v1, v0, v1
	v_lshrrev_b32_e32 v2, 4, v1
	v_bitop3_b32 v1, v2, v1, 32 bitop3:0x6c
	v_ashrrev_i32_e32 v3, 31, v1
	v_lshrrev_b32_e32 v3, 26, v3
	v_add_u32_e32 v3, v1, v3
	v_lshlrev_b32_e32 v2, 3, v9
	v_ashrrev_i32_e32 v10, 6, v3
	v_and_b32_e32 v3, 0xc0, v3
	v_and_b32_e32 v2, -16, v2
	v_sub_u32_e32 v1, v1, v3
	v_mov_b32_e32 v3, 1
	v_add_u32_e32 v2, v10, v2
	v_ashrrev_i16_sdwa v1, v3, sext(v1) dst_sel:DWORD dst_unused:UNUSED_PAD src0_sel:DWORD src1_sel:BYTE_0
	v_lshlrev_b32_e32 v4, 5, v9
	v_bfe_i32 v11, v1, 0, 16
	v_lshlrev_b32_e32 v1, 1, v2
	v_lshrrev_b32_e32 v5, 2, v2
	v_and_b32_e32 v6, 3, v10
	s_mov_b32 s1, 0xfffe0
	v_and_b32_e32 v4, 32, v4
	v_and_b32_e32 v1, 24, v1
	v_and_b32_e32 v5, 4, v5
	v_and_or_b32 v6, v2, s1, v6
	v_or3_b32 v1, v6, v5, v1
	v_add_lshl_u32 v4, v4, v11, 1
	v_add_u32_e32 v0, 0x2000, v0
	v_lshl_add_u32 v134, v1, 12, v4
	v_ashrrev_i32_e32 v1, 31, v0
	v_lshrrev_b32_e32 v1, 22, v1
	v_add_u32_e32 v1, v0, v1
	v_ashrrev_i32_e32 v12, 10, v1
	v_mul_i32_i24_e32 v1, 0x400, v12
	v_sub_u32_e32 v0, v0, v1
	v_lshrrev_b32_e32 v1, 4, v0
	v_bitop3_b32 v0, v1, v0, 32 bitop3:0x6c
	v_lshl_add_u32 v130, v2, 12, v4
	v_ashrrev_i32_e32 v2, 31, v0
	v_lshrrev_b32_e32 v2, 26, v2
	v_add_u32_e32 v2, v0, v2
	v_lshlrev_b32_e32 v1, 3, v12
	v_ashrrev_i32_e32 v13, 6, v2
	v_and_b32_e32 v2, 0xc0, v2
	v_and_b32_e32 v1, -16, v1
	v_sub_u32_e32 v0, v0, v2
	v_add_u32_e32 v1, v13, v1
	v_ashrrev_i16_sdwa v0, v3, sext(v0) dst_sel:DWORD dst_unused:UNUSED_PAD src0_sel:DWORD src1_sel:BYTE_0
	v_and_b32_e32 v3, 3, v13
	v_and_or_b32 v3, v1, s1, v3
	s_ashr_i32 s1, s8, 6
	s_ashr_i32 s5, s4, 31
	s_ashr_i32 s85, s84, 31
	s_ashr_i32 s0, s8, 8
	s_lshl_b32 s17, s1, 10
	s_lshl_b64 s[6:7], s[4:5], 20
	s_lshl_b64 s[12:13], s[84:85], 20
	s_add_u32 s88, s80, s12
	v_lshlrev_b32_e32 v4, 5, v12
	v_bfe_i32 v14, v0, 0, 16
	v_lshlrev_b32_e32 v0, 1, v1
	v_lshrrev_b32_e32 v2, 2, v1
	s_addc_u32 s89, s81, s13
	s_add_i32 s28, s17, 0
	v_and_b32_e32 v4, 32, v4
	v_and_b32_e32 v0, 24, v0
	v_and_b32_e32 v2, 4, v2
	s_add_i32 m0, s28, 0x10000
	v_or3_b32 v0, v3, v2, v0
	v_add_lshl_u32 v2, v4, v14, 1
	global_load_lds_dwordx4 v134, s[88:89]
	s_add_i32 m0, s28, 0x12000
	v_lshl_add_u32 v146, v0, 12, v2
	s_add_u32 s12, s88, 0x80000
	global_load_lds_dwordx4 v146, s[88:89]
	s_addc_u32 s13, s89, 0
	s_add_i32 m0, s28, 0x14000
	v_lshl_add_u32 v144, v1, 12, v2
	global_load_lds_dwordx4 v134, s[12:13]
	s_add_i32 m0, s28, 0x16000
	s_add_u32 s86, s48, s6
	s_addc_u32 s87, s49, s7
	s_add_i32 s29, s28, 0x2000
	global_load_lds_dwordx4 v146, s[12:13]
	s_mov_b32 m0, s28
	s_add_u32 s6, s86, 0x80000
	global_load_lds_dwordx4 v130, s[86:87]
	s_mov_b32 m0, s29
	s_addc_u32 s7, s87, 0
	s_add_i32 s71, s28, 0x4000
	global_load_lds_dwordx4 v144, s[86:87]
	s_mov_b32 m0, s71
	s_add_i32 s82, s28, 0x6000
	global_load_lds_dwordx4 v130, s[6:7]
	s_mov_b32 m0, s82
	v_mov_b32_e32 v135, 0
	global_load_lds_dwordx4 v144, s[6:7]
	v_mov_b32_e32 v147, v135
	v_mov_b32_e32 v131, v135
	v_mov_b32_e32 v145, v135
	s_cmp_eq_u32 s0, 1
	s_mov_b64 s[54:55], s[56:57]
	s_mov_b64 s[56:57], s[34:35]
	s_mov_b32 s83, 0
	v_lshl_add_u64 v[6:7], s[88:89], 0, v[134:135]
	v_lshl_add_u64 v[4:5], s[88:89], 0, v[146:147]
	v_lshl_add_u64 v[0:1], s[86:87], 0, v[130:131]
	s_cselect_b64 s[6:7], -1, 0
	s_cmp_lg_u32 s0, 1
	v_lshl_add_u64 v[2:3], s[86:87], 0, v[144:145]
	s_cbranch_scc1 .LBB0_264
	s_barrier
	s_setprio 1

; #define PG8_STAGE(bufoff, gbase, voff) do { _Pragma("unroll") for (int _i = 0; _i < 2; ++_i) \
;         __builtin_amdgcn_global_load_lds((const unsigned*)((const char*)(gbase) + (voff)[_i]), (LAS unsigned*)(lds + (bufoff) + ldsw + _i * 8192), 16, 0, 0); } while (0)
; #define PG8_LDA(dst, b, h) do { _Pragma("unroll") for (int m = 0; m < 4; ++m) _Pragma("unroll") for (int k = 0; k < 2; ++k) dst[m][k] = *(const LAS bf16x8*)(lds + PG8_SA(b, h) + aoff + m * 2048 + k * 1024); } while (0)
; #define PG8_LDB(dst, b, h) do { _Pragma("unroll") for (int n = 0; n < 2; ++n) _Pragma("unroll") for (int k = 0; k < 2; ++k) dst[n][k] = *(const LAS bf16x8*)(lds + PG8_SB(b, h) + boff + n * 2048 + k * 1024); } while (0)
; #define PG8_MMA(ai, bj, At, Bt) do { __builtin_amdgcn_s_setprio(1); _Pragma("unroll") for (int m = 0; m < 4; ++m) _Pragma("unroll") for (int n = 0; n < 2; ++n) _Pragma("unroll") for (int k = 0; k < 2; ++k) \
;         acc[ai][bj][m][n] = __builtin_amdgcn_mfma_f32_16x16x32_bf16(Bt[n][k], At[m][k], acc[ai][bj][m][n], 0, 0, 0); __builtin_amdgcn_s_setprio(0); } while (0)
; #define PG8_BAR __builtin_amdgcn_s_barrier()
; template <class Epi, bool ALIGN_EPI, class Hook = NoHook>
; __device__ __forceinline__ void gemm_phase(LAS unsigned char* lds, const Gemm g, const StaticOrder& S, const Epi& E, const Hook& HK = Hook()) {
;     ...
;         const bool has_next = S.next(ui + 1, nxt);
;         const char* nA = has_next ? (const char*)g.A + (size_t)nxt.pm * tstepA : cA; const char* nB = has_next ? (const char*)g.Bt + (size_t)nxt.pn * tstepB : cB;
;         for (int t = 0; t < nt; t += 2) {
;             if (Hook::AT > 0 && t == Hook::AT) HK(acc, cur, wr, wc, fr, fq);
;             const bool last = (t == nt - 2);
;             const char* a1 = cA + (size_t)(t + 1) * kstep;
;             const char* a2 = last ? nA : cA + (size_t)(t + 2) * kstep; const char* b2 = last ? nB : cB + (size_t)(t + 2) * kstep;
;             const char* a3 = a2 + kstep; const char* b3 = b2 + kstep;
;             PG8_LDB(B0, 0, 0); PG8_LDB(B1, 0, 1); PG8_SCHED; PG8_LDA(At, 0, 0); PG8_STAGE(PG8_SA(1, 1), a1 + hstepA, voffA);
;             PG8_WAIT_V(8); PG8_WAIT_L(0); PG8_BAR; PG8_MMA(0, 0, At, B0); PG8_MMA(0, 1, At, B1); PG8_BAR; PG8_SCHED;
;             PG8_LDA(At, 0, 1); PG8_STAGE(PG8_SB(0, 0), b2, voffB); PG8_STAGE(PG8_SB(0, 1), b2 + hstepB, voffB); PG8_STAGE(PG8_SA(0, 0), a2, voffA);
.LBB0_269:
	s_ashr_i32 s19, s18, 31
	s_lshl_b64 s[22:23], s[18:19], 20
	s_add_u32 s22, s48, s22
	s_addc_u32 s23, s49, s23
	s_and_b64 s[24:25], s[0:1], exec
	s_cselect_b32 s5, s23, s87
	s_cselect_b32 s19, s22, s86
	s_ashr_i32 s21, s20, 31
	s_lshl_b64 s[24:25], s[20:21], 20
	s_add_u32 s24, s80, s24
	s_addc_u32 s25, s81, s25
	s_and_b64 s[26:27], s[0:1], exec
	s_cselect_b32 s21, s25, s89
	s_cselect_b32 s26, s24, s88
	s_add_u32 s86, s86, 0x80080
	s_addc_u32 s87, s87, 0
	s_add_u32 s27, s88, 0x100
	s_addc_u32 s50, s89, 0
	s_mov_b32 s51, -2
	ds_read_b128 v[156:159], v141
	ds_read_b128 v[160:163], v141 offset:1024
	ds_read_b128 v[168:171], v141 offset:2048
	ds_read_b128 v[172:175], v141 offset:3072
	ds_read_b128 v[176:179], v143
	ds_read_b128 v[180:183], v143 offset:1024
	ds_read_b128 v[184:187], v143 offset:2048
	ds_read_b128 v[188:191], v143 offset:3072
	s_add_u32 s34, s86, 0xfff80080
	s_addc_u32 s35, s87, -1
	s_cmp_eq_u32 s51, 28
	s_cselect_b32 s91, s5, s35
	s_cselect_b32 s90, s19, s34
	s_cselect_b32 s89, s21, s50
	s_cselect_b32 s88, s26, s27
	v_lshl_add_u64 v[164:165], s[86:87], 0, v[148:149]
	s_add_i32 m0, s28, 0xc000
	ds_read_b128 v[192:195], v167
	ds_read_b128 v[196:199], v167 offset:1024
	ds_read_b128 v[204:207], v167 offset:2048
	ds_read_b128 v[208:211], v167 offset:3072
	ds_read_b128 v[212:215], v167 offset:4096
	ds_read_b128 v[216:219], v167 offset:5120
	ds_read_b128 v[220:223], v167 offset:6144
	ds_read_b128 v[224:227], v167 offset:7168
	global_load_lds_dwordx4 v[164:165], off
	v_lshl_add_u64 v[164:165], s[86:87], 0, v[150:151]
	s_add_i32 m0, s28, 0xe000
	s_nop 0
	global_load_lds_dwordx4 v[164:165], off
	s_waitcnt vmcnt(8)
	s_waitcnt lgkmcnt(0)
	s_barrier
	s_waitcnt lgkmcnt(0)
	v_mfma_f32_16x16x32_bf16 v[124:127], v[156:159], v[192:195], 0
	v_mfma_f32_16x16x32_bf16 v[120:123], v[168:171], v[192:195], 0
	v_mfma_f32_16x16x32_bf16 v[108:111], v[156:159], v[204:207], 0
	v_mfma_f32_16x16x32_bf16 v[104:107], v[168:171], v[204:207], 0
	v_mfma_f32_16x16x32_bf16 v[92:95], v[156:159], v[212:215], 0
	v_mfma_f32_16x16x32_bf16 v[88:91], v[168:171], v[212:215], 0
	v_mfma_f32_16x16x32_bf16 v[76:79], v[156:159], v[220:223], 0
	v_mfma_f32_16x16x32_bf16 v[72:75], v[168:171], v[220:223], 0
	v_mfma_f32_16x16x32_bf16 v[124:127], v[160:163], v[196:199], v[124:127]
	v_mfma_f32_16x16x32_bf16 v[120:123], v[172:175], v[196:199], v[120:123]
	v_mfma_f32_16x16x32_bf16 v[108:111], v[160:163], v[208:211], v[108:111]
	v_mfma_f32_16x16x32_bf16 v[104:107], v[172:175], v[208:211], v[104:107]
	v_mfma_f32_16x16x32_bf16 v[92:95], v[160:163], v[216:219], v[92:95]
	v_mfma_f32_16x16x32_bf16 v[88:91], v[172:175], v[216:219], v[88:91]
	v_mfma_f32_16x16x32_bf16 v[76:79], v[160:163], v[224:227], v[76:79]
	v_mfma_f32_16x16x32_bf16 v[72:75], v[172:175], v[224:227], v[72:75]
	v_mfma_f32_16x16x32_bf16 v[116:119], v[176:179], v[192:195], 0
	v_mfma_f32_16x16x32_bf16 v[112:115], v[184:187], v[192:195], 0
	v_mfma_f32_16x16x32_bf16 v[100:103], v[176:179], v[204:207], 0
	v_mfma_f32_16x16x32_bf16 v[96:99], v[184:187], v[204:207], 0
	v_mfma_f32_16x16x32_bf16 v[84:87], v[176:179], v[212:215], 0
	v_mfma_f32_16x16x32_bf16 v[80:83], v[184:187], v[212:215], 0
	v_mfma_f32_16x16x32_bf16 v[68:71], v[176:179], v[220:223], 0
	v_mfma_f32_16x16x32_bf16 v[64:67], v[184:187], v[220:223], 0
	v_mfma_f32_16x16x32_bf16 v[116:119], v[180:183], v[196:199], v[116:119]
	v_mfma_f32_16x16x32_bf16 v[112:115], v[188:191], v[196:199], v[112:115]
	v_mfma_f32_16x16x32_bf16 v[100:103], v[180:183], v[208:211], v[100:103]
	v_mfma_f32_16x16x32_bf16 v[96:99], v[188:191], v[208:211], v[96:99]
	v_mfma_f32_16x16x32_bf16 v[84:87], v[180:183], v[216:219], v[84:87]
	v_mfma_f32_16x16x32_bf16 v[80:83], v[188:191], v[216:219], v[80:83]
	v_mfma_f32_16x16x32_bf16 v[68:71], v[180:183], v[224:227], v[68:71]
	v_mfma_f32_16x16x32_bf16 v[64:67], v[188:191], v[224:227], v[64:67]
	s_barrier
	s_add_i32 s34, s97, s17
	v_lshl_add_u64 v[164:165], s[88:89], 0, v[134:135]
	s_mov_b32 m0, s34
	ds_read_b128 v[192:195], v167 offset:16384
	ds_read_b128 v[196:199], v167 offset:17408
	ds_read_b128 v[204:207], v167 offset:18432
	ds_read_b128 v[208:211], v167 offset:19456
	ds_read_b128 v[212:215], v167 offset:20480
	ds_read_b128 v[216:219], v167 offset:21504
	ds_read_b128 v[220:223], v167 offset:22528
	ds_read_b128 v[224:227], v167 offset:23552
	global_load_lds_dwordx4 v[164:165], off
	s_add_i32 m0, s34, 0x2000
	s_add_u32 s34, s88, 0x80000
	v_lshl_add_u64 v[228:229], s[88:89], 0, v[146:147]
	s_addc_u32 s35, s89, 0
	s_add_i32 s52, s8, s17
	global_load_lds_dwordx4 v[228:229], off
	v_lshl_add_u64 v[230:231], s[34:35], 0, v[134:135]
	s_mov_b32 m0, s52
	v_lshl_add_u64 v[232:233], s[90:91], 0, v[144:145]
	global_load_lds_dwordx4 v[230:231], off
	v_lshl_add_u64 v[230:231], s[34:35], 0, v[146:147]
	s_add_i32 m0, s52, 0x2000
	s_nop 0
	global_load_lds_dwordx4 v[230:231], off
	v_lshl_add_u64 v[230:231], s[90:91], 0, v[130:131]
	s_mov_b32 m0, s28
	s_nop 0
	global_load_lds_dwordx4 v[230:231], off
	s_mov_b32 m0, s29
	s_nop 0
	global_load_lds_dwordx4 v[232:233], off
	s_waitcnt vmcnt(8)
	s_waitcnt lgkmcnt(0)
	s_barrier
; #define PG8_STAGE(bufoff, gbase, voff) do { _Pragma("unroll") for (int _i = 0; _i < 2; ++_i) \
;         __builtin_amdgcn_global_load_lds((const unsigned*)((const char*)(gbase) + (voff)[_i]), (LAS unsigned*)(lds + (bufoff) + ldsw + _i * 8192), 16, 0, 0); } while (0)
; #define PG8_LDA(dst, b, h) do { _Pragma("unroll") for (int m = 0; m < 4; ++m) _Pragma("unroll") for (int k = 0; k < 2; ++k) dst[m][k] = *(const LAS bf16x8*)(lds + PG8_SA(b, h) + aoff + m * 2048 + k * 1024); } while (0)
; #define PG8_LDB(dst, b, h) do { _Pragma("unroll") for (int n = 0; n < 2; ++n) _Pragma("unroll") for (int k = 0; k < 2; ++k) dst[n][k] = *(const LAS bf16x8*)(lds + PG8_SB(b, h) + boff + n * 2048 + k * 1024); } while (0)
; #define PG8_MMA(ai, bj, At, Bt) do { __builtin_amdgcn_s_setprio(1); _Pragma("unroll") for (int m = 0; m < 4; ++m) _Pragma("unroll") for (int n = 0; n < 2; ++n) _Pragma("unroll") for (int k = 0; k < 2; ++k) \
;         acc[ai][bj][m][n] = __builtin_amdgcn_mfma_f32_16x16x32_bf16(Bt[n][k], At[m][k], acc[ai][bj][m][n], 0, 0, 0); __builtin_amdgcn_s_setprio(0); } while (0)
; #define PG8_WAIT_V(n) asm volatile("s_waitcnt vmcnt(" #n ")" ::: "memory")
; #define PG8_WAIT_L(n) asm volatile("s_waitcnt lgkmcnt(" #n ")" ::: "memory")
; #define PG8_BAR __builtin_amdgcn_s_barrier()
; template <class Epi, bool ALIGN_EPI, class Hook = NoHook>
; __device__ __forceinline__ void gemm_phase(LAS unsigned char* lds, const Gemm g, const StaticOrder& S, const Epi& E, const Hook& HK = Hook()) {
;     ...
;             PG8_WAIT_V(8); PG8_WAIT_L(0); PG8_BAR; PG8_MMA(0, 0, At, B0); PG8_MMA(0, 1, At, B1); PG8_BAR; PG8_SCHED;
;             PG8_LDA(At, 0, 1); PG8_STAGE(PG8_SB(0, 0), b2, voffB); PG8_STAGE(PG8_SB(0, 1), b2 + hstepB, voffB); PG8_STAGE(PG8_SA(0, 0), a2, voffA);
;             PG8_WAIT_V(8); PG8_WAIT_L(0); PG8_BAR; PG8_MMA(1, 0, At, B0); PG8_MMA(1, 1, At, B1); PG8_BAR; PG8_SCHED;
;             PG8_LDB(B0, 1, 0); PG8_LDB(B1, 1, 1); PG8_SCHED; PG8_LDA(At, 1, 0); PG8_STAGE(PG8_SA(0, 1), a2 + hstepA, voffA);
;             PG8_WAIT_V(8); PG8_WAIT_L(0); PG8_BAR; PG8_MMA(0, 0, At, B0); PG8_MMA(0, 1, At, B1); PG8_BAR; PG8_SCHED;
;             PG8_LDA(At, 1, 1); PG8_STAGE(PG8_SB(1, 0), b3, voffB); PG8_STAGE(PG8_SB(1, 1), b3 + hstepB, voffB); PG8_STAGE(PG8_SA(1, 0), a3, voffA);
;             PG8_WAIT_V(8); PG8_WAIT_L(0); PG8_BAR; PG8_MMA(1, 0, At, B0); PG8_MMA(1, 1, At, B1); PG8_BAR; PG8_SCHED;
	s_waitcnt lgkmcnt(0)
	v_mfma_f32_16x16x32_bf16 v[60:63], v[156:159], v[192:195], 0
	v_mfma_f32_16x16x32_bf16 v[56:59], v[168:171], v[192:195], 0
	v_mfma_f32_16x16x32_bf16 v[44:47], v[156:159], v[204:207], 0
	v_mfma_f32_16x16x32_bf16 v[40:43], v[168:171], v[204:207], 0
	v_mfma_f32_16x16x32_bf16 v[28:31], v[156:159], v[212:215], 0
	v_mfma_f32_16x16x32_bf16 v[24:27], v[168:171], v[212:215], 0
	v_mfma_f32_16x16x32_bf16 v[12:15], v[156:159], v[220:223], 0
	v_mfma_f32_16x16x32_bf16 v[8:11], v[168:171], v[220:223], 0
	v_mfma_f32_16x16x32_bf16 v[60:63], v[160:163], v[196:199], v[60:63]
	v_mfma_f32_16x16x32_bf16 v[56:59], v[172:175], v[196:199], v[56:59]
	v_mfma_f32_16x16x32_bf16 v[44:47], v[160:163], v[208:211], v[44:47]
	v_mfma_f32_16x16x32_bf16 v[40:43], v[172:175], v[208:211], v[40:43]
	v_mfma_f32_16x16x32_bf16 v[28:31], v[160:163], v[216:219], v[28:31]
	v_mfma_f32_16x16x32_bf16 v[24:27], v[172:175], v[216:219], v[24:27]
	v_mfma_f32_16x16x32_bf16 v[12:15], v[160:163], v[224:227], v[12:15]
	v_mfma_f32_16x16x32_bf16 v[8:11], v[172:175], v[224:227], v[8:11]
	v_mfma_f32_16x16x32_bf16 v[52:55], v[176:179], v[192:195], 0
	v_mfma_f32_16x16x32_bf16 v[48:51], v[184:187], v[192:195], 0
	v_mfma_f32_16x16x32_bf16 v[36:39], v[176:179], v[204:207], 0
	v_mfma_f32_16x16x32_bf16 v[32:35], v[184:187], v[204:207], 0
	v_mfma_f32_16x16x32_bf16 v[20:23], v[176:179], v[212:215], 0
	v_mfma_f32_16x16x32_bf16 v[16:19], v[184:187], v[212:215], 0
	v_mfma_f32_16x16x32_bf16 v[4:7], v[176:179], v[220:223], 0
	v_mfma_f32_16x16x32_bf16 v[0:3], v[184:187], v[220:223], 0
	v_mfma_f32_16x16x32_bf16 v[52:55], v[180:183], v[196:199], v[52:55]
	v_mfma_f32_16x16x32_bf16 v[48:51], v[188:191], v[196:199], v[48:51]
	v_mfma_f32_16x16x32_bf16 v[36:39], v[180:183], v[208:211], v[36:39]
	v_mfma_f32_16x16x32_bf16 v[32:35], v[188:191], v[208:211], v[32:35]
	v_mfma_f32_16x16x32_bf16 v[20:23], v[180:183], v[216:219], v[20:23]
	v_mfma_f32_16x16x32_bf16 v[16:19], v[188:191], v[216:219], v[16:19]
	v_mfma_f32_16x16x32_bf16 v[4:7], v[180:183], v[224:227], v[4:7]
	v_mfma_f32_16x16x32_bf16 v[0:3], v[188:191], v[224:227], v[0:3]
	s_barrier
	s_add_i32 s52, 0, 0x18000
	s_add_i32 s53, 0, 0x1c000
	v_add_u32_e32 v172, s52, v133
	v_add_u32_e32 v188, s53, v133
	ds_read_b128 v[156:159], v172
	ds_read_b128 v[160:163], v172 offset:1024
	ds_read_b128 v[168:171], v172 offset:2048
	ds_read_b128 v[172:175], v172 offset:3072
	ds_read_b128 v[176:179], v188
	ds_read_b128 v[180:183], v188 offset:1024
	ds_read_b128 v[184:187], v188 offset:2048
	ds_read_b128 v[188:191], v188 offset:3072
	s_add_u32 s34, s90, 0x80000
	s_addc_u32 s35, s91, 0
	s_mov_b32 m0, s71
	v_lshl_add_u64 v[234:235], s[34:35], 0, v[130:131]
	ds_read_b128 v[192:195], v167 offset:32768
	ds_read_b128 v[196:199], v167 offset:33792
	ds_read_b128 v[204:207], v167 offset:34816
	ds_read_b128 v[208:211], v167 offset:35840
	ds_read_b128 v[212:215], v167 offset:36864
	ds_read_b128 v[216:219], v167 offset:37888
	ds_read_b128 v[220:223], v167 offset:38912
	ds_read_b128 v[224:227], v167 offset:39936
	global_load_lds_dwordx4 v[234:235], off
	v_lshl_add_u64 v[234:235], s[34:35], 0, v[144:145]
	s_mov_b32 m0, s82
	s_nop 0
	global_load_lds_dwordx4 v[234:235], off
	s_waitcnt vmcnt(8)
	s_waitcnt lgkmcnt(0)
	s_barrier
	s_waitcnt lgkmcnt(0)
	v_mfma_f32_16x16x32_bf16 v[124:127], v[156:159], v[192:195], v[124:127]
	v_mfma_f32_16x16x32_bf16 v[120:123], v[168:171], v[192:195], v[120:123]
	v_mfma_f32_16x16x32_bf16 v[108:111], v[156:159], v[204:207], v[108:111]
	v_mfma_f32_16x16x32_bf16 v[104:107], v[168:171], v[204:207], v[104:107]
	v_mfma_f32_16x16x32_bf16 v[92:95], v[156:159], v[212:215], v[92:95]
	v_mfma_f32_16x16x32_bf16 v[88:91], v[168:171], v[212:215], v[88:91]
	v_mfma_f32_16x16x32_bf16 v[76:79], v[156:159], v[220:223], v[76:79]
	v_mfma_f32_16x16x32_bf16 v[72:75], v[168:171], v[220:223], v[72:75]
	v_mfma_f32_16x16x32_bf16 v[124:127], v[160:163], v[196:199], v[124:127]
	v_mfma_f32_16x16x32_bf16 v[120:123], v[172:175], v[196:199], v[120:123]
	v_mfma_f32_16x16x32_bf16 v[108:111], v[160:163], v[208:211], v[108:111]
	v_mfma_f32_16x16x32_bf16 v[104:107], v[172:175], v[208:211], v[104:107]
	v_mfma_f32_16x16x32_bf16 v[92:95], v[160:163], v[216:219], v[92:95]
	v_mfma_f32_16x16x32_bf16 v[88:91], v[172:175], v[216:219], v[88:91]
	v_mfma_f32_16x16x32_bf16 v[76:79], v[160:163], v[224:227], v[76:79]
	v_mfma_f32_16x16x32_bf16 v[72:75], v[172:175], v[224:227], v[72:75]
	v_mfma_f32_16x16x32_bf16 v[116:119], v[176:179], v[192:195], v[116:119]
	v_mfma_f32_16x16x32_bf16 v[112:115], v[184:187], v[192:195], v[112:115]
	v_mfma_f32_16x16x32_bf16 v[100:103], v[176:179], v[204:207], v[100:103]
	v_mfma_f32_16x16x32_bf16 v[96:99], v[184:187], v[204:207], v[96:99]
	v_mfma_f32_16x16x32_bf16 v[84:87], v[176:179], v[212:215], v[84:87]
	v_mfma_f32_16x16x32_bf16 v[80:83], v[184:187], v[212:215], v[80:83]
	v_mfma_f32_16x16x32_bf16 v[68:71], v[176:179], v[220:223], v[68:71]
	v_mfma_f32_16x16x32_bf16 v[64:67], v[184:187], v[220:223], v[64:67]
	v_mfma_f32_16x16x32_bf16 v[116:119], v[180:183], v[196:199], v[116:119]
	v_mfma_f32_16x16x32_bf16 v[112:115], v[188:191], v[196:199], v[112:115]
	v_mfma_f32_16x16x32_bf16 v[100:103], v[180:183], v[208:211], v[100:103]
	v_mfma_f32_16x16x32_bf16 v[96:99], v[188:191], v[208:211], v[96:99]
	v_mfma_f32_16x16x32_bf16 v[84:87], v[180:183], v[216:219], v[84:87]
	v_mfma_f32_16x16x32_bf16 v[80:83], v[188:191], v[216:219], v[80:83]
	v_mfma_f32_16x16x32_bf16 v[68:71], v[180:183], v[224:227], v[68:71]
	v_mfma_f32_16x16x32_bf16 v[64:67], v[188:191], v[224:227], v[64:67]
	s_barrier
; #define PG8_STAGE(bufoff, gbase, voff) do { _Pragma("unroll") for (int _i = 0; _i < 2; ++_i) \
;         __builtin_amdgcn_global_load_lds((const unsigned*)((const char*)(gbase) + (voff)[_i]), (LAS unsigned*)(lds + (bufoff) + ldsw + _i * 8192), 16, 0, 0); } while (0)
; #define PG8_LDA(dst, b, h) do { _Pragma("unroll") for (int m = 0; m < 4; ++m) _Pragma("unroll") for (int k = 0; k < 2; ++k) dst[m][k] = *(const LAS bf16x8*)(lds + PG8_SA(b, h) + aoff + m * 2048 + k * 1024); } while (0)
; #define PG8_LDB(dst, b, h) do { _Pragma("unroll") for (int n = 0; n < 2; ++n) _Pragma("unroll") for (int k = 0; k < 2; ++k) dst[n][k] = *(const LAS bf16x8*)(lds + PG8_SB(b, h) + boff + n * 2048 + k * 1024); } while (0)
; #define PG8_MMA(ai, bj, At, Bt) do { __builtin_amdgcn_s_setprio(1); _Pragma("unroll") for (int m = 0; m < 4; ++m) _Pragma("unroll") for (int n = 0; n < 2; ++n) _Pragma("unroll") for (int k = 0; k < 2; ++k) \
;         acc[ai][bj][m][n] = __builtin_amdgcn_mfma_f32_16x16x32_bf16(Bt[n][k], At[m][k], acc[ai][bj][m][n], 0, 0, 0); __builtin_amdgcn_s_setprio(0); } while (0)
; #define PG8_WAIT_V(n) asm volatile("s_waitcnt vmcnt(" #n ")" ::: "memory")
; #define PG8_WAIT_L(n) asm volatile("s_waitcnt lgkmcnt(" #n ")" ::: "memory")
; #define PG8_BAR __builtin_amdgcn_s_barrier()
; #define PG8_SCHED __builtin_amdgcn_sched_barrier(0)
; template <class Epi, bool ALIGN_EPI, class Hook = NoHook>
; __device__ __forceinline__ void gemm_phase(LAS unsigned char* lds, const Gemm g, const StaticOrder& S, const Epi& E, const Hook& HK = Hook()) {
;     ...
;             PG8_LDB(B0, 0, 0); PG8_LDB(B1, 0, 1); PG8_SCHED; PG8_LDA(At, 0, 0); PG8_STAGE(PG8_SA(1, 1), a1 + hstepA, voffA);
;             PG8_WAIT_V(8); PG8_WAIT_L(0); PG8_BAR; PG8_MMA(0, 0, At, B0); PG8_MMA(0, 1, At, B1); PG8_BAR; PG8_SCHED;
;     ...
;             PG8_LDA(At, 1, 1); PG8_STAGE(PG8_SB(1, 0), b3, voffB); PG8_STAGE(PG8_SB(1, 1), b3 + hstepB, voffB); PG8_STAGE(PG8_SA(1, 0), a3, voffA);
;             PG8_WAIT_V(8); PG8_WAIT_L(0); PG8_BAR; PG8_MMA(1, 0, At, B0); PG8_MMA(1, 1, At, B1); PG8_BAR; PG8_SCHED;
	s_add_i32 s34, s52, s17
	v_lshl_add_u64 v[164:165], v[164:165], 0, s[12:13]
	s_mov_b32 m0, s34
	ds_read_b128 v[192:195], v167 offset:49152
	ds_read_b128 v[196:199], v167 offset:50176
	ds_read_b128 v[204:207], v167 offset:51200
	ds_read_b128 v[208:211], v167 offset:52224
	ds_read_b128 v[212:215], v167 offset:53248
	ds_read_b128 v[216:219], v167 offset:54272
	ds_read_b128 v[220:223], v167 offset:55296
	ds_read_b128 v[224:227], v167 offset:56320
	global_load_lds_dwordx4 v[164:165], off
	s_add_i32 m0, s34, 0x2000
	s_add_u32 s34, s88, 0x80080
	v_lshl_add_u64 v[164:165], v[228:229], 0, s[12:13]
	s_addc_u32 s35, s89, 0
	s_add_i32 s52, s53, s17
	global_load_lds_dwordx4 v[164:165], off
	v_lshl_add_u64 v[164:165], s[34:35], 0, v[134:135]
	s_mov_b32 m0, s52
	s_nop 0
	global_load_lds_dwordx4 v[164:165], off
	v_lshl_add_u64 v[164:165], s[34:35], 0, v[146:147]
	s_add_i32 m0, s52, 0x2000
	s_nop 0
	global_load_lds_dwordx4 v[164:165], off
	v_lshl_add_u64 v[164:165], v[230:231], 0, s[12:13]
	s_mov_b32 m0, s92
	s_nop 0
	global_load_lds_dwordx4 v[164:165], off
	v_lshl_add_u64 v[164:165], v[232:233], 0, s[12:13]
	s_mov_b32 m0, s93
	s_nop 0
	global_load_lds_dwordx4 v[164:165], off
	s_waitcnt vmcnt(8)
	s_waitcnt lgkmcnt(0)
	s_barrier
	s_waitcnt lgkmcnt(0)
	v_mfma_f32_16x16x32_bf16 v[60:63], v[156:159], v[192:195], v[60:63]
	v_mfma_f32_16x16x32_bf16 v[56:59], v[168:171], v[192:195], v[56:59]
	v_mfma_f32_16x16x32_bf16 v[44:47], v[156:159], v[204:207], v[44:47]
	v_mfma_f32_16x16x32_bf16 v[40:43], v[168:171], v[204:207], v[40:43]
	v_mfma_f32_16x16x32_bf16 v[28:31], v[156:159], v[212:215], v[28:31]
	v_mfma_f32_16x16x32_bf16 v[24:27], v[168:171], v[212:215], v[24:27]
	v_mfma_f32_16x16x32_bf16 v[12:15], v[156:159], v[220:223], v[12:15]
	v_mfma_f32_16x16x32_bf16 v[8:11], v[168:171], v[220:223], v[8:11]
	v_mfma_f32_16x16x32_bf16 v[60:63], v[160:163], v[196:199], v[60:63]
	v_mfma_f32_16x16x32_bf16 v[56:59], v[172:175], v[196:199], v[56:59]
	v_mfma_f32_16x16x32_bf16 v[44:47], v[160:163], v[208:211], v[44:47]
	v_mfma_f32_16x16x32_bf16 v[40:43], v[172:175], v[208:211], v[40:43]
	v_mfma_f32_16x16x32_bf16 v[28:31], v[160:163], v[216:219], v[28:31]
	v_mfma_f32_16x16x32_bf16 v[24:27], v[172:175], v[216:219], v[24:27]
	v_mfma_f32_16x16x32_bf16 v[12:15], v[160:163], v[224:227], v[12:15]
	v_mfma_f32_16x16x32_bf16 v[8:11], v[172:175], v[224:227], v[8:11]
	v_mfma_f32_16x16x32_bf16 v[52:55], v[176:179], v[192:195], v[52:55]
	v_mfma_f32_16x16x32_bf16 v[48:51], v[184:187], v[192:195], v[48:51]
	v_mfma_f32_16x16x32_bf16 v[36:39], v[176:179], v[204:207], v[36:39]
	v_mfma_f32_16x16x32_bf16 v[32:35], v[184:187], v[204:207], v[32:35]
	v_mfma_f32_16x16x32_bf16 v[20:23], v[176:179], v[212:215], v[20:23]
	v_mfma_f32_16x16x32_bf16 v[16:19], v[184:187], v[212:215], v[16:19]
	v_mfma_f32_16x16x32_bf16 v[4:7], v[176:179], v[220:223], v[4:7]
	v_mfma_f32_16x16x32_bf16 v[0:3], v[184:187], v[220:223], v[0:3]
	v_mfma_f32_16x16x32_bf16 v[52:55], v[180:183], v[196:199], v[52:55]
	v_mfma_f32_16x16x32_bf16 v[48:51], v[188:191], v[196:199], v[48:51]
	v_mfma_f32_16x16x32_bf16 v[36:39], v[180:183], v[208:211], v[36:39]
	v_mfma_f32_16x16x32_bf16 v[32:35], v[188:191], v[208:211], v[32:35]
	v_mfma_f32_16x16x32_bf16 v[20:23], v[180:183], v[216:219], v[20:23]
	v_mfma_f32_16x16x32_bf16 v[16:19], v[188:191], v[216:219], v[16:19]
	v_mfma_f32_16x16x32_bf16 v[4:7], v[180:183], v[224:227], v[4:7]
	v_mfma_f32_16x16x32_bf16 v[0:3], v[188:191], v[224:227], v[0:3]
	s_barrier
	s_add_i32 s51, s51, 2
	s_add_u32 s86, s86, 0x100
	s_addc_u32 s87, s87, 0
	s_add_u32 s27, s27, 0x100
	s_addc_u32 s50, s50, 0
	s_cmp_gt_u32 s51, 29
.LBB0_270:
	ds_read_b128 v[156:159], v141
	ds_read_b128 v[160:163], v141 offset:1024
	ds_read_b128 v[168:171], v141 offset:2048
	ds_read_b128 v[172:175], v141 offset:3072
	ds_read_b128 v[176:179], v143
	ds_read_b128 v[180:183], v143 offset:1024
	ds_read_b128 v[184:187], v143 offset:2048
	ds_read_b128 v[188:191], v143 offset:3072
	s_add_u32 s34, s86, 0xfff80080
	s_addc_u32 s35, s87, -1
	s_cmp_eq_u32 s51, 28
	s_cselect_b32 s91, s5, s35
	s_cselect_b32 s90, s19, s34
	s_cselect_b32 s89, s21, s50
	s_cselect_b32 s88, s26, s27
	v_lshl_add_u64 v[164:165], s[86:87], 0, v[148:149]
	s_add_i32 m0, s28, 0xc000
	ds_read_b128 v[192:195], v167
	ds_read_b128 v[196:199], v167 offset:1024
	ds_read_b128 v[204:207], v167 offset:2048
	ds_read_b128 v[208:211], v167 offset:3072
	ds_read_b128 v[212:215], v167 offset:4096
	ds_read_b128 v[216:219], v167 offset:5120
	ds_read_b128 v[220:223], v167 offset:6144
	ds_read_b128 v[224:227], v167 offset:7168
	global_load_lds_dwordx4 v[164:165], off
	v_lshl_add_u64 v[164:165], s[86:87], 0, v[150:151]
	s_add_i32 m0, s28, 0xe000
	s_nop 0
	global_load_lds_dwordx4 v[164:165], off
	s_waitcnt vmcnt(8)
	s_waitcnt lgkmcnt(0)
	s_barrier
; #define PG8_STAGE(bufoff, gbase, voff) do { _Pragma("unroll") for (int _i = 0; _i < 2; ++_i) \
;         __builtin_amdgcn_global_load_lds((const unsigned*)((const char*)(gbase) + (voff)[_i]), (LAS unsigned*)(lds + (bufoff) + ldsw + _i * 8192), 16, 0, 0); } while (0)
; #define PG8_LDA(dst, b, h) do { _Pragma("unroll") for (int m = 0; m < 4; ++m) _Pragma("unroll") for (int k = 0; k < 2; ++k) dst[m][k] = *(const LAS bf16x8*)(lds + PG8_SA(b, h) + aoff + m * 2048 + k * 1024); } while (0)
; #define PG8_LDB(dst, b, h) do { _Pragma("unroll") for (int n = 0; n < 2; ++n) _Pragma("unroll") for (int k = 0; k < 2; ++k) dst[n][k] = *(const LAS bf16x8*)(lds + PG8_SB(b, h) + boff + n * 2048 + k * 1024); } while (0)
; #define PG8_MMA(ai, bj, At, Bt) do { __builtin_amdgcn_s_setprio(1); _Pragma("unroll") for (int m = 0; m < 4; ++m) _Pragma("unroll") for (int n = 0; n < 2; ++n) _Pragma("unroll") for (int k = 0; k < 2; ++k) \
;         acc[ai][bj][m][n] = __builtin_amdgcn_mfma_f32_16x16x32_bf16(Bt[n][k], At[m][k], acc[ai][bj][m][n], 0, 0, 0); __builtin_amdgcn_s_setprio(0); } while (0)
; #define PG8_WAIT_V(n) asm volatile("s_waitcnt vmcnt(" #n ")" ::: "memory")
; #define PG8_WAIT_L(n) asm volatile("s_waitcnt lgkmcnt(" #n ")" ::: "memory")
; #define PG8_BAR __builtin_amdgcn_s_barrier()
; #define PG8_SCHED __builtin_amdgcn_sched_barrier(0)
; template <class Epi, bool ALIGN_EPI, class Hook = NoHook>
; __device__ __forceinline__ void gemm_phase(LAS unsigned char* lds, const Gemm g, const StaticOrder& S, const Epi& E, const Hook& HK = Hook()) {
;     ...
;             PG8_WAIT_V(8); PG8_WAIT_L(0); PG8_BAR; PG8_MMA(0, 0, At, B0); PG8_MMA(0, 1, At, B1); PG8_BAR; PG8_SCHED;
;             PG8_LDA(At, 0, 1); PG8_STAGE(PG8_SB(0, 0), b2, voffB); PG8_STAGE(PG8_SB(0, 1), b2 + hstepB, voffB); PG8_STAGE(PG8_SA(0, 0), a2, voffA);
;             PG8_WAIT_V(8); PG8_WAIT_L(0); PG8_BAR; PG8_MMA(1, 0, At, B0); PG8_MMA(1, 1, At, B1); PG8_BAR; PG8_SCHED;
;             PG8_LDB(B0, 1, 0); PG8_LDB(B1, 1, 1); PG8_SCHED; PG8_LDA(At, 1, 0); PG8_STAGE(PG8_SA(0, 1), a2 + hstepA, voffA);
;             PG8_WAIT_V(8); PG8_WAIT_L(0); PG8_BAR; PG8_MMA(0, 0, At, B0); PG8_MMA(0, 1, At, B1); PG8_BAR; PG8_SCHED;
	s_waitcnt lgkmcnt(0)
	v_mfma_f32_16x16x32_bf16 v[124:127], v[156:159], v[192:195], v[124:127]
	v_mfma_f32_16x16x32_bf16 v[120:123], v[168:171], v[192:195], v[120:123]
	v_mfma_f32_16x16x32_bf16 v[108:111], v[156:159], v[204:207], v[108:111]
	v_mfma_f32_16x16x32_bf16 v[104:107], v[168:171], v[204:207], v[104:107]
	v_mfma_f32_16x16x32_bf16 v[92:95], v[156:159], v[212:215], v[92:95]
	v_mfma_f32_16x16x32_bf16 v[88:91], v[168:171], v[212:215], v[88:91]
	v_mfma_f32_16x16x32_bf16 v[76:79], v[156:159], v[220:223], v[76:79]
	v_mfma_f32_16x16x32_bf16 v[72:75], v[168:171], v[220:223], v[72:75]
	v_mfma_f32_16x16x32_bf16 v[124:127], v[160:163], v[196:199], v[124:127]
	v_mfma_f32_16x16x32_bf16 v[120:123], v[172:175], v[196:199], v[120:123]
	v_mfma_f32_16x16x32_bf16 v[108:111], v[160:163], v[208:211], v[108:111]
	v_mfma_f32_16x16x32_bf16 v[104:107], v[172:175], v[208:211], v[104:107]
	v_mfma_f32_16x16x32_bf16 v[92:95], v[160:163], v[216:219], v[92:95]
	v_mfma_f32_16x16x32_bf16 v[88:91], v[172:175], v[216:219], v[88:91]
	v_mfma_f32_16x16x32_bf16 v[76:79], v[160:163], v[224:227], v[76:79]
	v_mfma_f32_16x16x32_bf16 v[72:75], v[172:175], v[224:227], v[72:75]
	v_mfma_f32_16x16x32_bf16 v[116:119], v[176:179], v[192:195], v[116:119]
	v_mfma_f32_16x16x32_bf16 v[112:115], v[184:187], v[192:195], v[112:115]
	v_mfma_f32_16x16x32_bf16 v[100:103], v[176:179], v[204:207], v[100:103]
	v_mfma_f32_16x16x32_bf16 v[96:99], v[184:187], v[204:207], v[96:99]
	v_mfma_f32_16x16x32_bf16 v[84:87], v[176:179], v[212:215], v[84:87]
	v_mfma_f32_16x16x32_bf16 v[80:83], v[184:187], v[212:215], v[80:83]
	v_mfma_f32_16x16x32_bf16 v[68:71], v[176:179], v[220:223], v[68:71]
	v_mfma_f32_16x16x32_bf16 v[64:67], v[184:187], v[220:223], v[64:67]
	v_mfma_f32_16x16x32_bf16 v[116:119], v[180:183], v[196:199], v[116:119]
	v_mfma_f32_16x16x32_bf16 v[112:115], v[188:191], v[196:199], v[112:115]
	v_mfma_f32_16x16x32_bf16 v[100:103], v[180:183], v[208:211], v[100:103]
	v_mfma_f32_16x16x32_bf16 v[96:99], v[188:191], v[208:211], v[96:99]
	v_mfma_f32_16x16x32_bf16 v[84:87], v[180:183], v[216:219], v[84:87]
	v_mfma_f32_16x16x32_bf16 v[80:83], v[188:191], v[216:219], v[80:83]
	v_mfma_f32_16x16x32_bf16 v[68:71], v[180:183], v[224:227], v[68:71]
	v_mfma_f32_16x16x32_bf16 v[64:67], v[188:191], v[224:227], v[64:67]
	s_barrier
	s_add_i32 s34, s97, s17
	v_lshl_add_u64 v[164:165], s[88:89], 0, v[134:135]
	s_mov_b32 m0, s34
	ds_read_b128 v[192:195], v167 offset:16384
	ds_read_b128 v[196:199], v167 offset:17408
	ds_read_b128 v[204:207], v167 offset:18432
	ds_read_b128 v[208:211], v167 offset:19456
	ds_read_b128 v[212:215], v167 offset:20480
	ds_read_b128 v[216:219], v167 offset:21504
	ds_read_b128 v[220:223], v167 offset:22528
	ds_read_b128 v[224:227], v167 offset:23552
	global_load_lds_dwordx4 v[164:165], off
	s_add_i32 m0, s34, 0x2000
	s_add_u32 s34, s88, 0x80000
	v_lshl_add_u64 v[228:229], s[88:89], 0, v[146:147]
	s_addc_u32 s35, s89, 0
	s_add_i32 s52, s8, s17
	global_load_lds_dwordx4 v[228:229], off
	v_lshl_add_u64 v[230:231], s[34:35], 0, v[134:135]
	s_mov_b32 m0, s52
	v_lshl_add_u64 v[232:233], s[90:91], 0, v[144:145]
	global_load_lds_dwordx4 v[230:231], off
	v_lshl_add_u64 v[230:231], s[34:35], 0, v[146:147]
	s_add_i32 m0, s52, 0x2000
	s_nop 0
	global_load_lds_dwordx4 v[230:231], off
	v_lshl_add_u64 v[230:231], s[90:91], 0, v[130:131]
	s_mov_b32 m0, s28
	s_nop 0
	global_load_lds_dwordx4 v[230:231], off
	s_mov_b32 m0, s29
	s_nop 0
	global_load_lds_dwordx4 v[232:233], off
	s_waitcnt vmcnt(8)
	s_waitcnt lgkmcnt(0)
	s_barrier
	s_waitcnt lgkmcnt(0)
	v_mfma_f32_16x16x32_bf16 v[60:63], v[156:159], v[192:195], v[60:63]
	v_mfma_f32_16x16x32_bf16 v[56:59], v[168:171], v[192:195], v[56:59]
	v_mfma_f32_16x16x32_bf16 v[44:47], v[156:159], v[204:207], v[44:47]
	v_mfma_f32_16x16x32_bf16 v[40:43], v[168:171], v[204:207], v[40:43]
	v_mfma_f32_16x16x32_bf16 v[28:31], v[156:159], v[212:215], v[28:31]
	v_mfma_f32_16x16x32_bf16 v[24:27], v[168:171], v[212:215], v[24:27]
	v_mfma_f32_16x16x32_bf16 v[12:15], v[156:159], v[220:223], v[12:15]
	v_mfma_f32_16x16x32_bf16 v[8:11], v[168:171], v[220:223], v[8:11]
	v_mfma_f32_16x16x32_bf16 v[60:63], v[160:163], v[196:199], v[60:63]
	v_mfma_f32_16x16x32_bf16 v[56:59], v[172:175], v[196:199], v[56:59]
	v_mfma_f32_16x16x32_bf16 v[44:47], v[160:163], v[208:211], v[44:47]
	v_mfma_f32_16x16x32_bf16 v[40:43], v[172:175], v[208:211], v[40:43]
	v_mfma_f32_16x16x32_bf16 v[28:31], v[160:163], v[216:219], v[28:31]
	v_mfma_f32_16x16x32_bf16 v[24:27], v[172:175], v[216:219], v[24:27]
	v_mfma_f32_16x16x32_bf16 v[12:15], v[160:163], v[224:227], v[12:15]
	v_mfma_f32_16x16x32_bf16 v[8:11], v[172:175], v[224:227], v[8:11]
	v_mfma_f32_16x16x32_bf16 v[52:55], v[176:179], v[192:195], v[52:55]
	v_mfma_f32_16x16x32_bf16 v[48:51], v[184:187], v[192:195], v[48:51]
	v_mfma_f32_16x16x32_bf16 v[36:39], v[176:179], v[204:207], v[36:39]
	v_mfma_f32_16x16x32_bf16 v[32:35], v[184:187], v[204:207], v[32:35]
	v_mfma_f32_16x16x32_bf16 v[20:23], v[176:179], v[212:215], v[20:23]
	v_mfma_f32_16x16x32_bf16 v[16:19], v[184:187], v[212:215], v[16:19]
	v_mfma_f32_16x16x32_bf16 v[4:7], v[176:179], v[220:223], v[4:7]
	v_mfma_f32_16x16x32_bf16 v[0:3], v[184:187], v[220:223], v[0:3]
	v_mfma_f32_16x16x32_bf16 v[52:55], v[180:183], v[196:199], v[52:55]
	v_mfma_f32_16x16x32_bf16 v[48:51], v[188:191], v[196:199], v[48:51]
	v_mfma_f32_16x16x32_bf16 v[36:39], v[180:183], v[208:211], v[36:39]
	v_mfma_f32_16x16x32_bf16 v[32:35], v[188:191], v[208:211], v[32:35]
	v_mfma_f32_16x16x32_bf16 v[20:23], v[180:183], v[216:219], v[20:23]
	v_mfma_f32_16x16x32_bf16 v[16:19], v[188:191], v[216:219], v[16:19]
	v_mfma_f32_16x16x32_bf16 v[4:7], v[180:183], v[224:227], v[4:7]
	v_mfma_f32_16x16x32_bf16 v[0:3], v[188:191], v[224:227], v[0:3]
	s_barrier
; #define PG8_STAGE(bufoff, gbase, voff) do { _Pragma("unroll") for (int _i = 0; _i < 2; ++_i) \
;         __builtin_amdgcn_global_load_lds((const unsigned*)((const char*)(gbase) + (voff)[_i]), (LAS unsigned*)(lds + (bufoff) + ldsw + _i * 8192), 16, 0, 0); } while (0)
; #define PG8_LDA(dst, b, h) do { _Pragma("unroll") for (int m = 0; m < 4; ++m) _Pragma("unroll") for (int k = 0; k < 2; ++k) dst[m][k] = *(const LAS bf16x8*)(lds + PG8_SA(b, h) + aoff + m * 2048 + k * 1024); } while (0)
; #define PG8_LDB(dst, b, h) do { _Pragma("unroll") for (int n = 0; n < 2; ++n) _Pragma("unroll") for (int k = 0; k < 2; ++k) dst[n][k] = *(const LAS bf16x8*)(lds + PG8_SB(b, h) + boff + n * 2048 + k * 1024); } while (0)
; #define PG8_MMA(ai, bj, At, Bt) do { __builtin_amdgcn_s_setprio(1); _Pragma("unroll") for (int m = 0; m < 4; ++m) _Pragma("unroll") for (int n = 0; n < 2; ++n) _Pragma("unroll") for (int k = 0; k < 2; ++k) \
;         acc[ai][bj][m][n] = __builtin_amdgcn_mfma_f32_16x16x32_bf16(Bt[n][k], At[m][k], acc[ai][bj][m][n], 0, 0, 0); __builtin_amdgcn_s_setprio(0); } while (0)
; #define PG8_WAIT_V(n) asm volatile("s_waitcnt vmcnt(" #n ")" ::: "memory")
; #define PG8_WAIT_L(n) asm volatile("s_waitcnt lgkmcnt(" #n ")" ::: "memory")
; #define PG8_BAR __builtin_amdgcn_s_barrier()
; #define PG8_SCHED __builtin_amdgcn_sched_barrier(0)
; template <class Epi, bool ALIGN_EPI, class Hook = NoHook>
; __device__ __forceinline__ void gemm_phase(LAS unsigned char* lds, const Gemm g, const StaticOrder& S, const Epi& E, const Hook& HK = Hook()) {
;     ...
;             PG8_LDB(B0, 1, 0); PG8_LDB(B1, 1, 1); PG8_SCHED; PG8_LDA(At, 1, 0); PG8_STAGE(PG8_SA(0, 1), a2 + hstepA, voffA);
;             PG8_WAIT_V(8); PG8_WAIT_L(0); PG8_BAR; PG8_MMA(0, 0, At, B0); PG8_MMA(0, 1, At, B1); PG8_BAR; PG8_SCHED;
	s_add_i32 s52, 0, 0x18000
	s_add_i32 s53, 0, 0x1c000
	v_add_u32_e32 v172, s52, v133
	v_add_u32_e32 v188, s53, v133
	ds_read_b128 v[156:159], v172
	ds_read_b128 v[160:163], v172 offset:1024
	ds_read_b128 v[168:171], v172 offset:2048
	ds_read_b128 v[172:175], v172 offset:3072
	ds_read_b128 v[176:179], v188
	ds_read_b128 v[180:183], v188 offset:1024
	ds_read_b128 v[184:187], v188 offset:2048
	ds_read_b128 v[188:191], v188 offset:3072
	s_add_u32 s34, s90, 0x80000
	s_addc_u32 s35, s91, 0
	s_mov_b32 m0, s71
	v_lshl_add_u64 v[234:235], s[34:35], 0, v[130:131]
	ds_read_b128 v[192:195], v167 offset:32768
	ds_read_b128 v[196:199], v167 offset:33792
	ds_read_b128 v[204:207], v167 offset:34816
	ds_read_b128 v[208:211], v167 offset:35840
	ds_read_b128 v[212:215], v167 offset:36864
	ds_read_b128 v[216:219], v167 offset:37888
	ds_read_b128 v[220:223], v167 offset:38912
	ds_read_b128 v[224:227], v167 offset:39936
	global_load_lds_dwordx4 v[234:235], off
	v_lshl_add_u64 v[234:235], s[34:35], 0, v[144:145]
	s_mov_b32 m0, s82
	s_nop 0
	global_load_lds_dwordx4 v[234:235], off
	s_waitcnt vmcnt(8)
	s_waitcnt lgkmcnt(0)
	s_barrier
	s_waitcnt lgkmcnt(0)
	v_mfma_f32_16x16x32_bf16 v[124:127], v[156:159], v[192:195], v[124:127]
	v_mfma_f32_16x16x32_bf16 v[120:123], v[168:171], v[192:195], v[120:123]
	v_mfma_f32_16x16x32_bf16 v[108:111], v[156:159], v[204:207], v[108:111]
	v_mfma_f32_16x16x32_bf16 v[104:107], v[168:171], v[204:207], v[104:107]
	v_mfma_f32_16x16x32_bf16 v[92:95], v[156:159], v[212:215], v[92:95]
	v_mfma_f32_16x16x32_bf16 v[88:91], v[168:171], v[212:215], v[88:91]
	v_mfma_f32_16x16x32_bf16 v[76:79], v[156:159], v[220:223], v[76:79]
	v_mfma_f32_16x16x32_bf16 v[72:75], v[168:171], v[220:223], v[72:75]
	v_mfma_f32_16x16x32_bf16 v[124:127], v[160:163], v[196:199], v[124:127]
	v_mfma_f32_16x16x32_bf16 v[120:123], v[172:175], v[196:199], v[120:123]
	v_mfma_f32_16x16x32_bf16 v[108:111], v[160:163], v[208:211], v[108:111]
	v_mfma_f32_16x16x32_bf16 v[104:107], v[172:175], v[208:211], v[104:107]
	v_mfma_f32_16x16x32_bf16 v[92:95], v[160:163], v[216:219], v[92:95]
	v_mfma_f32_16x16x32_bf16 v[88:91], v[172:175], v[216:219], v[88:91]
	v_mfma_f32_16x16x32_bf16 v[76:79], v[160:163], v[224:227], v[76:79]
	v_mfma_f32_16x16x32_bf16 v[72:75], v[172:175], v[224:227], v[72:75]
	v_mfma_f32_16x16x32_bf16 v[116:119], v[176:179], v[192:195], v[116:119]
	v_mfma_f32_16x16x32_bf16 v[112:115], v[184:187], v[192:195], v[112:115]
	v_mfma_f32_16x16x32_bf16 v[100:103], v[176:179], v[204:207], v[100:103]
	v_mfma_f32_16x16x32_bf16 v[96:99], v[184:187], v[204:207], v[96:99]
	v_mfma_f32_16x16x32_bf16 v[84:87], v[176:179], v[212:215], v[84:87]
	v_mfma_f32_16x16x32_bf16 v[80:83], v[184:187], v[212:215], v[80:83]
	v_mfma_f32_16x16x32_bf16 v[68:71], v[176:179], v[220:223], v[68:71]
	v_mfma_f32_16x16x32_bf16 v[64:67], v[184:187], v[220:223], v[64:67]
	v_mfma_f32_16x16x32_bf16 v[116:119], v[180:183], v[196:199], v[116:119]
	v_mfma_f32_16x16x32_bf16 v[112:115], v[188:191], v[196:199], v[112:115]
	v_mfma_f32_16x16x32_bf16 v[100:103], v[180:183], v[208:211], v[100:103]
	v_mfma_f32_16x16x32_bf16 v[96:99], v[188:191], v[208:211], v[96:99]
	v_mfma_f32_16x16x32_bf16 v[84:87], v[180:183], v[216:219], v[84:87]
	v_mfma_f32_16x16x32_bf16 v[80:83], v[188:191], v[216:219], v[80:83]
	v_mfma_f32_16x16x32_bf16 v[68:71], v[180:183], v[224:227], v[68:71]
	v_mfma_f32_16x16x32_bf16 v[64:67], v[188:191], v[224:227], v[64:67]
	s_barrier
; #define PG8_STAGE(bufoff, gbase, voff) do { _Pragma("unroll") for (int _i = 0; _i < 2; ++_i) \
;         __builtin_amdgcn_global_load_lds((const unsigned*)((const char*)(gbase) + (voff)[_i]), (LAS unsigned*)(lds + (bufoff) + ldsw + _i * 8192), 16, 0, 0); } while (0)
; #define PG8_LDA(dst, b, h) do { _Pragma("unroll") for (int m = 0; m < 4; ++m) _Pragma("unroll") for (int k = 0; k < 2; ++k) dst[m][k] = *(const LAS bf16x8*)(lds + PG8_SA(b, h) + aoff + m * 2048 + k * 1024); } while (0)
; #define PG8_MMA(ai, bj, At, Bt) do { __builtin_amdgcn_s_setprio(1); _Pragma("unroll") for (int m = 0; m < 4; ++m) _Pragma("unroll") for (int n = 0; n < 2; ++n) _Pragma("unroll") for (int k = 0; k < 2; ++k) \
;         acc[ai][bj][m][n] = __builtin_amdgcn_mfma_f32_16x16x32_bf16(Bt[n][k], At[m][k], acc[ai][bj][m][n], 0, 0, 0); __builtin_amdgcn_s_setprio(0); } while (0)
; #define PG8_WAIT_V(n) asm volatile("s_waitcnt vmcnt(" #n ")" ::: "memory")
; #define PG8_WAIT_L(n) asm volatile("s_waitcnt lgkmcnt(" #n ")" ::: "memory")
; #define PG8_BAR __builtin_amdgcn_s_barrier()
; #define PG8_SCHED __builtin_amdgcn_sched_barrier(0)
; template <class Epi, bool ALIGN_EPI, class Hook = NoHook>
; __device__ __forceinline__ void gemm_phase(LAS unsigned char* lds, const Gemm g, const StaticOrder& S, const Epi& E, const Hook& HK = Hook()) {
;     ...
;             PG8_LDA(At, 1, 1); PG8_STAGE(PG8_SB(1, 0), b3, voffB); PG8_STAGE(PG8_SB(1, 1), b3 + hstepB, voffB); PG8_STAGE(PG8_SA(1, 0), a3, voffA);
;             PG8_WAIT_V(8); PG8_WAIT_L(0); PG8_BAR; PG8_MMA(1, 0, At, B0); PG8_MMA(1, 1, At, B1); PG8_BAR; PG8_SCHED;
;         }
	s_add_i32 s34, s52, s17
	v_lshl_add_u64 v[164:165], v[164:165], 0, s[12:13]
	s_mov_b32 m0, s34
	ds_read_b128 v[192:195], v167 offset:49152
	ds_read_b128 v[196:199], v167 offset:50176
	ds_read_b128 v[204:207], v167 offset:51200
	ds_read_b128 v[208:211], v167 offset:52224
	ds_read_b128 v[212:215], v167 offset:53248
	ds_read_b128 v[216:219], v167 offset:54272
	ds_read_b128 v[220:223], v167 offset:55296
	ds_read_b128 v[224:227], v167 offset:56320
	global_load_lds_dwordx4 v[164:165], off
	s_add_i32 m0, s34, 0x2000
	s_add_u32 s34, s88, 0x80080
	v_lshl_add_u64 v[164:165], v[228:229], 0, s[12:13]
	s_addc_u32 s35, s89, 0
	s_add_i32 s52, s53, s17
	global_load_lds_dwordx4 v[164:165], off
	v_lshl_add_u64 v[164:165], s[34:35], 0, v[134:135]
	s_mov_b32 m0, s52
	s_nop 0
	global_load_lds_dwordx4 v[164:165], off
	v_lshl_add_u64 v[164:165], s[34:35], 0, v[146:147]
	s_add_i32 m0, s52, 0x2000
	s_nop 0
	global_load_lds_dwordx4 v[164:165], off
	v_lshl_add_u64 v[164:165], v[230:231], 0, s[12:13]
	s_mov_b32 m0, s92
	s_nop 0
	global_load_lds_dwordx4 v[164:165], off
	v_lshl_add_u64 v[164:165], v[232:233], 0, s[12:13]
	s_mov_b32 m0, s93
	s_nop 0
	global_load_lds_dwordx4 v[164:165], off
	s_waitcnt vmcnt(8)
	s_waitcnt lgkmcnt(0)
	s_barrier
	s_waitcnt lgkmcnt(0)
	v_mfma_f32_16x16x32_bf16 v[60:63], v[156:159], v[192:195], v[60:63]
	v_mfma_f32_16x16x32_bf16 v[56:59], v[168:171], v[192:195], v[56:59]
	v_mfma_f32_16x16x32_bf16 v[44:47], v[156:159], v[204:207], v[44:47]
	v_mfma_f32_16x16x32_bf16 v[40:43], v[168:171], v[204:207], v[40:43]
	v_mfma_f32_16x16x32_bf16 v[28:31], v[156:159], v[212:215], v[28:31]
	v_mfma_f32_16x16x32_bf16 v[24:27], v[168:171], v[212:215], v[24:27]
	v_mfma_f32_16x16x32_bf16 v[12:15], v[156:159], v[220:223], v[12:15]
	v_mfma_f32_16x16x32_bf16 v[8:11], v[168:171], v[220:223], v[8:11]
	v_mfma_f32_16x16x32_bf16 v[60:63], v[160:163], v[196:199], v[60:63]
	v_mfma_f32_16x16x32_bf16 v[56:59], v[172:175], v[196:199], v[56:59]
	v_mfma_f32_16x16x32_bf16 v[44:47], v[160:163], v[208:211], v[44:47]
	v_mfma_f32_16x16x32_bf16 v[40:43], v[172:175], v[208:211], v[40:43]
	v_mfma_f32_16x16x32_bf16 v[28:31], v[160:163], v[216:219], v[28:31]
	v_mfma_f32_16x16x32_bf16 v[24:27], v[172:175], v[216:219], v[24:27]
	v_mfma_f32_16x16x32_bf16 v[12:15], v[160:163], v[224:227], v[12:15]
	v_mfma_f32_16x16x32_bf16 v[8:11], v[172:175], v[224:227], v[8:11]
	v_mfma_f32_16x16x32_bf16 v[52:55], v[176:179], v[192:195], v[52:55]
	v_mfma_f32_16x16x32_bf16 v[48:51], v[184:187], v[192:195], v[48:51]
	v_mfma_f32_16x16x32_bf16 v[36:39], v[176:179], v[204:207], v[36:39]
	v_mfma_f32_16x16x32_bf16 v[32:35], v[184:187], v[204:207], v[32:35]
	v_mfma_f32_16x16x32_bf16 v[20:23], v[176:179], v[212:215], v[20:23]
	v_mfma_f32_16x16x32_bf16 v[16:19], v[184:187], v[212:215], v[16:19]
	v_mfma_f32_16x16x32_bf16 v[4:7], v[176:179], v[220:223], v[4:7]
	v_mfma_f32_16x16x32_bf16 v[0:3], v[184:187], v[220:223], v[0:3]
	v_mfma_f32_16x16x32_bf16 v[52:55], v[180:183], v[196:199], v[52:55]
	v_mfma_f32_16x16x32_bf16 v[48:51], v[188:191], v[196:199], v[48:51]
	v_mfma_f32_16x16x32_bf16 v[36:39], v[180:183], v[208:211], v[36:39]
	v_mfma_f32_16x16x32_bf16 v[32:35], v[188:191], v[208:211], v[32:35]
	v_mfma_f32_16x16x32_bf16 v[20:23], v[180:183], v[216:219], v[20:23]
	v_mfma_f32_16x16x32_bf16 v[16:19], v[188:191], v[216:219], v[16:19]
	v_mfma_f32_16x16x32_bf16 v[4:7], v[180:183], v[224:227], v[4:7]
	v_mfma_f32_16x16x32_bf16 v[0:3], v[188:191], v[224:227], v[0:3]
	s_barrier
	s_add_i32 s51, s51, 2
	s_add_u32 s86, s86, 0x100
	s_addc_u32 s87, s87, 0
	s_add_u32 s27, s27, 0x100
	s_addc_u32 s50, s50, 0
	s_cmp_gt_u32 s51, 29
	s_cbranch_scc0 .LBB0_270
	s_and_b64 vcc, exec, s[14:15]
	s_cbranch_vccz .LBB0_273
	s_barrier

; #define PG8_WAIT_V(n) asm volatile("s_waitcnt vmcnt(" #n ")" ::: "memory")
; #define PG8_BAR __builtin_amdgcn_s_barrier()
; template <class Epi, bool ALIGN_EPI, class Hook = NoHook>
; __device__ __forceinline__ void gemm_phase(LAS unsigned char* lds, const Gemm g, const StaticOrder& S, const Epi& E, const Hook& HK = Hook()) {
;     ...
;     PG8_WAIT_V(0);
;     if constexpr (!ALIGN_EPI) { if (wr == 0) PG8_BAR; }
;     PG8_BAR;
.LBB0_348:
	s_setprio 0
	s_waitcnt vmcnt(0)
	s_mov_b64 s[34:35], s[56:57]
	s_mov_b64 s[56:57], s[54:55]
	s_barrier

; #define PG8_STAGE(bufoff, gbase, voff) do { _Pragma("unroll") for (int _i = 0; _i < 2; ++_i) \
;         __builtin_amdgcn_global_load_lds((const unsigned*)((const char*)(gbase) + (voff)[_i]), (LAS unsigned*)(lds + (bufoff) + ldsw + _i * 8192), 16, 0, 0); } while (0)
; #define PG8_LDA(dst, b, h) do { _Pragma("unroll") for (int m = 0; m < 4; ++m) _Pragma("unroll") for (int k = 0; k < 2; ++k) dst[m][k] = *(const LAS bf16x8*)(lds + PG8_SA(b, h) + aoff + m * 2048 + k * 1024); } while (0)
; #define PG8_LDB(dst, b, h) do { _Pragma("unroll") for (int n = 0; n < 2; ++n) _Pragma("unroll") for (int k = 0; k < 2; ++k) dst[n][k] = *(const LAS bf16x8*)(lds + PG8_SB(b, h) + boff + n * 2048 + k * 1024); } while (0)
; #define PG8_MMA(ai, bj, At, Bt) do { __builtin_amdgcn_s_setprio(1); _Pragma("unroll") for (int m = 0; m < 4; ++m) _Pragma("unroll") for (int n = 0; n < 2; ++n) _Pragma("unroll") for (int k = 0; k < 2; ++k) \
;         acc[ai][bj][m][n] = __builtin_amdgcn_mfma_f32_16x16x32_bf16(Bt[n][k], At[m][k], acc[ai][bj][m][n], 0, 0, 0); __builtin_amdgcn_s_setprio(0); } while (0)
; template <class Epi, bool ALIGN_EPI, class Hook = NoHook>
; __device__ __forceinline__ void gemm_phase(LAS unsigned char* lds, const Gemm g, const StaticOrder& S, const Epi& E, const Hook& HK = Hook()) {
;     ...
;             const bool last = (t == nt - 2);
;             const char* a1 = cA + (size_t)(t + 1) * kstep;
;             const char* a2 = last ? nA : cA + (size_t)(t + 2) * kstep; const char* b2 = last ? nB : cB + (size_t)(t + 2) * kstep;
;             const char* a3 = a2 + kstep; const char* b3 = b2 + kstep;
;             PG8_LDB(B0, 0, 0); PG8_LDB(B1, 0, 1); PG8_SCHED; PG8_LDA(At, 0, 0); PG8_STAGE(PG8_SA(1, 1), a1 + hstepA, voffA);
;             PG8_WAIT_V(8); PG8_WAIT_L(0); PG8_BAR; PG8_MMA(0, 0, At, B0); PG8_MMA(0, 1, At, B1); PG8_BAR; PG8_SCHED;
;             PG8_LDA(At, 0, 1); PG8_STAGE(PG8_SB(0, 0), b2, voffB); PG8_STAGE(PG8_SB(0, 1), b2 + hstepB, voffB); PG8_STAGE(PG8_SA(0, 0), a2, voffA);
;             PG8_WAIT_V(8); PG8_WAIT_L(0); PG8_BAR; PG8_MMA(1, 0, At, B0); PG8_MMA(1, 1, At, B1); PG8_BAR; PG8_SCHED;
;             PG8_LDB(B0, 1, 0); PG8_LDB(B1, 1, 1); PG8_SCHED; PG8_LDA(At, 1, 0); PG8_STAGE(PG8_SA(0, 1), a2 + hstepA, voffA);
;             PG8_WAIT_V(8); PG8_WAIT_L(0); PG8_BAR; PG8_MMA(0, 0, At, B0); PG8_MMA(0, 1, At, B1); PG8_BAR; PG8_SCHED;
.LBB0_708:
	s_add_u32 s34, s22, s24
	s_addc_u32 s35, s23, s25
	s_add_u32 s34, s34, 0x100
	s_addc_u32 s35, s35, 0
	s_add_u32 s36, s84, s24
	s_addc_u32 s37, s85, s25
	s_add_i32 s52, 0, 0x10000
	v_add_u32_e32 v1, s52, v193
	ds_read_b128 v[160:163], v1
	ds_read_b128 v[164:167], v1 offset:1024
	ds_read_b128 v[168:171], v1 offset:2048
	ds_read_b128 v[172:175], v1 offset:3072
	v_add_u32_e32 v1, s71, v193
	ds_read_b128 v[176:179], v1
	ds_read_b128 v[180:183], v1 offset:1024
	ds_read_b128 v[184:187], v1 offset:2048
	ds_read_b128 v[188:191], v1 offset:3072
	s_cmpk_eq_i32 s24, 0xf00
	s_cselect_b32 s39, s17, s35
	s_cselect_b32 s38, s72, s34
	s_cselect_b32 s37, s80, s37
	s_cselect_b32 s36, s81, s36
	v_lshl_add_u64 v[2:3], v[156:157], 0, s[24:25]
	s_add_i32 m0, s28, 0xc000
	ds_read_b128 v[196:199], v195
	ds_read_b128 v[208:211], v195 offset:1024
	ds_read_b128 v[212:215], v195 offset:2048
	ds_read_b128 v[216:219], v195 offset:3072
	ds_read_b128 v[220:223], v195 offset:4096
	ds_read_b128 v[224:227], v195 offset:5120
	ds_read_b128 v[228:231], v195 offset:6144
	ds_read_b128 v[232:235], v195 offset:7168
	global_load_lds_dwordx4 v[2:3], off
	v_lshl_add_u64 v[2:3], v[158:159], 0, s[24:25]
	s_add_i32 m0, s28, 0xe000
	s_nop 0
	global_load_lds_dwordx4 v[2:3], off
	s_waitcnt vmcnt(8)
	s_waitcnt lgkmcnt(0)
	s_barrier
	s_waitcnt lgkmcnt(0)
	v_mfma_f32_16x16x32_bf16 v[128:131], v[160:163], v[196:199], v[128:131]
	v_mfma_f32_16x16x32_bf16 v[124:127], v[168:171], v[196:199], v[124:127]
	v_mfma_f32_16x16x32_bf16 v[112:115], v[160:163], v[212:215], v[112:115]
	v_mfma_f32_16x16x32_bf16 v[108:111], v[168:171], v[212:215], v[108:111]
	v_mfma_f32_16x16x32_bf16 v[96:99], v[160:163], v[220:223], v[96:99]
	v_mfma_f32_16x16x32_bf16 v[92:95], v[168:171], v[220:223], v[92:95]
	v_mfma_f32_16x16x32_bf16 v[80:83], v[160:163], v[228:231], v[80:83]
	v_mfma_f32_16x16x32_bf16 v[76:79], v[168:171], v[228:231], v[76:79]
	v_mfma_f32_16x16x32_bf16 v[128:131], v[164:167], v[208:211], v[128:131]
	v_mfma_f32_16x16x32_bf16 v[124:127], v[172:175], v[208:211], v[124:127]
	v_mfma_f32_16x16x32_bf16 v[112:115], v[164:167], v[216:219], v[112:115]
	v_mfma_f32_16x16x32_bf16 v[108:111], v[172:175], v[216:219], v[108:111]
	v_mfma_f32_16x16x32_bf16 v[96:99], v[164:167], v[224:227], v[96:99]
	v_mfma_f32_16x16x32_bf16 v[92:95], v[172:175], v[224:227], v[92:95]
	v_mfma_f32_16x16x32_bf16 v[80:83], v[164:167], v[232:235], v[80:83]
	v_mfma_f32_16x16x32_bf16 v[76:79], v[172:175], v[232:235], v[76:79]
	v_mfma_f32_16x16x32_bf16 v[120:123], v[176:179], v[196:199], v[120:123]
	v_mfma_f32_16x16x32_bf16 v[116:119], v[184:187], v[196:199], v[116:119]
	v_mfma_f32_16x16x32_bf16 v[104:107], v[176:179], v[212:215], v[104:107]
	v_mfma_f32_16x16x32_bf16 v[100:103], v[184:187], v[212:215], v[100:103]
	v_mfma_f32_16x16x32_bf16 v[88:91], v[176:179], v[220:223], v[88:91]
	v_mfma_f32_16x16x32_bf16 v[84:87], v[184:187], v[220:223], v[84:87]
	v_mfma_f32_16x16x32_bf16 v[72:75], v[176:179], v[228:231], v[72:75]
	v_mfma_f32_16x16x32_bf16 v[68:71], v[184:187], v[228:231], v[68:71]
	v_mfma_f32_16x16x32_bf16 v[120:123], v[180:183], v[208:211], v[120:123]
	v_mfma_f32_16x16x32_bf16 v[116:119], v[188:191], v[208:211], v[116:119]
	v_mfma_f32_16x16x32_bf16 v[104:107], v[180:183], v[216:219], v[104:107]
	v_mfma_f32_16x16x32_bf16 v[100:103], v[188:191], v[216:219], v[100:103]
	v_mfma_f32_16x16x32_bf16 v[88:91], v[180:183], v[224:227], v[88:91]
	v_mfma_f32_16x16x32_bf16 v[84:87], v[188:191], v[224:227], v[84:87]
	v_mfma_f32_16x16x32_bf16 v[72:75], v[180:183], v[232:235], v[72:75]
	v_mfma_f32_16x16x32_bf16 v[68:71], v[188:191], v[232:235], v[68:71]
	s_barrier
	s_add_i32 s34, s52, s27
	v_lshl_add_u64 v[236:237], s[36:37], 0, v[134:135]
	s_mov_b32 m0, s34
	ds_read_b128 v[196:199], v195 offset:16384
	ds_read_b128 v[208:211], v195 offset:17408
	ds_read_b128 v[212:215], v195 offset:18432
	ds_read_b128 v[216:219], v195 offset:19456
	ds_read_b128 v[220:223], v195 offset:20480
	ds_read_b128 v[224:227], v195 offset:21504
	ds_read_b128 v[228:231], v195 offset:22528
	ds_read_b128 v[232:235], v195 offset:23552
	global_load_lds_dwordx4 v[236:237], off
	s_add_i32 m0, s34, 0x2000
	s_add_u32 s34, s36, 0x80000
	v_lshl_add_u64 v[238:239], s[36:37], 0, v[146:147]
	s_addc_u32 s35, s37, 0
	s_add_i32 s52, s71, s27
	global_load_lds_dwordx4 v[238:239], off
	v_lshl_add_u64 v[2:3], s[34:35], 0, v[134:135]
	s_mov_b32 m0, s52
	v_lshl_add_u64 v[240:241], s[38:39], 0, v[132:133]
	global_load_lds_dwordx4 v[2:3], off
	v_lshl_add_u64 v[2:3], s[34:35], 0, v[146:147]
	s_add_i32 m0, s52, 0x2000
	v_lshl_add_u64 v[242:243], s[38:39], 0, v[144:145]
	global_load_lds_dwordx4 v[2:3], off
	s_mov_b32 m0, s28
	s_nop 0
	global_load_lds_dwordx4 v[240:241], off
	s_mov_b32 m0, s29
	s_nop 0
	global_load_lds_dwordx4 v[242:243], off
	s_waitcnt vmcnt(8)
	s_waitcnt lgkmcnt(0)
	s_barrier
; #define PG8_STAGE(bufoff, gbase, voff) do { _Pragma("unroll") for (int _i = 0; _i < 2; ++_i) \
;         __builtin_amdgcn_global_load_lds((const unsigned*)((const char*)(gbase) + (voff)[_i]), (LAS unsigned*)(lds + (bufoff) + ldsw + _i * 8192), 16, 0, 0); } while (0)
; #define PG8_LDA(dst, b, h) do { _Pragma("unroll") for (int m = 0; m < 4; ++m) _Pragma("unroll") for (int k = 0; k < 2; ++k) dst[m][k] = *(const LAS bf16x8*)(lds + PG8_SA(b, h) + aoff + m * 2048 + k * 1024); } while (0)
; #define PG8_LDB(dst, b, h) do { _Pragma("unroll") for (int n = 0; n < 2; ++n) _Pragma("unroll") for (int k = 0; k < 2; ++k) dst[n][k] = *(const LAS bf16x8*)(lds + PG8_SB(b, h) + boff + n * 2048 + k * 1024); } while (0)
; #define PG8_MMA(ai, bj, At, Bt) do { __builtin_amdgcn_s_setprio(1); _Pragma("unroll") for (int m = 0; m < 4; ++m) _Pragma("unroll") for (int n = 0; n < 2; ++n) _Pragma("unroll") for (int k = 0; k < 2; ++k) \
;         acc[ai][bj][m][n] = __builtin_amdgcn_mfma_f32_16x16x32_bf16(Bt[n][k], At[m][k], acc[ai][bj][m][n], 0, 0, 0); __builtin_amdgcn_s_setprio(0); } while (0)
; #define PG8_WAIT_V(n) asm volatile("s_waitcnt vmcnt(" #n ")" ::: "memory")
; #define PG8_WAIT_L(n) asm volatile("s_waitcnt lgkmcnt(" #n ")" ::: "memory")
; #define PG8_BAR __builtin_amdgcn_s_barrier()
; #define PG8_SCHED __builtin_amdgcn_sched_barrier(0)
; template <class Epi, bool ALIGN_EPI, class Hook = NoHook>
; __device__ __forceinline__ void gemm_phase(LAS unsigned char* lds, const Gemm g, const StaticOrder& S, const Epi& E, const Hook& HK = Hook()) {
;     ...
;             PG8_WAIT_V(8); PG8_WAIT_L(0); PG8_BAR; PG8_MMA(1, 0, At, B0); PG8_MMA(1, 1, At, B1); PG8_BAR; PG8_SCHED;
;             PG8_LDB(B0, 1, 0); PG8_LDB(B1, 1, 1); PG8_SCHED; PG8_LDA(At, 1, 0); PG8_STAGE(PG8_SA(0, 1), a2 + hstepA, voffA);
;             PG8_WAIT_V(8); PG8_WAIT_L(0); PG8_BAR; PG8_MMA(0, 0, At, B0); PG8_MMA(0, 1, At, B1); PG8_BAR; PG8_SCHED;
	s_waitcnt lgkmcnt(0)
	v_mfma_f32_16x16x32_bf16 v[64:67], v[160:163], v[196:199], v[64:67]
	v_mfma_f32_16x16x32_bf16 v[60:63], v[168:171], v[196:199], v[60:63]
	v_mfma_f32_16x16x32_bf16 v[48:51], v[160:163], v[212:215], v[48:51]
	v_mfma_f32_16x16x32_bf16 v[44:47], v[168:171], v[212:215], v[44:47]
	v_mfma_f32_16x16x32_bf16 v[32:35], v[160:163], v[220:223], v[32:35]
	v_mfma_f32_16x16x32_bf16 v[28:31], v[168:171], v[220:223], v[28:31]
	v_mfma_f32_16x16x32_bf16 v[16:19], v[160:163], v[228:231], v[16:19]
	v_mfma_f32_16x16x32_bf16 v[12:15], v[168:171], v[228:231], v[12:15]
	v_mfma_f32_16x16x32_bf16 v[64:67], v[164:167], v[208:211], v[64:67]
	v_mfma_f32_16x16x32_bf16 v[60:63], v[172:175], v[208:211], v[60:63]
	v_mfma_f32_16x16x32_bf16 v[48:51], v[164:167], v[216:219], v[48:51]
	v_mfma_f32_16x16x32_bf16 v[44:47], v[172:175], v[216:219], v[44:47]
	v_mfma_f32_16x16x32_bf16 v[32:35], v[164:167], v[224:227], v[32:35]
	v_mfma_f32_16x16x32_bf16 v[28:31], v[172:175], v[224:227], v[28:31]
	v_mfma_f32_16x16x32_bf16 v[16:19], v[164:167], v[232:235], v[16:19]
	v_mfma_f32_16x16x32_bf16 v[12:15], v[172:175], v[232:235], v[12:15]
	v_mfma_f32_16x16x32_bf16 v[56:59], v[176:179], v[196:199], v[56:59]
	v_mfma_f32_16x16x32_bf16 v[52:55], v[184:187], v[196:199], v[52:55]
	v_mfma_f32_16x16x32_bf16 v[40:43], v[176:179], v[212:215], v[40:43]
	v_mfma_f32_16x16x32_bf16 v[36:39], v[184:187], v[212:215], v[36:39]
	v_mfma_f32_16x16x32_bf16 v[24:27], v[176:179], v[220:223], v[24:27]
	v_mfma_f32_16x16x32_bf16 v[20:23], v[184:187], v[220:223], v[20:23]
	v_mfma_f32_16x16x32_bf16 v[8:11], v[176:179], v[228:231], v[8:11]
	v_mfma_f32_16x16x32_bf16 v[2:5], v[184:187], v[228:231], v[4:7]
	v_mfma_f32_16x16x32_bf16 v[56:59], v[180:183], v[208:211], v[56:59]
	v_mfma_f32_16x16x32_bf16 v[52:55], v[188:191], v[208:211], v[52:55]
	v_mfma_f32_16x16x32_bf16 v[40:43], v[180:183], v[216:219], v[40:43]
	v_mfma_f32_16x16x32_bf16 v[36:39], v[188:191], v[216:219], v[36:39]
	v_mfma_f32_16x16x32_bf16 v[24:27], v[180:183], v[224:227], v[24:27]
	v_mfma_f32_16x16x32_bf16 v[20:23], v[188:191], v[224:227], v[20:23]
	v_mfma_f32_16x16x32_bf16 v[8:11], v[180:183], v[232:235], v[8:11]
	v_mfma_f32_16x16x32_bf16 v[2:5], v[188:191], v[232:235], v[2:5]
	s_barrier
	s_add_i32 s52, 0, 0x18000
	v_add_u32_e32 v1, s52, v193
	s_add_i32 s53, 0, 0x1c000
	ds_read_b128 v[160:163], v1
	ds_read_b128 v[164:167], v1 offset:1024
	ds_read_b128 v[168:171], v1 offset:2048
	ds_read_b128 v[172:175], v1 offset:3072
	v_add_u32_e32 v1, s53, v193
	ds_read_b128 v[176:179], v1
	ds_read_b128 v[180:183], v1 offset:1024
	ds_read_b128 v[184:187], v1 offset:2048
	ds_read_b128 v[188:191], v1 offset:3072
	s_add_u32 s34, s38, 0x80000
	s_addc_u32 s35, s39, 0
	s_mov_b32 m0, s40
	v_lshl_add_u64 v[6:7], s[34:35], 0, v[132:133]
	ds_read_b128 v[196:199], v195 offset:32768
	ds_read_b128 v[208:211], v195 offset:33792
	ds_read_b128 v[212:215], v195 offset:34816
	ds_read_b128 v[216:219], v195 offset:35840
	ds_read_b128 v[220:223], v195 offset:36864
	ds_read_b128 v[224:227], v195 offset:37888
	ds_read_b128 v[228:231], v195 offset:38912
	ds_read_b128 v[232:235], v195 offset:39936
	global_load_lds_dwordx4 v[6:7], off
	v_lshl_add_u64 v[6:7], s[34:35], 0, v[144:145]
	s_mov_b32 m0, s41
	s_nop 0
	global_load_lds_dwordx4 v[6:7], off
	s_waitcnt vmcnt(8)
	s_waitcnt lgkmcnt(0)
	s_barrier
	s_waitcnt lgkmcnt(0)
	v_mfma_f32_16x16x32_bf16 v[128:131], v[160:163], v[196:199], v[128:131]
	v_mfma_f32_16x16x32_bf16 v[124:127], v[168:171], v[196:199], v[124:127]
	v_mfma_f32_16x16x32_bf16 v[112:115], v[160:163], v[212:215], v[112:115]
	v_mfma_f32_16x16x32_bf16 v[108:111], v[168:171], v[212:215], v[108:111]
	v_mfma_f32_16x16x32_bf16 v[96:99], v[160:163], v[220:223], v[96:99]
	v_mfma_f32_16x16x32_bf16 v[92:95], v[168:171], v[220:223], v[92:95]
	v_mfma_f32_16x16x32_bf16 v[80:83], v[160:163], v[228:231], v[80:83]
	v_mfma_f32_16x16x32_bf16 v[76:79], v[168:171], v[228:231], v[76:79]
	v_mfma_f32_16x16x32_bf16 v[128:131], v[164:167], v[208:211], v[128:131]
	v_mfma_f32_16x16x32_bf16 v[124:127], v[172:175], v[208:211], v[124:127]
	v_mfma_f32_16x16x32_bf16 v[112:115], v[164:167], v[216:219], v[112:115]
	v_mfma_f32_16x16x32_bf16 v[108:111], v[172:175], v[216:219], v[108:111]
	v_mfma_f32_16x16x32_bf16 v[96:99], v[164:167], v[224:227], v[96:99]
	v_mfma_f32_16x16x32_bf16 v[92:95], v[172:175], v[224:227], v[92:95]
	v_mfma_f32_16x16x32_bf16 v[80:83], v[164:167], v[232:235], v[80:83]
	v_mfma_f32_16x16x32_bf16 v[76:79], v[172:175], v[232:235], v[76:79]
	v_mfma_f32_16x16x32_bf16 v[120:123], v[176:179], v[196:199], v[120:123]
	v_mfma_f32_16x16x32_bf16 v[116:119], v[184:187], v[196:199], v[116:119]
	v_mfma_f32_16x16x32_bf16 v[104:107], v[176:179], v[212:215], v[104:107]
	v_mfma_f32_16x16x32_bf16 v[100:103], v[184:187], v[212:215], v[100:103]
	v_mfma_f32_16x16x32_bf16 v[88:91], v[176:179], v[220:223], v[88:91]
	v_mfma_f32_16x16x32_bf16 v[84:87], v[184:187], v[220:223], v[84:87]
	v_mfma_f32_16x16x32_bf16 v[72:75], v[176:179], v[228:231], v[72:75]
	v_mfma_f32_16x16x32_bf16 v[68:71], v[184:187], v[228:231], v[68:71]
	v_mfma_f32_16x16x32_bf16 v[120:123], v[180:183], v[208:211], v[120:123]
	v_mfma_f32_16x16x32_bf16 v[116:119], v[188:191], v[208:211], v[116:119]
	v_mfma_f32_16x16x32_bf16 v[104:107], v[180:183], v[216:219], v[104:107]
	v_mfma_f32_16x16x32_bf16 v[100:103], v[188:191], v[216:219], v[100:103]
	v_mfma_f32_16x16x32_bf16 v[88:91], v[180:183], v[224:227], v[88:91]
	v_mfma_f32_16x16x32_bf16 v[84:87], v[188:191], v[224:227], v[84:87]
	v_mfma_f32_16x16x32_bf16 v[72:75], v[180:183], v[232:235], v[72:75]
	v_mfma_f32_16x16x32_bf16 v[68:71], v[188:191], v[232:235], v[68:71]
	s_barrier
; #define PG8_STAGE(bufoff, gbase, voff) do { _Pragma("unroll") for (int _i = 0; _i < 2; ++_i) \
;         __builtin_amdgcn_global_load_lds((const unsigned*)((const char*)(gbase) + (voff)[_i]), (LAS unsigned*)(lds + (bufoff) + ldsw + _i * 8192), 16, 0, 0); } while (0)
; #define PG8_LDA(dst, b, h) do { _Pragma("unroll") for (int m = 0; m < 4; ++m) _Pragma("unroll") for (int k = 0; k < 2; ++k) dst[m][k] = *(const LAS bf16x8*)(lds + PG8_SA(b, h) + aoff + m * 2048 + k * 1024); } while (0)
; #define PG8_MMA(ai, bj, At, Bt) do { __builtin_amdgcn_s_setprio(1); _Pragma("unroll") for (int m = 0; m < 4; ++m) _Pragma("unroll") for (int n = 0; n < 2; ++n) _Pragma("unroll") for (int k = 0; k < 2; ++k) \
;         acc[ai][bj][m][n] = __builtin_amdgcn_mfma_f32_16x16x32_bf16(Bt[n][k], At[m][k], acc[ai][bj][m][n], 0, 0, 0); __builtin_amdgcn_s_setprio(0); } while (0)
; #define PG8_WAIT_V(n) asm volatile("s_waitcnt vmcnt(" #n ")" ::: "memory")
; #define PG8_WAIT_L(n) asm volatile("s_waitcnt lgkmcnt(" #n ")" ::: "memory")
; #define PG8_BAR __builtin_amdgcn_s_barrier()
; #define PG8_SCHED __builtin_amdgcn_sched_barrier(0)
; template <class Epi, bool ALIGN_EPI, class Hook = NoHook>
; __device__ __forceinline__ void gemm_phase(LAS unsigned char* lds, const Gemm g, const StaticOrder& S, const Epi& E, const Hook& HK = Hook()) {
;     ...
;             PG8_LDA(At, 1, 1); PG8_STAGE(PG8_SB(1, 0), b3, voffB); PG8_STAGE(PG8_SB(1, 1), b3 + hstepB, voffB); PG8_STAGE(PG8_SA(1, 0), a3, voffA);
;             PG8_WAIT_V(8); PG8_WAIT_L(0); PG8_BAR; PG8_MMA(1, 0, At, B0); PG8_MMA(1, 1, At, B1); PG8_BAR; PG8_SCHED;
;         }
	s_add_i32 s34, s52, s27
	v_lshl_add_u64 v[6:7], v[236:237], 0, s[8:9]
	s_mov_b32 m0, s34
	ds_read_b128 v[196:199], v195 offset:49152
	ds_read_b128 v[208:211], v195 offset:50176
	ds_read_b128 v[212:215], v195 offset:51200
	ds_read_b128 v[216:219], v195 offset:52224
	ds_read_b128 v[220:223], v195 offset:53248
	ds_read_b128 v[224:227], v195 offset:54272
	ds_read_b128 v[228:231], v195 offset:55296
	ds_read_b128 v[232:235], v195 offset:56320
	global_load_lds_dwordx4 v[6:7], off
	s_add_i32 m0, s34, 0x2000
	s_add_u32 s34, s36, 0x80080
	v_lshl_add_u64 v[6:7], v[238:239], 0, s[8:9]
	s_addc_u32 s35, s37, 0
	s_add_i32 s36, s53, s27
	global_load_lds_dwordx4 v[6:7], off
	v_lshl_add_u64 v[6:7], s[34:35], 0, v[134:135]
	s_mov_b32 m0, s36
	s_nop 0
	global_load_lds_dwordx4 v[6:7], off
	v_lshl_add_u64 v[6:7], s[34:35], 0, v[146:147]
	s_add_i32 m0, s36, 0x2000
	s_nop 0
	global_load_lds_dwordx4 v[6:7], off
	v_lshl_add_u64 v[6:7], v[240:241], 0, s[8:9]
	s_mov_b32 m0, s45
	s_nop 0
	global_load_lds_dwordx4 v[6:7], off
	v_lshl_add_u64 v[6:7], v[242:243], 0, s[8:9]
	s_mov_b32 m0, s50
	s_nop 0
	global_load_lds_dwordx4 v[6:7], off
	s_waitcnt vmcnt(8)
	s_waitcnt lgkmcnt(0)
	s_barrier
	s_waitcnt lgkmcnt(0)
	v_mfma_f32_16x16x32_bf16 v[64:67], v[160:163], v[196:199], v[64:67]
	v_mfma_f32_16x16x32_bf16 v[60:63], v[168:171], v[196:199], v[60:63]
	v_mfma_f32_16x16x32_bf16 v[48:51], v[160:163], v[212:215], v[48:51]
	v_mfma_f32_16x16x32_bf16 v[44:47], v[168:171], v[212:215], v[44:47]
	v_mfma_f32_16x16x32_bf16 v[32:35], v[160:163], v[220:223], v[32:35]
	v_mfma_f32_16x16x32_bf16 v[28:31], v[168:171], v[220:223], v[28:31]
	v_mfma_f32_16x16x32_bf16 v[16:19], v[160:163], v[228:231], v[16:19]
	v_mfma_f32_16x16x32_bf16 v[12:15], v[168:171], v[228:231], v[12:15]
	v_mfma_f32_16x16x32_bf16 v[64:67], v[164:167], v[208:211], v[64:67]
	v_mfma_f32_16x16x32_bf16 v[60:63], v[172:175], v[208:211], v[60:63]
	v_mfma_f32_16x16x32_bf16 v[48:51], v[164:167], v[216:219], v[48:51]
	v_mfma_f32_16x16x32_bf16 v[44:47], v[172:175], v[216:219], v[44:47]
	v_mfma_f32_16x16x32_bf16 v[32:35], v[164:167], v[224:227], v[32:35]
	v_mfma_f32_16x16x32_bf16 v[28:31], v[172:175], v[224:227], v[28:31]
	v_mfma_f32_16x16x32_bf16 v[16:19], v[164:167], v[232:235], v[16:19]
	v_mfma_f32_16x16x32_bf16 v[12:15], v[172:175], v[232:235], v[12:15]
	v_mfma_f32_16x16x32_bf16 v[56:59], v[176:179], v[196:199], v[56:59]
	v_mfma_f32_16x16x32_bf16 v[52:55], v[184:187], v[196:199], v[52:55]
	v_mfma_f32_16x16x32_bf16 v[40:43], v[176:179], v[212:215], v[40:43]
	v_mfma_f32_16x16x32_bf16 v[36:39], v[184:187], v[212:215], v[36:39]
	v_mfma_f32_16x16x32_bf16 v[24:27], v[176:179], v[220:223], v[24:27]
	v_mfma_f32_16x16x32_bf16 v[20:23], v[184:187], v[220:223], v[20:23]
	v_mfma_f32_16x16x32_bf16 v[6:9], v[176:179], v[228:231], v[8:11]
	v_mfma_f32_16x16x32_bf16 v[2:5], v[184:187], v[228:231], v[2:5]
	v_mfma_f32_16x16x32_bf16 v[56:59], v[180:183], v[208:211], v[56:59]
	v_mfma_f32_16x16x32_bf16 v[52:55], v[188:191], v[208:211], v[52:55]
	v_mfma_f32_16x16x32_bf16 v[40:43], v[180:183], v[216:219], v[40:43]
	v_mfma_f32_16x16x32_bf16 v[36:39], v[188:191], v[216:219], v[36:39]
	v_mfma_f32_16x16x32_bf16 v[24:27], v[180:183], v[224:227], v[24:27]
	v_mfma_f32_16x16x32_bf16 v[20:23], v[188:191], v[224:227], v[20:23]
	v_mfma_f32_16x16x32_bf16 v[8:11], v[180:183], v[232:235], v[6:9]
	v_mfma_f32_16x16x32_bf16 v[4:7], v[188:191], v[232:235], v[2:5]
	s_barrier
	s_add_i32 s86, s86, 2
	s_add_u32 s24, s24, 0x100
	s_addc_u32 s25, s25, 0
	s_cmp_gt_u32 s86, 29
	s_cbranch_scc1 .LBB0_711

; #define PG8_BAR __builtin_amdgcn_s_barrier()
;     __host__ __device__ bool next(int i, Unit& u) const {
;         const long L = (long)i * G + c; if (L >= nwg) return false;
;         int wgid = (int)L; { const int q = nwg / NXCD, r = nwg % NXCD, xcd = wgid % NXCD, off = wgid / NXCD; wgid = (xcd < r ? xcd * (q + 1) : r * (q + 1) + (xcd - r) * q) + off; }
; template <class Epi, bool ALIGN_EPI, class Hook = NoHook>
; __device__ __forceinline__ void gemm_phase(LAS unsigned char* lds, const Gemm g, const StaticOrder& S, const Epi& E, const Hook& HK = Hook()) {
;     int tid = threadIdx.x; asm volatile("" : "+v"(tid));
;     const int wid = __builtin_amdgcn_readfirstlane(tid >> 6), lane = tid & 63, wr = wid >> 2, wc = wid & 3, fr = lane & 15, fq = lane >> 4;
;     const int K = g.K, nt = K / BK;
;     unsigned voffA[2], voffB[2];
; #pragma unroll
;     for (int i = 0; i < 2; ++i) { int R, C; stage_rc(tid * 16 + i * 8192, R, C); const int Rb = Epi::PERM ? ((R & ~31) + perm32(R & 31)) : R;
;         voffA[i] = (unsigned)(R * g.lda + C) * 2u; voffB[i] = (unsigned)(Rb * g.ldb + C) * 2u; }
;     const size_t kstep = (size_t)(BK * 2);
;     const size_t hstepA = (size_t)HALF * g.lda * 2, hstepB = (size_t)HALF * g.ldb * 2;
;     const size_t tstepA = 2 * hstepA, tstepB = 2 * hstepB;
;     const unsigned ldsw = (unsigned)wid * 1024u;
;     const int aoff = lds_byte(wr * 64 + fr, fq * 8), boff = lds_byte(wc * 32 + fr, fq * 8);
;     ...
;     Unit cur, nxt; int ui = 0;
;     if (!S.next(0, cur)) return;
;     f32x4 acc[2][2][4][2];
; #pragma unroll
;     for (int a = 0; a < 2; ++a)
; #pragma unroll
;         for (int b = 0; b < 2; ++b)
; #pragma unroll
;             for (int m = 0; m < 4; ++m)
; #pragma unroll
;                 for (int n = 0; n < 2; ++n) acc[a][b][m][n] = (f32x4){0.f, 0.f, 0.f, 0.f};
;     bf16x8 At[4][2], B0[2][2], B1[2][2];
;     const char* cA = (const char*)g.A + (size_t)cur.pm * tstepA; const char* cB = (const char*)g.Bt + (size_t)cur.pn * tstepB;
;     PG8_STAGE(PG8_SB(0, 0), cB, voffB); PG8_STAGE(PG8_SB(0, 1), cB + hstepB, voffB); PG8_STAGE(PG8_SA(0, 0), cA, voffA); PG8_STAGE(PG8_SA(0, 1), cA + hstepA, voffA);
;     if (wr == 1) PG8_BAR;
;     PG8_WAIT_V(2); PG8_BAR;
;     PG8_STAGE(PG8_SB(1, 0), cB + kstep, voffB); PG8_STAGE(PG8_SA(1, 0), cA + kstep, voffA); PG8_STAGE(PG8_SB(1, 1), cB + hstepB + kstep, voffB);
;     PG8_WAIT_V(6); PG8_BAR;
.LBB0_775:
	v_ashrrev_i32_e32 v1, 31, v8
	v_lshrrev_b32_e32 v1, 26, v1
	v_add_u32_e32 v1, v8, v1
	v_ashrrev_i32_e32 v9, 6, v1
	v_bfe_i32 v1, v8, 27, 1
	v_lshlrev_b32_e32 v0, 4, v8
	v_lshrrev_b32_e32 v1, 22, v1
	v_add_u32_e32 v1, v0, v1
	v_and_b32_e32 v1, 0xfffffc00, v1
	v_sub_u32_e32 v1, v0, v1
	v_lshrrev_b32_e32 v2, 4, v1
	v_bitop3_b32 v1, v2, v1, 32 bitop3:0x6c
	v_ashrrev_i32_e32 v3, 31, v1
	v_lshrrev_b32_e32 v3, 26, v3
	v_add_u32_e32 v3, v1, v3
	v_lshlrev_b32_e32 v2, 3, v9
	v_ashrrev_i32_e32 v10, 6, v3
	v_and_b32_e32 v3, 0xc0, v3
	v_and_b32_e32 v2, -16, v2
	v_sub_u32_e32 v1, v1, v3
	v_mov_b32_e32 v3, 1
	v_add_u32_e32 v2, v10, v2
	v_ashrrev_i16_sdwa v1, v3, sext(v1) dst_sel:DWORD dst_unused:UNUSED_PAD src0_sel:DWORD src1_sel:BYTE_0
	s_ashr_i32 s0, s7, 3
	v_lshlrev_b32_e32 v4, 5, v9
	v_bfe_i32 v11, v1, 0, 16
	v_lshlrev_b32_e32 v1, 1, v2
	v_lshrrev_b32_e32 v5, 2, v2
	v_and_b32_e32 v6, 3, v10
	s_mov_b32 s7, 0xfffe0
	v_and_b32_e32 v4, 32, v4
	v_and_b32_e32 v1, 24, v1
	v_and_b32_e32 v5, 4, v5
	v_and_or_b32 v6, v2, s7, v6
	v_or3_b32 v1, v6, v5, v1
	v_add_lshl_u32 v4, v4, v11, 1
	v_add_u32_e32 v0, 0x2000, v0
	v_lshl_add_u32 v130, v1, 12, v4
	v_ashrrev_i32_e32 v1, 31, v0
	v_lshrrev_b32_e32 v1, 22, v1
	v_add_u32_e32 v1, v0, v1
	v_ashrrev_i32_e32 v12, 10, v1
	v_mul_i32_i24_e32 v1, 0x400, v12
	v_sub_u32_e32 v0, v0, v1
	v_lshrrev_b32_e32 v1, 4, v0
	v_bitop3_b32 v0, v1, v0, 32 bitop3:0x6c
	v_lshl_add_u32 v128, v2, 12, v4
	v_ashrrev_i32_e32 v2, 31, v0
	v_lshrrev_b32_e32 v2, 26, v2
	v_add_u32_e32 v2, v0, v2
	s_add_i32 s0, s6, s0
	v_lshlrev_b32_e32 v1, 3, v12
	v_ashrrev_i32_e32 v13, 6, v2
	v_and_b32_e32 v2, 0xc0, v2
	s_ashr_i32 s6, s0, 31
	v_and_b32_e32 v1, -16, v1
	v_sub_u32_e32 v0, v0, v2
	s_lshr_b32 s6, s6, 27
	v_add_u32_e32 v1, v13, v1
	v_ashrrev_i16_sdwa v0, v3, sext(v0) dst_sel:DWORD dst_unused:UNUSED_PAD src0_sel:DWORD src1_sel:BYTE_0
	v_and_b32_e32 v3, 3, v13
	s_add_i32 s6, s0, s6
	v_and_or_b32 v3, v1, s7, v3
	s_ashr_i32 s7, s6, 5
	s_andn2_b32 s6, s6, 31
	s_sub_i32 s6, s0, s6
	s_bfe_i32 s0, s6, 0x80000
	s_bfe_u32 s0, s0, 0x2000d
	s_add_i32 s8, s6, s0
	s_bfe_i32 s0, s8, 0x80000
	s_and_b32 s8, s8, 0xfc
	s_sub_i32 s6, s6, s8
	s_lshl_b32 s7, s7, 2
	s_sext_i32_i16 s0, s0
	s_sext_i32_i8 s6, s6
	s_ashr_i32 s1, s12, 8
	s_lshr_b32 s0, s0, 2
	s_add_i32 s38, s7, s6
	s_ashr_i32 s10, s12, 6
	s_ashr_i32 s39, s38, 31
	s_bfe_i64 s[8:9], s[0:1], 0x100000
	s_lshl_b32 s27, s10, 10
	s_lshl_b64 s[6:7], s[38:39], 20
	s_lshl_b64 s[8:9], s[8:9], 20
	s_add_u32 s42, s74, s8
	v_lshlrev_b32_e32 v4, 5, v12
	v_bfe_i32 v14, v0, 0, 16
	v_lshlrev_b32_e32 v0, 1, v1
	v_lshrrev_b32_e32 v2, 2, v1
	s_addc_u32 s43, s75, s9
	s_add_i32 s28, s27, 0
	v_and_b32_e32 v4, 32, v4
	v_and_b32_e32 v0, 24, v0
	v_and_b32_e32 v2, 4, v2
	s_add_i32 m0, s28, 0x10000
	v_or3_b32 v0, v3, v2, v0
	v_add_lshl_u32 v2, v4, v14, 1
	global_load_lds_dwordx4 v130, s[42:43]
	s_add_i32 m0, s28, 0x12000
	v_lshl_add_u32 v134, v0, 12, v2
	s_add_u32 s8, s42, 0x80000
	global_load_lds_dwordx4 v134, s[42:43]
	s_addc_u32 s9, s43, 0
	s_add_i32 m0, s28, 0x14000
	v_lshl_add_u32 v132, v1, 12, v2
	global_load_lds_dwordx4 v130, s[8:9]
	s_add_i32 m0, s28, 0x16000
	s_add_u32 s40, s66, s6
	s_addc_u32 s41, s67, s7
	s_add_i32 s29, s28, 0x2000
	global_load_lds_dwordx4 v134, s[8:9]
	s_mov_b32 m0, s28
	s_add_u32 s6, s40, 0x80000
	global_load_lds_dwordx4 v128, s[40:41]
	s_mov_b32 m0, s29
	s_addc_u32 s7, s41, 0
	s_add_i32 s39, s28, 0x4000
	global_load_lds_dwordx4 v132, s[40:41]
	s_mov_b32 m0, s39
	s_add_i32 s50, s28, 0x6000
	global_load_lds_dwordx4 v128, s[6:7]
	s_mov_b32 m0, s50
	v_mov_b32_e32 v131, 0
	global_load_lds_dwordx4 v132, s[6:7]
	v_mov_b32_e32 v135, v131
	v_mov_b32_e32 v129, v131
	v_mov_b32_e32 v133, v131
	s_cmp_eq_u32 s1, 1
	s_mov_b32 s51, 0
	v_lshl_add_u64 v[6:7], s[42:43], 0, v[130:131]
	v_lshl_add_u64 v[2:3], s[42:43], 0, v[134:135]
	s_mov_b64 s[6:7], 0x80000
	v_lshl_add_u64 v[0:1], s[40:41], 0, v[128:129]
	s_cselect_b64 s[8:9], -1, 0
	s_cmp_lg_u32 s1, 1
	v_lshl_add_u64 v[4:5], s[40:41], 0, v[132:133]
	s_cbranch_scc1 .LBB0_777
	s_barrier
	s_setprio 1

; #define PG8_STAGE(bufoff, gbase, voff) do { _Pragma("unroll") for (int _i = 0; _i < 2; ++_i) \
;         __builtin_amdgcn_global_load_lds((const unsigned*)((const char*)(gbase) + (voff)[_i]), (LAS unsigned*)(lds + (bufoff) + ldsw + _i * 8192), 16, 0, 0); } while (0)
; #define PG8_LDA(dst, b, h) do { _Pragma("unroll") for (int m = 0; m < 4; ++m) _Pragma("unroll") for (int k = 0; k < 2; ++k) dst[m][k] = *(const LAS bf16x8*)(lds + PG8_SA(b, h) + aoff + m * 2048 + k * 1024); } while (0)
; #define PG8_LDB(dst, b, h) do { _Pragma("unroll") for (int n = 0; n < 2; ++n) _Pragma("unroll") for (int k = 0; k < 2; ++k) dst[n][k] = *(const LAS bf16x8*)(lds + PG8_SB(b, h) + boff + n * 2048 + k * 1024); } while (0)
; #define PG8_WAIT_V(n) asm volatile("s_waitcnt vmcnt(" #n ")" ::: "memory")
; #define PG8_WAIT_L(n) asm volatile("s_waitcnt lgkmcnt(" #n ")" ::: "memory")
; #define PG8_BAR __builtin_amdgcn_s_barrier()
; #define PG8_SCHED __builtin_amdgcn_sched_barrier(0)
; template <class Epi, bool ALIGN_EPI, class Hook = NoHook>
; __device__ __forceinline__ void gemm_phase(LAS unsigned char* lds, const Gemm g, const StaticOrder& S, const Epi& E, const Hook& HK = Hook()) {
;     ...
;         const bool has_next = S.next(ui + 1, nxt);
;         const char* nA = has_next ? (const char*)g.A + (size_t)nxt.pm * tstepA : cA; const char* nB = has_next ? (const char*)g.Bt + (size_t)nxt.pn * tstepB : cB;
;         for (int t = 0; t < nt; t += 2) {
;             if (Hook::AT > 0 && t == Hook::AT) HK(acc, cur, wr, wc, fr, fq);
;             const bool last = (t == nt - 2);
;             const char* a1 = cA + (size_t)(t + 1) * kstep;
;             const char* a2 = last ? nA : cA + (size_t)(t + 2) * kstep; const char* b2 = last ? nB : cB + (size_t)(t + 2) * kstep;
;             const char* a3 = a2 + kstep; const char* b3 = b2 + kstep;
;             PG8_LDB(B0, 0, 0); PG8_LDB(B1, 0, 1); PG8_SCHED; PG8_LDA(At, 0, 0); PG8_STAGE(PG8_SA(1, 1), a1 + hstepA, voffA);
;             PG8_WAIT_V(8); PG8_WAIT_L(0); PG8_BAR; PG8_MMA(0, 0, At, B0); PG8_MMA(0, 1, At, B1); PG8_BAR; PG8_SCHED;
;             PG8_LDA(At, 0, 1); PG8_STAGE(PG8_SB(0, 0), b2, voffB); PG8_STAGE(PG8_SB(0, 1), b2 + hstepB, voffB); PG8_STAGE(PG8_SA(0, 0), a2, voffA);
;             PG8_WAIT_V(8); PG8_WAIT_L(0); PG8_BAR; PG8_MMA(1, 0, At, B0); PG8_MMA(1, 1, At, B1); PG8_BAR; PG8_SCHED;
.LBB0_786:
	s_ashr_i32 s23, s22, 31
	s_lshl_b64 s[24:25], s[22:23], 20
	s_add_u32 s24, s66, s24
	s_addc_u32 s25, s67, s25
	s_and_b64 s[34:35], s[0:1], exec
	s_cselect_b32 s23, s25, s41
	s_cselect_b32 s81, s24, s40
	s_ashr_i32 s21, s20, 31
	s_lshl_b64 s[34:35], s[20:21], 20
	s_add_u32 s36, s74, s34
	s_addc_u32 s37, s75, s35
	s_and_b64 s[34:35], s[0:1], exec
	s_cselect_b32 s21, s37, s43
	s_cselect_b32 s82, s36, s42
	s_add_u32 s40, s40, 0x80080
	s_addc_u32 s41, s41, 0
	s_add_u32 s83, s42, 0x100
	s_addc_u32 s84, s43, 0
	s_mov_b32 s85, -2
	s_waitcnt vmcnt(0)
	ds_read_b128 v[152:155], v165
	ds_read_b128 v[156:159], v165 offset:1024
	ds_read_b128 v[160:163], v165 offset:2048
	ds_read_b128 v[168:171], v165 offset:3072
	ds_read_b128 v[172:175], v166
	ds_read_b128 v[176:179], v166 offset:1024
	ds_read_b128 v[180:183], v166 offset:2048
	ds_read_b128 v[184:187], v166 offset:3072
	s_add_u32 s34, s40, 0xfff80080
	s_addc_u32 s35, s41, -1
	s_cmp_eq_u32 s85, 28
	s_cselect_b32 s45, s23, s35
	s_cselect_b32 s44, s81, s34
	s_cselect_b32 s43, s21, s84
	s_cselect_b32 s42, s82, s83
	v_lshl_add_u64 v[228:229], s[40:41], 0, v[144:145]
	s_add_i32 m0, s28, 0xc000
	ds_read_b128 v[188:191], v167
	ds_read_b128 v[192:195], v167 offset:1024
	ds_read_b128 v[196:199], v167 offset:2048
	ds_read_b128 v[208:211], v167 offset:3072
	ds_read_b128 v[212:215], v167 offset:4096
	ds_read_b128 v[216:219], v167 offset:5120
	ds_read_b128 v[220:223], v167 offset:6144
	ds_read_b128 v[224:227], v167 offset:7168
	global_load_lds_dwordx4 v[228:229], off
	v_lshl_add_u64 v[228:229], s[40:41], 0, v[146:147]
	s_add_i32 m0, s28, 0xe000
	s_nop 0
	global_load_lds_dwordx4 v[228:229], off
	s_waitcnt vmcnt(8)
	s_waitcnt lgkmcnt(0)
	s_barrier
	s_waitcnt lgkmcnt(0)
	v_mfma_f32_16x16x32_bf16 v[124:127], v[152:155], v[188:191], 0
	v_mfma_f32_16x16x32_bf16 v[120:123], v[160:163], v[188:191], 0
	v_mfma_f32_16x16x32_bf16 v[112:115], v[152:155], v[196:199], 0
	v_mfma_f32_16x16x32_bf16 v[104:107], v[160:163], v[196:199], 0
	v_mfma_f32_16x16x32_bf16 v[96:99], v[152:155], v[212:215], 0
	v_mfma_f32_16x16x32_bf16 v[88:91], v[160:163], v[212:215], 0
	v_mfma_f32_16x16x32_bf16 v[80:83], v[152:155], v[220:223], 0
	v_mfma_f32_16x16x32_bf16 v[72:75], v[160:163], v[220:223], 0
	v_mfma_f32_16x16x32_bf16 v[124:127], v[156:159], v[192:195], v[124:127]
	v_mfma_f32_16x16x32_bf16 v[120:123], v[168:171], v[192:195], v[120:123]
	v_mfma_f32_16x16x32_bf16 v[112:115], v[156:159], v[208:211], v[112:115]
	v_mfma_f32_16x16x32_bf16 v[104:107], v[168:171], v[208:211], v[104:107]
	v_mfma_f32_16x16x32_bf16 v[96:99], v[156:159], v[216:219], v[96:99]
	v_mfma_f32_16x16x32_bf16 v[88:91], v[168:171], v[216:219], v[88:91]
	v_mfma_f32_16x16x32_bf16 v[80:83], v[156:159], v[224:227], v[80:83]
	v_mfma_f32_16x16x32_bf16 v[72:75], v[168:171], v[224:227], v[72:75]
	v_mfma_f32_16x16x32_bf16 v[116:119], v[172:175], v[188:191], 0
	v_mfma_f32_16x16x32_bf16 v[108:111], v[180:183], v[188:191], 0
	v_mfma_f32_16x16x32_bf16 v[100:103], v[172:175], v[196:199], 0
	v_mfma_f32_16x16x32_bf16 v[92:95], v[180:183], v[196:199], 0
	v_mfma_f32_16x16x32_bf16 v[84:87], v[172:175], v[212:215], 0
	v_mfma_f32_16x16x32_bf16 v[76:79], v[180:183], v[212:215], 0
	v_mfma_f32_16x16x32_bf16 v[68:71], v[172:175], v[220:223], 0
	v_mfma_f32_16x16x32_bf16 v[64:67], v[180:183], v[220:223], 0
	v_mfma_f32_16x16x32_bf16 v[116:119], v[176:179], v[192:195], v[116:119]
	v_mfma_f32_16x16x32_bf16 v[108:111], v[184:187], v[192:195], v[108:111]
	v_mfma_f32_16x16x32_bf16 v[100:103], v[176:179], v[208:211], v[100:103]
	v_mfma_f32_16x16x32_bf16 v[92:95], v[184:187], v[208:211], v[92:95]
	v_mfma_f32_16x16x32_bf16 v[84:87], v[176:179], v[216:219], v[84:87]
	v_mfma_f32_16x16x32_bf16 v[76:79], v[184:187], v[216:219], v[76:79]
	v_mfma_f32_16x16x32_bf16 v[68:71], v[176:179], v[224:227], v[68:71]
	v_mfma_f32_16x16x32_bf16 v[64:67], v[184:187], v[224:227], v[64:67]
	s_barrier
	s_add_i32 s34, s78, s27
	v_lshl_add_u64 v[228:229], s[42:43], 0, v[130:131]
	s_mov_b32 m0, s34
	ds_read_b128 v[188:191], v167 offset:16384
	ds_read_b128 v[192:195], v167 offset:17408
	ds_read_b128 v[196:199], v167 offset:18432
	ds_read_b128 v[208:211], v167 offset:19456
	ds_read_b128 v[212:215], v167 offset:20480
	ds_read_b128 v[216:219], v167 offset:21504
	ds_read_b128 v[220:223], v167 offset:22528
	ds_read_b128 v[224:227], v167 offset:23552
	global_load_lds_dwordx4 v[228:229], off
	s_add_i32 m0, s34, 0x2000
	s_add_u32 s34, s42, 0x80000
	v_lshl_add_u64 v[230:231], s[42:43], 0, v[134:135]
	s_addc_u32 s35, s43, 0
	s_add_i32 s52, s79, s27
	global_load_lds_dwordx4 v[230:231], off
	v_lshl_add_u64 v[232:233], s[34:35], 0, v[130:131]
	s_mov_b32 m0, s52
	v_lshl_add_u64 v[234:235], s[44:45], 0, v[132:133]
	global_load_lds_dwordx4 v[232:233], off
	v_lshl_add_u64 v[232:233], s[34:35], 0, v[134:135]
	s_add_i32 m0, s52, 0x2000
	s_nop 0
	global_load_lds_dwordx4 v[232:233], off
	v_lshl_add_u64 v[232:233], s[44:45], 0, v[128:129]
	s_mov_b32 m0, s28
	s_nop 0
	global_load_lds_dwordx4 v[232:233], off
	s_mov_b32 m0, s29
	s_nop 0
	global_load_lds_dwordx4 v[234:235], off
	s_waitcnt vmcnt(8)
	s_waitcnt lgkmcnt(0)
	s_barrier
; #define PG8_STAGE(bufoff, gbase, voff) do { _Pragma("unroll") for (int _i = 0; _i < 2; ++_i) \
;         __builtin_amdgcn_global_load_lds((const unsigned*)((const char*)(gbase) + (voff)[_i]), (LAS unsigned*)(lds + (bufoff) + ldsw + _i * 8192), 16, 0, 0); } while (0)
; #define PG8_LDA(dst, b, h) do { _Pragma("unroll") for (int m = 0; m < 4; ++m) _Pragma("unroll") for (int k = 0; k < 2; ++k) dst[m][k] = *(const LAS bf16x8*)(lds + PG8_SA(b, h) + aoff + m * 2048 + k * 1024); } while (0)
; #define PG8_LDB(dst, b, h) do { _Pragma("unroll") for (int n = 0; n < 2; ++n) _Pragma("unroll") for (int k = 0; k < 2; ++k) dst[n][k] = *(const LAS bf16x8*)(lds + PG8_SB(b, h) + boff + n * 2048 + k * 1024); } while (0)
; #define PG8_MMA(ai, bj, At, Bt) do { __builtin_amdgcn_s_setprio(1); _Pragma("unroll") for (int m = 0; m < 4; ++m) _Pragma("unroll") for (int n = 0; n < 2; ++n) _Pragma("unroll") for (int k = 0; k < 2; ++k) \
;         acc[ai][bj][m][n] = __builtin_amdgcn_mfma_f32_16x16x32_bf16(Bt[n][k], At[m][k], acc[ai][bj][m][n], 0, 0, 0); __builtin_amdgcn_s_setprio(0); } while (0)
; #define PG8_WAIT_V(n) asm volatile("s_waitcnt vmcnt(" #n ")" ::: "memory")
; #define PG8_WAIT_L(n) asm volatile("s_waitcnt lgkmcnt(" #n ")" ::: "memory")
; #define PG8_BAR __builtin_amdgcn_s_barrier()
; #define PG8_SCHED __builtin_amdgcn_sched_barrier(0)
; template <class Epi, bool ALIGN_EPI, class Hook = NoHook>
; __device__ __forceinline__ void gemm_phase(LAS unsigned char* lds, const Gemm g, const StaticOrder& S, const Epi& E, const Hook& HK = Hook()) {
;     ...
;             PG8_WAIT_V(8); PG8_WAIT_L(0); PG8_BAR; PG8_MMA(1, 0, At, B0); PG8_MMA(1, 1, At, B1); PG8_BAR; PG8_SCHED;
;             PG8_LDB(B0, 1, 0); PG8_LDB(B1, 1, 1); PG8_SCHED; PG8_LDA(At, 1, 0); PG8_STAGE(PG8_SA(0, 1), a2 + hstepA, voffA);
;             PG8_WAIT_V(8); PG8_WAIT_L(0); PG8_BAR; PG8_MMA(0, 0, At, B0); PG8_MMA(0, 1, At, B1); PG8_BAR; PG8_SCHED;
	s_waitcnt lgkmcnt(0)
	v_mfma_f32_16x16x32_bf16 v[60:63], v[152:155], v[188:191], 0
	v_mfma_f32_16x16x32_bf16 v[56:59], v[160:163], v[188:191], 0
	v_mfma_f32_16x16x32_bf16 v[48:51], v[152:155], v[196:199], 0
	v_mfma_f32_16x16x32_bf16 v[40:43], v[160:163], v[196:199], 0
	v_mfma_f32_16x16x32_bf16 v[32:35], v[152:155], v[212:215], 0
	v_mfma_f32_16x16x32_bf16 v[24:27], v[160:163], v[212:215], 0
	v_mfma_f32_16x16x32_bf16 v[16:19], v[152:155], v[220:223], 0
	v_mfma_f32_16x16x32_bf16 v[8:11], v[160:163], v[220:223], 0
	v_mfma_f32_16x16x32_bf16 v[60:63], v[156:159], v[192:195], v[60:63]
	v_mfma_f32_16x16x32_bf16 v[56:59], v[168:171], v[192:195], v[56:59]
	v_mfma_f32_16x16x32_bf16 v[48:51], v[156:159], v[208:211], v[48:51]
	v_mfma_f32_16x16x32_bf16 v[40:43], v[168:171], v[208:211], v[40:43]
	v_mfma_f32_16x16x32_bf16 v[32:35], v[156:159], v[216:219], v[32:35]
	v_mfma_f32_16x16x32_bf16 v[24:27], v[168:171], v[216:219], v[24:27]
	v_mfma_f32_16x16x32_bf16 v[16:19], v[156:159], v[224:227], v[16:19]
	v_mfma_f32_16x16x32_bf16 v[8:11], v[168:171], v[224:227], v[8:11]
	v_mfma_f32_16x16x32_bf16 v[52:55], v[172:175], v[188:191], 0
	v_mfma_f32_16x16x32_bf16 v[44:47], v[180:183], v[188:191], 0
	v_mfma_f32_16x16x32_bf16 v[36:39], v[172:175], v[196:199], 0
	v_mfma_f32_16x16x32_bf16 v[28:31], v[180:183], v[196:199], 0
	v_mfma_f32_16x16x32_bf16 v[20:23], v[172:175], v[212:215], 0
	v_mfma_f32_16x16x32_bf16 v[12:15], v[180:183], v[212:215], 0
	v_mfma_f32_16x16x32_bf16 v[4:7], v[172:175], v[220:223], 0
	v_mfma_f32_16x16x32_bf16 v[0:3], v[180:183], v[220:223], 0
	v_mfma_f32_16x16x32_bf16 v[52:55], v[176:179], v[192:195], v[52:55]
	v_mfma_f32_16x16x32_bf16 v[44:47], v[184:187], v[192:195], v[44:47]
	v_mfma_f32_16x16x32_bf16 v[36:39], v[176:179], v[208:211], v[36:39]
	v_mfma_f32_16x16x32_bf16 v[28:31], v[184:187], v[208:211], v[28:31]
	v_mfma_f32_16x16x32_bf16 v[20:23], v[176:179], v[216:219], v[20:23]
	v_mfma_f32_16x16x32_bf16 v[12:15], v[184:187], v[216:219], v[12:15]
	v_mfma_f32_16x16x32_bf16 v[4:7], v[176:179], v[224:227], v[4:7]
	v_mfma_f32_16x16x32_bf16 v[0:3], v[184:187], v[224:227], v[0:3]
	s_barrier
	s_add_i32 s52, 0, 0x18000
	s_add_i32 s53, 0, 0x1c000
	v_add_u32_e32 v168, s52, v143
	v_add_u32_e32 v184, s53, v143
	ds_read_b128 v[152:155], v168
	ds_read_b128 v[156:159], v168 offset:1024
	ds_read_b128 v[160:163], v168 offset:2048
	ds_read_b128 v[168:171], v168 offset:3072
	ds_read_b128 v[172:175], v184
	ds_read_b128 v[176:179], v184 offset:1024
	ds_read_b128 v[180:183], v184 offset:2048
	ds_read_b128 v[184:187], v184 offset:3072
	s_add_u32 s34, s44, 0x80000
	s_addc_u32 s35, s45, 0
	s_mov_b32 m0, s39
	v_lshl_add_u64 v[236:237], s[34:35], 0, v[128:129]
	ds_read_b128 v[188:191], v167 offset:32768
	ds_read_b128 v[192:195], v167 offset:33792
	ds_read_b128 v[196:199], v167 offset:34816
	ds_read_b128 v[208:211], v167 offset:35840
	ds_read_b128 v[212:215], v167 offset:36864
	ds_read_b128 v[216:219], v167 offset:37888
	ds_read_b128 v[220:223], v167 offset:38912
	ds_read_b128 v[224:227], v167 offset:39936
	global_load_lds_dwordx4 v[236:237], off
	v_lshl_add_u64 v[236:237], s[34:35], 0, v[132:133]
	s_mov_b32 m0, s50
	s_nop 0
	global_load_lds_dwordx4 v[236:237], off
	s_waitcnt vmcnt(8)
	s_waitcnt lgkmcnt(0)
	s_barrier
	s_waitcnt lgkmcnt(0)
	v_mfma_f32_16x16x32_bf16 v[124:127], v[152:155], v[188:191], v[124:127]
	v_mfma_f32_16x16x32_bf16 v[120:123], v[160:163], v[188:191], v[120:123]
	v_mfma_f32_16x16x32_bf16 v[112:115], v[152:155], v[196:199], v[112:115]
	v_mfma_f32_16x16x32_bf16 v[104:107], v[160:163], v[196:199], v[104:107]
	v_mfma_f32_16x16x32_bf16 v[96:99], v[152:155], v[212:215], v[96:99]
	v_mfma_f32_16x16x32_bf16 v[88:91], v[160:163], v[212:215], v[88:91]
	v_mfma_f32_16x16x32_bf16 v[80:83], v[152:155], v[220:223], v[80:83]
	v_mfma_f32_16x16x32_bf16 v[72:75], v[160:163], v[220:223], v[72:75]
	v_mfma_f32_16x16x32_bf16 v[124:127], v[156:159], v[192:195], v[124:127]
	v_mfma_f32_16x16x32_bf16 v[120:123], v[168:171], v[192:195], v[120:123]
	v_mfma_f32_16x16x32_bf16 v[112:115], v[156:159], v[208:211], v[112:115]
	v_mfma_f32_16x16x32_bf16 v[104:107], v[168:171], v[208:211], v[104:107]
	v_mfma_f32_16x16x32_bf16 v[96:99], v[156:159], v[216:219], v[96:99]
	v_mfma_f32_16x16x32_bf16 v[88:91], v[168:171], v[216:219], v[88:91]
	v_mfma_f32_16x16x32_bf16 v[80:83], v[156:159], v[224:227], v[80:83]
	v_mfma_f32_16x16x32_bf16 v[72:75], v[168:171], v[224:227], v[72:75]
	v_mfma_f32_16x16x32_bf16 v[116:119], v[172:175], v[188:191], v[116:119]
	v_mfma_f32_16x16x32_bf16 v[108:111], v[180:183], v[188:191], v[108:111]
	v_mfma_f32_16x16x32_bf16 v[100:103], v[172:175], v[196:199], v[100:103]
	v_mfma_f32_16x16x32_bf16 v[92:95], v[180:183], v[196:199], v[92:95]
	v_mfma_f32_16x16x32_bf16 v[84:87], v[172:175], v[212:215], v[84:87]
	v_mfma_f32_16x16x32_bf16 v[76:79], v[180:183], v[212:215], v[76:79]
	v_mfma_f32_16x16x32_bf16 v[68:71], v[172:175], v[220:223], v[68:71]
	v_mfma_f32_16x16x32_bf16 v[64:67], v[180:183], v[220:223], v[64:67]
	v_mfma_f32_16x16x32_bf16 v[116:119], v[176:179], v[192:195], v[116:119]
	v_mfma_f32_16x16x32_bf16 v[108:111], v[184:187], v[192:195], v[108:111]
	v_mfma_f32_16x16x32_bf16 v[100:103], v[176:179], v[208:211], v[100:103]
	v_mfma_f32_16x16x32_bf16 v[92:95], v[184:187], v[208:211], v[92:95]
	v_mfma_f32_16x16x32_bf16 v[84:87], v[176:179], v[216:219], v[84:87]
	v_mfma_f32_16x16x32_bf16 v[76:79], v[184:187], v[216:219], v[76:79]
	v_mfma_f32_16x16x32_bf16 v[68:71], v[176:179], v[224:227], v[68:71]
	v_mfma_f32_16x16x32_bf16 v[64:67], v[184:187], v[224:227], v[64:67]
	s_barrier
; #define PG8_STAGE(bufoff, gbase, voff) do { _Pragma("unroll") for (int _i = 0; _i < 2; ++_i) \
;         __builtin_amdgcn_global_load_lds((const unsigned*)((const char*)(gbase) + (voff)[_i]), (LAS unsigned*)(lds + (bufoff) + ldsw + _i * 8192), 16, 0, 0); } while (0)
; #define PG8_LDA(dst, b, h) do { _Pragma("unroll") for (int m = 0; m < 4; ++m) _Pragma("unroll") for (int k = 0; k < 2; ++k) dst[m][k] = *(const LAS bf16x8*)(lds + PG8_SA(b, h) + aoff + m * 2048 + k * 1024); } while (0)
; #define PG8_LDB(dst, b, h) do { _Pragma("unroll") for (int n = 0; n < 2; ++n) _Pragma("unroll") for (int k = 0; k < 2; ++k) dst[n][k] = *(const LAS bf16x8*)(lds + PG8_SB(b, h) + boff + n * 2048 + k * 1024); } while (0)
; #define PG8_MMA(ai, bj, At, Bt) do { __builtin_amdgcn_s_setprio(1); _Pragma("unroll") for (int m = 0; m < 4; ++m) _Pragma("unroll") for (int n = 0; n < 2; ++n) _Pragma("unroll") for (int k = 0; k < 2; ++k) \
;         acc[ai][bj][m][n] = __builtin_amdgcn_mfma_f32_16x16x32_bf16(Bt[n][k], At[m][k], acc[ai][bj][m][n], 0, 0, 0); __builtin_amdgcn_s_setprio(0); } while (0)
; #define PG8_WAIT_V(n) asm volatile("s_waitcnt vmcnt(" #n ")" ::: "memory")
; #define PG8_WAIT_L(n) asm volatile("s_waitcnt lgkmcnt(" #n ")" ::: "memory")
; #define PG8_BAR __builtin_amdgcn_s_barrier()
; #define PG8_SCHED __builtin_amdgcn_sched_barrier(0)
; template <class Epi, bool ALIGN_EPI, class Hook = NoHook>
; __device__ __forceinline__ void gemm_phase(LAS unsigned char* lds, const Gemm g, const StaticOrder& S, const Epi& E, const Hook& HK = Hook()) {
;     ...
;             PG8_LDB(B0, 0, 0); PG8_LDB(B1, 0, 1); PG8_SCHED; PG8_LDA(At, 0, 0); PG8_STAGE(PG8_SA(1, 1), a1 + hstepA, voffA);
;             PG8_WAIT_V(8); PG8_WAIT_L(0); PG8_BAR; PG8_MMA(0, 0, At, B0); PG8_MMA(0, 1, At, B1); PG8_BAR; PG8_SCHED;
;     ...
;             PG8_LDA(At, 1, 1); PG8_STAGE(PG8_SB(1, 0), b3, voffB); PG8_STAGE(PG8_SB(1, 1), b3 + hstepB, voffB); PG8_STAGE(PG8_SA(1, 0), a3, voffA);
;             PG8_WAIT_V(8); PG8_WAIT_L(0); PG8_BAR; PG8_MMA(1, 0, At, B0); PG8_MMA(1, 1, At, B1); PG8_BAR; PG8_SCHED;
	s_add_i32 s34, s52, s27
	v_lshl_add_u64 v[228:229], v[228:229], 0, s[10:11]
	s_mov_b32 m0, s34
	ds_read_b128 v[188:191], v167 offset:49152
	ds_read_b128 v[192:195], v167 offset:50176
	ds_read_b128 v[196:199], v167 offset:51200
	ds_read_b128 v[208:211], v167 offset:52224
	ds_read_b128 v[212:215], v167 offset:53248
	ds_read_b128 v[216:219], v167 offset:54272
	ds_read_b128 v[220:223], v167 offset:55296
	ds_read_b128 v[224:227], v167 offset:56320
	global_load_lds_dwordx4 v[228:229], off
	s_add_i32 m0, s34, 0x2000
	s_add_u32 s34, s42, 0x80080
	v_lshl_add_u64 v[228:229], v[230:231], 0, s[10:11]
	s_addc_u32 s35, s43, 0
	s_add_i32 s42, s53, s27
	global_load_lds_dwordx4 v[228:229], off
	v_lshl_add_u64 v[228:229], s[34:35], 0, v[130:131]
	s_mov_b32 m0, s42
	s_nop 0
	global_load_lds_dwordx4 v[228:229], off
	v_lshl_add_u64 v[228:229], s[34:35], 0, v[134:135]
	s_add_i32 m0, s42, 0x2000
	s_nop 0
	global_load_lds_dwordx4 v[228:229], off
	v_lshl_add_u64 v[228:229], v[232:233], 0, s[10:11]
	s_mov_b32 m0, s65
	s_nop 0
	global_load_lds_dwordx4 v[228:229], off
	v_lshl_add_u64 v[228:229], v[234:235], 0, s[10:11]
	s_mov_b32 m0, s71
	s_nop 0
	global_load_lds_dwordx4 v[228:229], off
	s_waitcnt vmcnt(8)
	s_waitcnt lgkmcnt(0)
	s_barrier
	s_waitcnt lgkmcnt(0)
	v_mfma_f32_16x16x32_bf16 v[60:63], v[152:155], v[188:191], v[60:63]
	v_mfma_f32_16x16x32_bf16 v[56:59], v[160:163], v[188:191], v[56:59]
	v_mfma_f32_16x16x32_bf16 v[48:51], v[152:155], v[196:199], v[48:51]
	v_mfma_f32_16x16x32_bf16 v[40:43], v[160:163], v[196:199], v[40:43]
	v_mfma_f32_16x16x32_bf16 v[32:35], v[152:155], v[212:215], v[32:35]
	v_mfma_f32_16x16x32_bf16 v[24:27], v[160:163], v[212:215], v[24:27]
	v_mfma_f32_16x16x32_bf16 v[16:19], v[152:155], v[220:223], v[16:19]
	v_mfma_f32_16x16x32_bf16 v[8:11], v[160:163], v[220:223], v[8:11]
	v_mfma_f32_16x16x32_bf16 v[60:63], v[156:159], v[192:195], v[60:63]
	v_mfma_f32_16x16x32_bf16 v[56:59], v[168:171], v[192:195], v[56:59]
	v_mfma_f32_16x16x32_bf16 v[48:51], v[156:159], v[208:211], v[48:51]
	v_mfma_f32_16x16x32_bf16 v[40:43], v[168:171], v[208:211], v[40:43]
	v_mfma_f32_16x16x32_bf16 v[32:35], v[156:159], v[216:219], v[32:35]
	v_mfma_f32_16x16x32_bf16 v[24:27], v[168:171], v[216:219], v[24:27]
	v_mfma_f32_16x16x32_bf16 v[16:19], v[156:159], v[224:227], v[16:19]
	v_mfma_f32_16x16x32_bf16 v[8:11], v[168:171], v[224:227], v[8:11]
	v_mfma_f32_16x16x32_bf16 v[52:55], v[172:175], v[188:191], v[52:55]
	v_mfma_f32_16x16x32_bf16 v[44:47], v[180:183], v[188:191], v[44:47]
	v_mfma_f32_16x16x32_bf16 v[36:39], v[172:175], v[196:199], v[36:39]
	v_mfma_f32_16x16x32_bf16 v[28:31], v[180:183], v[196:199], v[28:31]
	v_mfma_f32_16x16x32_bf16 v[20:23], v[172:175], v[212:215], v[20:23]
	v_mfma_f32_16x16x32_bf16 v[12:15], v[180:183], v[212:215], v[12:15]
	v_mfma_f32_16x16x32_bf16 v[4:7], v[172:175], v[220:223], v[4:7]
	v_mfma_f32_16x16x32_bf16 v[0:3], v[180:183], v[220:223], v[0:3]
	v_mfma_f32_16x16x32_bf16 v[52:55], v[176:179], v[192:195], v[52:55]
	v_mfma_f32_16x16x32_bf16 v[44:47], v[184:187], v[192:195], v[44:47]
	v_mfma_f32_16x16x32_bf16 v[36:39], v[176:179], v[208:211], v[36:39]
	v_mfma_f32_16x16x32_bf16 v[28:31], v[184:187], v[208:211], v[28:31]
	v_mfma_f32_16x16x32_bf16 v[20:23], v[176:179], v[216:219], v[20:23]
	v_mfma_f32_16x16x32_bf16 v[12:15], v[184:187], v[216:219], v[12:15]
	v_mfma_f32_16x16x32_bf16 v[4:7], v[176:179], v[224:227], v[4:7]
	v_mfma_f32_16x16x32_bf16 v[0:3], v[184:187], v[224:227], v[0:3]
	s_barrier
	s_add_i32 s85, s85, 2
	s_add_u32 s40, s40, 0x100
	s_addc_u32 s41, s41, 0
	s_add_u32 s83, s83, 0x100
	s_addc_u32 s84, s84, 0
	s_cmp_gt_u32 s85, 29
.LBB0_787:
	ds_read_b128 v[152:155], v165
	ds_read_b128 v[156:159], v165 offset:1024
	ds_read_b128 v[160:163], v165 offset:2048
	ds_read_b128 v[168:171], v165 offset:3072
	ds_read_b128 v[172:175], v166
	ds_read_b128 v[176:179], v166 offset:1024
	ds_read_b128 v[180:183], v166 offset:2048
	ds_read_b128 v[184:187], v166 offset:3072
	s_add_u32 s34, s40, 0xfff80080
	s_addc_u32 s35, s41, -1
	s_cmp_eq_u32 s85, 28
	s_cselect_b32 s45, s23, s35
	s_cselect_b32 s44, s81, s34
	s_cselect_b32 s43, s21, s84
	s_cselect_b32 s42, s82, s83
	v_lshl_add_u64 v[228:229], s[40:41], 0, v[144:145]
	s_add_i32 m0, s28, 0xc000
	ds_read_b128 v[188:191], v167
	ds_read_b128 v[192:195], v167 offset:1024
	ds_read_b128 v[196:199], v167 offset:2048
	ds_read_b128 v[208:211], v167 offset:3072
	ds_read_b128 v[212:215], v167 offset:4096
	ds_read_b128 v[216:219], v167 offset:5120
	ds_read_b128 v[220:223], v167 offset:6144
	ds_read_b128 v[224:227], v167 offset:7168
	global_load_lds_dwordx4 v[228:229], off
	v_lshl_add_u64 v[228:229], s[40:41], 0, v[146:147]
	s_add_i32 m0, s28, 0xe000
	s_nop 0
	global_load_lds_dwordx4 v[228:229], off
	s_waitcnt vmcnt(8)
	s_waitcnt lgkmcnt(0)
	s_barrier
; #define PG8_STAGE(bufoff, gbase, voff) do { _Pragma("unroll") for (int _i = 0; _i < 2; ++_i) \
;         __builtin_amdgcn_global_load_lds((const unsigned*)((const char*)(gbase) + (voff)[_i]), (LAS unsigned*)(lds + (bufoff) + ldsw + _i * 8192), 16, 0, 0); } while (0)
; #define PG8_LDA(dst, b, h) do { _Pragma("unroll") for (int m = 0; m < 4; ++m) _Pragma("unroll") for (int k = 0; k < 2; ++k) dst[m][k] = *(const LAS bf16x8*)(lds + PG8_SA(b, h) + aoff + m * 2048 + k * 1024); } while (0)
; #define PG8_LDB(dst, b, h) do { _Pragma("unroll") for (int n = 0; n < 2; ++n) _Pragma("unroll") for (int k = 0; k < 2; ++k) dst[n][k] = *(const LAS bf16x8*)(lds + PG8_SB(b, h) + boff + n * 2048 + k * 1024); } while (0)
; #define PG8_MMA(ai, bj, At, Bt) do { __builtin_amdgcn_s_setprio(1); _Pragma("unroll") for (int m = 0; m < 4; ++m) _Pragma("unroll") for (int n = 0; n < 2; ++n) _Pragma("unroll") for (int k = 0; k < 2; ++k) \
;         acc[ai][bj][m][n] = __builtin_amdgcn_mfma_f32_16x16x32_bf16(Bt[n][k], At[m][k], acc[ai][bj][m][n], 0, 0, 0); __builtin_amdgcn_s_setprio(0); } while (0)
; #define PG8_WAIT_V(n) asm volatile("s_waitcnt vmcnt(" #n ")" ::: "memory")
; #define PG8_WAIT_L(n) asm volatile("s_waitcnt lgkmcnt(" #n ")" ::: "memory")
; #define PG8_BAR __builtin_amdgcn_s_barrier()
; #define PG8_SCHED __builtin_amdgcn_sched_barrier(0)
; template <class Epi, bool ALIGN_EPI, class Hook = NoHook>
; __device__ __forceinline__ void gemm_phase(LAS unsigned char* lds, const Gemm g, const StaticOrder& S, const Epi& E, const Hook& HK = Hook()) {
;     ...
;             PG8_WAIT_V(8); PG8_WAIT_L(0); PG8_BAR; PG8_MMA(0, 0, At, B0); PG8_MMA(0, 1, At, B1); PG8_BAR; PG8_SCHED;
;             PG8_LDA(At, 0, 1); PG8_STAGE(PG8_SB(0, 0), b2, voffB); PG8_STAGE(PG8_SB(0, 1), b2 + hstepB, voffB); PG8_STAGE(PG8_SA(0, 0), a2, voffA);
;             PG8_WAIT_V(8); PG8_WAIT_L(0); PG8_BAR; PG8_MMA(1, 0, At, B0); PG8_MMA(1, 1, At, B1); PG8_BAR; PG8_SCHED;
;             PG8_LDB(B0, 1, 0); PG8_LDB(B1, 1, 1); PG8_SCHED; PG8_LDA(At, 1, 0); PG8_STAGE(PG8_SA(0, 1), a2 + hstepA, voffA);
;             PG8_WAIT_V(8); PG8_WAIT_L(0); PG8_BAR; PG8_MMA(0, 0, At, B0); PG8_MMA(0, 1, At, B1); PG8_BAR; PG8_SCHED;
	s_waitcnt lgkmcnt(0)
	v_mfma_f32_16x16x32_bf16 v[124:127], v[152:155], v[188:191], v[124:127]
	v_mfma_f32_16x16x32_bf16 v[120:123], v[160:163], v[188:191], v[120:123]
	v_mfma_f32_16x16x32_bf16 v[112:115], v[152:155], v[196:199], v[112:115]
	v_mfma_f32_16x16x32_bf16 v[104:107], v[160:163], v[196:199], v[104:107]
	v_mfma_f32_16x16x32_bf16 v[96:99], v[152:155], v[212:215], v[96:99]
	v_mfma_f32_16x16x32_bf16 v[88:91], v[160:163], v[212:215], v[88:91]
	v_mfma_f32_16x16x32_bf16 v[80:83], v[152:155], v[220:223], v[80:83]
	v_mfma_f32_16x16x32_bf16 v[72:75], v[160:163], v[220:223], v[72:75]
	v_mfma_f32_16x16x32_bf16 v[124:127], v[156:159], v[192:195], v[124:127]
	v_mfma_f32_16x16x32_bf16 v[120:123], v[168:171], v[192:195], v[120:123]
	v_mfma_f32_16x16x32_bf16 v[112:115], v[156:159], v[208:211], v[112:115]
	v_mfma_f32_16x16x32_bf16 v[104:107], v[168:171], v[208:211], v[104:107]
	v_mfma_f32_16x16x32_bf16 v[96:99], v[156:159], v[216:219], v[96:99]
	v_mfma_f32_16x16x32_bf16 v[88:91], v[168:171], v[216:219], v[88:91]
	v_mfma_f32_16x16x32_bf16 v[80:83], v[156:159], v[224:227], v[80:83]
	v_mfma_f32_16x16x32_bf16 v[72:75], v[168:171], v[224:227], v[72:75]
	v_mfma_f32_16x16x32_bf16 v[116:119], v[172:175], v[188:191], v[116:119]
	v_mfma_f32_16x16x32_bf16 v[108:111], v[180:183], v[188:191], v[108:111]
	v_mfma_f32_16x16x32_bf16 v[100:103], v[172:175], v[196:199], v[100:103]
	v_mfma_f32_16x16x32_bf16 v[92:95], v[180:183], v[196:199], v[92:95]
	v_mfma_f32_16x16x32_bf16 v[84:87], v[172:175], v[212:215], v[84:87]
	v_mfma_f32_16x16x32_bf16 v[76:79], v[180:183], v[212:215], v[76:79]
	v_mfma_f32_16x16x32_bf16 v[68:71], v[172:175], v[220:223], v[68:71]
	v_mfma_f32_16x16x32_bf16 v[64:67], v[180:183], v[220:223], v[64:67]
	v_mfma_f32_16x16x32_bf16 v[116:119], v[176:179], v[192:195], v[116:119]
	v_mfma_f32_16x16x32_bf16 v[108:111], v[184:187], v[192:195], v[108:111]
	v_mfma_f32_16x16x32_bf16 v[100:103], v[176:179], v[208:211], v[100:103]
	v_mfma_f32_16x16x32_bf16 v[92:95], v[184:187], v[208:211], v[92:95]
	v_mfma_f32_16x16x32_bf16 v[84:87], v[176:179], v[216:219], v[84:87]
	v_mfma_f32_16x16x32_bf16 v[76:79], v[184:187], v[216:219], v[76:79]
	v_mfma_f32_16x16x32_bf16 v[68:71], v[176:179], v[224:227], v[68:71]
	v_mfma_f32_16x16x32_bf16 v[64:67], v[184:187], v[224:227], v[64:67]
	s_barrier
	s_add_i32 s34, s78, s27
	v_lshl_add_u64 v[228:229], s[42:43], 0, v[130:131]
	s_mov_b32 m0, s34
	ds_read_b128 v[188:191], v167 offset:16384
	ds_read_b128 v[192:195], v167 offset:17408
	ds_read_b128 v[196:199], v167 offset:18432
	ds_read_b128 v[208:211], v167 offset:19456
	ds_read_b128 v[212:215], v167 offset:20480
	ds_read_b128 v[216:219], v167 offset:21504
	ds_read_b128 v[220:223], v167 offset:22528
	ds_read_b128 v[224:227], v167 offset:23552
	global_load_lds_dwordx4 v[228:229], off
	s_add_i32 m0, s34, 0x2000
	s_add_u32 s34, s42, 0x80000
	v_lshl_add_u64 v[230:231], s[42:43], 0, v[134:135]
	s_addc_u32 s35, s43, 0
	s_add_i32 s52, s79, s27
	global_load_lds_dwordx4 v[230:231], off
	v_lshl_add_u64 v[232:233], s[34:35], 0, v[130:131]
	s_mov_b32 m0, s52
	v_lshl_add_u64 v[234:235], s[44:45], 0, v[132:133]
	global_load_lds_dwordx4 v[232:233], off
	v_lshl_add_u64 v[232:233], s[34:35], 0, v[134:135]
	s_add_i32 m0, s52, 0x2000
	s_nop 0
	global_load_lds_dwordx4 v[232:233], off
	v_lshl_add_u64 v[232:233], s[44:45], 0, v[128:129]
	s_mov_b32 m0, s28
	s_nop 0
	global_load_lds_dwordx4 v[232:233], off
	s_mov_b32 m0, s29
	s_nop 0
	global_load_lds_dwordx4 v[234:235], off
	s_waitcnt vmcnt(8)
	s_waitcnt lgkmcnt(0)
	s_barrier
	s_waitcnt lgkmcnt(0)
	v_mfma_f32_16x16x32_bf16 v[60:63], v[152:155], v[188:191], v[60:63]
	v_mfma_f32_16x16x32_bf16 v[56:59], v[160:163], v[188:191], v[56:59]
	v_mfma_f32_16x16x32_bf16 v[48:51], v[152:155], v[196:199], v[48:51]
	v_mfma_f32_16x16x32_bf16 v[40:43], v[160:163], v[196:199], v[40:43]
	v_mfma_f32_16x16x32_bf16 v[32:35], v[152:155], v[212:215], v[32:35]
	v_mfma_f32_16x16x32_bf16 v[24:27], v[160:163], v[212:215], v[24:27]
	v_mfma_f32_16x16x32_bf16 v[16:19], v[152:155], v[220:223], v[16:19]
	v_mfma_f32_16x16x32_bf16 v[8:11], v[160:163], v[220:223], v[8:11]
	v_mfma_f32_16x16x32_bf16 v[60:63], v[156:159], v[192:195], v[60:63]
	v_mfma_f32_16x16x32_bf16 v[56:59], v[168:171], v[192:195], v[56:59]
	v_mfma_f32_16x16x32_bf16 v[48:51], v[156:159], v[208:211], v[48:51]
	v_mfma_f32_16x16x32_bf16 v[40:43], v[168:171], v[208:211], v[40:43]
	v_mfma_f32_16x16x32_bf16 v[32:35], v[156:159], v[216:219], v[32:35]
	v_mfma_f32_16x16x32_bf16 v[24:27], v[168:171], v[216:219], v[24:27]
	v_mfma_f32_16x16x32_bf16 v[16:19], v[156:159], v[224:227], v[16:19]
	v_mfma_f32_16x16x32_bf16 v[8:11], v[168:171], v[224:227], v[8:11]
	v_mfma_f32_16x16x32_bf16 v[52:55], v[172:175], v[188:191], v[52:55]
	v_mfma_f32_16x16x32_bf16 v[44:47], v[180:183], v[188:191], v[44:47]
	v_mfma_f32_16x16x32_bf16 v[36:39], v[172:175], v[196:199], v[36:39]
	v_mfma_f32_16x16x32_bf16 v[28:31], v[180:183], v[196:199], v[28:31]
	v_mfma_f32_16x16x32_bf16 v[20:23], v[172:175], v[212:215], v[20:23]
	v_mfma_f32_16x16x32_bf16 v[12:15], v[180:183], v[212:215], v[12:15]
	v_mfma_f32_16x16x32_bf16 v[4:7], v[172:175], v[220:223], v[4:7]
	v_mfma_f32_16x16x32_bf16 v[0:3], v[180:183], v[220:223], v[0:3]
	v_mfma_f32_16x16x32_bf16 v[52:55], v[176:179], v[192:195], v[52:55]
	v_mfma_f32_16x16x32_bf16 v[44:47], v[184:187], v[192:195], v[44:47]
	v_mfma_f32_16x16x32_bf16 v[36:39], v[176:179], v[208:211], v[36:39]
	v_mfma_f32_16x16x32_bf16 v[28:31], v[184:187], v[208:211], v[28:31]
	v_mfma_f32_16x16x32_bf16 v[20:23], v[176:179], v[216:219], v[20:23]
	v_mfma_f32_16x16x32_bf16 v[12:15], v[184:187], v[216:219], v[12:15]
	v_mfma_f32_16x16x32_bf16 v[4:7], v[176:179], v[224:227], v[4:7]
	v_mfma_f32_16x16x32_bf16 v[0:3], v[184:187], v[224:227], v[0:3]
	s_barrier
; #define PG8_STAGE(bufoff, gbase, voff) do { _Pragma("unroll") for (int _i = 0; _i < 2; ++_i) \
;         __builtin_amdgcn_global_load_lds((const unsigned*)((const char*)(gbase) + (voff)[_i]), (LAS unsigned*)(lds + (bufoff) + ldsw + _i * 8192), 16, 0, 0); } while (0)
; #define PG8_LDA(dst, b, h) do { _Pragma("unroll") for (int m = 0; m < 4; ++m) _Pragma("unroll") for (int k = 0; k < 2; ++k) dst[m][k] = *(const LAS bf16x8*)(lds + PG8_SA(b, h) + aoff + m * 2048 + k * 1024); } while (0)
; #define PG8_LDB(dst, b, h) do { _Pragma("unroll") for (int n = 0; n < 2; ++n) _Pragma("unroll") for (int k = 0; k < 2; ++k) dst[n][k] = *(const LAS bf16x8*)(lds + PG8_SB(b, h) + boff + n * 2048 + k * 1024); } while (0)
; #define PG8_MMA(ai, bj, At, Bt) do { __builtin_amdgcn_s_setprio(1); _Pragma("unroll") for (int m = 0; m < 4; ++m) _Pragma("unroll") for (int n = 0; n < 2; ++n) _Pragma("unroll") for (int k = 0; k < 2; ++k) \
;         acc[ai][bj][m][n] = __builtin_amdgcn_mfma_f32_16x16x32_bf16(Bt[n][k], At[m][k], acc[ai][bj][m][n], 0, 0, 0); __builtin_amdgcn_s_setprio(0); } while (0)
; #define PG8_WAIT_V(n) asm volatile("s_waitcnt vmcnt(" #n ")" ::: "memory")
; #define PG8_WAIT_L(n) asm volatile("s_waitcnt lgkmcnt(" #n ")" ::: "memory")
; #define PG8_BAR __builtin_amdgcn_s_barrier()
; #define PG8_SCHED __builtin_amdgcn_sched_barrier(0)
; template <class Epi, bool ALIGN_EPI, class Hook = NoHook>
; __device__ __forceinline__ void gemm_phase(LAS unsigned char* lds, const Gemm g, const StaticOrder& S, const Epi& E, const Hook& HK = Hook()) {
;     ...
;             PG8_LDB(B0, 1, 0); PG8_LDB(B1, 1, 1); PG8_SCHED; PG8_LDA(At, 1, 0); PG8_STAGE(PG8_SA(0, 1), a2 + hstepA, voffA);
;             PG8_WAIT_V(8); PG8_WAIT_L(0); PG8_BAR; PG8_MMA(0, 0, At, B0); PG8_MMA(0, 1, At, B1); PG8_BAR; PG8_SCHED;
	s_add_i32 s52, 0, 0x18000
	s_add_i32 s53, 0, 0x1c000
	v_add_u32_e32 v168, s52, v143
	v_add_u32_e32 v184, s53, v143
	ds_read_b128 v[152:155], v168
	ds_read_b128 v[156:159], v168 offset:1024
	ds_read_b128 v[160:163], v168 offset:2048
	ds_read_b128 v[168:171], v168 offset:3072
	ds_read_b128 v[172:175], v184
	ds_read_b128 v[176:179], v184 offset:1024
	ds_read_b128 v[180:183], v184 offset:2048
	ds_read_b128 v[184:187], v184 offset:3072
	s_add_u32 s34, s44, 0x80000
	s_addc_u32 s35, s45, 0
	s_mov_b32 m0, s39
	v_lshl_add_u64 v[236:237], s[34:35], 0, v[128:129]
	ds_read_b128 v[188:191], v167 offset:32768
	ds_read_b128 v[192:195], v167 offset:33792
	ds_read_b128 v[196:199], v167 offset:34816
	ds_read_b128 v[208:211], v167 offset:35840
	ds_read_b128 v[212:215], v167 offset:36864
	ds_read_b128 v[216:219], v167 offset:37888
	ds_read_b128 v[220:223], v167 offset:38912
	ds_read_b128 v[224:227], v167 offset:39936
	global_load_lds_dwordx4 v[236:237], off
	v_lshl_add_u64 v[236:237], s[34:35], 0, v[132:133]
	s_mov_b32 m0, s50
	s_nop 0
	global_load_lds_dwordx4 v[236:237], off
	s_waitcnt vmcnt(8)
	s_waitcnt lgkmcnt(0)
	s_barrier
	s_waitcnt lgkmcnt(0)
	v_mfma_f32_16x16x32_bf16 v[124:127], v[152:155], v[188:191], v[124:127]
	v_mfma_f32_16x16x32_bf16 v[120:123], v[160:163], v[188:191], v[120:123]
	v_mfma_f32_16x16x32_bf16 v[112:115], v[152:155], v[196:199], v[112:115]
	v_mfma_f32_16x16x32_bf16 v[104:107], v[160:163], v[196:199], v[104:107]
	v_mfma_f32_16x16x32_bf16 v[96:99], v[152:155], v[212:215], v[96:99]
	v_mfma_f32_16x16x32_bf16 v[88:91], v[160:163], v[212:215], v[88:91]
	v_mfma_f32_16x16x32_bf16 v[80:83], v[152:155], v[220:223], v[80:83]
	v_mfma_f32_16x16x32_bf16 v[72:75], v[160:163], v[220:223], v[72:75]
	v_mfma_f32_16x16x32_bf16 v[124:127], v[156:159], v[192:195], v[124:127]
	v_mfma_f32_16x16x32_bf16 v[120:123], v[168:171], v[192:195], v[120:123]
	v_mfma_f32_16x16x32_bf16 v[112:115], v[156:159], v[208:211], v[112:115]
	v_mfma_f32_16x16x32_bf16 v[104:107], v[168:171], v[208:211], v[104:107]
	v_mfma_f32_16x16x32_bf16 v[96:99], v[156:159], v[216:219], v[96:99]
	v_mfma_f32_16x16x32_bf16 v[88:91], v[168:171], v[216:219], v[88:91]
	v_mfma_f32_16x16x32_bf16 v[80:83], v[156:159], v[224:227], v[80:83]
	v_mfma_f32_16x16x32_bf16 v[72:75], v[168:171], v[224:227], v[72:75]
	v_mfma_f32_16x16x32_bf16 v[116:119], v[172:175], v[188:191], v[116:119]
	v_mfma_f32_16x16x32_bf16 v[108:111], v[180:183], v[188:191], v[108:111]
	v_mfma_f32_16x16x32_bf16 v[100:103], v[172:175], v[196:199], v[100:103]
	v_mfma_f32_16x16x32_bf16 v[92:95], v[180:183], v[196:199], v[92:95]
	v_mfma_f32_16x16x32_bf16 v[84:87], v[172:175], v[212:215], v[84:87]
	v_mfma_f32_16x16x32_bf16 v[76:79], v[180:183], v[212:215], v[76:79]
	v_mfma_f32_16x16x32_bf16 v[68:71], v[172:175], v[220:223], v[68:71]
	v_mfma_f32_16x16x32_bf16 v[64:67], v[180:183], v[220:223], v[64:67]
	v_mfma_f32_16x16x32_bf16 v[116:119], v[176:179], v[192:195], v[116:119]
	v_mfma_f32_16x16x32_bf16 v[108:111], v[184:187], v[192:195], v[108:111]
	v_mfma_f32_16x16x32_bf16 v[100:103], v[176:179], v[208:211], v[100:103]
	v_mfma_f32_16x16x32_bf16 v[92:95], v[184:187], v[208:211], v[92:95]
	v_mfma_f32_16x16x32_bf16 v[84:87], v[176:179], v[216:219], v[84:87]
	v_mfma_f32_16x16x32_bf16 v[76:79], v[184:187], v[216:219], v[76:79]
	v_mfma_f32_16x16x32_bf16 v[68:71], v[176:179], v[224:227], v[68:71]
	v_mfma_f32_16x16x32_bf16 v[64:67], v[184:187], v[224:227], v[64:67]
	s_barrier
; #define PG8_STAGE(bufoff, gbase, voff) do { _Pragma("unroll") for (int _i = 0; _i < 2; ++_i) \
;         __builtin_amdgcn_global_load_lds((const unsigned*)((const char*)(gbase) + (voff)[_i]), (LAS unsigned*)(lds + (bufoff) + ldsw + _i * 8192), 16, 0, 0); } while (0)
; #define PG8_LDA(dst, b, h) do { _Pragma("unroll") for (int m = 0; m < 4; ++m) _Pragma("unroll") for (int k = 0; k < 2; ++k) dst[m][k] = *(const LAS bf16x8*)(lds + PG8_SA(b, h) + aoff + m * 2048 + k * 1024); } while (0)
; #define PG8_MMA(ai, bj, At, Bt) do { __builtin_amdgcn_s_setprio(1); _Pragma("unroll") for (int m = 0; m < 4; ++m) _Pragma("unroll") for (int n = 0; n < 2; ++n) _Pragma("unroll") for (int k = 0; k < 2; ++k) \
;         acc[ai][bj][m][n] = __builtin_amdgcn_mfma_f32_16x16x32_bf16(Bt[n][k], At[m][k], acc[ai][bj][m][n], 0, 0, 0); __builtin_amdgcn_s_setprio(0); } while (0)
; #define PG8_WAIT_V(n) asm volatile("s_waitcnt vmcnt(" #n ")" ::: "memory")
; #define PG8_WAIT_L(n) asm volatile("s_waitcnt lgkmcnt(" #n ")" ::: "memory")
; #define PG8_BAR __builtin_amdgcn_s_barrier()
; #define PG8_SCHED __builtin_amdgcn_sched_barrier(0)
; template <class Epi, bool ALIGN_EPI, class Hook = NoHook>
; __device__ __forceinline__ void gemm_phase(LAS unsigned char* lds, const Gemm g, const StaticOrder& S, const Epi& E, const Hook& HK = Hook()) {
;     ...
;             PG8_LDA(At, 1, 1); PG8_STAGE(PG8_SB(1, 0), b3, voffB); PG8_STAGE(PG8_SB(1, 1), b3 + hstepB, voffB); PG8_STAGE(PG8_SA(1, 0), a3, voffA);
;             PG8_WAIT_V(8); PG8_WAIT_L(0); PG8_BAR; PG8_MMA(1, 0, At, B0); PG8_MMA(1, 1, At, B1); PG8_BAR; PG8_SCHED;
;         }
;         if constexpr (ALIGN_EPI) { if (wr == 0) PG8_BAR; }
	s_add_i32 s34, s52, s27
	v_lshl_add_u64 v[228:229], v[228:229], 0, s[10:11]
	s_mov_b32 m0, s34
	ds_read_b128 v[188:191], v167 offset:49152
	ds_read_b128 v[192:195], v167 offset:50176
	ds_read_b128 v[196:199], v167 offset:51200
	ds_read_b128 v[208:211], v167 offset:52224
	ds_read_b128 v[212:215], v167 offset:53248
	ds_read_b128 v[216:219], v167 offset:54272
	ds_read_b128 v[220:223], v167 offset:55296
	ds_read_b128 v[224:227], v167 offset:56320
	global_load_lds_dwordx4 v[228:229], off
	s_add_i32 m0, s34, 0x2000
	s_add_u32 s34, s42, 0x80080
	v_lshl_add_u64 v[228:229], v[230:231], 0, s[10:11]
	s_addc_u32 s35, s43, 0
	s_add_i32 s42, s53, s27
	global_load_lds_dwordx4 v[228:229], off
	v_lshl_add_u64 v[228:229], s[34:35], 0, v[130:131]
	s_mov_b32 m0, s42
	s_nop 0
	global_load_lds_dwordx4 v[228:229], off
	v_lshl_add_u64 v[228:229], s[34:35], 0, v[134:135]
	s_add_i32 m0, s42, 0x2000
	s_nop 0
	global_load_lds_dwordx4 v[228:229], off
	v_lshl_add_u64 v[228:229], v[232:233], 0, s[10:11]
	s_mov_b32 m0, s65
	s_nop 0
	global_load_lds_dwordx4 v[228:229], off
	v_lshl_add_u64 v[228:229], v[234:235], 0, s[10:11]
	s_mov_b32 m0, s71
	s_nop 0
	global_load_lds_dwordx4 v[228:229], off
	s_waitcnt vmcnt(8)
	s_waitcnt lgkmcnt(0)
	s_barrier
	s_waitcnt lgkmcnt(0)
	v_mfma_f32_16x16x32_bf16 v[60:63], v[152:155], v[188:191], v[60:63]
	v_mfma_f32_16x16x32_bf16 v[56:59], v[160:163], v[188:191], v[56:59]
	v_mfma_f32_16x16x32_bf16 v[48:51], v[152:155], v[196:199], v[48:51]
	v_mfma_f32_16x16x32_bf16 v[40:43], v[160:163], v[196:199], v[40:43]
	v_mfma_f32_16x16x32_bf16 v[32:35], v[152:155], v[212:215], v[32:35]
	v_mfma_f32_16x16x32_bf16 v[24:27], v[160:163], v[212:215], v[24:27]
	v_mfma_f32_16x16x32_bf16 v[16:19], v[152:155], v[220:223], v[16:19]
	v_mfma_f32_16x16x32_bf16 v[8:11], v[160:163], v[220:223], v[8:11]
	v_mfma_f32_16x16x32_bf16 v[60:63], v[156:159], v[192:195], v[60:63]
	v_mfma_f32_16x16x32_bf16 v[56:59], v[168:171], v[192:195], v[56:59]
	v_mfma_f32_16x16x32_bf16 v[48:51], v[156:159], v[208:211], v[48:51]
	v_mfma_f32_16x16x32_bf16 v[40:43], v[168:171], v[208:211], v[40:43]
	v_mfma_f32_16x16x32_bf16 v[32:35], v[156:159], v[216:219], v[32:35]
	v_mfma_f32_16x16x32_bf16 v[24:27], v[168:171], v[216:219], v[24:27]
	v_mfma_f32_16x16x32_bf16 v[16:19], v[156:159], v[224:227], v[16:19]
	v_mfma_f32_16x16x32_bf16 v[8:11], v[168:171], v[224:227], v[8:11]
	v_mfma_f32_16x16x32_bf16 v[52:55], v[172:175], v[188:191], v[52:55]
	v_mfma_f32_16x16x32_bf16 v[44:47], v[180:183], v[188:191], v[44:47]
	v_mfma_f32_16x16x32_bf16 v[36:39], v[172:175], v[196:199], v[36:39]
	v_mfma_f32_16x16x32_bf16 v[28:31], v[180:183], v[196:199], v[28:31]
	v_mfma_f32_16x16x32_bf16 v[20:23], v[172:175], v[212:215], v[20:23]
	v_mfma_f32_16x16x32_bf16 v[12:15], v[180:183], v[212:215], v[12:15]
	v_mfma_f32_16x16x32_bf16 v[4:7], v[172:175], v[220:223], v[4:7]
	v_mfma_f32_16x16x32_bf16 v[0:3], v[180:183], v[220:223], v[0:3]
	v_mfma_f32_16x16x32_bf16 v[52:55], v[176:179], v[192:195], v[52:55]
	v_mfma_f32_16x16x32_bf16 v[44:47], v[184:187], v[192:195], v[44:47]
	v_mfma_f32_16x16x32_bf16 v[36:39], v[176:179], v[208:211], v[36:39]
	v_mfma_f32_16x16x32_bf16 v[28:31], v[184:187], v[208:211], v[28:31]
	v_mfma_f32_16x16x32_bf16 v[20:23], v[176:179], v[216:219], v[20:23]
	v_mfma_f32_16x16x32_bf16 v[12:15], v[184:187], v[216:219], v[12:15]
	v_mfma_f32_16x16x32_bf16 v[4:7], v[176:179], v[224:227], v[4:7]
	v_mfma_f32_16x16x32_bf16 v[0:3], v[184:187], v[224:227], v[0:3]
	s_barrier
	s_add_i32 s85, s85, 2
	s_add_u32 s40, s40, 0x100
	s_addc_u32 s41, s41, 0
	s_add_u32 s83, s83, 0x100
	s_addc_u32 s84, s84, 0
	s_cmp_gt_u32 s85, 29
	s_cbranch_scc0 .LBB0_787
	s_and_b64 vcc, exec, s[12:13]
	s_cbranch_vccz .LBB0_790
	s_barrier

; #define PG8_WAIT_V(n) asm volatile("s_waitcnt vmcnt(" #n ")" ::: "memory")
; #define PG8_BAR __builtin_amdgcn_s_barrier()
; template <class Epi, bool ALIGN_EPI, class Hook = NoHook>
; __device__ __forceinline__ void gemm_phase(LAS unsigned char* lds, const Gemm g, const StaticOrder& S, const Epi& E, const Hook& HK = Hook()) {
;     ...
;     PG8_WAIT_V(0);
;     if constexpr (!ALIGN_EPI) { if (wr == 0) PG8_BAR; }
;     PG8_BAR;
.LBB0_793:
	s_setprio 0
	s_waitcnt vmcnt(0)
	v_readlane_b32 s80, v254, 5
	v_readlane_b32 s81, v254, 6
	v_readlane_b32 s82, v254, 7
	v_readlane_b32 s83, v254, 8
	v_readlane_b32 s84, v254, 9
	v_readlane_b32 s85, v254, 10
	v_readlane_b32 s86, v254, 11
	v_readlane_b32 s87, v254, 12
	s_barrier

; #define PG8_BAR __builtin_amdgcn_s_barrier()
;     __host__ __device__ bool next(int i, Unit& u) const {
;         const long L = (long)i * G + c; if (L >= nwg) return false;
;         int wgid = (int)L; { const int q = nwg / NXCD, r = nwg % NXCD, xcd = wgid % NXCD, off = wgid / NXCD; wgid = (xcd < r ? xcd * (q + 1) : r * (q + 1) + (xcd - r) * q) + off; }
; template <class Epi, bool ALIGN_EPI, class Hook = NoHook>
; __device__ __forceinline__ void gemm_phase(LAS unsigned char* lds, const Gemm g, const StaticOrder& S, const Epi& E, const Hook& HK = Hook()) {
;     int tid = threadIdx.x; asm volatile("" : "+v"(tid));
;     const int wid = __builtin_amdgcn_readfirstlane(tid >> 6), lane = tid & 63, wr = wid >> 2, wc = wid & 3, fr = lane & 15, fq = lane >> 4;
;     const int K = g.K, nt = K / BK;
;     unsigned voffA[2], voffB[2];
; #pragma unroll
;     for (int i = 0; i < 2; ++i) { int R, C; stage_rc(tid * 16 + i * 8192, R, C); const int Rb = Epi::PERM ? ((R & ~31) + perm32(R & 31)) : R;
;         voffA[i] = (unsigned)(R * g.lda + C) * 2u; voffB[i] = (unsigned)(Rb * g.ldb + C) * 2u; }
;     const size_t kstep = (size_t)(BK * 2);
;     const size_t hstepA = (size_t)HALF * g.lda * 2, hstepB = (size_t)HALF * g.ldb * 2;
;     const size_t tstepA = 2 * hstepA, tstepB = 2 * hstepB;
;     const unsigned ldsw = (unsigned)wid * 1024u;
;     const int aoff = lds_byte(wr * 64 + fr, fq * 8), boff = lds_byte(wc * 32 + fr, fq * 8);
;     ...
;     Unit cur, nxt; int ui = 0;
;     if (!S.next(0, cur)) return;
;     f32x4 acc[2][2][4][2];
; #pragma unroll
;     for (int a = 0; a < 2; ++a)
; #pragma unroll
;         for (int b = 0; b < 2; ++b)
; #pragma unroll
;             for (int m = 0; m < 4; ++m)
; #pragma unroll
;                 for (int n = 0; n < 2; ++n) acc[a][b][m][n] = (f32x4){0.f, 0.f, 0.f, 0.f};
;     bf16x8 At[4][2], B0[2][2], B1[2][2];
;     const char* cA = (const char*)g.A + (size_t)cur.pm * tstepA; const char* cB = (const char*)g.Bt + (size_t)cur.pn * tstepB;
;     PG8_STAGE(PG8_SB(0, 0), cB, voffB); PG8_STAGE(PG8_SB(0, 1), cB + hstepB, voffB); PG8_STAGE(PG8_SA(0, 0), cA, voffA); PG8_STAGE(PG8_SA(0, 1), cA + hstepA, voffA);
;     if (wr == 1) PG8_BAR;
;     PG8_WAIT_V(2); PG8_BAR;
;     PG8_STAGE(PG8_SB(1, 0), cB + kstep, voffB); PG8_STAGE(PG8_SA(1, 0), cA + kstep, voffA); PG8_STAGE(PG8_SB(1, 1), cB + hstepB + kstep, voffB);
;     PG8_WAIT_V(6); PG8_BAR;
.LBB0_910:
	s_or_b64 exec, exec, s[0:1]
	v_readlane_b32 s0, v254, 16
	v_mov_b32_e32 v9, v136
	v_readlane_b32 s1, v254, 17
	s_waitcnt lgkmcnt(0)
	s_barrier
	s_andn2_b64 vcc, exec, s[0:1]
	v_readfirstlane_b32 s1, v9
	s_cbranch_vccnz .LBB0_926
	v_lshlrev_b32_e32 v0, 4, v9
	v_add_u32_e32 v1, 0x2000, v0
	v_ashrrev_i32_e32 v2, 31, v1
	v_lshrrev_b32_e32 v2, 22, v2
	v_add_u32_e32 v2, v1, v2
	v_ashrrev_i32_e32 v8, 10, v2
	v_mul_i32_i24_e32 v2, 0x400, v8
	v_sub_u32_e32 v1, v1, v2
	v_lshrrev_b32_e32 v2, 4, v1
	v_bitop3_b32 v1, v2, v1, 32 bitop3:0x6c
	v_ashrrev_i32_e32 v2, 31, v1
	v_lshrrev_b32_e32 v2, 26, v2
	v_add_u32_e32 v2, v1, v2
	v_lshlrev_b32_e32 v3, 3, v8
	v_ashrrev_i32_e32 v10, 6, v2
	v_and_b32_e32 v3, -16, v3
	v_add_u32_e32 v3, v10, v3
	v_and_b32_e32 v4, 3, v10
	s_mov_b32 s0, 0xfffe0
	v_lshrrev_b32_e32 v5, 2, v3
	v_lshlrev_b32_e32 v6, 1, v3
	v_and_b32_e32 v2, 0xc0, v2
	v_and_or_b32 v4, v3, s0, v4
	v_and_b32_e32 v5, 4, v5
	v_and_b32_e32 v6, 24, v6
	v_sub_u32_e32 v1, v1, v2
	v_mov_b32_e32 v2, 1
	v_or3_b32 v4, v4, v5, v6
	v_lshlrev_b32_e32 v5, 5, v8
	v_ashrrev_i16_sdwa v1, v2, sext(v1) dst_sel:DWORD dst_unused:UNUSED_PAD src0_sel:DWORD src1_sel:BYTE_0
	v_and_b32_e32 v5, 32, v5
	v_bfe_i32 v11, v1, 0, 16
	v_add_lshl_u32 v1, v5, v11, 1
	v_lshl_add_u32 v128, v4, 12, v1
	v_lshl_add_u32 v130, v3, 12, v1
	v_bfe_i32 v1, v9, 27, 1
	v_lshrrev_b32_e32 v1, 22, v1
	v_add_u32_e32 v1, v0, v1
	v_and_b32_e32 v1, 0xfffffc00, v1
	v_sub_u32_e32 v0, v0, v1
	v_lshrrev_b32_e32 v1, 4, v0
	v_ashrrev_i32_e32 v3, 31, v9
	v_bitop3_b32 v0, v1, v0, 32 bitop3:0x6c
	v_lshrrev_b32_e32 v3, 26, v3
	v_ashrrev_i32_e32 v1, 31, v0
	v_add_u32_e32 v3, v9, v3
	v_lshrrev_b32_e32 v1, 26, v1
	v_ashrrev_i32_e32 v13, 6, v3
	v_add_u32_e32 v1, v0, v1
	v_lshlrev_b32_e32 v3, 3, v13
	v_ashrrev_i32_e32 v12, 6, v1
	v_and_b32_e32 v3, -16, v3
	v_add_u32_e32 v3, v12, v3
	v_and_b32_e32 v4, 3, v12
	s_ashr_i32 s26, s2, 31
	v_and_or_b32 v4, v3, s0, v4
	s_lshr_b32 s0, s26, 29
	s_add_i32 s0, s2, s0
	s_ashr_i32 s8, s1, 6
	s_ashr_i32 s6, s0, 3
	s_and_b32 s0, s0, -8
	s_ashr_i32 s10, s1, 8
	s_lshl_b32 s13, s8, 10
	s_sub_i32 s0, s2, s0
	s_cmp_lt_i32 s0, 0
	s_movk_i32 s27, 0x161
	s_cselect_b32 s7, s27, 0x160
	s_mul_i32 s0, s0, s7
	s_add_i32 s0, s0, s6
	s_mul_hi_i32 s6, s0, 0x2e8ba2e9
	s_lshr_b32 s7, s6, 31
	s_ashr_i32 s6, s6, 6
	s_add_i32 s6, s6, s7
	s_lshl_b32 s7, s6, 3
	s_mulk_i32 s6, 0x160
	s_sub_i32 s6, s0, s6
	s_sext_i32_i16 s0, s6
	s_bfe_u32 s0, s0, 0x3001c
	s_add_i32 s9, s6, s0
	s_sext_i32_i16 s0, s9
	s_and_b32 s9, s9, 0xfff8
	s_sub_i32 s6, s6, s9
	s_sext_i32_i16 s6, s6
	v_lshrrev_b32_e32 v5, 2, v3
	v_lshlrev_b32_e32 v6, 1, v3
	v_and_b32_e32 v1, 0xc0, v1
	s_lshr_b32 s0, s0, 3
	s_add_i32 s22, s7, s6
	v_and_b32_e32 v5, 4, v5
	v_and_b32_e32 v6, 24, v6
	v_sub_u32_e32 v0, v0, v1
	s_ashr_i32 s23, s22, 31
	s_bfe_i64 s[14:15], s[0:1], 0x100000
	v_or3_b32 v4, v4, v5, v6
	v_lshlrev_b32_e32 v5, 5, v13
	v_ashrrev_i16_sdwa v0, v2, sext(v0) dst_sel:DWORD dst_unused:UNUSED_PAD src0_sel:DWORD src1_sel:BYTE_0
	s_lshl_b64 s[6:7], s[22:23], 20
	s_lshl_b64 s[14:15], s[14:15], 20
	v_and_b32_e32 v5, 32, v5
	v_bfe_i32 v14, v0, 0, 16
	s_add_u32 s28, s66, s14
	v_add_lshl_u32 v0, v5, v14, 1
	s_addc_u32 s29, s67, s15
	s_add_i32 s23, s13, 0
	v_lshl_add_u32 v132, v4, 12, v0
	s_add_i32 m0, s23, 0x10000
	v_lshl_add_u32 v134, v3, 12, v0
	global_load_lds_dwordx4 v132, s[28:29]
	s_add_i32 m0, s23, 0x12000
	s_add_u32 s14, s28, 0x80000
	global_load_lds_dwordx4 v128, s[28:29]
	s_addc_u32 s15, s29, 0
	s_add_i32 m0, s23, 0x14000
	v_mov_b32_e32 v133, 0
	global_load_lds_dwordx4 v132, s[14:15]
	s_add_i32 m0, s23, 0x16000
	s_add_u32 s24, s48, s6
	s_addc_u32 s25, s49, s7
	s_add_i32 s33, s23, 0x2000
	global_load_lds_dwordx4 v128, s[14:15]
	s_mov_b32 m0, s23
	s_add_u32 s6, s24, 0x80000
	global_load_lds_dwordx4 v134, s[24:25]
	s_mov_b32 m0, s33
	s_addc_u32 s7, s25, 0
	s_add_i32 s38, s23, 0x4000
	global_load_lds_dwordx4 v130, s[24:25]
	s_mov_b32 m0, s38
	s_add_i32 s39, s23, 0x6000
	global_load_lds_dwordx4 v134, s[6:7]
	s_mov_b32 m0, s39
	v_mov_b32_e32 v129, v133
	global_load_lds_dwordx4 v130, s[6:7]
	v_mov_b32_e32 v135, v133
	v_mov_b32_e32 v131, v133
	s_cmp_eq_u32 s10, 1
	s_mov_b32 s40, 0
	v_lshl_add_u64 v[6:7], s[28:29], 0, v[132:133]
	v_lshl_add_u64 v[4:5], s[28:29], 0, v[128:129]
	v_lshl_add_u64 v[0:1], s[24:25], 0, v[134:135]
	s_cselect_b64 s[6:7], -1, 0
	s_cmp_lg_u32 s10, 1
	v_lshl_add_u64 v[2:3], s[24:25], 0, v[130:131]
	s_cbranch_scc1 .LBB0_913
	s_barrier
	s_setprio 1

; #define PG8_STAGE(bufoff, gbase, voff) do { _Pragma("unroll") for (int _i = 0; _i < 2; ++_i) \
;         __builtin_amdgcn_global_load_lds((const unsigned*)((const char*)(gbase) + (voff)[_i]), (LAS unsigned*)(lds + (bufoff) + ldsw + _i * 8192), 16, 0, 0); } while (0)
; #define PG8_LDA(dst, b, h) do { _Pragma("unroll") for (int m = 0; m < 4; ++m) _Pragma("unroll") for (int k = 0; k < 2; ++k) dst[m][k] = *(const LAS bf16x8*)(lds + PG8_SA(b, h) + aoff + m * 2048 + k * 1024); } while (0)
; #define PG8_LDB(dst, b, h) do { _Pragma("unroll") for (int n = 0; n < 2; ++n) _Pragma("unroll") for (int k = 0; k < 2; ++k) dst[n][k] = *(const LAS bf16x8*)(lds + PG8_SB(b, h) + boff + n * 2048 + k * 1024); } while (0)
; #define PG8_WAIT_V(n) asm volatile("s_waitcnt vmcnt(" #n ")" ::: "memory")
; #define PG8_WAIT_L(n) asm volatile("s_waitcnt lgkmcnt(" #n ")" ::: "memory")
; #define PG8_BAR __builtin_amdgcn_s_barrier()
; #define PG8_SCHED __builtin_amdgcn_sched_barrier(0)
; template <class Epi, bool ALIGN_EPI, class Hook = NoHook>
; __device__ __forceinline__ void gemm_phase(LAS unsigned char* lds, const Gemm g, const StaticOrder& S, const Epi& E, const Hook& HK = Hook()) {
;     ...
;         const bool has_next = S.next(ui + 1, nxt);
;         const char* nA = has_next ? (const char*)g.A + (size_t)nxt.pm * tstepA : cA; const char* nB = has_next ? (const char*)g.Bt + (size_t)nxt.pn * tstepB : cB;
;         for (int t = 0; t < nt; t += 2) {
;             if (Hook::AT > 0 && t == Hook::AT) HK(acc, cur, wr, wc, fr, fq);
;             const bool last = (t == nt - 2);
;             const char* a1 = cA + (size_t)(t + 1) * kstep;
;             const char* a2 = last ? nA : cA + (size_t)(t + 2) * kstep; const char* b2 = last ? nB : cB + (size_t)(t + 2) * kstep;
;             const char* a3 = a2 + kstep; const char* b3 = b2 + kstep;
;             PG8_LDB(B0, 0, 0); PG8_LDB(B1, 0, 1); PG8_SCHED; PG8_LDA(At, 0, 0); PG8_STAGE(PG8_SA(1, 1), a1 + hstepA, voffA);
;             PG8_WAIT_V(8); PG8_WAIT_L(0); PG8_BAR; PG8_MMA(0, 0, At, B0); PG8_MMA(0, 1, At, B1); PG8_BAR; PG8_SCHED;
;             PG8_LDA(At, 0, 1); PG8_STAGE(PG8_SB(0, 0), b2, voffB); PG8_STAGE(PG8_SB(0, 1), b2 + hstepB, voffB); PG8_STAGE(PG8_SA(0, 0), a2, voffA);
;             PG8_WAIT_V(8); PG8_WAIT_L(0); PG8_BAR; PG8_MMA(1, 0, At, B0); PG8_MMA(1, 1, At, B1); PG8_BAR; PG8_SCHED;
.LBB0_918:
	s_ashr_i32 s17, s16, 31
	s_lshl_b64 s[18:19], s[16:17], 20
	s_add_u32 s18, s48, s18
	s_addc_u32 s19, s49, s19
	s_and_b64 s[20:21], s[0:1], exec
	s_cselect_b32 s17, s19, s25
	s_cselect_b32 s53, s18, s24
	s_ashr_i32 s15, s14, 31
	s_lshl_b64 s[20:21], s[14:15], 20
	s_add_u32 s20, s66, s20
	s_addc_u32 s21, s67, s21
	s_and_b64 s[34:35], s[0:1], exec
	s_cselect_b32 s15, s21, s29
	s_cselect_b32 s54, s20, s28
	s_add_u32 s24, s24, 0x80080
	s_addc_u32 s25, s25, 0
	s_add_u32 s55, s28, 0x100
	s_addc_u32 s56, s29, 0
	s_mov_b32 s57, -2
	ds_read_b128 v[146:149], v152
	ds_read_b128 v[156:159], v152 offset:1024
	ds_read_b128 v[160:163], v152 offset:2048
	ds_read_b128 v[164:167], v152 offset:3072
	ds_read_b128 v[168:171], v153
	ds_read_b128 v[172:175], v153 offset:1024
	ds_read_b128 v[176:179], v153 offset:2048
	ds_read_b128 v[180:183], v153 offset:3072
	s_add_u32 s28, s24, 0xfff80080
	s_addc_u32 s29, s25, -1
	s_cmp_eq_u32 s57, 28
	s_cselect_b32 s37, s17, s29
	s_cselect_b32 s36, s53, s28
	s_cselect_b32 s29, s15, s56
	s_cselect_b32 s28, s54, s55
	v_lshl_add_u64 v[216:217], s[24:25], 0, v[138:139]
	s_add_i32 m0, s23, 0xc000
	ds_read_b128 v[184:187], v154
	ds_read_b128 v[188:191], v154 offset:1024
	ds_read_b128 v[192:195], v154 offset:2048
	ds_read_b128 v[196:199], v154 offset:3072
	ds_read_b128 v[200:203], v154 offset:4096
	ds_read_b128 v[204:207], v154 offset:5120
	ds_read_b128 v[208:211], v154 offset:6144
	ds_read_b128 v[212:215], v154 offset:7168
	global_load_lds_dwordx4 v[216:217], off
	v_lshl_add_u64 v[216:217], s[24:25], 0, v[140:141]
	s_add_i32 m0, s23, 0xe000
	s_nop 0
	global_load_lds_dwordx4 v[216:217], off
	s_waitcnt vmcnt(8)
	s_waitcnt lgkmcnt(0)
	s_barrier
	s_waitcnt lgkmcnt(0)
	v_mfma_f32_16x16x32_bf16 v[124:127], v[146:149], v[184:187], 0
	v_mfma_f32_16x16x32_bf16 v[120:123], v[160:163], v[184:187], 0
	v_mfma_f32_16x16x32_bf16 v[108:111], v[146:149], v[192:195], 0
	v_mfma_f32_16x16x32_bf16 v[104:107], v[160:163], v[192:195], 0
	v_mfma_f32_16x16x32_bf16 v[92:95], v[146:149], v[200:203], 0
	v_mfma_f32_16x16x32_bf16 v[88:91], v[160:163], v[200:203], 0
	v_mfma_f32_16x16x32_bf16 v[76:79], v[146:149], v[208:211], 0
	v_mfma_f32_16x16x32_bf16 v[72:75], v[160:163], v[208:211], 0
	v_mfma_f32_16x16x32_bf16 v[124:127], v[156:159], v[188:191], v[124:127]
	v_mfma_f32_16x16x32_bf16 v[120:123], v[164:167], v[188:191], v[120:123]
	v_mfma_f32_16x16x32_bf16 v[108:111], v[156:159], v[196:199], v[108:111]
	v_mfma_f32_16x16x32_bf16 v[104:107], v[164:167], v[196:199], v[104:107]
	v_mfma_f32_16x16x32_bf16 v[92:95], v[156:159], v[204:207], v[92:95]
	v_mfma_f32_16x16x32_bf16 v[88:91], v[164:167], v[204:207], v[88:91]
	v_mfma_f32_16x16x32_bf16 v[76:79], v[156:159], v[212:215], v[76:79]
	v_mfma_f32_16x16x32_bf16 v[72:75], v[164:167], v[212:215], v[72:75]
	v_mfma_f32_16x16x32_bf16 v[116:119], v[168:171], v[184:187], 0
	v_mfma_f32_16x16x32_bf16 v[112:115], v[176:179], v[184:187], 0
	v_mfma_f32_16x16x32_bf16 v[100:103], v[168:171], v[192:195], 0
	v_mfma_f32_16x16x32_bf16 v[96:99], v[176:179], v[192:195], 0
	v_mfma_f32_16x16x32_bf16 v[84:87], v[168:171], v[200:203], 0
	v_mfma_f32_16x16x32_bf16 v[80:83], v[176:179], v[200:203], 0
	v_mfma_f32_16x16x32_bf16 v[68:71], v[168:171], v[208:211], 0
	v_mfma_f32_16x16x32_bf16 v[64:67], v[176:179], v[208:211], 0
	v_mfma_f32_16x16x32_bf16 v[116:119], v[172:175], v[188:191], v[116:119]
	v_mfma_f32_16x16x32_bf16 v[112:115], v[180:183], v[188:191], v[112:115]
	v_mfma_f32_16x16x32_bf16 v[100:103], v[172:175], v[196:199], v[100:103]
	v_mfma_f32_16x16x32_bf16 v[96:99], v[180:183], v[196:199], v[96:99]
	v_mfma_f32_16x16x32_bf16 v[84:87], v[172:175], v[204:207], v[84:87]
	v_mfma_f32_16x16x32_bf16 v[80:83], v[180:183], v[204:207], v[80:83]
	v_mfma_f32_16x16x32_bf16 v[68:71], v[172:175], v[212:215], v[68:71]
	v_mfma_f32_16x16x32_bf16 v[64:67], v[180:183], v[212:215], v[64:67]
	s_barrier
	s_add_i32 s34, s45, s13
	v_lshl_add_u64 v[216:217], s[28:29], 0, v[132:133]
	s_mov_b32 m0, s34
	ds_read_b128 v[184:187], v154 offset:16384
	ds_read_b128 v[188:191], v154 offset:17408
	ds_read_b128 v[192:195], v154 offset:18432
	ds_read_b128 v[196:199], v154 offset:19456
	ds_read_b128 v[200:203], v154 offset:20480
	ds_read_b128 v[204:207], v154 offset:21504
	ds_read_b128 v[208:211], v154 offset:22528
	ds_read_b128 v[212:215], v154 offset:23552
	global_load_lds_dwordx4 v[216:217], off
	s_add_i32 m0, s34, 0x2000
	s_add_u32 s34, s28, 0x80000
	v_lshl_add_u64 v[218:219], s[28:29], 0, v[128:129]
	s_addc_u32 s35, s29, 0
	s_add_i32 s58, s50, s13
	global_load_lds_dwordx4 v[218:219], off
	v_lshl_add_u64 v[220:221], s[34:35], 0, v[132:133]
	s_mov_b32 m0, s58
	v_lshl_add_u64 v[222:223], s[36:37], 0, v[130:131]
	global_load_lds_dwordx4 v[220:221], off
	v_lshl_add_u64 v[220:221], s[34:35], 0, v[128:129]
	s_add_i32 m0, s58, 0x2000
	s_nop 0
	global_load_lds_dwordx4 v[220:221], off
	v_lshl_add_u64 v[220:221], s[36:37], 0, v[134:135]
	s_mov_b32 m0, s23
	s_nop 0
	global_load_lds_dwordx4 v[220:221], off
	s_mov_b32 m0, s33
	s_nop 0
	global_load_lds_dwordx4 v[222:223], off
	s_waitcnt vmcnt(8)
	s_waitcnt lgkmcnt(0)
	s_barrier
; #define PG8_STAGE(bufoff, gbase, voff) do { _Pragma("unroll") for (int _i = 0; _i < 2; ++_i) \
;         __builtin_amdgcn_global_load_lds((const unsigned*)((const char*)(gbase) + (voff)[_i]), (LAS unsigned*)(lds + (bufoff) + ldsw + _i * 8192), 16, 0, 0); } while (0)
; #define PG8_LDA(dst, b, h) do { _Pragma("unroll") for (int m = 0; m < 4; ++m) _Pragma("unroll") for (int k = 0; k < 2; ++k) dst[m][k] = *(const LAS bf16x8*)(lds + PG8_SA(b, h) + aoff + m * 2048 + k * 1024); } while (0)
; #define PG8_LDB(dst, b, h) do { _Pragma("unroll") for (int n = 0; n < 2; ++n) _Pragma("unroll") for (int k = 0; k < 2; ++k) dst[n][k] = *(const LAS bf16x8*)(lds + PG8_SB(b, h) + boff + n * 2048 + k * 1024); } while (0)
; #define PG8_MMA(ai, bj, At, Bt) do { __builtin_amdgcn_s_setprio(1); _Pragma("unroll") for (int m = 0; m < 4; ++m) _Pragma("unroll") for (int n = 0; n < 2; ++n) _Pragma("unroll") for (int k = 0; k < 2; ++k) \
;         acc[ai][bj][m][n] = __builtin_amdgcn_mfma_f32_16x16x32_bf16(Bt[n][k], At[m][k], acc[ai][bj][m][n], 0, 0, 0); __builtin_amdgcn_s_setprio(0); } while (0)
; #define PG8_WAIT_V(n) asm volatile("s_waitcnt vmcnt(" #n ")" ::: "memory")
; #define PG8_WAIT_L(n) asm volatile("s_waitcnt lgkmcnt(" #n ")" ::: "memory")
; #define PG8_BAR __builtin_amdgcn_s_barrier()
; #define PG8_SCHED __builtin_amdgcn_sched_barrier(0)
; template <class Epi, bool ALIGN_EPI, class Hook = NoHook>
; __device__ __forceinline__ void gemm_phase(LAS unsigned char* lds, const Gemm g, const StaticOrder& S, const Epi& E, const Hook& HK = Hook()) {
;     ...
;             PG8_WAIT_V(8); PG8_WAIT_L(0); PG8_BAR; PG8_MMA(1, 0, At, B0); PG8_MMA(1, 1, At, B1); PG8_BAR; PG8_SCHED;
;             PG8_LDB(B0, 1, 0); PG8_LDB(B1, 1, 1); PG8_SCHED; PG8_LDA(At, 1, 0); PG8_STAGE(PG8_SA(0, 1), a2 + hstepA, voffA);
;             PG8_WAIT_V(8); PG8_WAIT_L(0); PG8_BAR; PG8_MMA(0, 0, At, B0); PG8_MMA(0, 1, At, B1); PG8_BAR; PG8_SCHED;
	s_waitcnt lgkmcnt(0)
	v_mfma_f32_16x16x32_bf16 v[60:63], v[146:149], v[184:187], 0
	v_mfma_f32_16x16x32_bf16 v[56:59], v[160:163], v[184:187], 0
	v_mfma_f32_16x16x32_bf16 v[44:47], v[146:149], v[192:195], 0
	v_mfma_f32_16x16x32_bf16 v[40:43], v[160:163], v[192:195], 0
	v_mfma_f32_16x16x32_bf16 v[28:31], v[146:149], v[200:203], 0
	v_mfma_f32_16x16x32_bf16 v[24:27], v[160:163], v[200:203], 0
	v_mfma_f32_16x16x32_bf16 v[12:15], v[146:149], v[208:211], 0
	v_mfma_f32_16x16x32_bf16 v[8:11], v[160:163], v[208:211], 0
	v_mfma_f32_16x16x32_bf16 v[60:63], v[156:159], v[188:191], v[60:63]
	v_mfma_f32_16x16x32_bf16 v[56:59], v[164:167], v[188:191], v[56:59]
	v_mfma_f32_16x16x32_bf16 v[44:47], v[156:159], v[196:199], v[44:47]
	v_mfma_f32_16x16x32_bf16 v[40:43], v[164:167], v[196:199], v[40:43]
	v_mfma_f32_16x16x32_bf16 v[28:31], v[156:159], v[204:207], v[28:31]
	v_mfma_f32_16x16x32_bf16 v[24:27], v[164:167], v[204:207], v[24:27]
	v_mfma_f32_16x16x32_bf16 v[12:15], v[156:159], v[212:215], v[12:15]
	v_mfma_f32_16x16x32_bf16 v[8:11], v[164:167], v[212:215], v[8:11]
	v_mfma_f32_16x16x32_bf16 v[52:55], v[168:171], v[184:187], 0
	v_mfma_f32_16x16x32_bf16 v[48:51], v[176:179], v[184:187], 0
	v_mfma_f32_16x16x32_bf16 v[36:39], v[168:171], v[192:195], 0
	v_mfma_f32_16x16x32_bf16 v[32:35], v[176:179], v[192:195], 0
	v_mfma_f32_16x16x32_bf16 v[20:23], v[168:171], v[200:203], 0
	v_mfma_f32_16x16x32_bf16 v[16:19], v[176:179], v[200:203], 0
	v_mfma_f32_16x16x32_bf16 v[4:7], v[168:171], v[208:211], 0
	v_mfma_f32_16x16x32_bf16 v[0:3], v[176:179], v[208:211], 0
	v_mfma_f32_16x16x32_bf16 v[52:55], v[172:175], v[188:191], v[52:55]
	v_mfma_f32_16x16x32_bf16 v[48:51], v[180:183], v[188:191], v[48:51]
	v_mfma_f32_16x16x32_bf16 v[36:39], v[172:175], v[196:199], v[36:39]
	v_mfma_f32_16x16x32_bf16 v[32:35], v[180:183], v[196:199], v[32:35]
	v_mfma_f32_16x16x32_bf16 v[20:23], v[172:175], v[204:207], v[20:23]
	v_mfma_f32_16x16x32_bf16 v[16:19], v[180:183], v[204:207], v[16:19]
	v_mfma_f32_16x16x32_bf16 v[4:7], v[172:175], v[212:215], v[4:7]
	v_mfma_f32_16x16x32_bf16 v[0:3], v[180:183], v[212:215], v[0:3]
	s_barrier
	s_add_i32 s58, 0, 0x18000
	v_add_u32_e32 v155, s58, v150
	s_add_i32 s59, 0, 0x1c000
	ds_read_b128 v[146:149], v155
	ds_read_b128 v[156:159], v155 offset:1024
	ds_read_b128 v[160:163], v155 offset:2048
	ds_read_b128 v[164:167], v155 offset:3072
	v_add_u32_e32 v155, s59, v150
	ds_read_b128 v[168:171], v155
	ds_read_b128 v[172:175], v155 offset:1024
	ds_read_b128 v[176:179], v155 offset:2048
	ds_read_b128 v[180:183], v155 offset:3072
	s_add_u32 s34, s36, 0x80000
	s_addc_u32 s35, s37, 0
	s_mov_b32 m0, s38
	v_lshl_add_u64 v[224:225], s[34:35], 0, v[134:135]
	ds_read_b128 v[184:187], v154 offset:32768
	ds_read_b128 v[188:191], v154 offset:33792
	ds_read_b128 v[192:195], v154 offset:34816
	ds_read_b128 v[196:199], v154 offset:35840
	ds_read_b128 v[200:203], v154 offset:36864
	ds_read_b128 v[204:207], v154 offset:37888
	ds_read_b128 v[208:211], v154 offset:38912
	ds_read_b128 v[212:215], v154 offset:39936
	global_load_lds_dwordx4 v[224:225], off
	v_lshl_add_u64 v[224:225], s[34:35], 0, v[130:131]
	s_mov_b32 m0, s39
	s_nop 0
	global_load_lds_dwordx4 v[224:225], off
	s_waitcnt vmcnt(8)
	s_waitcnt lgkmcnt(0)
	s_barrier
	s_waitcnt lgkmcnt(0)
	v_mfma_f32_16x16x32_bf16 v[124:127], v[146:149], v[184:187], v[124:127]
	v_mfma_f32_16x16x32_bf16 v[120:123], v[160:163], v[184:187], v[120:123]
	v_mfma_f32_16x16x32_bf16 v[108:111], v[146:149], v[192:195], v[108:111]
	v_mfma_f32_16x16x32_bf16 v[104:107], v[160:163], v[192:195], v[104:107]
	v_mfma_f32_16x16x32_bf16 v[92:95], v[146:149], v[200:203], v[92:95]
	v_mfma_f32_16x16x32_bf16 v[88:91], v[160:163], v[200:203], v[88:91]
	v_mfma_f32_16x16x32_bf16 v[76:79], v[146:149], v[208:211], v[76:79]
	v_mfma_f32_16x16x32_bf16 v[72:75], v[160:163], v[208:211], v[72:75]
	v_mfma_f32_16x16x32_bf16 v[124:127], v[156:159], v[188:191], v[124:127]
	v_mfma_f32_16x16x32_bf16 v[120:123], v[164:167], v[188:191], v[120:123]
	v_mfma_f32_16x16x32_bf16 v[108:111], v[156:159], v[196:199], v[108:111]
	v_mfma_f32_16x16x32_bf16 v[104:107], v[164:167], v[196:199], v[104:107]
	v_mfma_f32_16x16x32_bf16 v[92:95], v[156:159], v[204:207], v[92:95]
	v_mfma_f32_16x16x32_bf16 v[88:91], v[164:167], v[204:207], v[88:91]
	v_mfma_f32_16x16x32_bf16 v[76:79], v[156:159], v[212:215], v[76:79]
	v_mfma_f32_16x16x32_bf16 v[72:75], v[164:167], v[212:215], v[72:75]
	v_mfma_f32_16x16x32_bf16 v[116:119], v[168:171], v[184:187], v[116:119]
	v_mfma_f32_16x16x32_bf16 v[112:115], v[176:179], v[184:187], v[112:115]
	v_mfma_f32_16x16x32_bf16 v[100:103], v[168:171], v[192:195], v[100:103]
	v_mfma_f32_16x16x32_bf16 v[96:99], v[176:179], v[192:195], v[96:99]
	v_mfma_f32_16x16x32_bf16 v[84:87], v[168:171], v[200:203], v[84:87]
	v_mfma_f32_16x16x32_bf16 v[80:83], v[176:179], v[200:203], v[80:83]
	v_mfma_f32_16x16x32_bf16 v[68:71], v[168:171], v[208:211], v[68:71]
	v_mfma_f32_16x16x32_bf16 v[64:67], v[176:179], v[208:211], v[64:67]
	v_mfma_f32_16x16x32_bf16 v[116:119], v[172:175], v[188:191], v[116:119]
	v_mfma_f32_16x16x32_bf16 v[112:115], v[180:183], v[188:191], v[112:115]
	v_mfma_f32_16x16x32_bf16 v[100:103], v[172:175], v[196:199], v[100:103]
	v_mfma_f32_16x16x32_bf16 v[96:99], v[180:183], v[196:199], v[96:99]
	v_mfma_f32_16x16x32_bf16 v[84:87], v[172:175], v[204:207], v[84:87]
	v_mfma_f32_16x16x32_bf16 v[80:83], v[180:183], v[204:207], v[80:83]
	v_mfma_f32_16x16x32_bf16 v[68:71], v[172:175], v[212:215], v[68:71]
	v_mfma_f32_16x16x32_bf16 v[64:67], v[180:183], v[212:215], v[64:67]
	s_barrier
; #define PG8_STAGE(bufoff, gbase, voff) do { _Pragma("unroll") for (int _i = 0; _i < 2; ++_i) \
;         __builtin_amdgcn_global_load_lds((const unsigned*)((const char*)(gbase) + (voff)[_i]), (LAS unsigned*)(lds + (bufoff) + ldsw + _i * 8192), 16, 0, 0); } while (0)
; #define PG8_LDA(dst, b, h) do { _Pragma("unroll") for (int m = 0; m < 4; ++m) _Pragma("unroll") for (int k = 0; k < 2; ++k) dst[m][k] = *(const LAS bf16x8*)(lds + PG8_SA(b, h) + aoff + m * 2048 + k * 1024); } while (0)
; #define PG8_LDB(dst, b, h) do { _Pragma("unroll") for (int n = 0; n < 2; ++n) _Pragma("unroll") for (int k = 0; k < 2; ++k) dst[n][k] = *(const LAS bf16x8*)(lds + PG8_SB(b, h) + boff + n * 2048 + k * 1024); } while (0)
; #define PG8_MMA(ai, bj, At, Bt) do { __builtin_amdgcn_s_setprio(1); _Pragma("unroll") for (int m = 0; m < 4; ++m) _Pragma("unroll") for (int n = 0; n < 2; ++n) _Pragma("unroll") for (int k = 0; k < 2; ++k) \
;         acc[ai][bj][m][n] = __builtin_amdgcn_mfma_f32_16x16x32_bf16(Bt[n][k], At[m][k], acc[ai][bj][m][n], 0, 0, 0); __builtin_amdgcn_s_setprio(0); } while (0)
; #define PG8_WAIT_V(n) asm volatile("s_waitcnt vmcnt(" #n ")" ::: "memory")
; #define PG8_WAIT_L(n) asm volatile("s_waitcnt lgkmcnt(" #n ")" ::: "memory")
; #define PG8_BAR __builtin_amdgcn_s_barrier()
; #define PG8_SCHED __builtin_amdgcn_sched_barrier(0)
; template <class Epi, bool ALIGN_EPI, class Hook = NoHook>
; __device__ __forceinline__ void gemm_phase(LAS unsigned char* lds, const Gemm g, const StaticOrder& S, const Epi& E, const Hook& HK = Hook()) {
;     ...
;             PG8_LDB(B0, 0, 0); PG8_LDB(B1, 0, 1); PG8_SCHED; PG8_LDA(At, 0, 0); PG8_STAGE(PG8_SA(1, 1), a1 + hstepA, voffA);
;             PG8_WAIT_V(8); PG8_WAIT_L(0); PG8_BAR; PG8_MMA(0, 0, At, B0); PG8_MMA(0, 1, At, B1); PG8_BAR; PG8_SCHED;
;     ...
;             PG8_LDA(At, 1, 1); PG8_STAGE(PG8_SB(1, 0), b3, voffB); PG8_STAGE(PG8_SB(1, 1), b3 + hstepB, voffB); PG8_STAGE(PG8_SA(1, 0), a3, voffA);
;             PG8_WAIT_V(8); PG8_WAIT_L(0); PG8_BAR; PG8_MMA(1, 0, At, B0); PG8_MMA(1, 1, At, B1); PG8_BAR; PG8_SCHED;
	s_add_i32 s34, s58, s13
	v_lshl_add_u64 v[216:217], v[216:217], 0, s[8:9]
	s_mov_b32 m0, s34
	ds_read_b128 v[184:187], v154 offset:49152
	ds_read_b128 v[188:191], v154 offset:50176
	ds_read_b128 v[192:195], v154 offset:51200
	ds_read_b128 v[196:199], v154 offset:52224
	ds_read_b128 v[200:203], v154 offset:53248
	ds_read_b128 v[204:207], v154 offset:54272
	ds_read_b128 v[208:211], v154 offset:55296
	ds_read_b128 v[212:215], v154 offset:56320
	global_load_lds_dwordx4 v[216:217], off
	s_add_i32 m0, s34, 0x2000
	s_add_u32 s28, s28, 0x80080
	v_lshl_add_u64 v[216:217], v[218:219], 0, s[8:9]
	s_addc_u32 s29, s29, 0
	s_add_i32 s34, s59, s13
	global_load_lds_dwordx4 v[216:217], off
	v_lshl_add_u64 v[216:217], s[28:29], 0, v[132:133]
	s_mov_b32 m0, s34
	s_nop 0
	global_load_lds_dwordx4 v[216:217], off
	v_lshl_add_u64 v[216:217], s[28:29], 0, v[128:129]
	s_add_i32 m0, s34, 0x2000
	s_nop 0
	global_load_lds_dwordx4 v[216:217], off
	v_lshl_add_u64 v[216:217], v[220:221], 0, s[8:9]
	s_mov_b32 m0, s41
	s_nop 0
	global_load_lds_dwordx4 v[216:217], off
	v_lshl_add_u64 v[216:217], v[222:223], 0, s[8:9]
	s_mov_b32 m0, s42
	s_nop 0
	global_load_lds_dwordx4 v[216:217], off
	s_waitcnt vmcnt(8)
	s_waitcnt lgkmcnt(0)
	s_barrier
	s_waitcnt lgkmcnt(0)
	v_mfma_f32_16x16x32_bf16 v[60:63], v[146:149], v[184:187], v[60:63]
	v_mfma_f32_16x16x32_bf16 v[56:59], v[160:163], v[184:187], v[56:59]
	v_mfma_f32_16x16x32_bf16 v[44:47], v[146:149], v[192:195], v[44:47]
	v_mfma_f32_16x16x32_bf16 v[40:43], v[160:163], v[192:195], v[40:43]
	v_mfma_f32_16x16x32_bf16 v[28:31], v[146:149], v[200:203], v[28:31]
	v_mfma_f32_16x16x32_bf16 v[24:27], v[160:163], v[200:203], v[24:27]
	v_mfma_f32_16x16x32_bf16 v[12:15], v[146:149], v[208:211], v[12:15]
	v_mfma_f32_16x16x32_bf16 v[8:11], v[160:163], v[208:211], v[8:11]
	v_mfma_f32_16x16x32_bf16 v[60:63], v[156:159], v[188:191], v[60:63]
	v_mfma_f32_16x16x32_bf16 v[56:59], v[164:167], v[188:191], v[56:59]
	v_mfma_f32_16x16x32_bf16 v[44:47], v[156:159], v[196:199], v[44:47]
	v_mfma_f32_16x16x32_bf16 v[40:43], v[164:167], v[196:199], v[40:43]
	v_mfma_f32_16x16x32_bf16 v[28:31], v[156:159], v[204:207], v[28:31]
	v_mfma_f32_16x16x32_bf16 v[24:27], v[164:167], v[204:207], v[24:27]
	v_mfma_f32_16x16x32_bf16 v[12:15], v[156:159], v[212:215], v[12:15]
	v_mfma_f32_16x16x32_bf16 v[8:11], v[164:167], v[212:215], v[8:11]
	v_mfma_f32_16x16x32_bf16 v[52:55], v[168:171], v[184:187], v[52:55]
	v_mfma_f32_16x16x32_bf16 v[48:51], v[176:179], v[184:187], v[48:51]
	v_mfma_f32_16x16x32_bf16 v[36:39], v[168:171], v[192:195], v[36:39]
	v_mfma_f32_16x16x32_bf16 v[32:35], v[176:179], v[192:195], v[32:35]
	v_mfma_f32_16x16x32_bf16 v[20:23], v[168:171], v[200:203], v[20:23]
	v_mfma_f32_16x16x32_bf16 v[16:19], v[176:179], v[200:203], v[16:19]
	v_mfma_f32_16x16x32_bf16 v[4:7], v[168:171], v[208:211], v[4:7]
	v_mfma_f32_16x16x32_bf16 v[0:3], v[176:179], v[208:211], v[0:3]
	v_mfma_f32_16x16x32_bf16 v[52:55], v[172:175], v[188:191], v[52:55]
	v_mfma_f32_16x16x32_bf16 v[48:51], v[180:183], v[188:191], v[48:51]
	v_mfma_f32_16x16x32_bf16 v[36:39], v[172:175], v[196:199], v[36:39]
	v_mfma_f32_16x16x32_bf16 v[32:35], v[180:183], v[196:199], v[32:35]
	v_mfma_f32_16x16x32_bf16 v[20:23], v[172:175], v[204:207], v[20:23]
	v_mfma_f32_16x16x32_bf16 v[16:19], v[180:183], v[204:207], v[16:19]
	v_mfma_f32_16x16x32_bf16 v[4:7], v[172:175], v[212:215], v[4:7]
	v_mfma_f32_16x16x32_bf16 v[0:3], v[180:183], v[212:215], v[0:3]
	s_barrier
	s_add_i32 s57, s57, 2
	s_add_u32 s24, s24, 0x100
	s_addc_u32 s25, s25, 0
	s_add_u32 s55, s55, 0x100
	s_addc_u32 s56, s56, 0
	s_cmp_gt_u32 s57, 29
.LBB0_919:
	ds_read_b128 v[146:149], v152
	ds_read_b128 v[156:159], v152 offset:1024
	ds_read_b128 v[160:163], v152 offset:2048
	ds_read_b128 v[164:167], v152 offset:3072
	ds_read_b128 v[168:171], v153
	ds_read_b128 v[172:175], v153 offset:1024
	ds_read_b128 v[176:179], v153 offset:2048
	ds_read_b128 v[180:183], v153 offset:3072
	s_add_u32 s28, s24, 0xfff80080
	s_addc_u32 s29, s25, -1
	s_cmp_eq_u32 s57, 28
	s_cselect_b32 s37, s17, s29
	s_cselect_b32 s36, s53, s28
	s_cselect_b32 s29, s15, s56
	s_cselect_b32 s28, s54, s55
	v_lshl_add_u64 v[216:217], s[24:25], 0, v[138:139]
	s_add_i32 m0, s23, 0xc000
	ds_read_b128 v[184:187], v154
	ds_read_b128 v[188:191], v154 offset:1024
	ds_read_b128 v[192:195], v154 offset:2048
	ds_read_b128 v[196:199], v154 offset:3072
	ds_read_b128 v[200:203], v154 offset:4096
	ds_read_b128 v[204:207], v154 offset:5120
	ds_read_b128 v[208:211], v154 offset:6144
	ds_read_b128 v[212:215], v154 offset:7168
	global_load_lds_dwordx4 v[216:217], off
	v_lshl_add_u64 v[216:217], s[24:25], 0, v[140:141]
	s_add_i32 m0, s23, 0xe000
	s_nop 0
	global_load_lds_dwordx4 v[216:217], off
	s_waitcnt vmcnt(8)
	s_waitcnt lgkmcnt(0)
	s_barrier
; #define PG8_STAGE(bufoff, gbase, voff) do { _Pragma("unroll") for (int _i = 0; _i < 2; ++_i) \
;         __builtin_amdgcn_global_load_lds((const unsigned*)((const char*)(gbase) + (voff)[_i]), (LAS unsigned*)(lds + (bufoff) + ldsw + _i * 8192), 16, 0, 0); } while (0)
; #define PG8_LDA(dst, b, h) do { _Pragma("unroll") for (int m = 0; m < 4; ++m) _Pragma("unroll") for (int k = 0; k < 2; ++k) dst[m][k] = *(const LAS bf16x8*)(lds + PG8_SA(b, h) + aoff + m * 2048 + k * 1024); } while (0)
; #define PG8_LDB(dst, b, h) do { _Pragma("unroll") for (int n = 0; n < 2; ++n) _Pragma("unroll") for (int k = 0; k < 2; ++k) dst[n][k] = *(const LAS bf16x8*)(lds + PG8_SB(b, h) + boff + n * 2048 + k * 1024); } while (0)
; #define PG8_MMA(ai, bj, At, Bt) do { __builtin_amdgcn_s_setprio(1); _Pragma("unroll") for (int m = 0; m < 4; ++m) _Pragma("unroll") for (int n = 0; n < 2; ++n) _Pragma("unroll") for (int k = 0; k < 2; ++k) \
;         acc[ai][bj][m][n] = __builtin_amdgcn_mfma_f32_16x16x32_bf16(Bt[n][k], At[m][k], acc[ai][bj][m][n], 0, 0, 0); __builtin_amdgcn_s_setprio(0); } while (0)
; #define PG8_WAIT_V(n) asm volatile("s_waitcnt vmcnt(" #n ")" ::: "memory")
; #define PG8_WAIT_L(n) asm volatile("s_waitcnt lgkmcnt(" #n ")" ::: "memory")
; #define PG8_BAR __builtin_amdgcn_s_barrier()
; #define PG8_SCHED __builtin_amdgcn_sched_barrier(0)
; template <class Epi, bool ALIGN_EPI, class Hook = NoHook>
; __device__ __forceinline__ void gemm_phase(LAS unsigned char* lds, const Gemm g, const StaticOrder& S, const Epi& E, const Hook& HK = Hook()) {
;     ...
;             PG8_WAIT_V(8); PG8_WAIT_L(0); PG8_BAR; PG8_MMA(0, 0, At, B0); PG8_MMA(0, 1, At, B1); PG8_BAR; PG8_SCHED;
;             PG8_LDA(At, 0, 1); PG8_STAGE(PG8_SB(0, 0), b2, voffB); PG8_STAGE(PG8_SB(0, 1), b2 + hstepB, voffB); PG8_STAGE(PG8_SA(0, 0), a2, voffA);
;             PG8_WAIT_V(8); PG8_WAIT_L(0); PG8_BAR; PG8_MMA(1, 0, At, B0); PG8_MMA(1, 1, At, B1); PG8_BAR; PG8_SCHED;
;             PG8_LDB(B0, 1, 0); PG8_LDB(B1, 1, 1); PG8_SCHED; PG8_LDA(At, 1, 0); PG8_STAGE(PG8_SA(0, 1), a2 + hstepA, voffA);
;             PG8_WAIT_V(8); PG8_WAIT_L(0); PG8_BAR; PG8_MMA(0, 0, At, B0); PG8_MMA(0, 1, At, B1); PG8_BAR; PG8_SCHED;
	s_waitcnt lgkmcnt(0)
	v_mfma_f32_16x16x32_bf16 v[124:127], v[146:149], v[184:187], v[124:127]
	v_mfma_f32_16x16x32_bf16 v[120:123], v[160:163], v[184:187], v[120:123]
	v_mfma_f32_16x16x32_bf16 v[108:111], v[146:149], v[192:195], v[108:111]
	v_mfma_f32_16x16x32_bf16 v[104:107], v[160:163], v[192:195], v[104:107]
	v_mfma_f32_16x16x32_bf16 v[92:95], v[146:149], v[200:203], v[92:95]
	v_mfma_f32_16x16x32_bf16 v[88:91], v[160:163], v[200:203], v[88:91]
	v_mfma_f32_16x16x32_bf16 v[76:79], v[146:149], v[208:211], v[76:79]
	v_mfma_f32_16x16x32_bf16 v[72:75], v[160:163], v[208:211], v[72:75]
	v_mfma_f32_16x16x32_bf16 v[124:127], v[156:159], v[188:191], v[124:127]
	v_mfma_f32_16x16x32_bf16 v[120:123], v[164:167], v[188:191], v[120:123]
	v_mfma_f32_16x16x32_bf16 v[108:111], v[156:159], v[196:199], v[108:111]
	v_mfma_f32_16x16x32_bf16 v[104:107], v[164:167], v[196:199], v[104:107]
	v_mfma_f32_16x16x32_bf16 v[92:95], v[156:159], v[204:207], v[92:95]
	v_mfma_f32_16x16x32_bf16 v[88:91], v[164:167], v[204:207], v[88:91]
	v_mfma_f32_16x16x32_bf16 v[76:79], v[156:159], v[212:215], v[76:79]
	v_mfma_f32_16x16x32_bf16 v[72:75], v[164:167], v[212:215], v[72:75]
	v_mfma_f32_16x16x32_bf16 v[116:119], v[168:171], v[184:187], v[116:119]
	v_mfma_f32_16x16x32_bf16 v[112:115], v[176:179], v[184:187], v[112:115]
	v_mfma_f32_16x16x32_bf16 v[100:103], v[168:171], v[192:195], v[100:103]
	v_mfma_f32_16x16x32_bf16 v[96:99], v[176:179], v[192:195], v[96:99]
	v_mfma_f32_16x16x32_bf16 v[84:87], v[168:171], v[200:203], v[84:87]
	v_mfma_f32_16x16x32_bf16 v[80:83], v[176:179], v[200:203], v[80:83]
	v_mfma_f32_16x16x32_bf16 v[68:71], v[168:171], v[208:211], v[68:71]
	v_mfma_f32_16x16x32_bf16 v[64:67], v[176:179], v[208:211], v[64:67]
	v_mfma_f32_16x16x32_bf16 v[116:119], v[172:175], v[188:191], v[116:119]
	v_mfma_f32_16x16x32_bf16 v[112:115], v[180:183], v[188:191], v[112:115]
	v_mfma_f32_16x16x32_bf16 v[100:103], v[172:175], v[196:199], v[100:103]
	v_mfma_f32_16x16x32_bf16 v[96:99], v[180:183], v[196:199], v[96:99]
	v_mfma_f32_16x16x32_bf16 v[84:87], v[172:175], v[204:207], v[84:87]
	v_mfma_f32_16x16x32_bf16 v[80:83], v[180:183], v[204:207], v[80:83]
	v_mfma_f32_16x16x32_bf16 v[68:71], v[172:175], v[212:215], v[68:71]
	v_mfma_f32_16x16x32_bf16 v[64:67], v[180:183], v[212:215], v[64:67]
	s_barrier
	s_add_i32 s34, s45, s13
	v_lshl_add_u64 v[216:217], s[28:29], 0, v[132:133]
	s_mov_b32 m0, s34
	ds_read_b128 v[184:187], v154 offset:16384
	ds_read_b128 v[188:191], v154 offset:17408
	ds_read_b128 v[192:195], v154 offset:18432
	ds_read_b128 v[196:199], v154 offset:19456
	ds_read_b128 v[200:203], v154 offset:20480
	ds_read_b128 v[204:207], v154 offset:21504
	ds_read_b128 v[208:211], v154 offset:22528
	ds_read_b128 v[212:215], v154 offset:23552
	global_load_lds_dwordx4 v[216:217], off
	s_add_i32 m0, s34, 0x2000
	s_add_u32 s34, s28, 0x80000
	v_lshl_add_u64 v[218:219], s[28:29], 0, v[128:129]
	s_addc_u32 s35, s29, 0
	s_add_i32 s58, s50, s13
	global_load_lds_dwordx4 v[218:219], off
	v_lshl_add_u64 v[220:221], s[34:35], 0, v[132:133]
	s_mov_b32 m0, s58
	v_lshl_add_u64 v[222:223], s[36:37], 0, v[130:131]
	global_load_lds_dwordx4 v[220:221], off
	v_lshl_add_u64 v[220:221], s[34:35], 0, v[128:129]
	s_add_i32 m0, s58, 0x2000
	s_nop 0
	global_load_lds_dwordx4 v[220:221], off
	v_lshl_add_u64 v[220:221], s[36:37], 0, v[134:135]
	s_mov_b32 m0, s23
	s_nop 0
	global_load_lds_dwordx4 v[220:221], off
	s_mov_b32 m0, s33
	s_nop 0
	global_load_lds_dwordx4 v[222:223], off
	s_waitcnt vmcnt(8)
	s_waitcnt lgkmcnt(0)
	s_barrier
	s_waitcnt lgkmcnt(0)
	v_mfma_f32_16x16x32_bf16 v[60:63], v[146:149], v[184:187], v[60:63]
	v_mfma_f32_16x16x32_bf16 v[56:59], v[160:163], v[184:187], v[56:59]
	v_mfma_f32_16x16x32_bf16 v[44:47], v[146:149], v[192:195], v[44:47]
	v_mfma_f32_16x16x32_bf16 v[40:43], v[160:163], v[192:195], v[40:43]
	v_mfma_f32_16x16x32_bf16 v[28:31], v[146:149], v[200:203], v[28:31]
	v_mfma_f32_16x16x32_bf16 v[24:27], v[160:163], v[200:203], v[24:27]
	v_mfma_f32_16x16x32_bf16 v[12:15], v[146:149], v[208:211], v[12:15]
	v_mfma_f32_16x16x32_bf16 v[8:11], v[160:163], v[208:211], v[8:11]
	v_mfma_f32_16x16x32_bf16 v[60:63], v[156:159], v[188:191], v[60:63]
	v_mfma_f32_16x16x32_bf16 v[56:59], v[164:167], v[188:191], v[56:59]
	v_mfma_f32_16x16x32_bf16 v[44:47], v[156:159], v[196:199], v[44:47]
	v_mfma_f32_16x16x32_bf16 v[40:43], v[164:167], v[196:199], v[40:43]
	v_mfma_f32_16x16x32_bf16 v[28:31], v[156:159], v[204:207], v[28:31]
	v_mfma_f32_16x16x32_bf16 v[24:27], v[164:167], v[204:207], v[24:27]
	v_mfma_f32_16x16x32_bf16 v[12:15], v[156:159], v[212:215], v[12:15]
	v_mfma_f32_16x16x32_bf16 v[8:11], v[164:167], v[212:215], v[8:11]
	v_mfma_f32_16x16x32_bf16 v[52:55], v[168:171], v[184:187], v[52:55]
	v_mfma_f32_16x16x32_bf16 v[48:51], v[176:179], v[184:187], v[48:51]
	v_mfma_f32_16x16x32_bf16 v[36:39], v[168:171], v[192:195], v[36:39]
	v_mfma_f32_16x16x32_bf16 v[32:35], v[176:179], v[192:195], v[32:35]
	v_mfma_f32_16x16x32_bf16 v[20:23], v[168:171], v[200:203], v[20:23]
	v_mfma_f32_16x16x32_bf16 v[16:19], v[176:179], v[200:203], v[16:19]
	v_mfma_f32_16x16x32_bf16 v[4:7], v[168:171], v[208:211], v[4:7]
	v_mfma_f32_16x16x32_bf16 v[0:3], v[176:179], v[208:211], v[0:3]
	v_mfma_f32_16x16x32_bf16 v[52:55], v[172:175], v[188:191], v[52:55]
	v_mfma_f32_16x16x32_bf16 v[48:51], v[180:183], v[188:191], v[48:51]
	v_mfma_f32_16x16x32_bf16 v[36:39], v[172:175], v[196:199], v[36:39]
	v_mfma_f32_16x16x32_bf16 v[32:35], v[180:183], v[196:199], v[32:35]
	v_mfma_f32_16x16x32_bf16 v[20:23], v[172:175], v[204:207], v[20:23]
	v_mfma_f32_16x16x32_bf16 v[16:19], v[180:183], v[204:207], v[16:19]
	v_mfma_f32_16x16x32_bf16 v[4:7], v[172:175], v[212:215], v[4:7]
	v_mfma_f32_16x16x32_bf16 v[0:3], v[180:183], v[212:215], v[0:3]
	s_barrier
; #define PG8_STAGE(bufoff, gbase, voff) do { _Pragma("unroll") for (int _i = 0; _i < 2; ++_i) \
;         __builtin_amdgcn_global_load_lds((const unsigned*)((const char*)(gbase) + (voff)[_i]), (LAS unsigned*)(lds + (bufoff) + ldsw + _i * 8192), 16, 0, 0); } while (0)
; #define PG8_LDA(dst, b, h) do { _Pragma("unroll") for (int m = 0; m < 4; ++m) _Pragma("unroll") for (int k = 0; k < 2; ++k) dst[m][k] = *(const LAS bf16x8*)(lds + PG8_SA(b, h) + aoff + m * 2048 + k * 1024); } while (0)
; #define PG8_LDB(dst, b, h) do { _Pragma("unroll") for (int n = 0; n < 2; ++n) _Pragma("unroll") for (int k = 0; k < 2; ++k) dst[n][k] = *(const LAS bf16x8*)(lds + PG8_SB(b, h) + boff + n * 2048 + k * 1024); } while (0)
; #define PG8_MMA(ai, bj, At, Bt) do { __builtin_amdgcn_s_setprio(1); _Pragma("unroll") for (int m = 0; m < 4; ++m) _Pragma("unroll") for (int n = 0; n < 2; ++n) _Pragma("unroll") for (int k = 0; k < 2; ++k) \
;         acc[ai][bj][m][n] = __builtin_amdgcn_mfma_f32_16x16x32_bf16(Bt[n][k], At[m][k], acc[ai][bj][m][n], 0, 0, 0); __builtin_amdgcn_s_setprio(0); } while (0)
; #define PG8_WAIT_V(n) asm volatile("s_waitcnt vmcnt(" #n ")" ::: "memory")
; #define PG8_WAIT_L(n) asm volatile("s_waitcnt lgkmcnt(" #n ")" ::: "memory")
; #define PG8_BAR __builtin_amdgcn_s_barrier()
; #define PG8_SCHED __builtin_amdgcn_sched_barrier(0)
; template <class Epi, bool ALIGN_EPI, class Hook = NoHook>
; __device__ __forceinline__ void gemm_phase(LAS unsigned char* lds, const Gemm g, const StaticOrder& S, const Epi& E, const Hook& HK = Hook()) {
;     ...
;             PG8_LDB(B0, 1, 0); PG8_LDB(B1, 1, 1); PG8_SCHED; PG8_LDA(At, 1, 0); PG8_STAGE(PG8_SA(0, 1), a2 + hstepA, voffA);
;             PG8_WAIT_V(8); PG8_WAIT_L(0); PG8_BAR; PG8_MMA(0, 0, At, B0); PG8_MMA(0, 1, At, B1); PG8_BAR; PG8_SCHED;
	s_add_i32 s58, 0, 0x18000
	v_add_u32_e32 v155, s58, v150
	s_add_i32 s59, 0, 0x1c000
	ds_read_b128 v[146:149], v155
	ds_read_b128 v[156:159], v155 offset:1024
	ds_read_b128 v[160:163], v155 offset:2048
	ds_read_b128 v[164:167], v155 offset:3072
	v_add_u32_e32 v155, s59, v150
	ds_read_b128 v[168:171], v155
	ds_read_b128 v[172:175], v155 offset:1024
	ds_read_b128 v[176:179], v155 offset:2048
	ds_read_b128 v[180:183], v155 offset:3072
	s_add_u32 s34, s36, 0x80000
	s_addc_u32 s35, s37, 0
	s_mov_b32 m0, s38
	v_lshl_add_u64 v[224:225], s[34:35], 0, v[134:135]
	ds_read_b128 v[184:187], v154 offset:32768
	ds_read_b128 v[188:191], v154 offset:33792
	ds_read_b128 v[192:195], v154 offset:34816
	ds_read_b128 v[196:199], v154 offset:35840
	ds_read_b128 v[200:203], v154 offset:36864
	ds_read_b128 v[204:207], v154 offset:37888
	ds_read_b128 v[208:211], v154 offset:38912
	ds_read_b128 v[212:215], v154 offset:39936
	global_load_lds_dwordx4 v[224:225], off
	v_lshl_add_u64 v[224:225], s[34:35], 0, v[130:131]
	s_mov_b32 m0, s39
	s_nop 0
	global_load_lds_dwordx4 v[224:225], off
	s_waitcnt vmcnt(8)
	s_waitcnt lgkmcnt(0)
	s_barrier
	s_waitcnt lgkmcnt(0)
	v_mfma_f32_16x16x32_bf16 v[124:127], v[146:149], v[184:187], v[124:127]
	v_mfma_f32_16x16x32_bf16 v[120:123], v[160:163], v[184:187], v[120:123]
	v_mfma_f32_16x16x32_bf16 v[108:111], v[146:149], v[192:195], v[108:111]
	v_mfma_f32_16x16x32_bf16 v[104:107], v[160:163], v[192:195], v[104:107]
	v_mfma_f32_16x16x32_bf16 v[92:95], v[146:149], v[200:203], v[92:95]
	v_mfma_f32_16x16x32_bf16 v[88:91], v[160:163], v[200:203], v[88:91]
	v_mfma_f32_16x16x32_bf16 v[76:79], v[146:149], v[208:211], v[76:79]
	v_mfma_f32_16x16x32_bf16 v[72:75], v[160:163], v[208:211], v[72:75]
	v_mfma_f32_16x16x32_bf16 v[124:127], v[156:159], v[188:191], v[124:127]
	v_mfma_f32_16x16x32_bf16 v[120:123], v[164:167], v[188:191], v[120:123]
	v_mfma_f32_16x16x32_bf16 v[108:111], v[156:159], v[196:199], v[108:111]
	v_mfma_f32_16x16x32_bf16 v[104:107], v[164:167], v[196:199], v[104:107]
	v_mfma_f32_16x16x32_bf16 v[92:95], v[156:159], v[204:207], v[92:95]
	v_mfma_f32_16x16x32_bf16 v[88:91], v[164:167], v[204:207], v[88:91]
	v_mfma_f32_16x16x32_bf16 v[76:79], v[156:159], v[212:215], v[76:79]
	v_mfma_f32_16x16x32_bf16 v[72:75], v[164:167], v[212:215], v[72:75]
	v_mfma_f32_16x16x32_bf16 v[116:119], v[168:171], v[184:187], v[116:119]
	v_mfma_f32_16x16x32_bf16 v[112:115], v[176:179], v[184:187], v[112:115]
	v_mfma_f32_16x16x32_bf16 v[100:103], v[168:171], v[192:195], v[100:103]
	v_mfma_f32_16x16x32_bf16 v[96:99], v[176:179], v[192:195], v[96:99]
	v_mfma_f32_16x16x32_bf16 v[84:87], v[168:171], v[200:203], v[84:87]
	v_mfma_f32_16x16x32_bf16 v[80:83], v[176:179], v[200:203], v[80:83]
	v_mfma_f32_16x16x32_bf16 v[68:71], v[168:171], v[208:211], v[68:71]
	v_mfma_f32_16x16x32_bf16 v[64:67], v[176:179], v[208:211], v[64:67]
	v_mfma_f32_16x16x32_bf16 v[116:119], v[172:175], v[188:191], v[116:119]
	v_mfma_f32_16x16x32_bf16 v[112:115], v[180:183], v[188:191], v[112:115]
	v_mfma_f32_16x16x32_bf16 v[100:103], v[172:175], v[196:199], v[100:103]
	v_mfma_f32_16x16x32_bf16 v[96:99], v[180:183], v[196:199], v[96:99]
	v_mfma_f32_16x16x32_bf16 v[84:87], v[172:175], v[204:207], v[84:87]
	v_mfma_f32_16x16x32_bf16 v[80:83], v[180:183], v[204:207], v[80:83]
	v_mfma_f32_16x16x32_bf16 v[68:71], v[172:175], v[212:215], v[68:71]
	v_mfma_f32_16x16x32_bf16 v[64:67], v[180:183], v[212:215], v[64:67]
	s_barrier
; #define PG8_STAGE(bufoff, gbase, voff) do { _Pragma("unroll") for (int _i = 0; _i < 2; ++_i) \
;         __builtin_amdgcn_global_load_lds((const unsigned*)((const char*)(gbase) + (voff)[_i]), (LAS unsigned*)(lds + (bufoff) + ldsw + _i * 8192), 16, 0, 0); } while (0)
; #define PG8_LDA(dst, b, h) do { _Pragma("unroll") for (int m = 0; m < 4; ++m) _Pragma("unroll") for (int k = 0; k < 2; ++k) dst[m][k] = *(const LAS bf16x8*)(lds + PG8_SA(b, h) + aoff + m * 2048 + k * 1024); } while (0)
; #define PG8_MMA(ai, bj, At, Bt) do { __builtin_amdgcn_s_setprio(1); _Pragma("unroll") for (int m = 0; m < 4; ++m) _Pragma("unroll") for (int n = 0; n < 2; ++n) _Pragma("unroll") for (int k = 0; k < 2; ++k) \
;         acc[ai][bj][m][n] = __builtin_amdgcn_mfma_f32_16x16x32_bf16(Bt[n][k], At[m][k], acc[ai][bj][m][n], 0, 0, 0); __builtin_amdgcn_s_setprio(0); } while (0)
; #define PG8_WAIT_V(n) asm volatile("s_waitcnt vmcnt(" #n ")" ::: "memory")
; #define PG8_WAIT_L(n) asm volatile("s_waitcnt lgkmcnt(" #n ")" ::: "memory")
; #define PG8_BAR __builtin_amdgcn_s_barrier()
; #define PG8_SCHED __builtin_amdgcn_sched_barrier(0)
; template <class Epi, bool ALIGN_EPI, class Hook = NoHook>
; __device__ __forceinline__ void gemm_phase(LAS unsigned char* lds, const Gemm g, const StaticOrder& S, const Epi& E, const Hook& HK = Hook()) {
;     ...
;             PG8_LDA(At, 1, 1); PG8_STAGE(PG8_SB(1, 0), b3, voffB); PG8_STAGE(PG8_SB(1, 1), b3 + hstepB, voffB); PG8_STAGE(PG8_SA(1, 0), a3, voffA);
;             PG8_WAIT_V(8); PG8_WAIT_L(0); PG8_BAR; PG8_MMA(1, 0, At, B0); PG8_MMA(1, 1, At, B1); PG8_BAR; PG8_SCHED;
;         }
;         if constexpr (ALIGN_EPI) { if (wr == 0) PG8_BAR; }
	s_add_i32 s34, s58, s13
	v_lshl_add_u64 v[216:217], v[216:217], 0, s[8:9]
	s_mov_b32 m0, s34
	ds_read_b128 v[184:187], v154 offset:49152
	ds_read_b128 v[188:191], v154 offset:50176
	ds_read_b128 v[192:195], v154 offset:51200
	ds_read_b128 v[196:199], v154 offset:52224
	ds_read_b128 v[200:203], v154 offset:53248
	ds_read_b128 v[204:207], v154 offset:54272
	ds_read_b128 v[208:211], v154 offset:55296
	ds_read_b128 v[212:215], v154 offset:56320
	global_load_lds_dwordx4 v[216:217], off
	s_add_i32 m0, s34, 0x2000
	s_add_u32 s28, s28, 0x80080
	v_lshl_add_u64 v[216:217], v[218:219], 0, s[8:9]
	s_addc_u32 s29, s29, 0
	s_add_i32 s34, s59, s13
	global_load_lds_dwordx4 v[216:217], off
	v_lshl_add_u64 v[216:217], s[28:29], 0, v[132:133]
	s_mov_b32 m0, s34
	s_nop 0
	global_load_lds_dwordx4 v[216:217], off
	v_lshl_add_u64 v[216:217], s[28:29], 0, v[128:129]
	s_add_i32 m0, s34, 0x2000
	s_nop 0
	global_load_lds_dwordx4 v[216:217], off
	v_lshl_add_u64 v[216:217], v[220:221], 0, s[8:9]
	s_mov_b32 m0, s41
	s_nop 0
	global_load_lds_dwordx4 v[216:217], off
	v_lshl_add_u64 v[216:217], v[222:223], 0, s[8:9]
	s_mov_b32 m0, s42
	s_nop 0
	global_load_lds_dwordx4 v[216:217], off
	s_waitcnt vmcnt(8)
	s_waitcnt lgkmcnt(0)
	s_barrier
	s_waitcnt lgkmcnt(0)
	v_mfma_f32_16x16x32_bf16 v[60:63], v[146:149], v[184:187], v[60:63]
	v_mfma_f32_16x16x32_bf16 v[56:59], v[160:163], v[184:187], v[56:59]
	v_mfma_f32_16x16x32_bf16 v[44:47], v[146:149], v[192:195], v[44:47]
	v_mfma_f32_16x16x32_bf16 v[40:43], v[160:163], v[192:195], v[40:43]
	v_mfma_f32_16x16x32_bf16 v[28:31], v[146:149], v[200:203], v[28:31]
	v_mfma_f32_16x16x32_bf16 v[24:27], v[160:163], v[200:203], v[24:27]
	v_mfma_f32_16x16x32_bf16 v[12:15], v[146:149], v[208:211], v[12:15]
	v_mfma_f32_16x16x32_bf16 v[8:11], v[160:163], v[208:211], v[8:11]
	v_mfma_f32_16x16x32_bf16 v[60:63], v[156:159], v[188:191], v[60:63]
	v_mfma_f32_16x16x32_bf16 v[56:59], v[164:167], v[188:191], v[56:59]
	v_mfma_f32_16x16x32_bf16 v[44:47], v[156:159], v[196:199], v[44:47]
	v_mfma_f32_16x16x32_bf16 v[40:43], v[164:167], v[196:199], v[40:43]
	v_mfma_f32_16x16x32_bf16 v[28:31], v[156:159], v[204:207], v[28:31]
	v_mfma_f32_16x16x32_bf16 v[24:27], v[164:167], v[204:207], v[24:27]
	v_mfma_f32_16x16x32_bf16 v[12:15], v[156:159], v[212:215], v[12:15]
	v_mfma_f32_16x16x32_bf16 v[8:11], v[164:167], v[212:215], v[8:11]
	v_mfma_f32_16x16x32_bf16 v[52:55], v[168:171], v[184:187], v[52:55]
	v_mfma_f32_16x16x32_bf16 v[48:51], v[176:179], v[184:187], v[48:51]
	v_mfma_f32_16x16x32_bf16 v[36:39], v[168:171], v[192:195], v[36:39]
	v_mfma_f32_16x16x32_bf16 v[32:35], v[176:179], v[192:195], v[32:35]
	v_mfma_f32_16x16x32_bf16 v[20:23], v[168:171], v[200:203], v[20:23]
	v_mfma_f32_16x16x32_bf16 v[16:19], v[176:179], v[200:203], v[16:19]
	v_mfma_f32_16x16x32_bf16 v[4:7], v[168:171], v[208:211], v[4:7]
	v_mfma_f32_16x16x32_bf16 v[0:3], v[176:179], v[208:211], v[0:3]
	v_mfma_f32_16x16x32_bf16 v[52:55], v[172:175], v[188:191], v[52:55]
	v_mfma_f32_16x16x32_bf16 v[48:51], v[180:183], v[188:191], v[48:51]
	v_mfma_f32_16x16x32_bf16 v[36:39], v[172:175], v[196:199], v[36:39]
	v_mfma_f32_16x16x32_bf16 v[32:35], v[180:183], v[196:199], v[32:35]
	v_mfma_f32_16x16x32_bf16 v[20:23], v[172:175], v[204:207], v[20:23]
	v_mfma_f32_16x16x32_bf16 v[16:19], v[180:183], v[204:207], v[16:19]
	v_mfma_f32_16x16x32_bf16 v[4:7], v[172:175], v[212:215], v[4:7]
	v_mfma_f32_16x16x32_bf16 v[0:3], v[180:183], v[212:215], v[0:3]
	s_barrier
	s_add_i32 s57, s57, 2
	s_add_u32 s24, s24, 0x100
	s_addc_u32 s25, s25, 0
	s_add_u32 s55, s55, 0x100
	s_addc_u32 s56, s56, 0
	s_cmp_gt_u32 s57, 29
	s_cbranch_scc0 .LBB0_919
	s_and_b64 vcc, exec, s[10:11]
	s_cbranch_vccz .LBB0_922
	s_barrier

; #define PG8_BAR __builtin_amdgcn_s_barrier()
;     __host__ __device__ bool next(int i, Unit& u) const {
;         const long L = (long)i * G + c; if (L >= nwg) return false;
;         int wgid = (int)L; { const int q = nwg / NXCD, r = nwg % NXCD, xcd = wgid % NXCD, off = wgid / NXCD; wgid = (xcd < r ? xcd * (q + 1) : r * (q + 1) + (xcd - r) * q) + off; }
; template <class Epi, bool ALIGN_EPI, class Hook = NoHook>
; __device__ __forceinline__ void gemm_phase(LAS unsigned char* lds, const Gemm g, const StaticOrder& S, const Epi& E, const Hook& HK = Hook()) {
;     int tid = threadIdx.x; asm volatile("" : "+v"(tid));
;     const int wid = __builtin_amdgcn_readfirstlane(tid >> 6), lane = tid & 63, wr = wid >> 2, wc = wid & 3, fr = lane & 15, fq = lane >> 4;
;     const int K = g.K, nt = K / BK;
;     unsigned voffA[2], voffB[2];
; #pragma unroll
;     for (int i = 0; i < 2; ++i) { int R, C; stage_rc(tid * 16 + i * 8192, R, C); const int Rb = Epi::PERM ? ((R & ~31) + perm32(R & 31)) : R;
;         voffA[i] = (unsigned)(R * g.lda + C) * 2u; voffB[i] = (unsigned)(Rb * g.ldb + C) * 2u; }
;     const size_t kstep = (size_t)(BK * 2);
;     const size_t hstepA = (size_t)HALF * g.lda * 2, hstepB = (size_t)HALF * g.ldb * 2;
;     const size_t tstepA = 2 * hstepA, tstepB = 2 * hstepB;
;     const unsigned ldsw = (unsigned)wid * 1024u;
;     const int aoff = lds_byte(wr * 64 + fr, fq * 8), boff = lds_byte(wc * 32 + fr, fq * 8);
;     ...
;     Unit cur, nxt; int ui = 0;
;     if (!S.next(0, cur)) return;
;     f32x4 acc[2][2][4][2];
; #pragma unroll
;     for (int a = 0; a < 2; ++a)
; #pragma unroll
;         for (int b = 0; b < 2; ++b)
; #pragma unroll
;             for (int m = 0; m < 4; ++m)
; #pragma unroll
;                 for (int n = 0; n < 2; ++n) acc[a][b][m][n] = (f32x4){0.f, 0.f, 0.f, 0.f};
;     bf16x8 At[4][2], B0[2][2], B1[2][2];
;     const char* cA = (const char*)g.A + (size_t)cur.pm * tstepA; const char* cB = (const char*)g.Bt + (size_t)cur.pn * tstepB;
;     PG8_STAGE(PG8_SB(0, 0), cB, voffB); PG8_STAGE(PG8_SB(0, 1), cB + hstepB, voffB); PG8_STAGE(PG8_SA(0, 0), cA, voffA); PG8_STAGE(PG8_SA(0, 1), cA + hstepA, voffA);
;     if (wr == 1) PG8_BAR;
;     PG8_WAIT_V(2); PG8_BAR;
;     PG8_STAGE(PG8_SB(1, 0), cB + kstep, voffB); PG8_STAGE(PG8_SA(1, 0), cA + kstep, voffA); PG8_STAGE(PG8_SB(1, 1), cB + hstepB + kstep, voffB);
;     PG8_WAIT_V(6); PG8_BAR;
.LBB0_983:
	v_ashrrev_i32_e32 v1, 31, v136
	v_lshrrev_b32_e32 v1, 26, v1
	v_add_u32_e32 v1, v136, v1
	v_ashrrev_i32_e32 v8, 6, v1
	v_bfe_i32 v1, v136, 27, 1
	v_lshlrev_b32_e32 v0, 4, v136
	v_lshrrev_b32_e32 v1, 22, v1
	v_add_u32_e32 v1, v0, v1
	v_and_b32_e32 v1, 0xfffffc00, v1
	v_sub_u32_e32 v1, v0, v1
	v_lshrrev_b32_e32 v2, 4, v1
	v_bitop3_b32 v1, v2, v1, 32 bitop3:0x6c
	v_ashrrev_i32_e32 v3, 31, v1
	v_lshrrev_b32_e32 v3, 26, v3
	v_lshlrev_b32_e32 v2, 3, v8
	v_add_u32_e32 v3, v1, v3
	v_and_b32_e32 v2, -16, v2
	v_ashrrev_i32_e32 v9, 6, v3
	v_and_b32_e32 v3, 0xc0, v3
	v_add_u32_e32 v2, v9, v2
	v_lshlrev_b32_e32 v4, 5, v8
	v_sub_u32_e32 v1, v1, v3
	v_mov_b32_e32 v3, 1
	v_and_b32_e32 v10, 32, v4
	v_ashrrev_i16_sdwa v1, v3, sext(v1) dst_sel:DWORD dst_unused:UNUSED_PAD src0_sel:DWORD src1_sel:BYTE_0
	v_lshlrev_b32_e32 v4, 1, v2
	v_lshrrev_b32_e32 v5, 2, v2
	v_and_b32_e32 v6, 3, v9
	s_mov_b32 s7, 0x7fffe0
	v_bfe_i32 v11, v1, 0, 16
	v_and_b32_e32 v4, 24, v4
	v_and_b32_e32 v5, 4, v5
	v_and_or_b32 v6, v2, s7, v6
	s_movk_i32 s1, 0x1600
	v_add_u32_e32 v1, v10, v11
	v_or3_b32 v4, v6, v5, v4
	v_mul_lo_u32 v2, v2, s1
	v_add_lshl_u32 v128, v1, v2, 1
	v_mul_u32_u24_e32 v2, 0x1600, v4
	v_add_u32_e32 v0, 0x2000, v0
	v_add_lshl_u32 v130, v2, v1, 1
	v_ashrrev_i32_e32 v1, 31, v0
	v_lshrrev_b32_e32 v1, 22, v1
	v_add_u32_e32 v1, v0, v1
	v_ashrrev_i32_e32 v12, 10, v1
	v_mul_i32_i24_e32 v1, 0x400, v12
	v_sub_u32_e32 v0, v0, v1
	v_lshrrev_b32_e32 v1, 4, v0
	v_bitop3_b32 v0, v1, v0, 32 bitop3:0x6c
	v_ashrrev_i32_e32 v2, 31, v0
	v_lshrrev_b32_e32 v2, 26, v2
	s_add_i32 s5, s5, s6
	v_lshlrev_b32_e32 v1, 3, v12
	v_add_u32_e32 v2, v0, v2
	s_ashr_i32 s6, s5, 31
	v_and_b32_e32 v1, -16, v1
	v_ashrrev_i32_e32 v13, 6, v2
	v_lshlrev_b32_e32 v4, 5, v12
	s_lshr_b32 s6, s6, 27
	v_add_u32_e32 v1, v13, v1
	v_and_b32_e32 v14, 32, v4
	v_and_b32_e32 v4, 3, v13
	s_add_i32 s6, s5, s6
	v_and_or_b32 v4, v1, s7, v4
	s_ashr_i32 s7, s6, 5
	s_and_b32 s6, s6, 0xffe0
	s_sub_i32 s6, s5, s6
	s_bfe_i32 s5, s6, 0x80000
	s_bfe_u32 s5, s5, 0x2000d
	s_add_i32 s9, s6, s5
	s_bfe_i32 s5, s9, 0x80000
	s_and_b32 s9, s9, 0xfc
	s_sub_i32 s6, s6, s9
	s_lshl_b32 s7, s7, 2
	s_sext_i32_i16 s10, s5
	s_sext_i32_i8 s6, s6
	v_and_b32_e32 v2, 0xc0, v2
	s_ashr_i32 s8, s4, 6
	s_add_i32 s39, s7, s6
	s_ashr_i32 s6, s10, 2
	s_ashr_i32 s0, s4, 8
	v_sub_u32_e32 v0, v0, v2
	s_lshl_b32 s22, s8, 10
	s_lshr_b32 s5, s10, 2
	s_mul_hi_i32 s7, s6, 0x2c0000
	s_mul_i32 s6, s6, 0x2c0000
	v_ashrrev_i16_sdwa v0, v3, sext(v0) dst_sel:DWORD dst_unused:UNUSED_PAD src0_sel:DWORD src1_sel:BYTE_0
	v_lshlrev_b32_e32 v2, 1, v1
	v_lshrrev_b32_e32 v3, 2, v1
	s_add_u32 s16, s88, s6
	v_bfe_i32 v15, v0, 0, 16
	v_and_b32_e32 v2, 24, v2
	v_and_b32_e32 v3, 4, v3
	s_addc_u32 s17, s89, s7
	s_add_i32 s23, s22, 0
	v_add_u32_e32 v0, v14, v15
	v_or3_b32 v2, v4, v3, v2
	v_mul_lo_u32 v1, v1, s1
	s_add_i32 m0, s23, 0x10000
	v_add_lshl_u32 v132, v0, v1, 1
	v_mul_u32_u24_e32 v1, 0x1600, v2
	global_load_lds_dwordx4 v130, s[16:17]
	s_add_i32 m0, s23, 0x12000
	v_add_lshl_u32 v134, v1, v0, 1
	s_add_u32 s6, s16, 0x160000
	global_load_lds_dwordx4 v134, s[16:17]
	s_addc_u32 s7, s17, 0
	s_add_i32 m0, s23, 0x14000
	s_mul_i32 s11, s39, 0x2c0000
	global_load_lds_dwordx4 v130, s[6:7]
	s_add_i32 m0, s23, 0x16000
	s_mul_hi_i32 s9, s39, 0x2c0000
	s_add_u32 s14, s46, s11
	s_addc_u32 s15, s47, s9
	s_add_i32 s24, s23, 0x2000
	global_load_lds_dwordx4 v134, s[6:7]
	s_mov_b32 m0, s23
	s_add_u32 s6, s14, 0x160000
	global_load_lds_dwordx4 v128, s[14:15]
	s_mov_b32 m0, s24
	s_addc_u32 s7, s15, 0
	s_add_i32 s25, s23, 0x4000
	global_load_lds_dwordx4 v132, s[14:15]
	s_mov_b32 m0, s25
	s_add_i32 s26, s23, 0x6000
	global_load_lds_dwordx4 v128, s[6:7]
	s_mov_b32 m0, s26
	v_mov_b32_e32 v131, 0
	global_load_lds_dwordx4 v132, s[6:7]
	v_mov_b32_e32 v135, v131
	v_mov_b32_e32 v129, v131
	v_mov_b32_e32 v133, v131
	s_cmp_eq_u32 s0, 1
	s_mov_b32 s27, 0
	v_lshl_add_u64 v[6:7], s[16:17], 0, v[130:131]
	v_lshl_add_u64 v[2:3], s[16:17], 0, v[134:135]
	s_mov_b32 s12, 0x16000
	v_lshl_add_u64 v[0:1], s[14:15], 0, v[128:129]
	s_cselect_b64 s[6:7], -1, 0
	s_cmp_lg_u32 s0, 1
	v_lshl_add_u64 v[4:5], s[14:15], 0, v[132:133]
	s_cbranch_scc1 .LBB0_985
	s_barrier
	s_setprio 1

; #define PG8_STAGE(bufoff, gbase, voff) do { _Pragma("unroll") for (int _i = 0; _i < 2; ++_i) \
;         __builtin_amdgcn_global_load_lds((const unsigned*)((const char*)(gbase) + (voff)[_i]), (LAS unsigned*)(lds + (bufoff) + ldsw + _i * 8192), 16, 0, 0); } while (0)
; #define PG8_LDA(dst, b, h) do { _Pragma("unroll") for (int m = 0; m < 4; ++m) _Pragma("unroll") for (int k = 0; k < 2; ++k) dst[m][k] = *(const LAS bf16x8*)(lds + PG8_SA(b, h) + aoff + m * 2048 + k * 1024); } while (0)
; #define PG8_LDB(dst, b, h) do { _Pragma("unroll") for (int n = 0; n < 2; ++n) _Pragma("unroll") for (int k = 0; k < 2; ++k) dst[n][k] = *(const LAS bf16x8*)(lds + PG8_SB(b, h) + boff + n * 2048 + k * 1024); } while (0)
; #define PG8_WAIT_V(n) asm volatile("s_waitcnt vmcnt(" #n ")" ::: "memory")
; #define PG8_WAIT_L(n) asm volatile("s_waitcnt lgkmcnt(" #n ")" ::: "memory")
; #define PG8_BAR __builtin_amdgcn_s_barrier()
; #define PG8_SCHED __builtin_amdgcn_sched_barrier(0)
; template <class Epi, bool ALIGN_EPI, class Hook = NoHook>
; __device__ __forceinline__ void gemm_phase(LAS unsigned char* lds, const Gemm g, const StaticOrder& S, const Epi& E, const Hook& HK = Hook()) {
;     ...
;         const bool has_next = S.next(ui + 1, nxt);
;         const char* nA = has_next ? (const char*)g.A + (size_t)nxt.pm * tstepA : cA; const char* nB = has_next ? (const char*)g.Bt + (size_t)nxt.pn * tstepB : cB;
;         for (int t = 0; t < nt; t += 2) {
;             if (Hook::AT > 0 && t == Hook::AT) HK(acc, cur, wr, wc, fr, fq);
;             const bool last = (t == nt - 2);
;             const char* a1 = cA + (size_t)(t + 1) * kstep;
;             const char* a2 = last ? nA : cA + (size_t)(t + 2) * kstep; const char* b2 = last ? nB : cB + (size_t)(t + 2) * kstep;
;             const char* a3 = a2 + kstep; const char* b3 = b2 + kstep;
;             PG8_LDB(B0, 0, 0); PG8_LDB(B1, 0, 1); PG8_SCHED; PG8_LDA(At, 0, 0); PG8_STAGE(PG8_SA(1, 1), a1 + hstepA, voffA);
;             PG8_WAIT_V(8); PG8_WAIT_L(0); PG8_BAR; PG8_MMA(0, 0, At, B0); PG8_MMA(0, 1, At, B1); PG8_BAR; PG8_SCHED;
;             PG8_LDA(At, 0, 1); PG8_STAGE(PG8_SB(0, 0), b2, voffB); PG8_STAGE(PG8_SB(0, 1), b2 + hstepB, voffB); PG8_STAGE(PG8_SA(0, 0), a2, voffA);
;             PG8_WAIT_V(8); PG8_WAIT_L(0); PG8_BAR; PG8_MMA(1, 0, At, B0); PG8_MMA(1, 1, At, B1); PG8_BAR; PG8_SCHED;
.LBB0_998:
	s_add_u32 s41, s16, 0x100
	s_addc_u32 s42, s17, 0
	s_mov_b32 s43, -2
	ds_read_b128 v[144:147], v153
	ds_read_b128 v[156:159], v153 offset:1024
	ds_read_b128 v[160:163], v153 offset:2048
	ds_read_b128 v[164:167], v153 offset:3072
	ds_read_b128 v[168:171], v154
	ds_read_b128 v[172:175], v154 offset:1024
	ds_read_b128 v[176:179], v154 offset:2048
	ds_read_b128 v[180:183], v154 offset:3072
	s_add_u32 s16, s14, 0x100
	s_addc_u32 s17, s15, 0
	s_cmpk_eq_i32 s43, 0x54
	s_cselect_b32 s21, s5, s17
	s_cselect_b32 s20, s4, s16
	s_cselect_b32 s19, s13, s42
	s_cselect_b32 s18, s12, s41
	v_lshl_add_u64 v[148:149], s[14:15], 0, v[136:137]
	s_add_i32 m0, s23, 0xc000
	ds_read_b128 v[184:187], v155
	ds_read_b128 v[188:191], v155 offset:1024
	ds_read_b128 v[192:195], v155 offset:2048
	ds_read_b128 v[196:199], v155 offset:3072
	ds_read_b128 v[200:203], v155 offset:4096
	ds_read_b128 v[204:207], v155 offset:5120
	ds_read_b128 v[208:211], v155 offset:6144
	ds_read_b128 v[212:215], v155 offset:7168
	global_load_lds_dwordx4 v[148:149], off
	v_lshl_add_u64 v[148:149], s[14:15], 0, v[138:139]
	s_add_i32 m0, s23, 0xe000
	s_nop 0
	global_load_lds_dwordx4 v[148:149], off
	s_waitcnt vmcnt(8)
	s_waitcnt lgkmcnt(0)
	s_barrier
	s_waitcnt lgkmcnt(0)
	v_mfma_f32_16x16x32_bf16 v[124:127], v[144:147], v[184:187], 0
	v_mfma_f32_16x16x32_bf16 v[120:123], v[160:163], v[184:187], 0
	v_mfma_f32_16x16x32_bf16 v[112:115], v[144:147], v[192:195], 0
	v_mfma_f32_16x16x32_bf16 v[104:107], v[160:163], v[192:195], 0
	v_mfma_f32_16x16x32_bf16 v[96:99], v[144:147], v[200:203], 0
	v_mfma_f32_16x16x32_bf16 v[88:91], v[160:163], v[200:203], 0
	v_mfma_f32_16x16x32_bf16 v[80:83], v[144:147], v[208:211], 0
	v_mfma_f32_16x16x32_bf16 v[72:75], v[160:163], v[208:211], 0
	v_mfma_f32_16x16x32_bf16 v[124:127], v[156:159], v[188:191], v[124:127]
	v_mfma_f32_16x16x32_bf16 v[120:123], v[164:167], v[188:191], v[120:123]
	v_mfma_f32_16x16x32_bf16 v[112:115], v[156:159], v[196:199], v[112:115]
	v_mfma_f32_16x16x32_bf16 v[104:107], v[164:167], v[196:199], v[104:107]
	v_mfma_f32_16x16x32_bf16 v[96:99], v[156:159], v[204:207], v[96:99]
	v_mfma_f32_16x16x32_bf16 v[88:91], v[164:167], v[204:207], v[88:91]
	v_mfma_f32_16x16x32_bf16 v[80:83], v[156:159], v[212:215], v[80:83]
	v_mfma_f32_16x16x32_bf16 v[72:75], v[164:167], v[212:215], v[72:75]
	v_mfma_f32_16x16x32_bf16 v[116:119], v[168:171], v[184:187], 0
	v_mfma_f32_16x16x32_bf16 v[108:111], v[176:179], v[184:187], 0
	v_mfma_f32_16x16x32_bf16 v[100:103], v[168:171], v[192:195], 0
	v_mfma_f32_16x16x32_bf16 v[92:95], v[176:179], v[192:195], 0
	v_mfma_f32_16x16x32_bf16 v[84:87], v[168:171], v[200:203], 0
	v_mfma_f32_16x16x32_bf16 v[76:79], v[176:179], v[200:203], 0
	v_mfma_f32_16x16x32_bf16 v[68:71], v[168:171], v[208:211], 0
	v_mfma_f32_16x16x32_bf16 v[64:67], v[176:179], v[208:211], 0
	v_mfma_f32_16x16x32_bf16 v[116:119], v[172:175], v[188:191], v[116:119]
	v_mfma_f32_16x16x32_bf16 v[108:111], v[180:183], v[188:191], v[108:111]
	v_mfma_f32_16x16x32_bf16 v[100:103], v[172:175], v[196:199], v[100:103]
	v_mfma_f32_16x16x32_bf16 v[92:95], v[180:183], v[196:199], v[92:95]
	v_mfma_f32_16x16x32_bf16 v[84:87], v[172:175], v[204:207], v[84:87]
	v_mfma_f32_16x16x32_bf16 v[76:79], v[180:183], v[204:207], v[76:79]
	v_mfma_f32_16x16x32_bf16 v[68:71], v[172:175], v[212:215], v[68:71]
	v_mfma_f32_16x16x32_bf16 v[64:67], v[180:183], v[212:215], v[64:67]
	s_barrier
	s_add_i32 s14, s33, s22
	v_lshl_add_u64 v[148:149], s[18:19], 0, v[130:131]
	s_mov_b32 m0, s14
	ds_read_b128 v[184:187], v155 offset:16384
	ds_read_b128 v[188:191], v155 offset:17408
	ds_read_b128 v[192:195], v155 offset:18432
	ds_read_b128 v[196:199], v155 offset:19456
	ds_read_b128 v[200:203], v155 offset:20480
	ds_read_b128 v[204:207], v155 offset:21504
	ds_read_b128 v[208:211], v155 offset:22528
	ds_read_b128 v[212:215], v155 offset:23552
	global_load_lds_dwordx4 v[148:149], off
	s_add_i32 m0, s14, 0x2000
	s_add_u32 s14, s18, 0x160000
	v_lshl_add_u64 v[216:217], s[18:19], 0, v[134:135]
	s_addc_u32 s15, s19, 0
	s_add_i32 s34, s36, s22
	global_load_lds_dwordx4 v[216:217], off
	v_lshl_add_u64 v[218:219], s[14:15], 0, v[130:131]
	s_mov_b32 m0, s34
	v_lshl_add_u64 v[220:221], s[20:21], 0, v[132:133]
	global_load_lds_dwordx4 v[218:219], off
	v_lshl_add_u64 v[218:219], s[14:15], 0, v[134:135]
	s_add_i32 m0, s34, 0x2000
	s_nop 0
	global_load_lds_dwordx4 v[218:219], off
	v_lshl_add_u64 v[218:219], s[20:21], 0, v[128:129]
	s_mov_b32 m0, s23
	s_nop 0
	global_load_lds_dwordx4 v[218:219], off
	s_mov_b32 m0, s24
	s_nop 0
	global_load_lds_dwordx4 v[220:221], off
	s_waitcnt vmcnt(8)
	s_waitcnt lgkmcnt(0)
	s_barrier
; #define PG8_STAGE(bufoff, gbase, voff) do { _Pragma("unroll") for (int _i = 0; _i < 2; ++_i) \
;         __builtin_amdgcn_global_load_lds((const unsigned*)((const char*)(gbase) + (voff)[_i]), (LAS unsigned*)(lds + (bufoff) + ldsw + _i * 8192), 16, 0, 0); } while (0)
; #define PG8_LDA(dst, b, h) do { _Pragma("unroll") for (int m = 0; m < 4; ++m) _Pragma("unroll") for (int k = 0; k < 2; ++k) dst[m][k] = *(const LAS bf16x8*)(lds + PG8_SA(b, h) + aoff + m * 2048 + k * 1024); } while (0)
; #define PG8_LDB(dst, b, h) do { _Pragma("unroll") for (int n = 0; n < 2; ++n) _Pragma("unroll") for (int k = 0; k < 2; ++k) dst[n][k] = *(const LAS bf16x8*)(lds + PG8_SB(b, h) + boff + n * 2048 + k * 1024); } while (0)
; #define PG8_MMA(ai, bj, At, Bt) do { __builtin_amdgcn_s_setprio(1); _Pragma("unroll") for (int m = 0; m < 4; ++m) _Pragma("unroll") for (int n = 0; n < 2; ++n) _Pragma("unroll") for (int k = 0; k < 2; ++k) \
;         acc[ai][bj][m][n] = __builtin_amdgcn_mfma_f32_16x16x32_bf16(Bt[n][k], At[m][k], acc[ai][bj][m][n], 0, 0, 0); __builtin_amdgcn_s_setprio(0); } while (0)
; #define PG8_WAIT_V(n) asm volatile("s_waitcnt vmcnt(" #n ")" ::: "memory")
; #define PG8_WAIT_L(n) asm volatile("s_waitcnt lgkmcnt(" #n ")" ::: "memory")
; #define PG8_BAR __builtin_amdgcn_s_barrier()
; #define PG8_SCHED __builtin_amdgcn_sched_barrier(0)
; template <class Epi, bool ALIGN_EPI, class Hook = NoHook>
; __device__ __forceinline__ void gemm_phase(LAS unsigned char* lds, const Gemm g, const StaticOrder& S, const Epi& E, const Hook& HK = Hook()) {
;     ...
;             PG8_WAIT_V(8); PG8_WAIT_L(0); PG8_BAR; PG8_MMA(1, 0, At, B0); PG8_MMA(1, 1, At, B1); PG8_BAR; PG8_SCHED;
;             PG8_LDB(B0, 1, 0); PG8_LDB(B1, 1, 1); PG8_SCHED; PG8_LDA(At, 1, 0); PG8_STAGE(PG8_SA(0, 1), a2 + hstepA, voffA);
;             PG8_WAIT_V(8); PG8_WAIT_L(0); PG8_BAR; PG8_MMA(0, 0, At, B0); PG8_MMA(0, 1, At, B1); PG8_BAR; PG8_SCHED;
	s_waitcnt lgkmcnt(0)
	v_mfma_f32_16x16x32_bf16 v[60:63], v[144:147], v[184:187], 0
	v_mfma_f32_16x16x32_bf16 v[56:59], v[160:163], v[184:187], 0
	v_mfma_f32_16x16x32_bf16 v[48:51], v[144:147], v[192:195], 0
	v_mfma_f32_16x16x32_bf16 v[40:43], v[160:163], v[192:195], 0
	v_mfma_f32_16x16x32_bf16 v[32:35], v[144:147], v[200:203], 0
	v_mfma_f32_16x16x32_bf16 v[24:27], v[160:163], v[200:203], 0
	v_mfma_f32_16x16x32_bf16 v[16:19], v[144:147], v[208:211], 0
	v_mfma_f32_16x16x32_bf16 v[8:11], v[160:163], v[208:211], 0
	v_mfma_f32_16x16x32_bf16 v[60:63], v[156:159], v[188:191], v[60:63]
	v_mfma_f32_16x16x32_bf16 v[56:59], v[164:167], v[188:191], v[56:59]
	v_mfma_f32_16x16x32_bf16 v[48:51], v[156:159], v[196:199], v[48:51]
	v_mfma_f32_16x16x32_bf16 v[40:43], v[164:167], v[196:199], v[40:43]
	v_mfma_f32_16x16x32_bf16 v[32:35], v[156:159], v[204:207], v[32:35]
	v_mfma_f32_16x16x32_bf16 v[24:27], v[164:167], v[204:207], v[24:27]
	v_mfma_f32_16x16x32_bf16 v[16:19], v[156:159], v[212:215], v[16:19]
	v_mfma_f32_16x16x32_bf16 v[8:11], v[164:167], v[212:215], v[8:11]
	v_mfma_f32_16x16x32_bf16 v[52:55], v[168:171], v[184:187], 0
	v_mfma_f32_16x16x32_bf16 v[44:47], v[176:179], v[184:187], 0
	v_mfma_f32_16x16x32_bf16 v[36:39], v[168:171], v[192:195], 0
	v_mfma_f32_16x16x32_bf16 v[28:31], v[176:179], v[192:195], 0
	v_mfma_f32_16x16x32_bf16 v[20:23], v[168:171], v[200:203], 0
	v_mfma_f32_16x16x32_bf16 v[12:15], v[176:179], v[200:203], 0
	v_mfma_f32_16x16x32_bf16 v[4:7], v[168:171], v[208:211], 0
	v_mfma_f32_16x16x32_bf16 v[0:3], v[176:179], v[208:211], 0
	v_mfma_f32_16x16x32_bf16 v[52:55], v[172:175], v[188:191], v[52:55]
	v_mfma_f32_16x16x32_bf16 v[44:47], v[180:183], v[188:191], v[44:47]
	v_mfma_f32_16x16x32_bf16 v[36:39], v[172:175], v[196:199], v[36:39]
	v_mfma_f32_16x16x32_bf16 v[28:31], v[180:183], v[196:199], v[28:31]
	v_mfma_f32_16x16x32_bf16 v[20:23], v[172:175], v[204:207], v[20:23]
	v_mfma_f32_16x16x32_bf16 v[12:15], v[180:183], v[204:207], v[12:15]
	v_mfma_f32_16x16x32_bf16 v[4:7], v[172:175], v[212:215], v[4:7]
	v_mfma_f32_16x16x32_bf16 v[0:3], v[180:183], v[212:215], v[0:3]
	s_barrier
	s_add_i32 s34, 0, 0x18000
	s_add_i32 s35, 0, 0x1c000
	v_add_u32_e32 v164, s34, v151
	v_add_u32_e32 v180, s35, v151
	ds_read_b128 v[144:147], v164
	ds_read_b128 v[156:159], v164 offset:1024
	ds_read_b128 v[160:163], v164 offset:2048
	ds_read_b128 v[164:167], v164 offset:3072
	ds_read_b128 v[168:171], v180
	ds_read_b128 v[172:175], v180 offset:1024
	ds_read_b128 v[176:179], v180 offset:2048
	ds_read_b128 v[180:183], v180 offset:3072
	s_add_u32 s14, s20, 0x160000
	s_addc_u32 s15, s21, 0
	s_mov_b32 m0, s25
	v_lshl_add_u64 v[222:223], s[14:15], 0, v[128:129]
	ds_read_b128 v[184:187], v155 offset:32768
	ds_read_b128 v[188:191], v155 offset:33792
	ds_read_b128 v[192:195], v155 offset:34816
	ds_read_b128 v[196:199], v155 offset:35840
	ds_read_b128 v[200:203], v155 offset:36864
	ds_read_b128 v[204:207], v155 offset:37888
	ds_read_b128 v[208:211], v155 offset:38912
	ds_read_b128 v[212:215], v155 offset:39936
	global_load_lds_dwordx4 v[222:223], off
	v_lshl_add_u64 v[222:223], s[14:15], 0, v[132:133]
	s_mov_b32 m0, s26
	s_nop 0
	global_load_lds_dwordx4 v[222:223], off
	s_waitcnt vmcnt(8)
	s_waitcnt lgkmcnt(0)
	s_barrier
	s_waitcnt lgkmcnt(0)
	v_mfma_f32_16x16x32_bf16 v[124:127], v[144:147], v[184:187], v[124:127]
	v_mfma_f32_16x16x32_bf16 v[120:123], v[160:163], v[184:187], v[120:123]
	v_mfma_f32_16x16x32_bf16 v[112:115], v[144:147], v[192:195], v[112:115]
	v_mfma_f32_16x16x32_bf16 v[104:107], v[160:163], v[192:195], v[104:107]
	v_mfma_f32_16x16x32_bf16 v[96:99], v[144:147], v[200:203], v[96:99]
	v_mfma_f32_16x16x32_bf16 v[88:91], v[160:163], v[200:203], v[88:91]
	v_mfma_f32_16x16x32_bf16 v[80:83], v[144:147], v[208:211], v[80:83]
	v_mfma_f32_16x16x32_bf16 v[72:75], v[160:163], v[208:211], v[72:75]
	v_mfma_f32_16x16x32_bf16 v[124:127], v[156:159], v[188:191], v[124:127]
	v_mfma_f32_16x16x32_bf16 v[120:123], v[164:167], v[188:191], v[120:123]
	v_mfma_f32_16x16x32_bf16 v[112:115], v[156:159], v[196:199], v[112:115]
	v_mfma_f32_16x16x32_bf16 v[104:107], v[164:167], v[196:199], v[104:107]
	v_mfma_f32_16x16x32_bf16 v[96:99], v[156:159], v[204:207], v[96:99]
	v_mfma_f32_16x16x32_bf16 v[88:91], v[164:167], v[204:207], v[88:91]
	v_mfma_f32_16x16x32_bf16 v[80:83], v[156:159], v[212:215], v[80:83]
	v_mfma_f32_16x16x32_bf16 v[72:75], v[164:167], v[212:215], v[72:75]
	v_mfma_f32_16x16x32_bf16 v[116:119], v[168:171], v[184:187], v[116:119]
	v_mfma_f32_16x16x32_bf16 v[108:111], v[176:179], v[184:187], v[108:111]
	v_mfma_f32_16x16x32_bf16 v[100:103], v[168:171], v[192:195], v[100:103]
	v_mfma_f32_16x16x32_bf16 v[92:95], v[176:179], v[192:195], v[92:95]
	v_mfma_f32_16x16x32_bf16 v[84:87], v[168:171], v[200:203], v[84:87]
	v_mfma_f32_16x16x32_bf16 v[76:79], v[176:179], v[200:203], v[76:79]
	v_mfma_f32_16x16x32_bf16 v[68:71], v[168:171], v[208:211], v[68:71]
	v_mfma_f32_16x16x32_bf16 v[64:67], v[176:179], v[208:211], v[64:67]
	v_mfma_f32_16x16x32_bf16 v[116:119], v[172:175], v[188:191], v[116:119]
	v_mfma_f32_16x16x32_bf16 v[108:111], v[180:183], v[188:191], v[108:111]
	v_mfma_f32_16x16x32_bf16 v[100:103], v[172:175], v[196:199], v[100:103]
	v_mfma_f32_16x16x32_bf16 v[92:95], v[180:183], v[196:199], v[92:95]
	v_mfma_f32_16x16x32_bf16 v[84:87], v[172:175], v[204:207], v[84:87]
	v_mfma_f32_16x16x32_bf16 v[76:79], v[180:183], v[204:207], v[76:79]
	v_mfma_f32_16x16x32_bf16 v[68:71], v[172:175], v[212:215], v[68:71]
	v_mfma_f32_16x16x32_bf16 v[64:67], v[180:183], v[212:215], v[64:67]
	s_barrier
; #define PG8_STAGE(bufoff, gbase, voff) do { _Pragma("unroll") for (int _i = 0; _i < 2; ++_i) \
;         __builtin_amdgcn_global_load_lds((const unsigned*)((const char*)(gbase) + (voff)[_i]), (LAS unsigned*)(lds + (bufoff) + ldsw + _i * 8192), 16, 0, 0); } while (0)
; #define PG8_LDA(dst, b, h) do { _Pragma("unroll") for (int m = 0; m < 4; ++m) _Pragma("unroll") for (int k = 0; k < 2; ++k) dst[m][k] = *(const LAS bf16x8*)(lds + PG8_SA(b, h) + aoff + m * 2048 + k * 1024); } while (0)
; #define PG8_LDB(dst, b, h) do { _Pragma("unroll") for (int n = 0; n < 2; ++n) _Pragma("unroll") for (int k = 0; k < 2; ++k) dst[n][k] = *(const LAS bf16x8*)(lds + PG8_SB(b, h) + boff + n * 2048 + k * 1024); } while (0)
; #define PG8_MMA(ai, bj, At, Bt) do { __builtin_amdgcn_s_setprio(1); _Pragma("unroll") for (int m = 0; m < 4; ++m) _Pragma("unroll") for (int n = 0; n < 2; ++n) _Pragma("unroll") for (int k = 0; k < 2; ++k) \
;         acc[ai][bj][m][n] = __builtin_amdgcn_mfma_f32_16x16x32_bf16(Bt[n][k], At[m][k], acc[ai][bj][m][n], 0, 0, 0); __builtin_amdgcn_s_setprio(0); } while (0)
; #define PG8_WAIT_V(n) asm volatile("s_waitcnt vmcnt(" #n ")" ::: "memory")
; #define PG8_WAIT_L(n) asm volatile("s_waitcnt lgkmcnt(" #n ")" ::: "memory")
; #define PG8_BAR __builtin_amdgcn_s_barrier()
; #define PG8_SCHED __builtin_amdgcn_sched_barrier(0)
; template <class Epi, bool ALIGN_EPI, class Hook = NoHook>
; __device__ __forceinline__ void gemm_phase(LAS unsigned char* lds, const Gemm g, const StaticOrder& S, const Epi& E, const Hook& HK = Hook()) {
;     ...
;             PG8_LDB(B0, 0, 0); PG8_LDB(B1, 0, 1); PG8_SCHED; PG8_LDA(At, 0, 0); PG8_STAGE(PG8_SA(1, 1), a1 + hstepA, voffA);
;             PG8_WAIT_V(8); PG8_WAIT_L(0); PG8_BAR; PG8_MMA(0, 0, At, B0); PG8_MMA(0, 1, At, B1); PG8_BAR; PG8_SCHED;
;     ...
;             PG8_LDA(At, 1, 1); PG8_STAGE(PG8_SB(1, 0), b3, voffB); PG8_STAGE(PG8_SB(1, 1), b3 + hstepB, voffB); PG8_STAGE(PG8_SA(1, 0), a3, voffA);
;             PG8_WAIT_V(8); PG8_WAIT_L(0); PG8_BAR; PG8_MMA(1, 0, At, B0); PG8_MMA(1, 1, At, B1); PG8_BAR; PG8_SCHED;
	s_add_i32 s14, s34, s22
	v_lshl_add_u64 v[148:149], v[148:149], 0, s[8:9]
	s_mov_b32 m0, s14
	ds_read_b128 v[184:187], v155 offset:49152
	ds_read_b128 v[188:191], v155 offset:50176
	ds_read_b128 v[192:195], v155 offset:51200
	ds_read_b128 v[196:199], v155 offset:52224
	ds_read_b128 v[200:203], v155 offset:53248
	ds_read_b128 v[204:207], v155 offset:54272
	ds_read_b128 v[208:211], v155 offset:55296
	ds_read_b128 v[212:215], v155 offset:56320
	global_load_lds_dwordx4 v[148:149], off
	s_add_i32 m0, s14, 0x2000
	s_add_u32 s14, s18, 0x160080
	v_lshl_add_u64 v[148:149], v[216:217], 0, s[8:9]
	s_addc_u32 s15, s19, 0
	s_add_i32 s18, s35, s22
	global_load_lds_dwordx4 v[148:149], off
	v_lshl_add_u64 v[148:149], s[14:15], 0, v[130:131]
	s_mov_b32 m0, s18
	s_nop 0
	global_load_lds_dwordx4 v[148:149], off
	v_lshl_add_u64 v[148:149], s[14:15], 0, v[134:135]
	s_add_i32 m0, s18, 0x2000
	s_nop 0
	global_load_lds_dwordx4 v[148:149], off
	v_lshl_add_u64 v[148:149], v[218:219], 0, s[8:9]
	s_mov_b32 m0, s28
	s_nop 0
	global_load_lds_dwordx4 v[148:149], off
	v_lshl_add_u64 v[148:149], v[220:221], 0, s[8:9]
	s_mov_b32 m0, s29
	s_nop 0
	global_load_lds_dwordx4 v[148:149], off
	s_waitcnt vmcnt(8)
	s_waitcnt lgkmcnt(0)
	s_barrier
	s_waitcnt lgkmcnt(0)
	v_mfma_f32_16x16x32_bf16 v[60:63], v[144:147], v[184:187], v[60:63]
	v_mfma_f32_16x16x32_bf16 v[56:59], v[160:163], v[184:187], v[56:59]
	v_mfma_f32_16x16x32_bf16 v[48:51], v[144:147], v[192:195], v[48:51]
	v_mfma_f32_16x16x32_bf16 v[40:43], v[160:163], v[192:195], v[40:43]
	v_mfma_f32_16x16x32_bf16 v[32:35], v[144:147], v[200:203], v[32:35]
	v_mfma_f32_16x16x32_bf16 v[24:27], v[160:163], v[200:203], v[24:27]
	v_mfma_f32_16x16x32_bf16 v[16:19], v[144:147], v[208:211], v[16:19]
	v_mfma_f32_16x16x32_bf16 v[8:11], v[160:163], v[208:211], v[8:11]
	v_mfma_f32_16x16x32_bf16 v[60:63], v[156:159], v[188:191], v[60:63]
	v_mfma_f32_16x16x32_bf16 v[56:59], v[164:167], v[188:191], v[56:59]
	v_mfma_f32_16x16x32_bf16 v[48:51], v[156:159], v[196:199], v[48:51]
	v_mfma_f32_16x16x32_bf16 v[40:43], v[164:167], v[196:199], v[40:43]
	v_mfma_f32_16x16x32_bf16 v[32:35], v[156:159], v[204:207], v[32:35]
	v_mfma_f32_16x16x32_bf16 v[24:27], v[164:167], v[204:207], v[24:27]
	v_mfma_f32_16x16x32_bf16 v[16:19], v[156:159], v[212:215], v[16:19]
	v_mfma_f32_16x16x32_bf16 v[8:11], v[164:167], v[212:215], v[8:11]
	v_mfma_f32_16x16x32_bf16 v[52:55], v[168:171], v[184:187], v[52:55]
	v_mfma_f32_16x16x32_bf16 v[44:47], v[176:179], v[184:187], v[44:47]
	v_mfma_f32_16x16x32_bf16 v[36:39], v[168:171], v[192:195], v[36:39]
	v_mfma_f32_16x16x32_bf16 v[28:31], v[176:179], v[192:195], v[28:31]
	v_mfma_f32_16x16x32_bf16 v[20:23], v[168:171], v[200:203], v[20:23]
	v_mfma_f32_16x16x32_bf16 v[12:15], v[176:179], v[200:203], v[12:15]
	v_mfma_f32_16x16x32_bf16 v[4:7], v[168:171], v[208:211], v[4:7]
	v_mfma_f32_16x16x32_bf16 v[0:3], v[176:179], v[208:211], v[0:3]
	v_mfma_f32_16x16x32_bf16 v[52:55], v[172:175], v[188:191], v[52:55]
	v_mfma_f32_16x16x32_bf16 v[44:47], v[180:183], v[188:191], v[44:47]
	v_mfma_f32_16x16x32_bf16 v[36:39], v[172:175], v[196:199], v[36:39]
	v_mfma_f32_16x16x32_bf16 v[28:31], v[180:183], v[196:199], v[28:31]
	v_mfma_f32_16x16x32_bf16 v[20:23], v[172:175], v[204:207], v[20:23]
	v_mfma_f32_16x16x32_bf16 v[12:15], v[180:183], v[204:207], v[12:15]
	v_mfma_f32_16x16x32_bf16 v[4:7], v[172:175], v[212:215], v[4:7]
	v_mfma_f32_16x16x32_bf16 v[0:3], v[180:183], v[212:215], v[0:3]
	s_barrier
	s_add_i32 s43, s43, 2
	s_add_u32 s41, s41, 0x100
	s_addc_u32 s42, s42, 0
	s_cmpk_gt_u32 s43, 0x55
	s_mov_b64 s[14:15], s[16:17]
.LBB0_999:
	ds_read_b128 v[144:147], v153
	ds_read_b128 v[156:159], v153 offset:1024
	ds_read_b128 v[160:163], v153 offset:2048
	ds_read_b128 v[164:167], v153 offset:3072
	ds_read_b128 v[168:171], v154
	ds_read_b128 v[172:175], v154 offset:1024
	ds_read_b128 v[176:179], v154 offset:2048
	ds_read_b128 v[180:183], v154 offset:3072
	s_add_u32 s16, s14, 0x100
	s_addc_u32 s17, s15, 0
	s_cmpk_eq_i32 s43, 0x54
	s_cselect_b32 s21, s5, s17
	s_cselect_b32 s20, s4, s16
	s_cselect_b32 s19, s13, s42
	s_cselect_b32 s18, s12, s41
	v_lshl_add_u64 v[148:149], s[14:15], 0, v[136:137]
	s_add_i32 m0, s23, 0xc000
	ds_read_b128 v[184:187], v155
	ds_read_b128 v[188:191], v155 offset:1024
	ds_read_b128 v[192:195], v155 offset:2048
	ds_read_b128 v[196:199], v155 offset:3072
	ds_read_b128 v[200:203], v155 offset:4096
	ds_read_b128 v[204:207], v155 offset:5120
	ds_read_b128 v[208:211], v155 offset:6144
	ds_read_b128 v[212:215], v155 offset:7168
	global_load_lds_dwordx4 v[148:149], off
	v_lshl_add_u64 v[148:149], s[14:15], 0, v[138:139]
	s_add_i32 m0, s23, 0xe000
	s_nop 0
	global_load_lds_dwordx4 v[148:149], off
	s_waitcnt vmcnt(8)
	s_waitcnt lgkmcnt(0)
	s_barrier
; #define PG8_STAGE(bufoff, gbase, voff) do { _Pragma("unroll") for (int _i = 0; _i < 2; ++_i) \
;         __builtin_amdgcn_global_load_lds((const unsigned*)((const char*)(gbase) + (voff)[_i]), (LAS unsigned*)(lds + (bufoff) + ldsw + _i * 8192), 16, 0, 0); } while (0)
; #define PG8_LDA(dst, b, h) do { _Pragma("unroll") for (int m = 0; m < 4; ++m) _Pragma("unroll") for (int k = 0; k < 2; ++k) dst[m][k] = *(const LAS bf16x8*)(lds + PG8_SA(b, h) + aoff + m * 2048 + k * 1024); } while (0)
; #define PG8_LDB(dst, b, h) do { _Pragma("unroll") for (int n = 0; n < 2; ++n) _Pragma("unroll") for (int k = 0; k < 2; ++k) dst[n][k] = *(const LAS bf16x8*)(lds + PG8_SB(b, h) + boff + n * 2048 + k * 1024); } while (0)
; #define PG8_MMA(ai, bj, At, Bt) do { __builtin_amdgcn_s_setprio(1); _Pragma("unroll") for (int m = 0; m < 4; ++m) _Pragma("unroll") for (int n = 0; n < 2; ++n) _Pragma("unroll") for (int k = 0; k < 2; ++k) \
;         acc[ai][bj][m][n] = __builtin_amdgcn_mfma_f32_16x16x32_bf16(Bt[n][k], At[m][k], acc[ai][bj][m][n], 0, 0, 0); __builtin_amdgcn_s_setprio(0); } while (0)
; #define PG8_WAIT_V(n) asm volatile("s_waitcnt vmcnt(" #n ")" ::: "memory")
; #define PG8_WAIT_L(n) asm volatile("s_waitcnt lgkmcnt(" #n ")" ::: "memory")
; #define PG8_BAR __builtin_amdgcn_s_barrier()
; #define PG8_SCHED __builtin_amdgcn_sched_barrier(0)
; template <class Epi, bool ALIGN_EPI, class Hook = NoHook>
; __device__ __forceinline__ void gemm_phase(LAS unsigned char* lds, const Gemm g, const StaticOrder& S, const Epi& E, const Hook& HK = Hook()) {
;     ...
;             PG8_LDB(B0, 0, 0); PG8_LDB(B1, 0, 1); PG8_SCHED; PG8_LDA(At, 0, 0); PG8_STAGE(PG8_SA(1, 1), a1 + hstepA, voffA);
;             PG8_WAIT_V(8); PG8_WAIT_L(0); PG8_BAR; PG8_MMA(0, 0, At, B0); PG8_MMA(0, 1, At, B1); PG8_BAR; PG8_SCHED;
;             PG8_LDA(At, 0, 1); PG8_STAGE(PG8_SB(0, 0), b2, voffB); PG8_STAGE(PG8_SB(0, 1), b2 + hstepB, voffB); PG8_STAGE(PG8_SA(0, 0), a2, voffA);
;             PG8_WAIT_V(8); PG8_WAIT_L(0); PG8_BAR; PG8_MMA(1, 0, At, B0); PG8_MMA(1, 1, At, B1); PG8_BAR; PG8_SCHED;
;             PG8_LDB(B0, 1, 0); PG8_LDB(B1, 1, 1); PG8_SCHED; PG8_LDA(At, 1, 0); PG8_STAGE(PG8_SA(0, 1), a2 + hstepA, voffA);
	s_waitcnt lgkmcnt(0)
	v_mfma_f32_16x16x32_bf16 v[124:127], v[144:147], v[184:187], v[124:127]
	v_mfma_f32_16x16x32_bf16 v[120:123], v[160:163], v[184:187], v[120:123]
	v_mfma_f32_16x16x32_bf16 v[112:115], v[144:147], v[192:195], v[112:115]
	v_mfma_f32_16x16x32_bf16 v[104:107], v[160:163], v[192:195], v[104:107]
	v_mfma_f32_16x16x32_bf16 v[96:99], v[144:147], v[200:203], v[96:99]
	v_mfma_f32_16x16x32_bf16 v[88:91], v[160:163], v[200:203], v[88:91]
	v_mfma_f32_16x16x32_bf16 v[80:83], v[144:147], v[208:211], v[80:83]
	v_mfma_f32_16x16x32_bf16 v[72:75], v[160:163], v[208:211], v[72:75]
	v_mfma_f32_16x16x32_bf16 v[124:127], v[156:159], v[188:191], v[124:127]
	v_mfma_f32_16x16x32_bf16 v[120:123], v[164:167], v[188:191], v[120:123]
	v_mfma_f32_16x16x32_bf16 v[112:115], v[156:159], v[196:199], v[112:115]
	v_mfma_f32_16x16x32_bf16 v[104:107], v[164:167], v[196:199], v[104:107]
	v_mfma_f32_16x16x32_bf16 v[96:99], v[156:159], v[204:207], v[96:99]
	v_mfma_f32_16x16x32_bf16 v[88:91], v[164:167], v[204:207], v[88:91]
	v_mfma_f32_16x16x32_bf16 v[80:83], v[156:159], v[212:215], v[80:83]
	v_mfma_f32_16x16x32_bf16 v[72:75], v[164:167], v[212:215], v[72:75]
	v_mfma_f32_16x16x32_bf16 v[116:119], v[168:171], v[184:187], v[116:119]
	v_mfma_f32_16x16x32_bf16 v[108:111], v[176:179], v[184:187], v[108:111]
	v_mfma_f32_16x16x32_bf16 v[100:103], v[168:171], v[192:195], v[100:103]
	v_mfma_f32_16x16x32_bf16 v[92:95], v[176:179], v[192:195], v[92:95]
	v_mfma_f32_16x16x32_bf16 v[84:87], v[168:171], v[200:203], v[84:87]
	v_mfma_f32_16x16x32_bf16 v[76:79], v[176:179], v[200:203], v[76:79]
	v_mfma_f32_16x16x32_bf16 v[68:71], v[168:171], v[208:211], v[68:71]
	v_mfma_f32_16x16x32_bf16 v[64:67], v[176:179], v[208:211], v[64:67]
	v_mfma_f32_16x16x32_bf16 v[116:119], v[172:175], v[188:191], v[116:119]
	v_mfma_f32_16x16x32_bf16 v[108:111], v[180:183], v[188:191], v[108:111]
	v_mfma_f32_16x16x32_bf16 v[100:103], v[172:175], v[196:199], v[100:103]
	v_mfma_f32_16x16x32_bf16 v[92:95], v[180:183], v[196:199], v[92:95]
	v_mfma_f32_16x16x32_bf16 v[84:87], v[172:175], v[204:207], v[84:87]
	v_mfma_f32_16x16x32_bf16 v[76:79], v[180:183], v[204:207], v[76:79]
	v_mfma_f32_16x16x32_bf16 v[68:71], v[172:175], v[212:215], v[68:71]
	v_mfma_f32_16x16x32_bf16 v[64:67], v[180:183], v[212:215], v[64:67]
	s_barrier
	s_add_i32 s14, s33, s22
	v_lshl_add_u64 v[148:149], s[18:19], 0, v[130:131]
	s_mov_b32 m0, s14
	ds_read_b128 v[184:187], v155 offset:16384
	ds_read_b128 v[188:191], v155 offset:17408
	ds_read_b128 v[192:195], v155 offset:18432
	ds_read_b128 v[196:199], v155 offset:19456
	ds_read_b128 v[200:203], v155 offset:20480
	ds_read_b128 v[204:207], v155 offset:21504
	ds_read_b128 v[208:211], v155 offset:22528
	ds_read_b128 v[212:215], v155 offset:23552
	global_load_lds_dwordx4 v[148:149], off
	s_add_i32 m0, s14, 0x2000
	s_add_u32 s14, s18, 0x160000
	v_lshl_add_u64 v[216:217], s[18:19], 0, v[134:135]
	s_addc_u32 s15, s19, 0
	s_add_i32 s34, s36, s22
	global_load_lds_dwordx4 v[216:217], off
	v_lshl_add_u64 v[218:219], s[14:15], 0, v[130:131]
	s_mov_b32 m0, s34
	v_lshl_add_u64 v[220:221], s[20:21], 0, v[132:133]
	global_load_lds_dwordx4 v[218:219], off
	v_lshl_add_u64 v[218:219], s[14:15], 0, v[134:135]
	s_add_i32 m0, s34, 0x2000
	s_nop 0
	global_load_lds_dwordx4 v[218:219], off
	v_lshl_add_u64 v[218:219], s[20:21], 0, v[128:129]
	s_mov_b32 m0, s23
	s_nop 0
	global_load_lds_dwordx4 v[218:219], off
	s_mov_b32 m0, s24
	s_nop 0
	global_load_lds_dwordx4 v[220:221], off
	s_waitcnt vmcnt(8)
	s_waitcnt lgkmcnt(0)
	s_barrier
	s_waitcnt lgkmcnt(0)
	v_mfma_f32_16x16x32_bf16 v[60:63], v[144:147], v[184:187], v[60:63]
	v_mfma_f32_16x16x32_bf16 v[56:59], v[160:163], v[184:187], v[56:59]
	v_mfma_f32_16x16x32_bf16 v[48:51], v[144:147], v[192:195], v[48:51]
	v_mfma_f32_16x16x32_bf16 v[40:43], v[160:163], v[192:195], v[40:43]
	v_mfma_f32_16x16x32_bf16 v[32:35], v[144:147], v[200:203], v[32:35]
	v_mfma_f32_16x16x32_bf16 v[24:27], v[160:163], v[200:203], v[24:27]
	v_mfma_f32_16x16x32_bf16 v[16:19], v[144:147], v[208:211], v[16:19]
	v_mfma_f32_16x16x32_bf16 v[8:11], v[160:163], v[208:211], v[8:11]
	v_mfma_f32_16x16x32_bf16 v[60:63], v[156:159], v[188:191], v[60:63]
	v_mfma_f32_16x16x32_bf16 v[56:59], v[164:167], v[188:191], v[56:59]
	v_mfma_f32_16x16x32_bf16 v[48:51], v[156:159], v[196:199], v[48:51]
	v_mfma_f32_16x16x32_bf16 v[40:43], v[164:167], v[196:199], v[40:43]
	v_mfma_f32_16x16x32_bf16 v[32:35], v[156:159], v[204:207], v[32:35]
	v_mfma_f32_16x16x32_bf16 v[24:27], v[164:167], v[204:207], v[24:27]
	v_mfma_f32_16x16x32_bf16 v[16:19], v[156:159], v[212:215], v[16:19]
	v_mfma_f32_16x16x32_bf16 v[8:11], v[164:167], v[212:215], v[8:11]
	v_mfma_f32_16x16x32_bf16 v[52:55], v[168:171], v[184:187], v[52:55]
	v_mfma_f32_16x16x32_bf16 v[44:47], v[176:179], v[184:187], v[44:47]
	v_mfma_f32_16x16x32_bf16 v[36:39], v[168:171], v[192:195], v[36:39]
	v_mfma_f32_16x16x32_bf16 v[28:31], v[176:179], v[192:195], v[28:31]
	v_mfma_f32_16x16x32_bf16 v[20:23], v[168:171], v[200:203], v[20:23]
	v_mfma_f32_16x16x32_bf16 v[12:15], v[176:179], v[200:203], v[12:15]
	v_mfma_f32_16x16x32_bf16 v[4:7], v[168:171], v[208:211], v[4:7]
	v_mfma_f32_16x16x32_bf16 v[0:3], v[176:179], v[208:211], v[0:3]
	v_mfma_f32_16x16x32_bf16 v[52:55], v[172:175], v[188:191], v[52:55]
	v_mfma_f32_16x16x32_bf16 v[44:47], v[180:183], v[188:191], v[44:47]
	v_mfma_f32_16x16x32_bf16 v[36:39], v[172:175], v[196:199], v[36:39]
	v_mfma_f32_16x16x32_bf16 v[28:31], v[180:183], v[196:199], v[28:31]
	v_mfma_f32_16x16x32_bf16 v[20:23], v[172:175], v[204:207], v[20:23]
	v_mfma_f32_16x16x32_bf16 v[12:15], v[180:183], v[204:207], v[12:15]
	v_mfma_f32_16x16x32_bf16 v[4:7], v[172:175], v[212:215], v[4:7]
	v_mfma_f32_16x16x32_bf16 v[0:3], v[180:183], v[212:215], v[0:3]
	s_barrier
; #define PG8_STAGE(bufoff, gbase, voff) do { _Pragma("unroll") for (int _i = 0; _i < 2; ++_i) \
;         __builtin_amdgcn_global_load_lds((const unsigned*)((const char*)(gbase) + (voff)[_i]), (LAS unsigned*)(lds + (bufoff) + ldsw + _i * 8192), 16, 0, 0); } while (0)
; #define PG8_LDA(dst, b, h) do { _Pragma("unroll") for (int m = 0; m < 4; ++m) _Pragma("unroll") for (int k = 0; k < 2; ++k) dst[m][k] = *(const LAS bf16x8*)(lds + PG8_SA(b, h) + aoff + m * 2048 + k * 1024); } while (0)
; #define PG8_LDB(dst, b, h) do { _Pragma("unroll") for (int n = 0; n < 2; ++n) _Pragma("unroll") for (int k = 0; k < 2; ++k) dst[n][k] = *(const LAS bf16x8*)(lds + PG8_SB(b, h) + boff + n * 2048 + k * 1024); } while (0)
; #define PG8_MMA(ai, bj, At, Bt) do { __builtin_amdgcn_s_setprio(1); _Pragma("unroll") for (int m = 0; m < 4; ++m) _Pragma("unroll") for (int n = 0; n < 2; ++n) _Pragma("unroll") for (int k = 0; k < 2; ++k) \
;         acc[ai][bj][m][n] = __builtin_amdgcn_mfma_f32_16x16x32_bf16(Bt[n][k], At[m][k], acc[ai][bj][m][n], 0, 0, 0); __builtin_amdgcn_s_setprio(0); } while (0)
; #define PG8_WAIT_V(n) asm volatile("s_waitcnt vmcnt(" #n ")" ::: "memory")
; #define PG8_WAIT_L(n) asm volatile("s_waitcnt lgkmcnt(" #n ")" ::: "memory")
; #define PG8_BAR __builtin_amdgcn_s_barrier()
; #define PG8_SCHED __builtin_amdgcn_sched_barrier(0)
; template <class Epi, bool ALIGN_EPI, class Hook = NoHook>
; __device__ __forceinline__ void gemm_phase(LAS unsigned char* lds, const Gemm g, const StaticOrder& S, const Epi& E, const Hook& HK = Hook()) {
;     ...
;             PG8_LDB(B0, 1, 0); PG8_LDB(B1, 1, 1); PG8_SCHED; PG8_LDA(At, 1, 0); PG8_STAGE(PG8_SA(0, 1), a2 + hstepA, voffA);
;             PG8_WAIT_V(8); PG8_WAIT_L(0); PG8_BAR; PG8_MMA(0, 0, At, B0); PG8_MMA(0, 1, At, B1); PG8_BAR; PG8_SCHED;
	s_add_i32 s34, 0, 0x18000
	s_add_i32 s35, 0, 0x1c000
	v_add_u32_e32 v164, s34, v151
	v_add_u32_e32 v180, s35, v151
	ds_read_b128 v[144:147], v164
	ds_read_b128 v[156:159], v164 offset:1024
	ds_read_b128 v[160:163], v164 offset:2048
	ds_read_b128 v[164:167], v164 offset:3072
	ds_read_b128 v[168:171], v180
	ds_read_b128 v[172:175], v180 offset:1024
	ds_read_b128 v[176:179], v180 offset:2048
	ds_read_b128 v[180:183], v180 offset:3072
	s_add_u32 s14, s20, 0x160000
	s_addc_u32 s15, s21, 0
	s_mov_b32 m0, s25
	v_lshl_add_u64 v[222:223], s[14:15], 0, v[128:129]
	ds_read_b128 v[184:187], v155 offset:32768
	ds_read_b128 v[188:191], v155 offset:33792
	ds_read_b128 v[192:195], v155 offset:34816
	ds_read_b128 v[196:199], v155 offset:35840
	ds_read_b128 v[200:203], v155 offset:36864
	ds_read_b128 v[204:207], v155 offset:37888
	ds_read_b128 v[208:211], v155 offset:38912
	ds_read_b128 v[212:215], v155 offset:39936
	global_load_lds_dwordx4 v[222:223], off
	v_lshl_add_u64 v[222:223], s[14:15], 0, v[132:133]
	s_mov_b32 m0, s26
	s_nop 0
	global_load_lds_dwordx4 v[222:223], off
	s_waitcnt vmcnt(8)
	s_waitcnt lgkmcnt(0)
	s_barrier
	s_waitcnt lgkmcnt(0)
	v_mfma_f32_16x16x32_bf16 v[124:127], v[144:147], v[184:187], v[124:127]
	v_mfma_f32_16x16x32_bf16 v[120:123], v[160:163], v[184:187], v[120:123]
	v_mfma_f32_16x16x32_bf16 v[112:115], v[144:147], v[192:195], v[112:115]
	v_mfma_f32_16x16x32_bf16 v[104:107], v[160:163], v[192:195], v[104:107]
	v_mfma_f32_16x16x32_bf16 v[96:99], v[144:147], v[200:203], v[96:99]
	v_mfma_f32_16x16x32_bf16 v[88:91], v[160:163], v[200:203], v[88:91]
	v_mfma_f32_16x16x32_bf16 v[80:83], v[144:147], v[208:211], v[80:83]
	v_mfma_f32_16x16x32_bf16 v[72:75], v[160:163], v[208:211], v[72:75]
	v_mfma_f32_16x16x32_bf16 v[124:127], v[156:159], v[188:191], v[124:127]
	v_mfma_f32_16x16x32_bf16 v[120:123], v[164:167], v[188:191], v[120:123]
	v_mfma_f32_16x16x32_bf16 v[112:115], v[156:159], v[196:199], v[112:115]
	v_mfma_f32_16x16x32_bf16 v[104:107], v[164:167], v[196:199], v[104:107]
	v_mfma_f32_16x16x32_bf16 v[96:99], v[156:159], v[204:207], v[96:99]
	v_mfma_f32_16x16x32_bf16 v[88:91], v[164:167], v[204:207], v[88:91]
	v_mfma_f32_16x16x32_bf16 v[80:83], v[156:159], v[212:215], v[80:83]
	v_mfma_f32_16x16x32_bf16 v[72:75], v[164:167], v[212:215], v[72:75]
	v_mfma_f32_16x16x32_bf16 v[116:119], v[168:171], v[184:187], v[116:119]
	v_mfma_f32_16x16x32_bf16 v[108:111], v[176:179], v[184:187], v[108:111]
	v_mfma_f32_16x16x32_bf16 v[100:103], v[168:171], v[192:195], v[100:103]
	v_mfma_f32_16x16x32_bf16 v[92:95], v[176:179], v[192:195], v[92:95]
	v_mfma_f32_16x16x32_bf16 v[84:87], v[168:171], v[200:203], v[84:87]
	v_mfma_f32_16x16x32_bf16 v[76:79], v[176:179], v[200:203], v[76:79]
	v_mfma_f32_16x16x32_bf16 v[68:71], v[168:171], v[208:211], v[68:71]
	v_mfma_f32_16x16x32_bf16 v[64:67], v[176:179], v[208:211], v[64:67]
	v_mfma_f32_16x16x32_bf16 v[116:119], v[172:175], v[188:191], v[116:119]
	v_mfma_f32_16x16x32_bf16 v[108:111], v[180:183], v[188:191], v[108:111]
	v_mfma_f32_16x16x32_bf16 v[100:103], v[172:175], v[196:199], v[100:103]
	v_mfma_f32_16x16x32_bf16 v[92:95], v[180:183], v[196:199], v[92:95]
	v_mfma_f32_16x16x32_bf16 v[84:87], v[172:175], v[204:207], v[84:87]
	v_mfma_f32_16x16x32_bf16 v[76:79], v[180:183], v[204:207], v[76:79]
	v_mfma_f32_16x16x32_bf16 v[68:71], v[172:175], v[212:215], v[68:71]
	v_mfma_f32_16x16x32_bf16 v[64:67], v[180:183], v[212:215], v[64:67]
	s_barrier
; #define PG8_STAGE(bufoff, gbase, voff) do { _Pragma("unroll") for (int _i = 0; _i < 2; ++_i) \
;         __builtin_amdgcn_global_load_lds((const unsigned*)((const char*)(gbase) + (voff)[_i]), (LAS unsigned*)(lds + (bufoff) + ldsw + _i * 8192), 16, 0, 0); } while (0)
; #define PG8_LDA(dst, b, h) do { _Pragma("unroll") for (int m = 0; m < 4; ++m) _Pragma("unroll") for (int k = 0; k < 2; ++k) dst[m][k] = *(const LAS bf16x8*)(lds + PG8_SA(b, h) + aoff + m * 2048 + k * 1024); } while (0)
; #define PG8_MMA(ai, bj, At, Bt) do { __builtin_amdgcn_s_setprio(1); _Pragma("unroll") for (int m = 0; m < 4; ++m) _Pragma("unroll") for (int n = 0; n < 2; ++n) _Pragma("unroll") for (int k = 0; k < 2; ++k) \
;         acc[ai][bj][m][n] = __builtin_amdgcn_mfma_f32_16x16x32_bf16(Bt[n][k], At[m][k], acc[ai][bj][m][n], 0, 0, 0); __builtin_amdgcn_s_setprio(0); } while (0)
; #define PG8_WAIT_V(n) asm volatile("s_waitcnt vmcnt(" #n ")" ::: "memory")
; #define PG8_WAIT_L(n) asm volatile("s_waitcnt lgkmcnt(" #n ")" ::: "memory")
; #define PG8_BAR __builtin_amdgcn_s_barrier()
; #define PG8_SCHED __builtin_amdgcn_sched_barrier(0)
; template <class Epi, bool ALIGN_EPI, class Hook = NoHook>
; __device__ __forceinline__ void gemm_phase(LAS unsigned char* lds, const Gemm g, const StaticOrder& S, const Epi& E, const Hook& HK = Hook()) {
;     ...
;             PG8_LDA(At, 1, 1); PG8_STAGE(PG8_SB(1, 0), b3, voffB); PG8_STAGE(PG8_SB(1, 1), b3 + hstepB, voffB); PG8_STAGE(PG8_SA(1, 0), a3, voffA);
;             PG8_WAIT_V(8); PG8_WAIT_L(0); PG8_BAR; PG8_MMA(1, 0, At, B0); PG8_MMA(1, 1, At, B1); PG8_BAR; PG8_SCHED;
;         }
;         if constexpr (ALIGN_EPI) { if (wr == 0) PG8_BAR; }
	s_add_i32 s14, s34, s22
	v_lshl_add_u64 v[148:149], v[148:149], 0, s[8:9]
	s_mov_b32 m0, s14
	ds_read_b128 v[184:187], v155 offset:49152
	ds_read_b128 v[188:191], v155 offset:50176
	ds_read_b128 v[192:195], v155 offset:51200
	ds_read_b128 v[196:199], v155 offset:52224
	ds_read_b128 v[200:203], v155 offset:53248
	ds_read_b128 v[204:207], v155 offset:54272
	ds_read_b128 v[208:211], v155 offset:55296
	ds_read_b128 v[212:215], v155 offset:56320
	global_load_lds_dwordx4 v[148:149], off
	s_add_i32 m0, s14, 0x2000
	s_add_u32 s14, s18, 0x160080
	v_lshl_add_u64 v[148:149], v[216:217], 0, s[8:9]
	s_addc_u32 s15, s19, 0
	s_add_i32 s18, s35, s22
	global_load_lds_dwordx4 v[148:149], off
	v_lshl_add_u64 v[148:149], s[14:15], 0, v[130:131]
	s_mov_b32 m0, s18
	s_nop 0
	global_load_lds_dwordx4 v[148:149], off
	v_lshl_add_u64 v[148:149], s[14:15], 0, v[134:135]
	s_add_i32 m0, s18, 0x2000
	s_nop 0
	global_load_lds_dwordx4 v[148:149], off
	v_lshl_add_u64 v[148:149], v[218:219], 0, s[8:9]
	s_mov_b32 m0, s28
	s_nop 0
	global_load_lds_dwordx4 v[148:149], off
	v_lshl_add_u64 v[148:149], v[220:221], 0, s[8:9]
	s_mov_b32 m0, s29
	s_nop 0
	global_load_lds_dwordx4 v[148:149], off
	s_waitcnt vmcnt(8)
	s_waitcnt lgkmcnt(0)
	s_barrier
	s_waitcnt lgkmcnt(0)
	v_mfma_f32_16x16x32_bf16 v[60:63], v[144:147], v[184:187], v[60:63]
	v_mfma_f32_16x16x32_bf16 v[56:59], v[160:163], v[184:187], v[56:59]
	v_mfma_f32_16x16x32_bf16 v[48:51], v[144:147], v[192:195], v[48:51]
	v_mfma_f32_16x16x32_bf16 v[40:43], v[160:163], v[192:195], v[40:43]
	v_mfma_f32_16x16x32_bf16 v[32:35], v[144:147], v[200:203], v[32:35]
	v_mfma_f32_16x16x32_bf16 v[24:27], v[160:163], v[200:203], v[24:27]
	v_mfma_f32_16x16x32_bf16 v[16:19], v[144:147], v[208:211], v[16:19]
	v_mfma_f32_16x16x32_bf16 v[8:11], v[160:163], v[208:211], v[8:11]
	v_mfma_f32_16x16x32_bf16 v[60:63], v[156:159], v[188:191], v[60:63]
	v_mfma_f32_16x16x32_bf16 v[56:59], v[164:167], v[188:191], v[56:59]
	v_mfma_f32_16x16x32_bf16 v[48:51], v[156:159], v[196:199], v[48:51]
	v_mfma_f32_16x16x32_bf16 v[40:43], v[164:167], v[196:199], v[40:43]
	v_mfma_f32_16x16x32_bf16 v[32:35], v[156:159], v[204:207], v[32:35]
	v_mfma_f32_16x16x32_bf16 v[24:27], v[164:167], v[204:207], v[24:27]
	v_mfma_f32_16x16x32_bf16 v[16:19], v[156:159], v[212:215], v[16:19]
	v_mfma_f32_16x16x32_bf16 v[8:11], v[164:167], v[212:215], v[8:11]
	v_mfma_f32_16x16x32_bf16 v[52:55], v[168:171], v[184:187], v[52:55]
	v_mfma_f32_16x16x32_bf16 v[44:47], v[176:179], v[184:187], v[44:47]
	v_mfma_f32_16x16x32_bf16 v[36:39], v[168:171], v[192:195], v[36:39]
	v_mfma_f32_16x16x32_bf16 v[28:31], v[176:179], v[192:195], v[28:31]
	v_mfma_f32_16x16x32_bf16 v[20:23], v[168:171], v[200:203], v[20:23]
	v_mfma_f32_16x16x32_bf16 v[12:15], v[176:179], v[200:203], v[12:15]
	v_mfma_f32_16x16x32_bf16 v[4:7], v[168:171], v[208:211], v[4:7]
	v_mfma_f32_16x16x32_bf16 v[0:3], v[176:179], v[208:211], v[0:3]
	v_mfma_f32_16x16x32_bf16 v[52:55], v[172:175], v[188:191], v[52:55]
	v_mfma_f32_16x16x32_bf16 v[44:47], v[180:183], v[188:191], v[44:47]
	v_mfma_f32_16x16x32_bf16 v[36:39], v[172:175], v[196:199], v[36:39]
	v_mfma_f32_16x16x32_bf16 v[28:31], v[180:183], v[196:199], v[28:31]
	v_mfma_f32_16x16x32_bf16 v[20:23], v[172:175], v[204:207], v[20:23]
	v_mfma_f32_16x16x32_bf16 v[12:15], v[180:183], v[204:207], v[12:15]
	v_mfma_f32_16x16x32_bf16 v[4:7], v[172:175], v[212:215], v[4:7]
	v_mfma_f32_16x16x32_bf16 v[0:3], v[180:183], v[212:215], v[0:3]
	s_barrier
	s_add_i32 s43, s43, 2
	s_add_u32 s41, s41, 0x100
	s_addc_u32 s42, s42, 0
	s_cmpk_gt_u32 s43, 0x55
	s_mov_b64 s[14:15], s[16:17]
	s_cbranch_scc0 .LBB0_999
	s_and_b64 vcc, exec, s[10:11]
	s_cbranch_vccz .LBB0_1002
	s_barrier
